# prefetch epilogue loads also in gate0/gate1/G7; hoist loads to loop top in P1/P2/P3 token loops
# speedup vs baseline: 1.0167x; 1.0167x over previous
; __global__ void __launch_bounds__(NTHREADS, 2) fwd_megakernel(Params P) {
;     ...
;         _Pragma("unroll 1") for (int rp_ = 0; rp_ < REP_PREP; ++rp_) for (int tok = gw; tok < M; tok += ngw) {
;             const bf16_t* z = Z + (size_t)tok * EV_INP; const int pos = tok_pos(tok);
;             { const u32x4 w = *(const u32x4*)(z + 8 * lane);
;               float v[8] = {bflo(w.x), bfhi(w.x), bflo(w.y), bfhi(w.y), bflo(w.z), bfhi(w.z), bflo(w.w), bfhi(w.w)}; float s = 0.f;
; #pragma unroll
;               for (int j = 0; j < 8; ++j) s += v[j] * v[j];
;               const float ri = 1.0f / sqrtf(wave_sum(s) * (1.f / 512.f) + EPS); const float* g = kp->in[I_QA_NORM] + 8 * lane;
;               u32x4 o; o.x = cvt_pk_bf16(v[0] * ri * g[0], v[1] * ri * g[1]); o.y = cvt_pk_bf16(v[2] * ri * g[2], v[3] * ri * g[3]); o.z = cvt_pk_bf16(v[4] * ri * g[4], v[5] * ri * g[5]); o.w = cvt_pk_bf16(v[6] * ri * g[6], v[7] * ri * g[7]);
;               *(u32x4*)(QN + (size_t)tok * 512 + 8 * lane) = o; }
;             { const u32x2 w = *(const u32x2*)(z + 512 + 4 * lane);
;               float v[4] = {bflo(w.x), bfhi(w.x), bflo(w.y), bfhi(w.y)}; const float s = (v[0] * v[0] + v[1] * v[1]) + (v[2] * v[2] + v[3] * v[3]);
;               const float ri = 1.0f / sqrtf(wave_sum(s) * (1.f / 256.f) + EPS); const float* g = kp->in[I_KVA_NORM] + 4 * lane;
;               u32x2 o; o.x = cvt_pk_bf16(v[0] * ri * g[0], v[1] * ri * g[1]); o.y = cvt_pk_bf16(v[2] * ri * g[2], v[3] * ri * g[3]);
;               *(u32x2*)(KVN + (size_t)tok * 256 + 4 * lane) = o; }
;             { const float v = bf2f(z[768 + lane]); const float ri = 1.0f / sqrtf(wave_sum(v * v) * (1.f / 64.f) + EPS);
;               const float y = v * ri * kp->in[I_KROPE_NORM][lane]; const float yp = __shfl_xor(y, 32);
;               const float c = ROPE64[pos * 32 + (lane & 31)], s = ROPE64[4096 * 32 + pos * 32 + (lane & 31)];
;               const float o = lane < 32 ? y * c - yp * s : y * c + yp * s;
;               KR[(size_t)tok * 64 + lane] = f2bf(o); }
; #pragma unroll
;             for (int p = 0; p < 2; ++p) {
;                 const int d0 = 8 * (lane & 15);
;                 { const u32x4 w = *(const u32x4*)(z + 832 + p * 512 + 8 * lane);
;                   float v[8] = {bflo(w.x), bfhi(w.x), bflo(w.y), bfhi(w.y), bflo(w.z), bfhi(w.z), bflo(w.w), bfhi(w.w)}; float s = 0.f;
; #pragma unroll
.LBB0_170:
	s_andn2_b64 vcc, exec, s[6:7]
	s_cbranch_vccnz .LBB0_165
	s_andn2_b64 vcc, exec, s[38:39]
	s_cbranch_vccnz .LBB0_165
	v_and_b32_e32 v0, 64, v203
	v_add_u32_e32 v0, 64, v0
	v_xor_b32_e32 v17, 1, v203
	v_cmp_lt_i32_e32 vcc, v17, v0
	s_load_dwordx2 s[6:7], s[10:11], 0x60
	v_mov_b64_e32 v[20:21], v[14:15]
	v_cndmask_b32_e32 v17, v203, v17, vcc
	v_lshlrev_b32_e32 v60, 2, v17
	v_xor_b32_e32 v17, 2, v203
	v_cmp_lt_i32_e32 vcc, v17, v0
	v_mov_b64_e32 v[22:23], v[10:11]
	v_mov_b64_e32 v[24:25], v[12:13]
	v_cndmask_b32_e32 v17, v203, v17, vcc
	v_lshlrev_b32_e32 v61, 2, v17
	v_xor_b32_e32 v17, 4, v203
	v_cmp_lt_i32_e32 vcc, v17, v0
	v_mov_b64_e32 v[26:27], v[8:9]
	v_mov_b64_e32 v[28:29], v[6:7]
	v_cndmask_b32_e32 v17, v203, v17, vcc
	v_lshlrev_b32_e32 v62, 2, v17
	v_xor_b32_e32 v17, 8, v203
	v_cmp_lt_i32_e32 vcc, v17, v0
	v_mov_b64_e32 v[30:31], v[4:5]
	v_mov_b64_e32 v[32:33], v[2:3]
	v_cndmask_b32_e32 v17, v203, v17, vcc
	v_lshlrev_b32_e32 v63, 2, v17
	v_xor_b32_e32 v17, 16, v203
	v_cmp_lt_i32_e32 vcc, v17, v0
	s_mov_b32 s70, s34
	s_nop 0
	v_cndmask_b32_e32 v17, v203, v17, vcc
	v_lshlrev_b32_e32 v64, 2, v17
	v_xor_b32_e32 v17, 32, v203
	v_cmp_lt_i32_e32 vcc, v17, v0
	s_nop 1
	v_cndmask_b32_e32 v0, v203, v17, vcc
	v_mov_b32_e32 v17, v1
	v_lshlrev_b32_e32 v65, 2, v0
	s_waitcnt lgkmcnt(0)
	v_lshl_add_u64 v[18:19], s[6:7], 0, v[16:17]
	s_load_dwordx2 s[72:73], s[10:11], 0x70
	s_load_dwordx4 s[16:19], s[10:11], 0x98
	s_load_dwordx2 s[52:53], s[10:11], 0xa8
	s_waitcnt lgkmcnt(0)
.LBB0_173:
	v_mov_b32_e32 v91, v1
	v_lshl_add_u64 v[100:101], s[30:31], 0, v[22:23]
	v_add_co_u32_e32 v102, vcc, 0xec00000, v100
	s_nop 1
	global_load_dwordx2 v[110:111], v[18:19], off
	v_addc_co_u32_e32 v103, vcc, 0, v101, vcc
	s_nop 1
	global_load_dwordx4 v[112:115], v[102:103], off
	s_cmpk_lt_i32 s70, 0x2000
	s_nop 0
	s_cselect_b32 s8, s63, 0x7ff
	s_nop 0
	s_and_b32 s8, s8, s70
	s_nop 0
	v_lshl_or_b32 v90, s8, 7, v58
	v_lshl_add_u64 v[108:109], s[36:37], 0, v[90:91]
	v_add_co_u32_e32 v108, vcc, s65, v108
	s_nop 1
	v_addc_co_u32_e32 v109, vcc, 0, v109, vcc
	s_nop 1
	v_lshl_add_u64 v[104:105], s[30:31], 0, v[24:25]
	v_lshl_add_u64 v[106:107], s[30:31], 0, v[20:21]
	global_load_dwordx2 v[116:117], v[18:19], off offset:8
	global_load_dwordx2 v[118:119], v[18:19], off offset:16
	global_load_dwordx2 v[120:121], v[18:19], off offset:24
	global_load_dwordx2 v[122:123], v[104:105], off
	global_load_dwordx2 v[124:125], v56, s[72:73]
	global_load_dwordx2 v[126:127], v56, s[72:73] offset:8
	global_load_ushort v80, v[106:107], off
	global_load_dword v82, v57, s[16:17]
	global_load_dword v84, v90, s[36:37]
	global_load_dword v86, v[108:109], off
	global_load_dwordx4 v[128:131], v[102:103], off offset:1664
	global_load_dwordx2 v[132:133], v59, s[18:19]
	global_load_dwordx2 v[134:135], v59, s[18:19] offset:8
	global_load_dwordx2 v[136:137], v59, s[18:19] offset:16
	global_load_dwordx2 v[138:139], v59, s[18:19] offset:24
	global_load_dwordx4 v[140:143], v[102:103], off offset:3712
	global_load_dwordx2 v[144:145], v59, s[52:53]
	global_load_dwordx2 v[146:147], v59, s[52:53] offset:8
	global_load_dwordx2 v[148:149], v59, s[52:53] offset:16
	global_load_dwordx2 v[150:151], v59, s[52:53] offset:24
	global_load_dwordx4 v[152:155], v[102:103], off offset:2688
	global_load_dwordx2 v[156:157], v59, s[18:19]
	global_load_dwordx2 v[158:159], v59, s[18:19] offset:8
	v_add_co_u32_e32 v100, vcc, s69, v100
	s_nop 1
	global_load_dwordx2 v[160:161], v59, s[18:19] offset:16
	v_addc_co_u32_e32 v101, vcc, 0, v101, vcc
	s_nop 1
	global_load_dwordx2 v[162:163], v59, s[18:19] offset:24
	global_load_dwordx4 v[164:167], v[100:101], off offset:640
	global_load_dwordx2 v[168:169], v59, s[52:53]
	global_load_dwordx2 v[170:171], v59, s[52:53] offset:8
	global_load_dwordx2 v[172:173], v59, s[52:53] offset:16
	global_load_dwordx2 v[174:175], v59, s[52:53] offset:24
	v_lshl_add_u64 v[34:35], s[30:31], 0, v[22:23]
	v_add_co_u32_e32 v38, vcc, 0xec00000, v34
	s_waitcnt vmcnt(31)
	s_nop 0
	v_mov_b64_e32 v[42:43], v[110:111]
	s_nop 1
	s_nop 0
	v_addc_co_u32_e32 v39, vcc, 0, v35, vcc
	s_waitcnt vmcnt(30)
	s_nop 0
	v_mov_b64_e32 v[66:67], v[112:113]
	v_mov_b64_e32 v[68:69], v[114:115]
	s_nop 1
	s_cmpk_lt_i32 s70, 0x2000
	s_cselect_b32 s8, s63, 0x7ff
	s_and_b32 s8, s8, s70
	v_lshl_or_b32 v0, s8, 7, v58
	v_lshl_add_u64 v[70:71], s[36:37], 0, v[0:1]
	v_add_co_u32_e32 v70, vcc, s65, v70
	v_lshl_add_u64 v[44:45], s[30:31], 0, v[26:27]
	s_nop 0
	v_addc_co_u32_e32 v71, vcc, 0, v71, vcc
	v_lshl_add_u64 v[46:47], s[30:31], 0, v[24:25]
	v_lshl_add_u64 v[48:49], s[30:31], 0, v[30:31]
	v_lshl_add_u64 v[50:51], s[30:31], 0, v[20:21]
	v_lshl_add_u64 v[52:53], s[30:31], 0, v[32:33]
	v_lshl_add_u64 v[40:41], s[30:31], 0, v[28:29]
	v_add_co_u32_e64 v36, s[6:7], s67, v40
	s_add_i32 s70, s70, s26
	v_lshl_add_u64 v[32:33], v[32:33], 0, s[12:13]
	v_lshl_add_u64 v[30:31], v[30:31], 0, s[42:43]
	v_lshl_add_u64 v[28:29], v[28:29], 0, s[44:45]
	v_lshl_add_u64 v[26:27], v[26:27], 0, s[28:29]
	v_lshl_add_u64 v[24:25], v[24:25], 0, s[46:47]
	v_lshl_add_u64 v[22:23], v[22:23], 0, s[46:47]
	v_lshl_add_u64 v[20:21], v[20:21], 0, s[46:47]
	s_cmpk_gt_i32 s70, 0x3fff
	v_and_b32_e32 v37, 0xffff0000, v66
	v_lshlrev_b32_e32 v17, 16, v66
	v_mul_f32_e32 v74, v37, v37
	v_lshlrev_b32_e32 v66, 16, v67
	v_fmac_f32_e32 v74, v17, v17
	v_and_b32_e32 v67, 0xffff0000, v67
	v_fmac_f32_e32 v74, v66, v66
	v_lshlrev_b32_e32 v72, 16, v68
	v_fmac_f32_e32 v74, v67, v67
	v_and_b32_e32 v68, 0xffff0000, v68
	v_fmac_f32_e32 v74, v72, v72
	v_lshlrev_b32_e32 v73, 16, v69
	v_fmac_f32_e32 v74, v68, v68
	v_and_b32_e32 v69, 0xffff0000, v69
	v_fmac_f32_e32 v74, v73, v73
	v_fmac_f32_e32 v74, v69, v69
	ds_bpermute_b32 v75, v60, v74
	s_waitcnt lgkmcnt(0)
; __device__ __forceinline__ unsigned cvt_pk_bf16(float lo, float hi) { unsigned r; asm volatile("v_cvt_pk_bf16_f32 %0, %1, %2" : "=v"(r) : "v"(lo), "v"(hi)); return r; }
; __device__ __forceinline__ float bflo(unsigned w) { return __uint_as_float(w << 16); }
; __device__ __forceinline__ float bfhi(unsigned w) { return __uint_as_float(w & 0xffff0000u); }
; __global__ void __launch_bounds__(NTHREADS, 2) fwd_megakernel(Params P) {
;     ...
;             { const u32x4 w = *(const u32x4*)(z + 8 * lane);
;               float v[8] = {bflo(w.x), bfhi(w.x), bflo(w.y), bfhi(w.y), bflo(w.z), bfhi(w.z), bflo(w.w), bfhi(w.w)}; float s = 0.f;
; #pragma unroll
;               for (int j = 0; j < 8; ++j) s += v[j] * v[j];
;               const float ri = 1.0f / sqrtf(wave_sum(s) * (1.f / 512.f) + EPS); const float* g = kp->in[I_QA_NORM] + 8 * lane;
;               u32x4 o; o.x = cvt_pk_bf16(v[0] * ri * g[0], v[1] * ri * g[1]); o.y = cvt_pk_bf16(v[2] * ri * g[2], v[3] * ri * g[3]); o.z = cvt_pk_bf16(v[4] * ri * g[4], v[5] * ri * g[5]); o.w = cvt_pk_bf16(v[6] * ri * g[6], v[7] * ri * g[7]);
;               *(u32x4*)(QN + (size_t)tok * 512 + 8 * lane) = o; }
;             { const u32x2 w = *(const u32x2*)(z + 512 + 4 * lane);
;               float v[4] = {bflo(w.x), bfhi(w.x), bflo(w.y), bfhi(w.y)}; const float s = (v[0] * v[0] + v[1] * v[1]) + (v[2] * v[2] + v[3] * v[3]);
;               const float ri = 1.0f / sqrtf(wave_sum(s) * (1.f / 256.f) + EPS); const float* g = kp->in[I_KVA_NORM] + 4 * lane;
;               u32x2 o; o.x = cvt_pk_bf16(v[0] * ri * g[0], v[1] * ri * g[1]); o.y = cvt_pk_bf16(v[2] * ri * g[2], v[3] * ri * g[3]);
;               *(u32x2*)(KVN + (size_t)tok * 256 + 4 * lane) = o; }
	v_add_f32_e32 v74, v74, v75
	ds_bpermute_b32 v75, v61, v74
	s_waitcnt lgkmcnt(0)
	v_add_f32_e32 v74, v74, v75
	ds_bpermute_b32 v75, v62, v74
	s_waitcnt lgkmcnt(0)
	v_add_f32_e32 v74, v74, v75
	ds_bpermute_b32 v75, v63, v74
	s_waitcnt lgkmcnt(0)
	v_add_f32_e32 v74, v74, v75
	ds_bpermute_b32 v75, v64, v74
	s_waitcnt lgkmcnt(0)
	v_add_f32_e32 v74, v74, v75
	ds_bpermute_b32 v75, v65, v74
	s_waitcnt lgkmcnt(0)
	v_add_f32_e32 v74, v74, v75
	v_fmamk_f32 v74, v74, 0x3b000000, v54
	v_mul_f32_e32 v75, 0x4f800000, v74
	v_cmp_gt_f32_e32 vcc, s64, v74
	s_nop 1
	v_cndmask_b32_e32 v74, v74, v75, vcc
	v_sqrt_f32_e32 v75, v74
	s_nop 0
	v_add_u32_e32 v76, -1, v75
	v_add_u32_e32 v77, 1, v75
	v_fma_f32 v78, -v76, v75, v74
	v_fma_f32 v79, -v77, v75, v74
	v_cmp_ge_f32_e64 s[8:9], 0, v78
	s_nop 1
	v_cndmask_b32_e64 v75, v75, v76, s[8:9]
	v_cmp_lt_f32_e64 s[8:9], 0, v79
	s_nop 1
	v_cndmask_b32_e64 v75, v75, v77, s[8:9]
	v_mul_f32_e32 v76, 0x37800000, v75
	v_cndmask_b32_e32 v75, v75, v76, vcc
	v_cmp_class_f32_e32 vcc, v74, v55
	s_nop 1
	v_cndmask_b32_e32 v74, v75, v74, vcc
	v_div_scale_f32 v75, s[8:9], v74, v74, 1.0
	v_rcp_f32_e32 v77, v75
	v_div_scale_f32 v76, vcc, 1.0, v74, 1.0
	v_fma_f32 v78, -v75, v77, 1.0
	v_fmac_f32_e32 v77, v78, v77
	v_mul_f32_e32 v78, v76, v77
	v_fma_f32 v79, -v75, v78, v76
	v_fmac_f32_e32 v78, v79, v77
	v_fma_f32 v75, -v75, v78, v76
	v_div_fmas_f32 v75, v75, v77, v78
	v_div_fixup_f32 v74, v75, v74, 1.0
	v_mul_f32_e32 v17, v74, v17
	v_mul_f32_e32 v37, v74, v37
	v_mul_f32_e32 v75, v74, v66
	v_mul_f32_e32 v17, v42, v17
	v_mul_f32_e32 v37, v43, v37
	v_cvt_pk_bf16_f32 v66, v17, v37
	s_waitcnt vmcnt(29)
	s_nop 0
	v_mov_b64_e32 v[42:43], v[116:117]
	s_nop 1
	v_mul_f32_e32 v67, v74, v67
	v_mul_f32_e32 v72, v74, v72
	v_mul_f32_e32 v68, v74, v68
	v_mul_f32_e32 v73, v74, v73
	v_mul_f32_e32 v69, v74, v69
	v_mul_f32_e32 v17, v42, v75
	v_mul_f32_e32 v37, v43, v67
	v_cvt_pk_bf16_f32 v67, v17, v37
	s_waitcnt vmcnt(28)
	s_nop 0
	v_mov_b64_e32 v[42:43], v[118:119]
	s_nop 1
	v_mul_f32_e32 v17, v72, v42
	v_mul_f32_e32 v37, v68, v43
	v_cvt_pk_bf16_f32 v68, v17, v37
	s_waitcnt vmcnt(27)
	s_nop 0
	v_mov_b64_e32 v[42:43], v[120:121]
	s_nop 1
	v_mul_f32_e32 v17, v73, v42
	v_mul_f32_e32 v37, v69, v43
	v_cvt_pk_bf16_f32 v69, v17, v37
	global_store_dwordx4 v[44:45], v[66:69], off
	s_waitcnt vmcnt(27)
	s_nop 0
	v_mov_b64_e32 v[42:43], v[122:123]
	s_nop 1
	s_load_dwordx2 s[72:73], s[10:11], 0x70
	s_load_dwordx4 s[16:19], s[10:11], 0x98
	s_load_dwordx2 s[52:53], s[10:11], 0xa8
	s_waitcnt lgkmcnt(0)
	s_waitcnt vmcnt(26)
	s_nop 0
	v_mov_b64_e32 v[44:45], v[124:125]
	s_nop 1
	v_lshlrev_b32_e32 v17, 16, v42
	v_and_b32_e32 v37, 0xffff0000, v42
	v_lshlrev_b32_e32 v42, 16, v43
	v_and_b32_e32 v43, 0xffff0000, v43
	v_mul_f32_e32 v46, v37, v37
	v_mul_f32_e32 v47, v43, v43
	v_fmac_f32_e32 v46, v17, v17
	v_fmac_f32_e32 v47, v42, v42
	v_add_f32_e32 v46, v46, v47
	ds_bpermute_b32 v47, v60, v46
	s_waitcnt lgkmcnt(0)
	v_add_f32_e32 v46, v46, v47
	ds_bpermute_b32 v47, v61, v46
	s_waitcnt lgkmcnt(0)
	v_add_f32_e32 v46, v46, v47
	ds_bpermute_b32 v47, v62, v46
	s_waitcnt lgkmcnt(0)
	v_add_f32_e32 v46, v46, v47
	ds_bpermute_b32 v47, v63, v46
	s_waitcnt lgkmcnt(0)
	v_add_f32_e32 v46, v46, v47
	ds_bpermute_b32 v47, v64, v46
	s_waitcnt lgkmcnt(0)
	v_add_f32_e32 v46, v46, v47
	ds_bpermute_b32 v47, v65, v46
	s_waitcnt lgkmcnt(0)
	v_add_f32_e32 v46, v46, v47
	v_fmamk_f32 v46, v46, 0x3b800000, v54
	v_mul_f32_e32 v47, 0x4f800000, v46
	v_cmp_gt_f32_e32 vcc, s64, v46
	s_nop 1
	v_cndmask_b32_e32 v46, v46, v47, vcc
	v_sqrt_f32_e32 v47, v46
	s_nop 0
	v_add_u32_e32 v66, -1, v47
	v_add_u32_e32 v67, 1, v47
	v_fma_f32 v68, -v66, v47, v46
	v_fma_f32 v69, -v67, v47, v46
	v_cmp_ge_f32_e64 s[8:9], 0, v68
	s_nop 1
	v_cndmask_b32_e64 v47, v47, v66, s[8:9]
	v_cmp_lt_f32_e64 s[8:9], 0, v69
	s_nop 1
	v_cndmask_b32_e64 v47, v47, v67, s[8:9]
	v_mul_f32_e32 v66, 0x37800000, v47
	v_cndmask_b32_e32 v47, v47, v66, vcc
	v_cmp_class_f32_e32 vcc, v46, v55
	s_nop 1
	v_cndmask_b32_e32 v46, v47, v46, vcc
	v_div_scale_f32 v47, s[8:9], v46, v46, 1.0
	v_rcp_f32_e32 v67, v47
	v_div_scale_f32 v66, vcc, 1.0, v46, 1.0
	v_fma_f32 v68, -v47, v67, 1.0
	v_fmac_f32_e32 v67, v68, v67
	v_mul_f32_e32 v68, v66, v67
	v_fma_f32 v69, -v47, v68, v66
	v_fmac_f32_e32 v68, v69, v67
	v_fma_f32 v47, -v47, v68, v66
	v_div_fmas_f32 v47, v47, v67, v68
	v_div_fixup_f32 v46, v47, v46, 1.0
	v_mul_f32_e32 v17, v46, v17
	v_mul_f32_e32 v37, v46, v37
	v_mul_f32_e32 v47, v46, v42
	v_mul_f32_e32 v17, v44, v17
	v_mul_f32_e32 v37, v45, v37
	v_cvt_pk_bf16_f32 v42, v17, v37
	s_waitcnt vmcnt(25)
	s_nop 0
	v_mov_b64_e32 v[44:45], v[126:127]
	s_nop 1
	v_mul_f32_e32 v43, v46, v43
	v_mul_f32_e32 v17, v44, v47
	v_mul_f32_e32 v37, v45, v43
	v_cvt_pk_bf16_f32 v43, v17, v37
	global_store_dwordx2 v[48:49], v[42:43], off
	s_waitcnt vmcnt(25)
	s_nop 0
	v_mov_b32_e32 v17, v80
	s_nop 1
	s_waitcnt vmcnt(24)
	s_nop 0
	v_mov_b32_e32 v37, v82
	s_nop 1
	s_nop 0
	s_waitcnt vmcnt(23)
	s_nop 0
	v_mov_b32_e32 v0, v84
	s_nop 1
	s_nop 0
	s_waitcnt vmcnt(22)
	s_nop 0
	v_mov_b32_e32 v42, v86
	s_nop 1
	v_lshlrev_b32_e32 v17, 16, v17
	v_mul_f32_e32 v43, v17, v17
	ds_bpermute_b32 v43, v60, v43
	s_waitcnt lgkmcnt(0)
	v_fmac_f32_e32 v43, v17, v17
	ds_bpermute_b32 v44, v61, v43
	s_waitcnt lgkmcnt(0)
	v_add_f32_e32 v43, v43, v44
	ds_bpermute_b32 v44, v62, v43
	s_waitcnt lgkmcnt(0)
	v_add_f32_e32 v43, v43, v44
	ds_bpermute_b32 v44, v63, v43
	s_waitcnt lgkmcnt(0)
	v_add_f32_e32 v43, v43, v44
	ds_bpermute_b32 v44, v64, v43
	s_waitcnt lgkmcnt(0)
	v_add_f32_e32 v43, v43, v44
	ds_bpermute_b32 v44, v65, v43
	s_waitcnt lgkmcnt(0)
; __device__ __forceinline__ unsigned cvt_pk_bf16(float lo, float hi) { unsigned r; asm volatile("v_cvt_pk_bf16_f32 %0, %1, %2" : "=v"(r) : "v"(lo), "v"(hi)); return r; }
; __device__ __forceinline__ float bf2f(unsigned short b) { return __uint_as_float(((unsigned)b) << 16); }
; __device__ __forceinline__ float bflo(unsigned w) { return __uint_as_float(w << 16); }
; __device__ __forceinline__ float bfhi(unsigned w) { return __uint_as_float(w & 0xffff0000u); }
; __device__ __forceinline__ unsigned short f2bf(float f) { return (unsigned short)(cvt_pk_bf16(f, 0.f) & 0xffffu); }
; __global__ void __launch_bounds__(NTHREADS, 2) fwd_megakernel(Params P) {
;     ...
;             { const float v = bf2f(z[768 + lane]); const float ri = 1.0f / sqrtf(wave_sum(v * v) * (1.f / 64.f) + EPS);
;               const float y = v * ri * kp->in[I_KROPE_NORM][lane]; const float yp = __shfl_xor(y, 32);
;               const float c = ROPE64[pos * 32 + (lane & 31)], s = ROPE64[4096 * 32 + pos * 32 + (lane & 31)];
;               const float o = lane < 32 ? y * c - yp * s : y * c + yp * s;
;               KR[(size_t)tok * 64 + lane] = f2bf(o); }
; #pragma unroll
;             for (int p = 0; p < 2; ++p) {
;                 const int d0 = 8 * (lane & 15);
;                 { const u32x4 w = *(const u32x4*)(z + 832 + p * 512 + 8 * lane);
;                   float v[8] = {bflo(w.x), bfhi(w.x), bflo(w.y), bfhi(w.y), bflo(w.z), bfhi(w.z), bflo(w.w), bfhi(w.w)}; float s = 0.f;
; #pragma unroll
;                   for (int j = 0; j < 8; ++j) s += v[j] * v[j];
;                   const float ri = CNA / sqrtf(group_sum<16>(s) * (1.f / 128.f) + EPS); const float* g = kp->in[I_NAQ_NORM] + d0;
;                   u32x4 o; o.x = cvt_pk_bf16(v[0] * ri * g[0], v[1] * ri * g[1]); o.y = cvt_pk_bf16(v[2] * ri * g[2], v[3] * ri * g[3]); o.z = cvt_pk_bf16(v[4] * ri * g[4], v[5] * ri * g[5]); o.w = cvt_pk_bf16(v[6] * ri * g[6], v[7] * ri * g[7]);
;                   *(u32x4*)(NQ + (size_t)tok * 1024 + p * 512 + 8 * lane) = o; }
	v_add_f32_e32 v43, v43, v44
	v_fmamk_f32 v43, v43, 0x3c800000, v54
	v_mul_f32_e32 v44, 0x4f800000, v43
	v_cmp_gt_f32_e32 vcc, s64, v43
	s_nop 1
	v_cndmask_b32_e32 v43, v43, v44, vcc
	v_sqrt_f32_e32 v44, v43
	s_nop 0
	v_add_u32_e32 v45, -1, v44
	v_add_u32_e32 v46, 1, v44
	v_fma_f32 v47, -v45, v44, v43
	v_fma_f32 v48, -v46, v44, v43
	v_cmp_ge_f32_e64 s[8:9], 0, v47
	s_nop 1
	v_cndmask_b32_e64 v44, v44, v45, s[8:9]
	v_cmp_lt_f32_e64 s[8:9], 0, v48
	s_nop 1
	v_cndmask_b32_e64 v44, v44, v46, s[8:9]
	v_mul_f32_e32 v45, 0x37800000, v44
	v_cndmask_b32_e32 v44, v44, v45, vcc
	v_cmp_class_f32_e32 vcc, v43, v55
	s_nop 1
	v_cndmask_b32_e32 v43, v44, v43, vcc
	v_div_scale_f32 v44, s[8:9], v43, v43, 1.0
	v_rcp_f32_e32 v46, v44
	v_div_scale_f32 v45, vcc, 1.0, v43, 1.0
	v_fma_f32 v47, -v44, v46, 1.0
	v_fmac_f32_e32 v46, v47, v46
	v_mul_f32_e32 v47, v45, v46
	v_fma_f32 v48, -v44, v47, v45
	v_fmac_f32_e32 v47, v48, v46
	v_fma_f32 v44, -v44, v47, v45
	v_div_fmas_f32 v44, v44, v46, v47
	v_div_fixup_f32 v43, v44, v43, 1.0
	v_mul_f32_e32 v17, v43, v17
	v_mul_f32_e32 v17, v37, v17
	ds_bpermute_b32 v37, v65, v17
	s_waitcnt lgkmcnt(0)
	v_mul_f32_e32 v37, v42, v37
	v_cndmask_b32_e64 v37, v37, -v37, s[4:5]
	v_fmac_f32_e32 v37, v0, v17
	v_cvt_pk_bf16_f32 v0, v37, v1
	global_store_short v[52:53], v0, off
	s_waitcnt vmcnt(22)
	s_nop 0
	v_mov_b64_e32 v[42:43], v[128:129]
	v_mov_b64_e32 v[44:45], v[130:131]
	s_nop 1
	s_waitcnt vmcnt(21)
	s_nop 0
	v_mov_b64_e32 v[46:47], v[132:133]
	s_nop 1
	v_and_b32_e32 v17, 0xffff0000, v42
	v_lshlrev_b32_e32 v0, 16, v42
	v_lshlrev_b32_e32 v37, 16, v43
	v_and_b32_e32 v42, 0xffff0000, v43
	v_lshlrev_b32_e32 v43, 16, v44
	v_and_b32_e32 v48, 0xffff0000, v44
	v_mul_f32_e32 v44, v17, v17
	v_fmac_f32_e32 v44, v0, v0
	v_fmac_f32_e32 v44, v37, v37
	v_fmac_f32_e32 v44, v42, v42
	v_fmac_f32_e32 v44, v43, v43
	v_lshlrev_b32_e32 v49, 16, v45
	v_fmac_f32_e32 v44, v48, v48
	v_and_b32_e32 v50, 0xffff0000, v45
	v_fmac_f32_e32 v44, v49, v49
	v_fmac_f32_e32 v44, v50, v50
	ds_bpermute_b32 v45, v60, v44
	s_waitcnt lgkmcnt(0)
	v_add_f32_e32 v44, v44, v45
	ds_bpermute_b32 v45, v61, v44
	s_waitcnt lgkmcnt(0)
	v_add_f32_e32 v44, v44, v45
	ds_bpermute_b32 v45, v62, v44
	s_waitcnt lgkmcnt(0)
	v_add_f32_e32 v44, v44, v45
	ds_bpermute_b32 v45, v63, v44
	s_waitcnt lgkmcnt(0)
	v_add_f32_e32 v44, v44, v45
	v_fmamk_f32 v44, v44, 0x3c000000, v54
	v_mul_f32_e32 v45, 0x4f800000, v44
	v_cmp_gt_f32_e32 vcc, s64, v44
	s_nop 1
	v_cndmask_b32_e32 v44, v44, v45, vcc
	v_sqrt_f32_e32 v45, v44
	s_nop 0
	v_add_u32_e32 v51, -1, v45
	v_add_u32_e32 v52, 1, v45
	v_fma_f32 v53, -v51, v45, v44
	v_fma_f32 v66, -v52, v45, v44
	v_cmp_ge_f32_e64 s[8:9], 0, v53
	s_nop 1
	v_cndmask_b32_e64 v45, v45, v51, s[8:9]
	v_cmp_lt_f32_e64 s[8:9], 0, v66
	s_nop 1
	v_cndmask_b32_e64 v45, v45, v52, s[8:9]
	v_mul_f32_e32 v51, 0x37800000, v45
	v_cndmask_b32_e32 v45, v45, v51, vcc
	v_cmp_class_f32_e32 vcc, v44, v55
	s_nop 1
	v_cndmask_b32_e32 v44, v45, v44, vcc
	v_div_scale_f32 v45, s[8:9], v44, v44, s66
	v_rcp_f32_e32 v52, v45
	v_div_scale_f32 v51, vcc, s66, v44, s66
	v_fma_f32 v53, -v45, v52, 1.0
	v_fmac_f32_e32 v52, v53, v52
	v_mul_f32_e32 v53, v51, v52
	v_fma_f32 v66, -v45, v53, v51
	v_fmac_f32_e32 v53, v66, v52
	v_fma_f32 v45, -v45, v53, v51
	v_div_fmas_f32 v45, v45, v52, v53
	v_div_fixup_f32 v51, v45, v44, s66
	v_mul_f32_e32 v0, v51, v0
	v_mul_f32_e32 v17, v51, v17
	v_mul_f32_e32 v52, v51, v42
	v_mul_f32_e32 v0, v46, v0
	v_mul_f32_e32 v17, v47, v17
	v_cvt_pk_bf16_f32 v42, v0, v17
	s_waitcnt vmcnt(20)
	s_nop 0
	v_mov_b64_e32 v[44:45], v[134:135]
	s_nop 1
	v_mul_f32_e32 v37, v51, v37
	v_mul_f32_e32 v53, v51, v43
	v_mul_f32_e32 v0, v44, v37
	v_mul_f32_e32 v17, v45, v52
	v_cvt_pk_bf16_f32 v43, v0, v17
	s_waitcnt vmcnt(19)
	s_nop 0
	v_mov_b64_e32 v[44:45], v[136:137]
	s_nop 1
	v_mul_f32_e32 v0, v51, v48
	v_addc_co_u32_e64 v37, vcc, 0, v41, s[6:7]
	v_mul_f32_e32 v17, v53, v44
	v_mul_f32_e32 v0, v0, v45
	v_cvt_pk_bf16_f32 v44, v17, v0
	s_waitcnt vmcnt(18)
	s_nop 0
	v_mov_b64_e32 v[46:47], v[138:139]
	s_nop 1
	v_mul_f32_e32 v0, v51, v49
	v_mul_f32_e32 v17, v51, v50
	v_mul_f32_e32 v0, v0, v46
	v_mul_f32_e32 v17, v17, v47
	v_cvt_pk_bf16_f32 v45, v0, v17
	global_store_dwordx4 v[36:37], v[42:45], off
	s_waitcnt vmcnt(18)
	s_nop 0
	v_mov_b64_e32 v[42:43], v[140:141]
	v_mov_b64_e32 v[44:45], v[142:143]
	s_nop 1
	s_nop 0
	s_waitcnt vmcnt(17)
	s_nop 0
	v_mov_b64_e32 v[46:47], v[144:145]
	s_nop 1
	v_and_b32_e32 v17, 0xffff0000, v42
	v_lshlrev_b32_e32 v0, 16, v42
	v_mul_f32_e32 v42, v17, v17
	v_lshlrev_b32_e32 v48, 16, v43
	v_fmac_f32_e32 v42, v0, v0
	v_and_b32_e32 v43, 0xffff0000, v43
	v_fmac_f32_e32 v42, v48, v48
	v_lshlrev_b32_e32 v49, 16, v44
	v_fmac_f32_e32 v42, v43, v43
	v_and_b32_e32 v50, 0xffff0000, v44
	v_fmac_f32_e32 v42, v49, v49
	v_lshlrev_b32_e32 v51, 16, v45
	v_fmac_f32_e32 v42, v50, v50
	v_and_b32_e32 v52, 0xffff0000, v45
	v_fmac_f32_e32 v42, v51, v51
	v_fmac_f32_e32 v42, v52, v52
	ds_bpermute_b32 v44, v60, v42
	s_waitcnt lgkmcnt(0)
	v_add_f32_e32 v42, v42, v44
	ds_bpermute_b32 v44, v61, v42
	s_waitcnt lgkmcnt(0)
	v_add_f32_e32 v42, v42, v44
	ds_bpermute_b32 v44, v62, v42
	s_waitcnt lgkmcnt(0)
	v_add_f32_e32 v42, v42, v44
	ds_bpermute_b32 v44, v63, v42
	s_waitcnt lgkmcnt(0)
; __device__ __forceinline__ unsigned cvt_pk_bf16(float lo, float hi) { unsigned r; asm volatile("v_cvt_pk_bf16_f32 %0, %1, %2" : "=v"(r) : "v"(lo), "v"(hi)); return r; }
; __device__ __forceinline__ float bflo(unsigned w) { return __uint_as_float(w << 16); }
; __device__ __forceinline__ float bfhi(unsigned w) { return __uint_as_float(w & 0xffff0000u); }
; __global__ void __launch_bounds__(NTHREADS, 2) fwd_megakernel(Params P) {
;     ...
;                   const float ri = CNA / sqrtf(group_sum<16>(s) * (1.f / 128.f) + EPS); const float* g = kp->in[I_NAQ_NORM] + d0;
;                   u32x4 o; o.x = cvt_pk_bf16(v[0] * ri * g[0], v[1] * ri * g[1]); o.y = cvt_pk_bf16(v[2] * ri * g[2], v[3] * ri * g[3]); o.z = cvt_pk_bf16(v[4] * ri * g[4], v[5] * ri * g[5]); o.w = cvt_pk_bf16(v[6] * ri * g[6], v[7] * ri * g[7]);
;                   *(u32x4*)(NQ + (size_t)tok * 1024 + p * 512 + 8 * lane) = o; }
;                 { const u32x4 w = *(const u32x4*)(z + 1856 + p * 512 + 8 * lane);
;                   float v[8] = {bflo(w.x), bfhi(w.x), bflo(w.y), bfhi(w.y), bflo(w.z), bfhi(w.z), bflo(w.w), bfhi(w.w)}; float s = 0.f;
; #pragma unroll
;                   for (int j = 0; j < 8; ++j) s += v[j] * v[j];
;                   const float ri = 1.0f / sqrtf(group_sum<16>(s) * (1.f / 128.f) + EPS); const float* g = kp->in[I_NAK_NORM] + d0;
;                   u32x4 o; o.x = cvt_pk_bf16(v[0] * ri * g[0], v[1] * ri * g[1]); o.y = cvt_pk_bf16(v[2] * ri * g[2], v[3] * ri * g[3]); o.z = cvt_pk_bf16(v[4] * ri * g[4], v[5] * ri * g[5]); o.w = cvt_pk_bf16(v[6] * ri * g[6], v[7] * ri * g[7]);
;                   *(u32x4*)(NK + (size_t)tok * 1024 + p * 512 + 8 * lane) = o; }
	v_add_f32_e32 v42, v42, v44
	v_fmamk_f32 v42, v42, 0x3c000000, v54
	v_mul_f32_e32 v44, 0x4f800000, v42
	v_cmp_gt_f32_e32 vcc, s64, v42
	s_nop 1
	v_cndmask_b32_e32 v42, v42, v44, vcc
	v_sqrt_f32_e32 v44, v42
	s_nop 0
	v_add_u32_e32 v45, -1, v44
	v_add_u32_e32 v53, 1, v44
	v_fma_f32 v66, -v45, v44, v42
	v_fma_f32 v67, -v53, v44, v42
	v_cmp_ge_f32_e64 s[6:7], 0, v66
	s_nop 1
	v_cndmask_b32_e64 v44, v44, v45, s[6:7]
	v_cmp_lt_f32_e64 s[6:7], 0, v67
	s_nop 1
	v_cndmask_b32_e64 v44, v44, v53, s[6:7]
	v_mul_f32_e32 v45, 0x37800000, v44
	v_cndmask_b32_e32 v44, v44, v45, vcc
	v_cmp_class_f32_e32 vcc, v42, v55
	s_nop 1
	v_cndmask_b32_e32 v42, v44, v42, vcc
	v_div_scale_f32 v44, s[6:7], v42, v42, 1.0
	v_rcp_f32_e32 v53, v44
	v_div_scale_f32 v45, vcc, 1.0, v42, 1.0
	v_fma_f32 v66, -v44, v53, 1.0
	v_fmac_f32_e32 v53, v66, v53
	v_mul_f32_e32 v66, v45, v53
	v_fma_f32 v67, -v44, v66, v45
	v_fmac_f32_e32 v66, v67, v53
	v_fma_f32 v44, -v44, v66, v45
	v_div_fmas_f32 v44, v44, v53, v66
	v_div_fixup_f32 v53, v44, v42, 1.0
	v_mul_f32_e32 v0, v53, v0
	v_mul_f32_e32 v17, v53, v17
	v_mul_f32_e32 v0, v46, v0
	v_mul_f32_e32 v17, v47, v17
	v_cvt_pk_bf16_f32 v42, v0, v17
	s_waitcnt vmcnt(16)
	s_nop 0
	v_mov_b64_e32 v[44:45], v[146:147]
	s_nop 1
	v_mul_f32_e32 v0, v53, v48
	v_mul_f32_e32 v17, v53, v43
	v_add_co_u32_e32 v40, vcc, s68, v40
	v_mul_f32_e32 v0, v44, v0
	v_mul_f32_e32 v17, v45, v17
	v_cvt_pk_bf16_f32 v43, v0, v17
	s_waitcnt vmcnt(15)
	s_nop 0
	v_mov_b64_e32 v[44:45], v[148:149]
	s_nop 1
	v_mul_f32_e32 v0, v53, v49
	v_mul_f32_e32 v17, v53, v50
	v_addc_co_u32_e32 v41, vcc, 0, v41, vcc
	v_mul_f32_e32 v0, v0, v44
	v_mul_f32_e32 v17, v17, v45
	v_cvt_pk_bf16_f32 v44, v0, v17
	s_waitcnt vmcnt(14)
	s_nop 0
	v_mov_b64_e32 v[46:47], v[150:151]
	s_nop 1
	v_mul_f32_e32 v0, v53, v51
	v_mul_f32_e32 v17, v53, v52
	v_mul_f32_e32 v0, v0, v46
	v_mul_f32_e32 v17, v17, v47
	v_cvt_pk_bf16_f32 v45, v0, v17
	global_store_dwordx4 v[40:41], v[42:45], off
	s_waitcnt vmcnt(14)
	s_nop 0
	v_mov_b64_e32 v[42:43], v[152:153]
	v_mov_b64_e32 v[44:45], v[154:155]
	s_nop 1
	s_nop 0
	s_waitcnt vmcnt(13)
	s_nop 0
	v_mov_b64_e32 v[38:39], v[156:157]
	s_nop 1
	v_and_b32_e32 v17, 0xffff0000, v42
	v_lshlrev_b32_e32 v0, 16, v42
	v_mul_f32_e32 v42, v17, v17
	v_lshlrev_b32_e32 v46, 16, v43
	v_fmac_f32_e32 v42, v0, v0
	v_and_b32_e32 v43, 0xffff0000, v43
	v_fmac_f32_e32 v42, v46, v46
	v_lshlrev_b32_e32 v47, 16, v44
	v_fmac_f32_e32 v42, v43, v43
	v_and_b32_e32 v44, 0xffff0000, v44
	v_fmac_f32_e32 v42, v47, v47
	v_lshlrev_b32_e32 v48, 16, v45
	v_fmac_f32_e32 v42, v44, v44
	v_and_b32_e32 v45, 0xffff0000, v45
	v_fmac_f32_e32 v42, v48, v48
	v_fmac_f32_e32 v42, v45, v45
	ds_bpermute_b32 v49, v60, v42
	s_waitcnt lgkmcnt(0)
	v_add_f32_e32 v42, v42, v49
	ds_bpermute_b32 v49, v61, v42
	s_waitcnt lgkmcnt(0)
	v_add_f32_e32 v42, v42, v49
	ds_bpermute_b32 v49, v62, v42
	s_waitcnt lgkmcnt(0)
	v_add_f32_e32 v42, v42, v49
	ds_bpermute_b32 v49, v63, v42
	s_waitcnt lgkmcnt(0)
	v_add_f32_e32 v42, v42, v49
	v_fmamk_f32 v42, v42, 0x3c000000, v54
	v_mul_f32_e32 v49, 0x4f800000, v42
	v_cmp_gt_f32_e32 vcc, s64, v42
	s_nop 1
	v_cndmask_b32_e32 v42, v42, v49, vcc
	v_sqrt_f32_e32 v49, v42
	s_nop 0
	v_add_u32_e32 v50, -1, v49
	v_add_u32_e32 v51, 1, v49
	v_fma_f32 v52, -v50, v49, v42
	v_fma_f32 v53, -v51, v49, v42
	v_cmp_ge_f32_e64 s[6:7], 0, v52
	s_nop 1
	v_cndmask_b32_e64 v49, v49, v50, s[6:7]
	v_cmp_lt_f32_e64 s[6:7], 0, v53
	s_nop 1
	v_cndmask_b32_e64 v49, v49, v51, s[6:7]
	v_mul_f32_e32 v50, 0x37800000, v49
	v_cndmask_b32_e32 v49, v49, v50, vcc
	v_cmp_class_f32_e32 vcc, v42, v55
	s_nop 1
	v_cndmask_b32_e32 v42, v49, v42, vcc
	v_div_scale_f32 v49, s[6:7], v42, v42, s66
	v_rcp_f32_e32 v51, v49
	v_div_scale_f32 v50, vcc, s66, v42, s66
	v_fma_f32 v52, -v49, v51, 1.0
	v_fmac_f32_e32 v51, v52, v51
	v_mul_f32_e32 v52, v50, v51
	v_fma_f32 v53, -v49, v52, v50
	v_fmac_f32_e32 v52, v53, v51
	v_fma_f32 v49, -v49, v52, v50
	v_div_fmas_f32 v49, v49, v51, v52
	v_div_fixup_f32 v49, v49, v42, s66
	v_mul_f32_e32 v0, v49, v0
	v_mul_f32_e32 v17, v49, v17
	v_mul_f32_e32 v0, v38, v0
	v_mul_f32_e32 v17, v39, v17
	v_cvt_pk_bf16_f32 v42, v0, v17
	s_waitcnt vmcnt(12)
; __device__ __forceinline__ unsigned cvt_pk_bf16(float lo, float hi) { unsigned r; asm volatile("v_cvt_pk_bf16_f32 %0, %1, %2" : "=v"(r) : "v"(lo), "v"(hi)); return r; }
; __device__ __forceinline__ float bflo(unsigned w) { return __uint_as_float(w << 16); }
; __device__ __forceinline__ float bfhi(unsigned w) { return __uint_as_float(w & 0xffff0000u); }
; __global__ void __launch_bounds__(NTHREADS, 2) fwd_megakernel(Params P) {
;     ...
;                 const int d0 = 8 * (lane & 15);
;                 { const u32x4 w = *(const u32x4*)(z + 832 + p * 512 + 8 * lane);
;                   float v[8] = {bflo(w.x), bfhi(w.x), bflo(w.y), bfhi(w.y), bflo(w.z), bfhi(w.z), bflo(w.w), bfhi(w.w)}; float s = 0.f;
; #pragma unroll
;                   for (int j = 0; j < 8; ++j) s += v[j] * v[j];
;                   const float ri = CNA / sqrtf(group_sum<16>(s) * (1.f / 128.f) + EPS); const float* g = kp->in[I_NAQ_NORM] + d0;
;                   u32x4 o; o.x = cvt_pk_bf16(v[0] * ri * g[0], v[1] * ri * g[1]); o.y = cvt_pk_bf16(v[2] * ri * g[2], v[3] * ri * g[3]); o.z = cvt_pk_bf16(v[4] * ri * g[4], v[5] * ri * g[5]); o.w = cvt_pk_bf16(v[6] * ri * g[6], v[7] * ri * g[7]);
;                   *(u32x4*)(NQ + (size_t)tok * 1024 + p * 512 + 8 * lane) = o; }
;                 { const u32x4 w = *(const u32x4*)(z + 1856 + p * 512 + 8 * lane);
;                   float v[8] = {bflo(w.x), bfhi(w.x), bflo(w.y), bfhi(w.y), bflo(w.z), bfhi(w.z), bflo(w.w), bfhi(w.w)}; float s = 0.f;
; #pragma unroll
;                   for (int j = 0; j < 8; ++j) s += v[j] * v[j];
;                   const float ri = 1.0f / sqrtf(group_sum<16>(s) * (1.f / 128.f) + EPS); const float* g = kp->in[I_NAK_NORM] + d0;
;                   u32x4 o; o.x = cvt_pk_bf16(v[0] * ri * g[0], v[1] * ri * g[1]); o.y = cvt_pk_bf16(v[2] * ri * g[2], v[3] * ri * g[3]); o.z = cvt_pk_bf16(v[4] * ri * g[4], v[5] * ri * g[5]); o.w = cvt_pk_bf16(v[6] * ri * g[6], v[7] * ri * g[7]);
;                   *(u32x4*)(NK + (size_t)tok * 1024 + p * 512 + 8 * lane) = o; }
;             }
	s_nop 0
	v_mov_b64_e32 v[38:39], v[158:159]
	s_nop 1
	v_mul_f32_e32 v0, v49, v46
	v_mul_f32_e32 v17, v49, v43
	v_add_co_u32_e32 v34, vcc, s69, v34
	v_mul_f32_e32 v0, v38, v0
	v_mul_f32_e32 v17, v39, v17
	v_cvt_pk_bf16_f32 v43, v0, v17
	s_waitcnt vmcnt(11)
	s_nop 0
	v_mov_b64_e32 v[38:39], v[160:161]
	s_nop 1
	v_mul_f32_e32 v0, v49, v47
	v_mul_f32_e32 v17, v49, v44
	v_addc_co_u32_e32 v35, vcc, 0, v35, vcc
	v_mul_f32_e32 v0, v0, v38
	v_mul_f32_e32 v17, v17, v39
	v_cvt_pk_bf16_f32 v44, v0, v17
	s_waitcnt vmcnt(10)
	s_nop 0
	v_mov_b64_e32 v[38:39], v[162:163]
	s_nop 1
	v_mul_f32_e32 v0, v49, v48
	v_mul_f32_e32 v17, v49, v45
	v_mul_f32_e32 v0, v0, v38
	v_mul_f32_e32 v17, v17, v39
	v_cvt_pk_bf16_f32 v45, v0, v17
	global_store_dwordx4 v[36:37], v[42:45], off offset:1024
	s_waitcnt vmcnt(10)
	s_nop 0
	v_mov_b64_e32 v[34:35], v[164:165]
	v_mov_b64_e32 v[36:37], v[166:167]
	s_nop 1
	s_nop 0
	s_waitcnt vmcnt(9)
	s_nop 0
	v_mov_b64_e32 v[38:39], v[168:169]
	s_nop 1
	v_and_b32_e32 v17, 0xffff0000, v34
	v_lshlrev_b32_e32 v0, 16, v34
	v_mul_f32_e32 v34, v17, v17
	v_lshlrev_b32_e32 v42, 16, v35
	v_fmac_f32_e32 v34, v0, v0
	v_and_b32_e32 v35, 0xffff0000, v35
	v_fmac_f32_e32 v34, v42, v42
	v_lshlrev_b32_e32 v43, 16, v36
	v_fmac_f32_e32 v34, v35, v35
	v_and_b32_e32 v44, 0xffff0000, v36
	v_fmac_f32_e32 v34, v43, v43
	v_lshlrev_b32_e32 v45, 16, v37
	v_fmac_f32_e32 v34, v44, v44
	v_and_b32_e32 v46, 0xffff0000, v37
	v_fmac_f32_e32 v34, v45, v45
	v_fmac_f32_e32 v34, v46, v46
	ds_bpermute_b32 v36, v60, v34
	s_waitcnt lgkmcnt(0)
	v_add_f32_e32 v34, v34, v36
	ds_bpermute_b32 v36, v61, v34
	s_waitcnt lgkmcnt(0)
	v_add_f32_e32 v34, v34, v36
	ds_bpermute_b32 v36, v62, v34
	s_waitcnt lgkmcnt(0)
	v_add_f32_e32 v34, v34, v36
	ds_bpermute_b32 v36, v63, v34
	s_waitcnt lgkmcnt(0)
	v_add_f32_e32 v34, v34, v36
	v_fmamk_f32 v34, v34, 0x3c000000, v54
	v_mul_f32_e32 v36, 0x4f800000, v34
	v_cmp_gt_f32_e32 vcc, s64, v34
	s_nop 1
	v_cndmask_b32_e32 v34, v34, v36, vcc
	v_sqrt_f32_e32 v36, v34
	s_nop 0
	v_add_u32_e32 v37, -1, v36
	v_add_u32_e32 v47, 1, v36
	v_fma_f32 v48, -v37, v36, v34
	v_fma_f32 v49, -v47, v36, v34
	v_cmp_ge_f32_e64 s[6:7], 0, v48
	s_nop 1
	v_cndmask_b32_e64 v36, v36, v37, s[6:7]
	v_cmp_lt_f32_e64 s[6:7], 0, v49
	s_nop 1
	v_cndmask_b32_e64 v36, v36, v47, s[6:7]
	v_mul_f32_e32 v37, 0x37800000, v36
	v_cndmask_b32_e32 v36, v36, v37, vcc
	v_cmp_class_f32_e32 vcc, v34, v55
	s_nop 1
	v_cndmask_b32_e32 v34, v36, v34, vcc
	v_div_scale_f32 v36, s[6:7], v34, v34, 1.0
	v_rcp_f32_e32 v47, v36
	v_div_scale_f32 v37, vcc, 1.0, v34, 1.0
	v_fma_f32 v48, -v36, v47, 1.0
	v_fmac_f32_e32 v47, v48, v47
	v_mul_f32_e32 v48, v37, v47
	v_fma_f32 v49, -v36, v48, v37
	v_fmac_f32_e32 v48, v49, v47
	v_fma_f32 v36, -v36, v48, v37
	v_div_fmas_f32 v36, v36, v47, v48
	v_div_fixup_f32 v47, v36, v34, 1.0
	v_mul_f32_e32 v0, v47, v0
	v_mul_f32_e32 v17, v47, v17
	v_mul_f32_e32 v0, v38, v0
	v_mul_f32_e32 v17, v39, v17
	v_cvt_pk_bf16_f32 v34, v0, v17
	s_waitcnt vmcnt(8)
	s_nop 0
	v_mov_b64_e32 v[36:37], v[170:171]
	s_nop 1
	v_mul_f32_e32 v0, v47, v42
	v_mul_f32_e32 v17, v47, v35
	v_mul_f32_e32 v0, v36, v0
	v_mul_f32_e32 v17, v37, v17
	v_cvt_pk_bf16_f32 v35, v0, v17
	s_waitcnt vmcnt(7)
	s_nop 0
	v_mov_b64_e32 v[36:37], v[172:173]
	s_nop 1
	v_mul_f32_e32 v0, v47, v43
	v_mul_f32_e32 v17, v47, v44
	v_mul_f32_e32 v0, v0, v36
	v_mul_f32_e32 v17, v17, v37
	v_cvt_pk_bf16_f32 v36, v0, v17
	s_waitcnt vmcnt(6)
	s_nop 0
	v_mov_b64_e32 v[38:39], v[174:175]
	s_nop 1
	v_mul_f32_e32 v0, v47, v45
	v_mul_f32_e32 v17, v47, v46
	v_mul_f32_e32 v0, v0, v38
	v_mul_f32_e32 v17, v17, v39
	v_cvt_pk_bf16_f32 v37, v0, v17
	global_store_dwordx4 v[40:41], v[34:37], off offset:1024
	s_cbranch_scc0 .LBB0_173
	s_branch .LBB0_165

; __device__ __forceinline__ float bflo(unsigned w) { return __uint_as_float(w << 16); }
; __device__ __forceinline__ float bfhi(unsigned w) { return __uint_as_float(w & 0xffff0000u); }
; __global__ void __launch_bounds__(NTHREADS, 2) fwd_megakernel(Params P) {
;     ...
;         _Pragma("unroll 1") for (int rp_ = 0; rp_ < REP_PREP; ++rp_) for (int tok = gw; tok < M; tok += ngw) {
;             const int pos = tok_pos(tok);
;             const bf16_t* q = Q1 + (size_t)tok * 1536 + hq * 192; bf16_t* qo = QM + (size_t)tok * 1536 + hq * 192;
;             const bf16_t* k = KV1 + (size_t)tok * 2048 + hq * 256; bf16_t* ko = KM + (size_t)tok * 1536 + hq * 192;
;             const u32x4 qa = *(const u32x4*)(q + sl * 16), qb = *(const u32x4*)(q + sl * 16 + 8), qr = *(const u32x4*)(q + 128 + sl * 8);
;             const u32x4 ka = *(const u32x4*)(k + sl * 16), kb = *(const u32x4*)(k + sl * 16 + 8), krv = *(const u32x4*)(KR + (size_t)tok * 64 + sl * 8);
;             const f32x4 c0 = *(const f32x4*)(ROPE64 + pos * 32 + (sl & 3) * 8), c1 = *(const f32x4*)(ROPE64 + pos * 32 + (sl & 3) * 8 + 4);
;             const f32x4 s0 = *(const f32x4*)(ROPE64 + 4096 * 32 + pos * 32 + (sl & 3) * 8), s1 = *(const f32x4*)(ROPE64 + 4096 * 32 + pos * 32 + (sl & 3) * 8 + 4);
;             { float v[16] = {bflo(qa.x), bfhi(qa.x), bflo(qa.y), bfhi(qa.y), bflo(qa.z), bfhi(qa.z), bflo(qa.w), bfhi(qa.w), bflo(qb.x), bfhi(qb.x), bflo(qb.y), bfhi(qb.y), bflo(qb.z), bfhi(qb.z), bflo(qb.w), bfhi(qb.w)};
;               float ss = 0.f;
; #pragma unroll
;               for (int j = 0; j < 16; ++j) ss += v[j] * v[j];
.LBB0_314:
	v_lshl_add_u64 v[168:169], s[18:19], 0, v[70:71]
	v_lshl_add_u64 v[166:167], s[18:19], 0, v[72:73]
	v_add_co_u32_e32 v156, vcc, 0xec00000, v168
	s_nop 1
	s_cmpk_lt_i32 s65, 0x2000
	s_nop 0
	v_addc_co_u32_e32 v157, vcc, 0, v169, vcc
	s_nop 1
	s_cselect_b32 s8, s58, 0x7ff
	s_nop 0
	v_add_co_u32_e32 v160, vcc, s59, v166
	s_nop 1
	v_lshl_add_u64 v[150:151], s[18:19], 0, v[74:75]
	v_lshl_add_u64 v[154:155], v[168:169], 0, s[46:47]
	s_and_b32 s6, s8, s65
	s_nop 0
	global_load_dwordx4 v[172:175], v[156:157], off
	global_load_dwordx4 v[176:179], v[154:155], off offset:16
	v_addc_co_u32_e32 v161, vcc, 0, v167, vcc
	s_nop 1
	v_lshl_add_u64 v[158:159], v[150:151], 0, s[36:37]
	v_add_co_u32_e32 v150, vcc, s60, v150
	s_nop 1
	s_lshl_b32 s44, s6, 7
	s_nop 0
	global_load_dwordx4 v[180:183], v[160:161], off offset:256
	global_load_dwordx4 v[184:187], v[158:159], off offset:16
	v_lshl_add_u64 v[152:153], s[18:19], 0, v[76:77]
	v_addc_co_u32_e32 v151, vcc, 0, v151, vcc
	s_nop 1
	v_lshl_add_u64 v[162:163], v[58:59], 0, s[44:45]
	v_lshl_add_u64 v[164:165], v[60:61], 0, s[44:45]
	global_load_dwordx4 v[188:191], v[162:163], off
	global_load_dwordx4 v[192:195], v[164:165], off
	global_load_dwordx4 v[196:199], v[162:163], off offset:16
	global_load_dwordx4 v[204:207], v[164:165], off offset:16
	global_load_dwordx4 v[208:211], v[150:151], off
	global_load_dwordx4 v[212:215], v[152:153], off
	v_lshl_add_u64 v[80:81], s[18:19], 0, v[70:71]
	v_add_co_u32_e64 v84, s[6:7], s63, v80
	v_lshl_add_u64 v[78:79], s[18:19], 0, v[72:73]
	v_add_co_u32_e32 v46, vcc, 0xec00000, v80
	v_addc_co_u32_e64 v85, s[6:7], 0, v81, s[6:7]
	s_cmpk_lt_i32 s65, 0x2000
	v_add_co_u32_e64 v82, s[6:7], s63, v78
	v_addc_co_u32_e32 v47, vcc, 0, v81, vcc
	s_cselect_b32 s8, s58, 0x7ff
	v_addc_co_u32_e64 v83, s[6:7], 0, v79, s[6:7]
	v_add_co_u32_e32 v50, vcc, s59, v78
	v_lshl_add_u64 v[40:41], s[18:19], 0, v[74:75]
	v_lshl_add_u64 v[44:45], v[80:81], 0, s[46:47]
	s_and_b32 s6, s8, s65
	s_waitcnt vmcnt(9)
	s_nop 0
	v_mov_b64_e32 v[86:87], v[172:173]
	v_mov_b64_e32 v[88:89], v[174:175]
	s_nop 1
	s_waitcnt vmcnt(8)
	s_nop 0
	v_mov_b64_e32 v[94:95], v[176:177]
	v_mov_b64_e32 v[96:97], v[178:179]
	s_nop 1
	v_addc_co_u32_e32 v51, vcc, 0, v79, vcc
	v_lshl_add_u64 v[48:49], v[40:41], 0, s[36:37]
	v_add_co_u32_e32 v40, vcc, s60, v40
	s_lshl_b32 s44, s6, 7
	s_waitcnt vmcnt(7)
	s_nop 0
	v_mov_b64_e32 v[98:99], v[180:181]
	v_mov_b64_e32 v[100:101], v[182:183]
	s_nop 1
	s_waitcnt vmcnt(6)
	s_nop 0
	v_mov_b64_e32 v[102:103], v[184:185]
	v_mov_b64_e32 v[104:105], v[186:187]
	s_nop 1
	v_lshl_add_u64 v[42:43], s[18:19], 0, v[76:77]
	v_addc_co_u32_e32 v41, vcc, 0, v41, vcc
	v_lshl_add_u64 v[52:53], v[58:59], 0, s[44:45]
	v_lshl_add_u64 v[54:55], v[60:61], 0, s[44:45]
	s_waitcnt vmcnt(5)
	s_nop 0
	v_mov_b64_e32 v[44:45], v[188:189]
	v_mov_b64_e32 v[46:47], v[190:191]
	s_nop 1
	s_waitcnt vmcnt(4)
	s_nop 0
	v_mov_b64_e32 v[48:49], v[192:193]
	v_mov_b64_e32 v[50:51], v[194:195]
	s_nop 1
	s_waitcnt vmcnt(3)
	s_nop 0
	v_mov_b64_e32 v[106:107], v[196:197]
	v_mov_b64_e32 v[108:109], v[198:199]
	s_nop 1
	s_nop 0
	s_waitcnt vmcnt(2)
	s_nop 0
	v_mov_b64_e32 v[52:53], v[204:205]
	v_mov_b64_e32 v[54:55], v[206:207]
	s_nop 1
	s_nop 0
	s_waitcnt vmcnt(1)
	s_nop 0
	v_mov_b64_e32 v[110:111], v[208:209]
	v_mov_b64_e32 v[112:113], v[210:211]
	s_nop 1
	s_nop 0
	s_waitcnt vmcnt(0)
	s_nop 0
	v_mov_b64_e32 v[40:41], v[212:213]
	v_mov_b64_e32 v[42:43], v[214:215]
	s_nop 1
	s_add_i32 s65, s65, s26
	v_lshl_add_u64 v[76:77], v[76:77], 0, s[12:13]
	v_lshl_add_u64 v[74:75], v[74:75], 0, s[34:35]
	v_lshl_add_u64 v[72:73], v[72:73], 0, s[42:43]
	v_lshl_add_u64 v[70:71], v[70:71], 0, s[42:43]
	s_cmpk_gt_i32 s65, 0x3fff
	v_and_b32_e32 v115, 0xffff0000, v86
	v_lshlrev_b32_e32 v114, 16, v86
	v_mul_f32_e32 v128, v115, v115
	v_lshlrev_b32_e32 v116, 16, v87
	v_fmac_f32_e32 v128, v114, v114
	v_and_b32_e32 v117, 0xffff0000, v87
	v_lshlrev_b32_e32 v120, 16, v89
	v_and_b32_e32 v130, 0xffff0000, v98
	v_lshlrev_b32_e32 v129, 16, v98
	v_mul_f32_e32 v141, v130, v130
	v_and_b32_e32 v121, 0xffff0000, v89
	v_lshlrev_b32_e32 v131, 16, v99
	v_mov_b32_e32 v89, v54
	v_mov_b32_e32 v54, v109
	v_and_b32_e32 v109, 0xffff0000, v110
	v_fmac_f32_e32 v128, v116, v116
	v_fmac_f32_e32 v141, v129, v129
	v_lshlrev_b32_e32 v118, 16, v88
	v_and_b32_e32 v132, 0xffff0000, v99
	v_mov_b32_e32 v86, v46
	v_mov_b32_e32 v87, v50
	v_mov_b32_e32 v50, v47
	v_mov_b32_e32 v46, v106
	v_mov_b32_e32 v47, v52
	v_mov_b32_e32 v52, v107
	v_lshlrev_b32_e32 v107, 16, v110
	v_mul_f32_e32 v106, v109, v109
	v_fmac_f32_e32 v128, v117, v117
	v_fmac_f32_e32 v141, v131, v131
	v_and_b32_e32 v119, 0xffff0000, v88
	v_lshlrev_b32_e32 v133, 16, v100
	v_lshlrev_b32_e32 v142, 16, v111
	v_fmac_f32_e32 v106, v107, v107
	v_fmac_f32_e32 v128, v118, v118
	v_fmac_f32_e32 v141, v132, v132
	v_and_b32_e32 v134, 0xffff0000, v100
	v_lshlrev_b32_e32 v98, 16, v101
	v_and_b32_e32 v99, 0xffff0000, v101
	v_and_b32_e32 v111, 0xffff0000, v111
	v_fmac_f32_e32 v106, v142, v142
	v_fmac_f32_e32 v128, v119, v119
	v_fmac_f32_e32 v141, v133, v133
	v_pk_mul_f32 v[100:101], v[98:99], v[98:99]
	v_lshlrev_b32_e32 v143, 16, v112
	v_fmac_f32_e32 v106, v111, v111
	v_fmac_f32_e32 v128, v120, v120
	v_fmac_f32_e32 v141, v134, v134
	v_lshlrev_b32_e32 v122, 16, v94
	v_and_b32_e32 v144, 0xffff0000, v112
	v_fmac_f32_e32 v106, v143, v143
	v_fmac_f32_e32 v128, v121, v121
	v_add_f32_e32 v100, v141, v100
	v_and_b32_e32 v123, 0xffff0000, v94
	v_lshlrev_b32_e32 v145, 16, v113
	v_fmac_f32_e32 v106, v144, v144
	v_fmac_f32_e32 v128, v122, v122
	v_add_f32_e32 v100, v100, v101
	v_lshlrev_b32_e32 v124, 16, v95
	v_and_b32_e32 v113, 0xffff0000, v113
	v_fmac_f32_e32 v106, v145, v145
	v_fmac_f32_e32 v128, v123, v123
	ds_bpermute_b32 v101, v56, v100
	v_and_b32_e32 v125, 0xffff0000, v95
	v_lshlrev_b32_e32 v135, 16, v102
	v_fmac_f32_e32 v106, v113, v113
	v_fmac_f32_e32 v128, v124, v124
	v_lshlrev_b32_e32 v126, 16, v96
	v_and_b32_e32 v136, 0xffff0000, v102
	v_fmac_f32_e32 v106, v135, v135
	v_fmac_f32_e32 v128, v125, v125
	v_and_b32_e32 v127, 0xffff0000, v96
	v_lshlrev_b32_e32 v94, 16, v97
	v_and_b32_e32 v95, 0xffff0000, v97
	v_lshlrev_b32_e32 v137, 16, v103
	v_fmac_f32_e32 v106, v136, v136
	v_fmac_f32_e32 v128, v126, v126
	v_pk_mul_f32 v[96:97], v[94:95], v[94:95]
	v_and_b32_e32 v138, 0xffff0000, v103
	v_fmac_f32_e32 v106, v137, v137
	v_fmac_f32_e32 v128, v127, v127
	v_lshlrev_b32_e32 v139, 16, v104
	v_fmac_f32_e32 v106, v138, v138
	v_add_f32_e32 v96, v128, v96
	s_waitcnt lgkmcnt(0)
; __device__ __forceinline__ unsigned cvt_pk_bf16(float lo, float hi) { unsigned r; asm volatile("v_cvt_pk_bf16_f32 %0, %1, %2" : "=v"(r) : "v"(lo), "v"(hi)); return r; }
; __device__ __forceinline__ float bflo(unsigned w) { return __uint_as_float(w << 16); }
; __global__ void __launch_bounds__(NTHREADS, 2) fwd_megakernel(Params P) {
;     ...
;             { float v[16] = {bflo(qa.x), bfhi(qa.x), bflo(qa.y), bfhi(qa.y), bflo(qa.z), bfhi(qa.z), bflo(qa.w), bfhi(qa.w), bflo(qb.x), bfhi(qb.x), bflo(qb.y), bfhi(qb.y), bflo(qb.z), bfhi(qb.z), bflo(qb.w), bfhi(qb.w)};
;               float ss = 0.f;
; #pragma unroll
;               for (int j = 0; j < 16; ++j) ss += v[j] * v[j];
;               const float ri = CM / sqrtf(group_sum<8>(ss) * (1.f / 128.f) + EPS);
;               u32x4 o0, o1;
;               o0.x = cvt_pk_bf16(v[0] * ri * gqn[0], v[1] * ri * gqn[1]); o0.y = cvt_pk_bf16(v[2] * ri * gqn[2], v[3] * ri * gqn[3]); o0.z = cvt_pk_bf16(v[4] * ri * gqn[4], v[5] * ri * gqn[5]); o0.w = cvt_pk_bf16(v[6] * ri * gqn[6], v[7] * ri * gqn[7]);
;               o1.x = cvt_pk_bf16(v[8] * ri * gqn[8], v[9] * ri * gqn[9]); o1.y = cvt_pk_bf16(v[10] * ri * gqn[10], v[11] * ri * gqn[11]); o1.z = cvt_pk_bf16(v[12] * ri * gqn[12], v[13] * ri * gqn[13]); o1.w = cvt_pk_bf16(v[14] * ri * gqn[14], v[15] * ri * gqn[15]);
;               *(u32x4*)(qo + sl * 16) = o0; *(u32x4*)(qo + sl * 16 + 8) = o1; }
;             { float v[8] = {bflo(qr.x), bfhi(qr.x), bflo(qr.y), bfhi(qr.y), bflo(qr.z), bfhi(qr.z), bflo(qr.w), bfhi(qr.w)};
;               const float cc[8] = {c0[0], c0[1], c0[2], c0[3], c1[0], c1[1], c1[2], c1[3]}, sn[8] = {s0[0], s0[1], s0[2], s0[3], s1[0], s1[1], s1[2], s1[3]};
;               float ss = 0.f;
; #pragma unroll
;               for (int j = 0; j < 8; ++j) ss += v[j] * v[j];
;               const float ri = 1.0f / sqrtf(group_sum<8>(ss) * (1.f / 64.f) + EPS);
;               float o[8];
; #pragma unroll
;               for (int j = 0; j < 8; ++j) { const float y = v[j] * ri * gqr[j]; const float yp = __shfl_xor(y, 4); o[j] = (sl < 4 ? y * cc[j] - yp * sn[j] : y * cc[j] + yp * sn[j]) * CM; }
;               u32x4 w; w.x = cvt_pk_bf16(o[0], o[1]); w.y = cvt_pk_bf16(o[2], o[3]); w.z = cvt_pk_bf16(o[4], o[5]); w.w = cvt_pk_bf16(o[6], o[7]);
;               *(u32x4*)(qo + 128 + sl * 8) = w; }
	v_add_f32_e32 v100, v100, v101
	v_and_b32_e32 v140, 0xffff0000, v104
	v_lshlrev_b32_e32 v102, 16, v105
	v_and_b32_e32 v103, 0xffff0000, v105
	v_fmac_f32_e32 v106, v139, v139
	v_add_f32_e32 v96, v96, v97
	ds_bpermute_b32 v97, v92, v100
	v_pk_mul_f32 v[104:105], v[102:103], v[102:103]
	v_fmac_f32_e32 v106, v140, v140
	ds_bpermute_b32 v101, v56, v96
	v_add_f32_e32 v104, v106, v104
	v_add_f32_e32 v104, v104, v105
	ds_bpermute_b32 v105, v56, v104
	s_waitcnt lgkmcnt(2)
	v_add_f32_e32 v97, v100, v97
	s_waitcnt lgkmcnt(1)
	v_add_f32_e32 v96, v96, v101
	ds_bpermute_b32 v100, v93, v97
	ds_bpermute_b32 v101, v92, v96
	s_waitcnt lgkmcnt(2)
	v_add_f32_e32 v104, v104, v105
	ds_bpermute_b32 v105, v92, v104
	v_mov_b32_e32 v88, v108
	s_waitcnt lgkmcnt(2)
	v_add_f32_e32 v97, v97, v100
	s_waitcnt lgkmcnt(1)
	v_add_f32_e32 v96, v96, v101
	v_fmamk_f32 v97, v97, 0x3c800000, v90
	ds_bpermute_b32 v100, v93, v96
	v_mul_f32_e32 v101, 0x4f800000, v97
	v_cmp_gt_f32_e32 vcc, s61, v97
	s_waitcnt lgkmcnt(0)
	v_add_f32_e32 v96, v96, v100
	v_cndmask_b32_e32 v97, v97, v101, vcc
	v_add_f32_e32 v101, v104, v105
	v_sqrt_f32_e32 v104, v97
	ds_bpermute_b32 v105, v93, v101
	v_fmamk_f32 v96, v96, 0x3c000000, v90
	v_mul_f32_e32 v108, 0x4f800000, v96
	v_add_u32_e32 v100, -1, v104
	v_add_u32_e32 v106, 1, v104
	v_fma_f32 v110, -v100, v104, v97
	v_cmp_gt_f32_e64 s[6:7], s61, v96
	v_fma_f32 v112, -v106, v104, v97
	s_waitcnt lgkmcnt(0)
	v_add_f32_e32 v101, v101, v105
	v_cndmask_b32_e64 v96, v96, v108, s[6:7]
	v_cmp_ge_f32_e64 s[8:9], 0, v110
	v_fmamk_f32 v101, v101, 0x3c000000, v90
	v_mul_f32_e32 v105, 0x4f800000, v101
	v_cndmask_b32_e64 v100, v104, v100, s[8:9]
	v_cmp_lt_f32_e64 s[8:9], 0, v112
	v_sqrt_f32_e32 v104, v96
	s_nop 0
	v_cndmask_b32_e64 v100, v100, v106, s[8:9]
	v_cmp_gt_f32_e64 s[8:9], s61, v101
	v_mul_f32_e32 v106, 0x37800000, v100
	v_cndmask_b32_e32 v100, v100, v106, vcc
	v_cndmask_b32_e64 v101, v101, v105, s[8:9]
	v_sqrt_f32_e32 v105, v101
	v_cmp_class_f32_e32 vcc, v97, v91
	v_add_u32_e32 v106, 1, v104
	v_fma_f32 v128, -v106, v104, v96
	v_cndmask_b32_e32 v97, v100, v97, vcc
	v_add_u32_e32 v100, -1, v104
	v_fma_f32 v112, -v100, v104, v96
	v_cmp_ge_f32_e32 vcc, 0, v112
	v_div_scale_f32 v108, s[10:11], v97, v97, 1.0
	s_nop 0
	v_cndmask_b32_e32 v100, v104, v100, vcc
	v_add_u32_e32 v104, -1, v105
	v_cmp_lt_f32_e32 vcc, 0, v128
	v_rcp_f32_e32 v141, v108
	v_add_u32_e32 v112, 1, v105
	v_cndmask_b32_e32 v100, v100, v106, vcc
	v_fma_f32 v106, -v104, v105, v101
	v_fma_f32 v128, -v112, v105, v101
	v_cmp_ge_f32_e32 vcc, 0, v106
	v_mul_f32_e32 v146, 0x37800000, v100
	v_cndmask_b32_e64 v100, v100, v146, s[6:7]
	v_cndmask_b32_e32 v104, v105, v104, vcc
	v_cmp_lt_f32_e32 vcc, 0, v128
	v_fma_f32 v105, -v108, v141, 1.0
	v_div_scale_f32 v110, s[10:11], 1.0, v97, 1.0
	v_cndmask_b32_e32 v104, v104, v112, vcc
	v_cmp_class_f32_e32 vcc, v96, v91
	v_fmac_f32_e32 v141, v105, v141
	v_mul_f32_e32 v112, v110, v141
	v_cndmask_b32_e32 v96, v100, v96, vcc
	v_mul_f32_e32 v100, 0x37800000, v104
	v_div_scale_f32 v105, s[6:7], v96, v96, s62
	v_cndmask_b32_e64 v100, v104, v100, s[8:9]
	v_cmp_class_f32_e64 s[6:7], v101, v91
	v_rcp_f32_e32 v104, v105
	v_fma_f32 v128, -v108, v112, v110
	v_cndmask_b32_e64 v100, v100, v101, s[6:7]
	v_fmac_f32_e32 v112, v128, v141
	v_div_scale_f32 v101, s[6:7], v100, v100, 1.0
	v_fma_f32 v108, -v108, v112, v110
	v_rcp_f32_e32 v110, v101
	v_fma_f32 v146, -v105, v104, 1.0
	v_div_scale_f32 v106, vcc, s62, v96, s62
	v_fmac_f32_e32 v104, v146, v104
	v_mul_f32_e32 v146, v106, v104
	v_fma_f32 v147, -v101, v110, 1.0
	v_fma_f32 v148, -v105, v146, v106
	v_div_scale_f32 v128, s[6:7], 1.0, v100, 1.0
	v_fmac_f32_e32 v110, v147, v110
	v_fmac_f32_e32 v146, v148, v104
	v_mul_f32_e32 v147, v128, v110
	v_fma_f32 v105, -v105, v146, v106
	v_fma_f32 v106, -v101, v147, v128
	v_div_fmas_f32 v104, v105, v104, v146
	s_mov_b64 vcc, s[10:11]
	v_fmac_f32_e32 v147, v106, v110
	v_div_fixup_f32 v96, v104, v96, s62
	v_div_fmas_f32 v104, v108, v141, v112
	v_fma_f32 v101, -v101, v147, v128
	v_mul_f32_e32 v105, v96, v114
	v_mul_f32_e32 v106, v96, v115
	v_mul_f32_e32 v108, v96, v116
	v_mul_f32_e32 v112, v96, v117
	v_mul_f32_e32 v114, v96, v118
	v_mul_f32_e32 v115, v96, v119
	v_mul_f32_e32 v116, v96, v120
	v_mul_f32_e32 v117, v96, v121
	v_mul_f32_e32 v118, v96, v122
	v_mul_f32_e32 v119, v96, v123
	v_mul_f32_e32 v120, v96, v124
	v_mul_f32_e32 v121, v96, v125
	v_mul_f32_e32 v122, v96, v126
	v_mul_f32_e32 v123, v96, v127
	v_mul_f32_e32 v94, v96, v94
	v_mul_f32_e32 v95, v96, v95
	v_div_fixup_f32 v96, v104, v97, 1.0
	s_mov_b64 vcc, s[6:7]
	v_div_fmas_f32 v97, v101, v110, v147
	v_mul_f32_e32 v101, v0, v105
	v_mul_f32_e32 v105, v2, v108
	v_mul_f32_e32 v108, v4, v114
	v_mul_f32_e32 v110, v5, v115
	v_mul_f32_e32 v114, v7, v117
	v_mul_f32_e32 v115, v8, v118
	v_mul_f32_e32 v117, v10, v120
	v_mul_f32_e32 v118, v11, v121
	v_mul_f32_e32 v120, v13, v123
	v_mul_f32_e32 v123, v96, v129
	v_mul_f32_e32 v104, v1, v106
	v_mul_f32_e32 v106, v3, v112
	v_mul_f32_e32 v112, v6, v116
	v_mul_f32_e32 v116, v9, v119
	v_mul_f32_e32 v119, v12, v122
	v_mul_f32_e32 v121, v14, v94
	v_mul_f32_e32 v122, v15, v95
	v_mul_f32_e32 v124, v96, v130
	v_mul_f32_e32 v125, v96, v131
	v_mul_f32_e32 v126, v96, v132
	v_mul_f32_e32 v127, v96, v133
	v_mul_f32_e32 v128, v96, v134
	v_mul_f32_e32 v129, v96, v98
	v_mul_f32_e32 v130, v96, v99
	v_div_fixup_f32 v131, v97, v100, 1.0
	v_cvt_pk_bf16_f32 v94, v101, v104
	v_cvt_pk_bf16_f32 v95, v105, v106
	v_cvt_pk_bf16_f32 v96, v108, v110
	v_cvt_pk_bf16_f32 v97, v112, v114
	v_cvt_pk_bf16_f32 v98, v115, v116
	v_cvt_pk_bf16_f32 v99, v117, v118
	v_mul_f32_e32 v118, v123, v32
	v_cvt_pk_bf16_f32 v100, v119, v120
	v_cvt_pk_bf16_f32 v101, v121, v122
	v_mul_f32_e32 v104, v124, v33
	v_mul_f32_e32 v106, v125, v34
	v_mul_f32_e32 v108, v126, v35
	v_mul_f32_e32 v110, v127, v36
	v_mul_f32_e32 v112, v128, v37
	global_store_dwordx4 v[84:85], v[94:97], off
	global_store_dwordx4 v[84:85], v[98:101], off offset:16
	ds_bpermute_b32 v84, v93, v118
	v_mul_f32_e32 v114, v129, v38
	v_mul_f32_e32 v116, v130, v39
	v_mul_f32_e32 v119, v131, v107
	v_mul_f32_e32 v120, v131, v109
	v_mul_f32_e32 v122, v131, v111
	v_mul_f32_e32 v126, v131, v113
	ds_bpermute_b32 v105, v93, v104
	ds_bpermute_b32 v107, v93, v106
	ds_bpermute_b32 v109, v93, v108
	ds_bpermute_b32 v111, v93, v110
	ds_bpermute_b32 v113, v93, v112
	ds_bpermute_b32 v115, v93, v114
	ds_bpermute_b32 v117, v93, v116
	v_mul_f32_e32 v125, v131, v145
	v_mul_f32_e32 v100, v22, v125
	s_waitcnt lgkmcnt(7)
; __device__ __forceinline__ unsigned cvt_pk_bf16(float lo, float hi) { unsigned r; asm volatile("v_cvt_pk_bf16_f32 %0, %1, %2" : "=v"(r) : "v"(lo), "v"(hi)); return r; }
; __device__ __forceinline__ float bflo(unsigned w) { return __uint_as_float(w << 16); }
; __device__ __forceinline__ float bfhi(unsigned w) { return __uint_as_float(w & 0xffff0000u); }
; __global__ void __launch_bounds__(NTHREADS, 2) fwd_megakernel(Params P) {
;     ...
; #pragma unroll
;               for (int j = 0; j < 8; ++j) { const float y = v[j] * ri * gqr[j]; const float yp = __shfl_xor(y, 4); o[j] = (sl < 4 ? y * cc[j] - yp * sn[j] : y * cc[j] + yp * sn[j]) * CM; }
;               u32x4 w; w.x = cvt_pk_bf16(o[0], o[1]); w.y = cvt_pk_bf16(o[2], o[3]); w.z = cvt_pk_bf16(o[4], o[5]); w.w = cvt_pk_bf16(o[6], o[7]);
;               *(u32x4*)(qo + 128 + sl * 8) = w; }
;             { float v[16] = {bflo(ka.x), bfhi(ka.x), bflo(ka.y), bfhi(ka.y), bflo(ka.z), bfhi(ka.z), bflo(ka.w), bfhi(ka.w), bflo(kb.x), bfhi(kb.x), bflo(kb.y), bfhi(kb.y), bflo(kb.z), bfhi(kb.z), bflo(kb.w), bfhi(kb.w)};
;               float ss = 0.f;
; #pragma unroll
;               for (int j = 0; j < 16; ++j) ss += v[j] * v[j];
;               const float ri = 1.0f / sqrtf(group_sum<8>(ss) * (1.f / 128.f) + EPS);
;               u32x4 o0, o1;
;               o0.x = cvt_pk_bf16(v[0] * ri * gkn[0], v[1] * ri * gkn[1]); o0.y = cvt_pk_bf16(v[2] * ri * gkn[2], v[3] * ri * gkn[3]); o0.z = cvt_pk_bf16(v[4] * ri * gkn[4], v[5] * ri * gkn[5]); o0.w = cvt_pk_bf16(v[6] * ri * gkn[6], v[7] * ri * gkn[7]);
;               o1.x = cvt_pk_bf16(v[8] * ri * gkn[8], v[9] * ri * gkn[9]); o1.y = cvt_pk_bf16(v[10] * ri * gkn[10], v[11] * ri * gkn[11]); o1.z = cvt_pk_bf16(v[12] * ri * gkn[12], v[13] * ri * gkn[13]); o1.w = cvt_pk_bf16(v[14] * ri * gkn[14], v[15] * ri * gkn[15]);
;               *(u32x4*)(ko + sl * 16) = o0; *(u32x4*)(ko + sl * 16 + 8) = o1; }
;             *(u32x4*)(ko + 128 + sl * 8) = krv;
	v_mul_f32_e32 v125, v48, v84
	v_mov_b32_e32 v48, v45
	s_waitcnt lgkmcnt(5)
	v_pk_mul_f32 v[84:85], v[106:107], v[86:87]
	s_waitcnt lgkmcnt(4)
	v_pk_mul_f32 v[50:51], v[108:109], v[50:51]
	s_waitcnt lgkmcnt(3)
	v_pk_mul_f32 v[46:47], v[110:111], v[46:47]
	s_waitcnt lgkmcnt(2)
	v_pk_mul_f32 v[52:53], v[112:113], v[52:53]
	v_cndmask_b32_e64 v45, v125, -v125, s[4:5]
	v_pk_mul_f32 v[48:49], v[104:105], v[48:49]
	s_waitcnt lgkmcnt(1)
	v_pk_mul_f32 v[86:87], v[114:115], v[88:89]
	s_waitcnt lgkmcnt(0)
	v_pk_mul_f32 v[54:55], v[116:117], v[54:55]
	v_sub_f32_e32 v88, v84, v85
	v_add_f32_e32 v84, v84, v85
	v_sub_f32_e32 v85, v50, v51
	v_add_f32_e32 v50, v50, v51
	v_sub_f32_e32 v51, v46, v47
	v_add_f32_e32 v46, v46, v47
	v_sub_f32_e32 v47, v52, v53
	v_add_f32_e32 v52, v52, v53
	v_fmac_f32_e32 v45, v118, v44
	v_sub_f32_e32 v44, v48, v49
	v_add_f32_e32 v48, v48, v49
	v_sub_f32_e32 v53, v86, v87
	v_add_f32_e32 v86, v86, v87
	v_sub_f32_e32 v87, v54, v55
	v_add_f32_e32 v54, v54, v55
	v_cndmask_b32_e64 v46, v46, v51, s[4:5]
	v_cndmask_b32_e64 v47, v52, v47, s[4:5]
	v_cndmask_b32_e64 v44, v48, v44, s[4:5]
	v_add_co_u32_e32 v80, vcc, s64, v80
	v_cndmask_b32_e64 v49, v84, v88, s[4:5]
	v_cndmask_b32_e64 v50, v50, v85, s[4:5]
	v_cndmask_b32_e64 v51, v86, v53, s[4:5]
	v_cndmask_b32_e64 v52, v54, v87, s[4:5]
	v_mul_f32_e32 v45, 0x3dd53b94, v45
	v_mul_f32_e32 v46, 0x3dd53b94, v46
	v_mul_f32_e32 v47, 0x3dd53b94, v47
	v_mul_f32_e32 v44, 0x3dd53b94, v44
	v_addc_co_u32_e32 v81, vcc, 0, v81, vcc
	v_mul_f32_e32 v121, v131, v142
	v_mul_f32_e32 v123, v131, v143
	v_mul_f32_e32 v124, v131, v144
	v_mul_f32_e32 v48, 0x3dd53b94, v49
	v_mul_f32_e32 v49, 0x3dd53b94, v50
	v_mul_f32_e32 v50, 0x3dd53b94, v51
	v_mul_f32_e32 v51, 0x3dd53b94, v52
	v_cvt_pk_bf16_f32 v44, v45, v44
	v_cvt_pk_bf16_f32 v45, v48, v49
	v_cvt_pk_bf16_f32 v46, v46, v47
	v_cvt_pk_bf16_f32 v47, v50, v51
	v_add_co_u32_e32 v78, vcc, 0x9400000, v78
	v_mul_f32_e32 v127, v131, v135
	v_mul_f32_e32 v128, v131, v136
	v_mul_f32_e32 v129, v131, v137
	v_mul_f32_e32 v130, v131, v138
	v_mul_f32_e32 v132, v131, v139
	v_mul_f32_e32 v133, v131, v140
	v_mul_f32_e32 v102, v131, v102
	v_mul_f32_e32 v103, v131, v103
	v_mul_f32_e32 v94, v16, v119
	v_mul_f32_e32 v95, v17, v120
	v_mul_f32_e32 v96, v18, v121
	v_mul_f32_e32 v97, v19, v122
	v_mul_f32_e32 v98, v20, v123
	v_mul_f32_e32 v99, v21, v124
	v_mul_f32_e32 v101, v23, v126
	global_store_dwordx4 v[82:83], v[44:47], off offset:256
	v_addc_co_u32_e32 v79, vcc, 0, v79, vcc
	s_nop 0
	v_cvt_pk_bf16_f32 v44, v94, v95
	v_cvt_pk_bf16_f32 v45, v96, v97
	v_cvt_pk_bf16_f32 v46, v98, v99
	v_cvt_pk_bf16_f32 v47, v100, v101
	v_mul_f32_e32 v119, v24, v127
	v_mul_f32_e32 v120, v25, v128
	v_mul_f32_e32 v121, v26, v129
	v_mul_f32_e32 v122, v27, v130
	v_mul_f32_e32 v123, v28, v132
	v_mul_f32_e32 v124, v29, v133
	v_mul_f32_e32 v102, v30, v102
	v_mul_f32_e32 v103, v31, v103
	v_cvt_pk_bf16_f32 v48, v119, v120
	v_cvt_pk_bf16_f32 v49, v121, v122
	v_cvt_pk_bf16_f32 v50, v123, v124
	v_cvt_pk_bf16_f32 v51, v102, v103
	global_store_dwordx4 v[80:81], v[44:47], off
	global_store_dwordx4 v[80:81], v[48:51], off offset:16
	global_store_dwordx4 v[78:79], v[40:43], off offset:256
	s_cbranch_scc0 .LBB0_314
	s_branch .LBB0_306

; #define PG8_STAGE(bufoff, gbase, voff) do { _Pragma("unroll") for (int _i = 0; _i < 2; ++_i) \
;         __builtin_amdgcn_global_load_lds((const unsigned*)((const char*)(gbase) + (voff)[_i]), (LAS unsigned*)(lds + (bufoff) + ldsw + _i * 8192), 16, 0, 0); } while (0)
; #define PG8_LDA(dst, b, h) do { _Pragma("unroll") for (int m = 0; m < 4; ++m) _Pragma("unroll") for (int k = 0; k < 2; ++k) dst[m][k] = *(const LAS bf16x8*)(lds + PG8_SA(b, h) + aoff + m * 2048 + k * 1024); } while (0)
; #define PG8_LDB(dst, b, h) do { _Pragma("unroll") for (int n = 0; n < 2; ++n) _Pragma("unroll") for (int k = 0; k < 2; ++k) dst[n][k] = *(const LAS bf16x8*)(lds + PG8_SB(b, h) + boff + n * 2048 + k * 1024); } while (0)
; #define PG8_MMA(ai, bj, At, Bt) do { __builtin_amdgcn_s_setprio(1); _Pragma("unroll") for (int m = 0; m < 4; ++m) _Pragma("unroll") for (int n = 0; n < 2; ++n) _Pragma("unroll") for (int k = 0; k < 2; ++k) \
;         acc[ai][bj][m][n] = __builtin_amdgcn_mfma_f32_16x16x32_bf16(Bt[n][k], At[m][k], acc[ai][bj][m][n], 0, 0, 0); __builtin_amdgcn_s_setprio(0); } while (0)
; #define PG8_WAIT_V(n) asm volatile("s_waitcnt vmcnt(" #n ")" ::: "memory")
; #define PG8_WAIT_L(n) asm volatile("s_waitcnt lgkmcnt(" #n ")" ::: "memory")
; #define PG8_BAR __builtin_amdgcn_s_barrier()
; #define PG8_SCHED __builtin_amdgcn_sched_barrier(0)
; template <class Epi>
; __device__ __forceinline__ void gemm_phase(LAS unsigned char* lds, const Gemm g, const StaticOrder& S, const Epi& E) {
;     ...
;             PG8_LDB(B0, 0, 0); PG8_SCHED; PG8_LDA(At, 0, 0); PG8_STAGE(PG8_SA(1, 1), a1 + hstep, voffA);
;             PG8_WAIT_L(8); PG8_BAR; PG8_WAIT_L(0); PG8_MMA(0, 0, At, B0); PG8_BAR; PG8_SCHED;
;             PG8_LDB(B1, 0, 1); PG8_STAGE(PG8_SB(0, 0), b2, voffB0);
;             PG8_BAR; PG8_WAIT_L(0); PG8_MMA(0, 1, At, B1); PG8_BAR;
;             PG8_LDA(At, 0, 1); PG8_STAGE(PG8_SA(0, 0), a2, voffA);
;             PG8_BAR; PG8_WAIT_L(0); PG8_MMA(1, 0, At, B0); PG8_BAR; PG8_SCHED;
;             PG8_STAGE(PG8_SB(0, 1), b2, voffB1);
;             PG8_WAIT_V(6); PG8_BAR; PG8_MMA(1, 1, At, B1); PG8_BAR;
.LBB0_882:
	ds_read_b128 v[32:35], v177
	ds_read_b128 v[40:43], v177 offset:1024
	ds_read_b128 v[48:51], v177 offset:2048
	ds_read_b128 v[52:55], v177 offset:3072
	s_add_u32 s33, s60, 0xfff80080
	s_addc_u32 s62, s61, -1
	s_cmp_eq_u32 s86, 28
	s_cselect_b32 s63, s49, s62
	s_cselect_b32 s62, s57, s33
	s_cselect_b32 s65, s47, s85
	s_cselect_b32 s64, s83, s84
	v_lshl_add_u64 v[170:171], s[60:61], 0, v[156:157]
	s_add_i32 m0, s59, 0xc000
	ds_read_b128 v[162:165], v178
	ds_read_b128 v[166:169], v178 offset:1024
	ds_read_b128 v[182:185], v178 offset:2048
	ds_read_b128 v[186:189], v178 offset:3072
	ds_read_b128 v[190:193], v178 offset:4096
	ds_read_b128 v[194:197], v178 offset:5120
	ds_read_b128 v[198:201], v178 offset:6144
	ds_read_b128 v[204:207], v178 offset:7168
	global_load_lds_dwordx4 v[170:171], off
	v_lshl_add_u64 v[170:171], s[60:61], 0, v[158:159]
	s_add_i32 m0, s59, 0xe000
	s_nop 0
	global_load_lds_dwordx4 v[170:171], off
	s_waitcnt lgkmcnt(8)
	s_barrier
	s_waitcnt lgkmcnt(0)
	s_setprio 1
	s_waitcnt lgkmcnt(0)
	v_mfma_f32_16x16x32_bf16 v[140:143], v[32:35], v[162:165], v[140:143]
	v_mfma_f32_16x16x32_bf16 v[136:139], v[48:51], v[162:165], v[136:139]
	v_mfma_f32_16x16x32_bf16 v[124:127], v[32:35], v[182:185], v[124:127]
	v_mfma_f32_16x16x32_bf16 v[120:123], v[48:51], v[182:185], v[120:123]
	v_mfma_f32_16x16x32_bf16 v[108:111], v[32:35], v[190:193], v[108:111]
	v_mfma_f32_16x16x32_bf16 v[104:107], v[48:51], v[190:193], v[104:107]
	v_mfma_f32_16x16x32_bf16 v[92:95], v[32:35], v[198:201], v[92:95]
	v_mfma_f32_16x16x32_bf16 v[88:91], v[48:51], v[198:201], v[88:91]
	v_mfma_f32_16x16x32_bf16 v[140:143], v[40:43], v[166:169], v[140:143]
	v_mfma_f32_16x16x32_bf16 v[136:139], v[52:55], v[166:169], v[136:139]
	v_mfma_f32_16x16x32_bf16 v[124:127], v[40:43], v[186:189], v[124:127]
	v_mfma_f32_16x16x32_bf16 v[120:123], v[52:55], v[186:189], v[120:123]
	v_mfma_f32_16x16x32_bf16 v[108:111], v[40:43], v[194:197], v[108:111]
	v_mfma_f32_16x16x32_bf16 v[104:107], v[52:55], v[194:197], v[104:107]
	v_mfma_f32_16x16x32_bf16 v[92:95], v[40:43], v[204:207], v[92:95]
	v_mfma_f32_16x16x32_bf16 v[88:91], v[52:55], v[204:207], v[88:91]
	s_setprio 0
	s_barrier
	s_add_i32 s33, s81, s69
	v_lshl_add_u64 v[170:171], s[64:65], 0, v[146:147]
	s_mov_b32 m0, s33
	ds_read_b128 v[208:211], v179
	ds_read_b128 v[212:215], v179 offset:1024
	ds_read_b128 v[216:219], v179 offset:2048
	ds_read_b128 v[220:223], v179 offset:3072
	global_load_lds_dwordx4 v[170:171], off
	v_lshl_add_u64 v[224:225], s[64:65], 0, v[152:153]
	s_add_i32 m0, s33, 0x2000
	s_nop 0
	global_load_lds_dwordx4 v[224:225], off
	s_barrier
	s_waitcnt lgkmcnt(0)
	s_setprio 1
	s_waitcnt lgkmcnt(0)
	v_mfma_f32_16x16x32_bf16 v[132:135], v[208:211], v[162:165], v[132:135]
	v_mfma_f32_16x16x32_bf16 v[128:131], v[216:219], v[162:165], v[128:131]
	v_mfma_f32_16x16x32_bf16 v[116:119], v[208:211], v[182:185], v[116:119]
	v_mfma_f32_16x16x32_bf16 v[112:115], v[216:219], v[182:185], v[112:115]
	v_mfma_f32_16x16x32_bf16 v[100:103], v[208:211], v[190:193], v[100:103]
	v_mfma_f32_16x16x32_bf16 v[96:99], v[216:219], v[190:193], v[96:99]
	v_mfma_f32_16x16x32_bf16 v[84:87], v[208:211], v[198:201], v[84:87]
	v_mfma_f32_16x16x32_bf16 v[80:83], v[216:219], v[198:201], v[80:83]
	v_mfma_f32_16x16x32_bf16 v[132:135], v[212:215], v[166:169], v[132:135]
	v_mfma_f32_16x16x32_bf16 v[128:131], v[220:223], v[166:169], v[128:131]
	v_mfma_f32_16x16x32_bf16 v[116:119], v[212:215], v[186:189], v[116:119]
	v_mfma_f32_16x16x32_bf16 v[112:115], v[220:223], v[186:189], v[112:115]
	v_mfma_f32_16x16x32_bf16 v[100:103], v[212:215], v[194:197], v[100:103]
	v_mfma_f32_16x16x32_bf16 v[96:99], v[220:223], v[194:197], v[96:99]
	v_mfma_f32_16x16x32_bf16 v[84:87], v[212:215], v[204:207], v[84:87]
	v_mfma_f32_16x16x32_bf16 v[80:83], v[220:223], v[204:207], v[80:83]
	s_setprio 0
	s_mov_b32 m0, s59
	v_lshl_add_u64 v[226:227], s[62:63], 0, v[144:145]
	s_barrier
	ds_read_b128 v[162:165], v178 offset:16384
	ds_read_b128 v[166:169], v178 offset:17408
	ds_read_b128 v[182:185], v178 offset:18432
	ds_read_b128 v[186:189], v178 offset:19456
	ds_read_b128 v[190:193], v178 offset:20480
	ds_read_b128 v[194:197], v178 offset:21504
	ds_read_b128 v[198:201], v178 offset:22528
	ds_read_b128 v[204:207], v178 offset:23552
	global_load_lds_dwordx4 v[226:227], off
	v_lshl_add_u64 v[228:229], s[62:63], 0, v[150:151]
	s_mov_b32 m0, s70
	s_nop 0
	global_load_lds_dwordx4 v[228:229], off
	s_barrier
	s_waitcnt lgkmcnt(0)
	s_setprio 1
	s_waitcnt lgkmcnt(0)
	v_mfma_f32_16x16x32_bf16 v[76:79], v[32:35], v[162:165], v[76:79]
	v_mfma_f32_16x16x32_bf16 v[72:75], v[48:51], v[162:165], v[72:75]
	v_mfma_f32_16x16x32_bf16 v[60:63], v[32:35], v[182:185], v[60:63]
	v_mfma_f32_16x16x32_bf16 v[56:59], v[48:51], v[182:185], v[56:59]
	v_mfma_f32_16x16x32_bf16 v[28:31], v[32:35], v[190:193], v[28:31]
	v_mfma_f32_16x16x32_bf16 v[24:27], v[48:51], v[190:193], v[24:27]
	v_mfma_f32_16x16x32_bf16 v[12:15], v[32:35], v[198:201], v[12:15]
	v_mfma_f32_16x16x32_bf16 v[8:11], v[48:51], v[198:201], v[8:11]
	v_mfma_f32_16x16x32_bf16 v[76:79], v[40:43], v[166:169], v[76:79]
	v_mfma_f32_16x16x32_bf16 v[72:75], v[52:55], v[166:169], v[72:75]
	v_mfma_f32_16x16x32_bf16 v[60:63], v[40:43], v[186:189], v[60:63]
	v_mfma_f32_16x16x32_bf16 v[56:59], v[52:55], v[186:189], v[56:59]
	v_mfma_f32_16x16x32_bf16 v[28:31], v[40:43], v[194:197], v[28:31]
	v_mfma_f32_16x16x32_bf16 v[24:27], v[52:55], v[194:197], v[24:27]
	v_mfma_f32_16x16x32_bf16 v[12:15], v[40:43], v[204:207], v[12:15]
	v_mfma_f32_16x16x32_bf16 v[8:11], v[52:55], v[204:207], v[8:11]
	s_setprio 0
	s_barrier
; #define PG8_STAGE(bufoff, gbase, voff) do { _Pragma("unroll") for (int _i = 0; _i < 2; ++_i) \
;         __builtin_amdgcn_global_load_lds((const unsigned*)((const char*)(gbase) + (voff)[_i]), (LAS unsigned*)(lds + (bufoff) + ldsw + _i * 8192), 16, 0, 0); } while (0)
; #define PG8_LDA(dst, b, h) do { _Pragma("unroll") for (int m = 0; m < 4; ++m) _Pragma("unroll") for (int k = 0; k < 2; ++k) dst[m][k] = *(const LAS bf16x8*)(lds + PG8_SA(b, h) + aoff + m * 2048 + k * 1024); } while (0)
; #define PG8_LDB(dst, b, h) do { _Pragma("unroll") for (int n = 0; n < 2; ++n) _Pragma("unroll") for (int k = 0; k < 2; ++k) dst[n][k] = *(const LAS bf16x8*)(lds + PG8_SB(b, h) + boff + n * 2048 + k * 1024); } while (0)
; #define PG8_MMA(ai, bj, At, Bt) do { __builtin_amdgcn_s_setprio(1); _Pragma("unroll") for (int m = 0; m < 4; ++m) _Pragma("unroll") for (int n = 0; n < 2; ++n) _Pragma("unroll") for (int k = 0; k < 2; ++k) \
;         acc[ai][bj][m][n] = __builtin_amdgcn_mfma_f32_16x16x32_bf16(Bt[n][k], At[m][k], acc[ai][bj][m][n], 0, 0, 0); __builtin_amdgcn_s_setprio(0); } while (0)
; #define PG8_WAIT_V(n) asm volatile("s_waitcnt vmcnt(" #n ")" ::: "memory")
; #define PG8_WAIT_L(n) asm volatile("s_waitcnt lgkmcnt(" #n ")" ::: "memory")
; #define PG8_BAR __builtin_amdgcn_s_barrier()
; #define PG8_SCHED __builtin_amdgcn_sched_barrier(0)
; template <class Epi>
; __device__ __forceinline__ void gemm_phase(LAS unsigned char* lds, const Gemm g, const StaticOrder& S, const Epi& E) {
;     ...
;             PG8_WAIT_V(6); PG8_BAR; PG8_MMA(1, 1, At, B1); PG8_BAR;
;             PG8_LDB(B0, 1, 0); PG8_SCHED; PG8_LDA(At, 1, 0); PG8_STAGE(PG8_SA(0, 1), a2 + hstep, voffA);
;             PG8_WAIT_L(8); PG8_BAR; PG8_WAIT_L(0); PG8_MMA(0, 0, At, B0); PG8_BAR; PG8_SCHED;
;             PG8_LDB(B1, 1, 1); PG8_STAGE(PG8_SB(1, 0), b3, voffB0);
;             PG8_BAR; PG8_WAIT_L(0); PG8_MMA(0, 1, At, B1); PG8_BAR;
;             PG8_LDA(At, 1, 1); PG8_STAGE(PG8_SA(1, 0), a3, voffA);
;             PG8_BAR; PG8_WAIT_L(0); PG8_MMA(1, 0, At, B0); PG8_BAR; PG8_SCHED;
	s_add_i32 s33, s82, s69
	v_lshl_add_u64 v[230:231], s[64:65], 0, v[148:149]
	s_mov_b32 m0, s33
	v_lshl_add_u64 v[232:233], s[64:65], 0, v[154:155]
	global_load_lds_dwordx4 v[230:231], off
	s_add_i32 m0, s33, 0x2000
	s_nop 0
	global_load_lds_dwordx4 v[232:233], off
	s_waitcnt vmcnt(6)
	s_barrier
	s_setprio 1
	v_mfma_f32_16x16x32_bf16 v[44:47], v[208:211], v[182:185], v[44:47]
	v_mfma_f32_16x16x32_bf16 v[36:39], v[216:219], v[182:185], v[36:39]
	v_mfma_f32_16x16x32_bf16 v[20:23], v[208:211], v[190:193], v[20:23]
	v_mfma_f32_16x16x32_bf16 v[16:19], v[216:219], v[190:193], v[16:19]
	v_mfma_f32_16x16x32_bf16 v[4:7], v[208:211], v[198:201], v[4:7]
	v_mfma_f32_16x16x32_bf16 v[0:3], v[216:219], v[198:201], v[0:3]
	v_mfma_f32_16x16x32_bf16 v[32:35], v[208:211], v[162:165], v[68:71]
	v_mfma_f32_16x16x32_bf16 v[40:43], v[216:219], v[162:165], v[64:67]
	v_mfma_f32_16x16x32_bf16 v[44:47], v[212:215], v[186:189], v[44:47]
	v_mfma_f32_16x16x32_bf16 v[36:39], v[220:223], v[186:189], v[36:39]
	v_mfma_f32_16x16x32_bf16 v[20:23], v[212:215], v[194:197], v[20:23]
	v_mfma_f32_16x16x32_bf16 v[16:19], v[220:223], v[194:197], v[16:19]
	v_mfma_f32_16x16x32_bf16 v[4:7], v[212:215], v[204:207], v[4:7]
	v_mfma_f32_16x16x32_bf16 v[0:3], v[220:223], v[204:207], v[0:3]
	v_mfma_f32_16x16x32_bf16 v[32:35], v[212:215], v[166:169], v[32:35]
	v_mfma_f32_16x16x32_bf16 v[40:43], v[220:223], v[166:169], v[40:43]
	s_setprio 0
	s_add_i32 s33, 0, 0x18000
	v_add_u32_e32 v68, s33, v173
	s_barrier
	ds_read_b128 v[48:51], v68
	ds_read_b128 v[52:55], v68 offset:1024
	ds_read_b128 v[64:67], v68 offset:2048
	ds_read_b128 v[68:71], v68 offset:3072
	s_add_u32 s62, s62, 0x80000
	s_addc_u32 s63, s63, 0
	s_mov_b32 m0, s71
	v_lshl_add_u64 v[208:209], s[62:63], 0, v[144:145]
	ds_read_b128 v[162:165], v178 offset:32768
	ds_read_b128 v[166:169], v178 offset:33792
	ds_read_b128 v[182:185], v178 offset:34816
	ds_read_b128 v[186:189], v178 offset:35840
	ds_read_b128 v[190:193], v178 offset:36864
	ds_read_b128 v[194:197], v178 offset:37888
	ds_read_b128 v[198:201], v178 offset:38912
	ds_read_b128 v[204:207], v178 offset:39936
	global_load_lds_dwordx4 v[208:209], off
	v_lshl_add_u64 v[208:209], s[62:63], 0, v[150:151]
	s_mov_b32 m0, s72
	s_nop 0
	global_load_lds_dwordx4 v[208:209], off
	s_waitcnt lgkmcnt(8)
	s_barrier
	s_waitcnt lgkmcnt(0)
	s_setprio 1
	s_waitcnt lgkmcnt(0)
	v_mfma_f32_16x16x32_bf16 v[140:143], v[48:51], v[162:165], v[140:143]
	v_mfma_f32_16x16x32_bf16 v[136:139], v[64:67], v[162:165], v[136:139]
	v_mfma_f32_16x16x32_bf16 v[124:127], v[48:51], v[182:185], v[124:127]
	v_mfma_f32_16x16x32_bf16 v[120:123], v[64:67], v[182:185], v[120:123]
	v_mfma_f32_16x16x32_bf16 v[108:111], v[48:51], v[190:193], v[108:111]
	v_mfma_f32_16x16x32_bf16 v[104:107], v[64:67], v[190:193], v[104:107]
	v_mfma_f32_16x16x32_bf16 v[92:95], v[48:51], v[198:201], v[92:95]
	v_mfma_f32_16x16x32_bf16 v[88:91], v[64:67], v[198:201], v[88:91]
	v_mfma_f32_16x16x32_bf16 v[140:143], v[52:55], v[166:169], v[140:143]
	v_mfma_f32_16x16x32_bf16 v[136:139], v[68:71], v[166:169], v[136:139]
	v_mfma_f32_16x16x32_bf16 v[124:127], v[52:55], v[186:189], v[124:127]
	v_mfma_f32_16x16x32_bf16 v[120:123], v[68:71], v[186:189], v[120:123]
	v_mfma_f32_16x16x32_bf16 v[108:111], v[52:55], v[194:197], v[108:111]
	v_mfma_f32_16x16x32_bf16 v[104:107], v[68:71], v[194:197], v[104:107]
	v_mfma_f32_16x16x32_bf16 v[92:95], v[52:55], v[204:207], v[92:95]
	v_mfma_f32_16x16x32_bf16 v[88:91], v[68:71], v[204:207], v[88:91]
	s_setprio 0
	s_barrier
	s_add_i32 s62, 0, 0x1c000
	s_add_i32 s33, s33, s69
	v_add_u32_e32 v181, s62, v173
	v_lshl_add_u64 v[170:171], v[170:171], 0, s[42:43]
	s_mov_b32 m0, s33
	ds_read_b128 v[208:211], v181
	ds_read_b128 v[212:215], v181 offset:1024
	ds_read_b128 v[216:219], v181 offset:2048
	ds_read_b128 v[220:223], v181 offset:3072
	global_load_lds_dwordx4 v[170:171], off
	v_lshl_add_u64 v[170:171], v[224:225], 0, s[42:43]
	s_add_i32 m0, s33, 0x2000
	s_nop 0
	global_load_lds_dwordx4 v[170:171], off
	s_barrier
	s_waitcnt lgkmcnt(0)
	s_setprio 1
	s_waitcnt lgkmcnt(0)
	v_mfma_f32_16x16x32_bf16 v[132:135], v[208:211], v[162:165], v[132:135]
	v_mfma_f32_16x16x32_bf16 v[128:131], v[216:219], v[162:165], v[128:131]
	v_mfma_f32_16x16x32_bf16 v[116:119], v[208:211], v[182:185], v[116:119]
	v_mfma_f32_16x16x32_bf16 v[112:115], v[216:219], v[182:185], v[112:115]
	v_mfma_f32_16x16x32_bf16 v[100:103], v[208:211], v[190:193], v[100:103]
	v_mfma_f32_16x16x32_bf16 v[96:99], v[216:219], v[190:193], v[96:99]
	v_mfma_f32_16x16x32_bf16 v[84:87], v[208:211], v[198:201], v[84:87]
	v_mfma_f32_16x16x32_bf16 v[80:83], v[216:219], v[198:201], v[80:83]
	v_mfma_f32_16x16x32_bf16 v[132:135], v[212:215], v[166:169], v[132:135]
	v_mfma_f32_16x16x32_bf16 v[128:131], v[220:223], v[166:169], v[128:131]
	v_mfma_f32_16x16x32_bf16 v[116:119], v[212:215], v[186:189], v[116:119]
	v_mfma_f32_16x16x32_bf16 v[112:115], v[220:223], v[186:189], v[112:115]
	v_mfma_f32_16x16x32_bf16 v[100:103], v[212:215], v[194:197], v[100:103]
	v_mfma_f32_16x16x32_bf16 v[96:99], v[220:223], v[194:197], v[96:99]
	v_mfma_f32_16x16x32_bf16 v[84:87], v[212:215], v[204:207], v[84:87]
	v_mfma_f32_16x16x32_bf16 v[80:83], v[220:223], v[204:207], v[80:83]
	s_setprio 0
	s_mov_b32 m0, s74
	v_lshl_add_u64 v[170:171], v[226:227], 0, s[42:43]
	s_barrier
	ds_read_b128 v[162:165], v178 offset:49152
	ds_read_b128 v[166:169], v178 offset:50176
	ds_read_b128 v[182:185], v178 offset:51200
	ds_read_b128 v[186:189], v178 offset:52224
	ds_read_b128 v[190:193], v178 offset:53248
	ds_read_b128 v[194:197], v178 offset:54272
	ds_read_b128 v[198:201], v178 offset:55296
	ds_read_b128 v[204:207], v178 offset:56320
	global_load_lds_dwordx4 v[170:171], off
	v_lshl_add_u64 v[170:171], v[228:229], 0, s[42:43]
	s_mov_b32 m0, s75
	s_nop 0
	global_load_lds_dwordx4 v[170:171], off
	s_barrier
; __device__ __forceinline__ float bflo(unsigned w) { return __uint_as_float(w << 16); }
; __device__ __forceinline__ float bfhi(unsigned w) { return __uint_as_float(w & 0xffff0000u); }
; #define PG8_STAGE(bufoff, gbase, voff) do { _Pragma("unroll") for (int _i = 0; _i < 2; ++_i) \
;         __builtin_amdgcn_global_load_lds((const unsigned*)((const char*)(gbase) + (voff)[_i]), (LAS unsigned*)(lds + (bufoff) + ldsw + _i * 8192), 16, 0, 0); } while (0)
;     __device__ __forceinline__ void operator()(const f32x4 (&acc)[2][2][4][2], const Unit& u, int wr, int wc, int fr, int fq) const {
;         const int row0 = u.pm * BM + wr * 64 + fr, col0 = u.pn * BM + wc * 64 + 16 * fq;
;         f32x4 gv[2][2];
; #pragma unroll
;         for (int bj = 0; bj < 2; ++bj) { gv[bj][0] = *(const f32x4*)(g + col0 + 8 * bj); gv[bj][1] = *(const f32x4*)(g + col0 + 8 * bj + 4); }
; #pragma unroll
;         for (int ai = 0; ai < 2; ++ai)
; #pragma unroll
;             for (int m = 0; m < 4; ++m) { const int row = row0 + ai * HALF + m * 16; const size_t off = (size_t)row * D + col0; const float ri = __builtin_amdgcn_rsqf(sse[row] * (1.f / D) + EPS); float sq = 0.f; u32x4 w[2];
;                 u32x4 rr[2], ee[2]; load_pair_lines(R, D, row, fr, col0, rr[0], rr[1]); load_pair_lines(E, D, row, fr, col0, ee[0], ee[1]);
; #pragma unroll
;                 for (int bj = 0; bj < 2; ++bj) { const u32x4 rw = rr[bj], ew = ee[bj];
;                     const float r[8] = {bflo(rw.x), bfhi(rw.x), bflo(rw.y), bfhi(rw.y), bflo(rw.z), bfhi(rw.z), bflo(rw.w), bfhi(rw.w)};
;                     const float e[8] = {bflo(ew.x), bfhi(ew.x), bflo(ew.y), bfhi(ew.y), bflo(ew.z), bfhi(ew.z), bflo(ew.w), bfhi(ew.w)};
;                     float o[8];
; #pragma unroll
;                     for (int j = 0; j < 8; ++j) { const float a = acc[ai][bj][m][j >> 2][j & 3]; const float gg = gv[bj][j >> 2][j & 3];
;                         o[j] = r[j] + e[j] * ri * gg * __builtin_amdgcn_rcpf(1.f + __builtin_amdgcn_exp2f(-a * LOG2E)); }
; template <class Epi>
; __device__ __forceinline__ void gemm_phase(LAS unsigned char* lds, const Gemm g, const StaticOrder& S, const Epi& E) {
;     ...
;             PG8_BAR; PG8_WAIT_L(0); PG8_MMA(1, 0, At, B0); PG8_BAR; PG8_SCHED;
;             PG8_STAGE(PG8_SB(1, 1), b3, voffB1);
;             PG8_WAIT_V(6); PG8_BAR; PG8_MMA(1, 1, At, B1); PG8_BAR;
;         }
	s_waitcnt lgkmcnt(0)
	s_setprio 1
	s_waitcnt lgkmcnt(0)
	v_mfma_f32_16x16x32_bf16 v[76:79], v[48:51], v[162:165], v[76:79]
	v_mfma_f32_16x16x32_bf16 v[72:75], v[64:67], v[162:165], v[72:75]
	v_mfma_f32_16x16x32_bf16 v[60:63], v[48:51], v[182:185], v[60:63]
	v_mfma_f32_16x16x32_bf16 v[56:59], v[64:67], v[182:185], v[56:59]
	v_mfma_f32_16x16x32_bf16 v[28:31], v[48:51], v[190:193], v[28:31]
	v_mfma_f32_16x16x32_bf16 v[24:27], v[64:67], v[190:193], v[24:27]
	v_mfma_f32_16x16x32_bf16 v[12:15], v[48:51], v[198:201], v[12:15]
	v_mfma_f32_16x16x32_bf16 v[8:11], v[64:67], v[198:201], v[8:11]
	v_mfma_f32_16x16x32_bf16 v[76:79], v[52:55], v[166:169], v[76:79]
	v_mfma_f32_16x16x32_bf16 v[72:75], v[68:71], v[166:169], v[72:75]
	v_mfma_f32_16x16x32_bf16 v[60:63], v[52:55], v[186:189], v[60:63]
	v_mfma_f32_16x16x32_bf16 v[56:59], v[68:71], v[186:189], v[56:59]
	v_mfma_f32_16x16x32_bf16 v[28:31], v[52:55], v[194:197], v[28:31]
	v_mfma_f32_16x16x32_bf16 v[24:27], v[68:71], v[194:197], v[24:27]
	v_mfma_f32_16x16x32_bf16 v[12:15], v[52:55], v[204:207], v[12:15]
	v_mfma_f32_16x16x32_bf16 v[8:11], v[68:71], v[204:207], v[8:11]
	s_setprio 0
	s_barrier
	s_add_i32 s33, s62, s69
	v_lshl_add_u64 v[48:49], v[230:231], 0, s[42:43]
	s_mov_b32 m0, s33
	s_nop 0
	global_load_lds_dwordx4 v[48:49], off
	v_lshl_add_u64 v[48:49], v[232:233], 0, s[42:43]
	s_add_i32 m0, s33, 0x2000
	s_nop 0
	global_load_lds_dwordx4 v[48:49], off
	s_waitcnt vmcnt(6)
	s_barrier
	s_setprio 1
	v_mfma_f32_16x16x32_bf16 v[32:35], v[208:211], v[162:165], v[32:35]
	v_mfma_f32_16x16x32_bf16 v[68:71], v[212:215], v[166:169], v[32:35]
	v_mfma_f32_16x16x32_bf16 v[32:35], v[216:219], v[162:165], v[40:43]
	v_mfma_f32_16x16x32_bf16 v[64:67], v[220:223], v[166:169], v[32:35]
	v_mfma_f32_16x16x32_bf16 v[32:35], v[208:211], v[182:185], v[44:47]
	v_mfma_f32_16x16x32_bf16 v[44:47], v[212:215], v[186:189], v[32:35]
	v_mfma_f32_16x16x32_bf16 v[32:35], v[216:219], v[182:185], v[36:39]
	v_mfma_f32_16x16x32_bf16 v[20:23], v[208:211], v[190:193], v[20:23]
	v_mfma_f32_16x16x32_bf16 v[16:19], v[216:219], v[190:193], v[16:19]
	v_mfma_f32_16x16x32_bf16 v[4:7], v[208:211], v[198:201], v[4:7]
	v_mfma_f32_16x16x32_bf16 v[0:3], v[216:219], v[198:201], v[0:3]
	v_mfma_f32_16x16x32_bf16 v[36:39], v[220:223], v[186:189], v[32:35]
	v_mfma_f32_16x16x32_bf16 v[20:23], v[212:215], v[194:197], v[20:23]
	v_mfma_f32_16x16x32_bf16 v[16:19], v[220:223], v[194:197], v[16:19]
	v_mfma_f32_16x16x32_bf16 v[4:7], v[212:215], v[204:207], v[4:7]
	v_mfma_f32_16x16x32_bf16 v[0:3], v[220:223], v[204:207], v[0:3]
	s_setprio 0
	s_add_i32 s86, s86, 2
	s_add_u32 s60, s60, 0x100
	s_addc_u32 s61, s61, 0
	s_add_u32 s84, s84, 0x100
	s_addc_u32 s85, s85, 0
	s_cmp_gt_u32 s86, 29
	s_barrier
	s_cbranch_scc0 .LBB0_882
	s_lshl_b32 s33, s58, 8
	s_add_i32 s33, s33, s77
	v_lshl_or_b32 v32, s56, 8, v176
	v_or_b32_e32 v40, s33, v174
	v_or_b32_e32 v34, v32, v175
	v_ashrrev_i32_e32 v41, 31, v40
	v_ashrrev_i32_e32 v35, 31, v34
	v_lshlrev_b64 v[168:169], 12, v[40:41]
	v_lshl_add_u64 v[42:43], s[16:17], 0, v[168:169]
	v_lshlrev_b64 v[162:163], 1, v[34:35]
	v_lshl_add_u64 v[34:35], v[42:43], 0, v[162:163]
	global_load_dwordx4 v[182:185], v[34:35], off
	v_or_b32_e32 v34, 8, v40
	v_ashrrev_i32_e32 v35, 31, v34
	v_or_b32_e32 v164, s33, v172
	v_lshlrev_b64 v[170:171], 12, v[34:35]
	v_ashrrev_i32_e32 v165, 31, v164
	v_lshl_add_u64 v[34:35], s[16:17], 0, v[170:171]
	v_lshl_add_u64 v[166:167], v[164:165], 2, s[40:41]
	v_lshl_add_u64 v[34:35], v[34:35], 0, v[162:163]
	global_load_dword v181, v[166:167], off
	v_lshl_add_u64 v[40:41], s[38:39], 0, v[168:169]
	global_load_dwordx4 v[190:193], v[34:35], off
	v_lshl_add_u64 v[34:35], s[38:39], 0, v[170:171]
	v_lshl_add_u64 v[40:41], v[40:41], 0, v[162:163]
	v_lshl_add_u64 v[34:35], v[34:35], 0, v[162:163]
	global_load_dwordx4 v[186:189], v[40:41], off
	global_load_dwordx4 v[194:197], v[34:35], off
	v_ashrrev_i32_e32 v33, 31, v32
	v_lshl_add_u64 v[40:41], v[32:33], 2, s[10:11]
	global_load_dwordx4 v[52:55], v[40:41], off
	global_load_dwordx4 v[48:51], v[40:41], off offset:16
	global_load_dwordx4 v[32:35], v[40:41], off offset:48
	s_nop 0
	global_load_dwordx4 v[40:43], v[40:41], off offset:32
	v_or_b32_e32 v216, 16, v164
	v_ashrrev_i32_e32 v217, 31, v216
	v_lshl_add_u64 v[218:219], v[216:217], 2, s[40:41]
	global_load_dword v226, v[218:219], off
	v_sub_u32_e32 v218, v216, v172
	v_add_u32_e32 v218, v218, v174
	v_ashrrev_i32_e32 v219, 31, v218
	v_lshlrev_b64 v[218:219], 12, v[218:219]
	v_lshl_add_u64 v[220:221], s[16:17], 0, v[218:219]
	v_lshl_add_u64 v[220:221], v[220:221], 0, v[162:163]
	global_load_dwordx4 v[228:231], v[220:221], off
	v_lshl_add_u64 v[220:221], s[38:39], 0, v[218:219]
	v_lshl_add_u64 v[220:221], v[220:221], 0, v[162:163]
	global_load_dwordx4 v[232:235], v[220:221], off
	v_lshl_add_u64 v[220:221], v[218:219], 0, s[44:45]
	v_lshl_add_u64 v[224:225], s[38:39], 0, v[220:221]
	v_lshl_add_u64 v[222:223], s[16:17], 0, v[220:221]
	v_lshl_add_u64 v[224:225], v[224:225], 0, v[162:163]
	v_lshl_add_u64 v[222:223], v[222:223], 0, v[162:163]
	global_load_dwordx4 v[236:239], v[224:225], off
	global_load_dwordx4 v[240:243], v[222:223], off
	v_mul_f32_e32 v140, 0xbfb8aa3b, v140
	v_exp_f32_e32 v140, v140
	v_mul_f32_e32 v141, 0xbfb8aa3b, v141
	v_exp_f32_e32 v141, v141
	v_mov_b32_e32 v212, 0
	v_mov_b32_e32 v204, 0
	v_mov_b32_e32 v208, 0
	v_add_f32_e32 v140, 1.0, v140
	v_mov_b32_e32 v198, 0
	v_rcp_f32_e32 v140, v140
	v_add_f32_e32 v141, 1.0, v141
	v_rcp_f32_e32 v141, v141
	v_mov_b32_e32 v213, 0
	v_mul_f32_e32 v136, 0xbfb8aa3b, v136
	v_mov_b32_e32 v205, 0
	v_mov_b32_e32 v209, 0
	v_exp_f32_e32 v136, v136
	v_mov_b32_e32 v199, 0
	v_mul_f32_e32 v137, 0xbfb8aa3b, v137
	v_exp_f32_e32 v137, v137
	v_mov_b32_e32 v214, 0
	v_mov_b32_e32 v206, 0
	v_mov_b32_e32 v210, 0
	v_add_f32_e32 v136, 1.0, v136
	v_mov_b32_e32 v200, 0
	v_rcp_f32_e32 v136, v136
	v_add_f32_e32 v137, 1.0, v137
	v_mul_f32_e32 v132, 0xbfb8aa3b, v132
	v_rcp_f32_e32 v137, v137
	v_exp_f32_e32 v132, v132
	v_mul_f32_e32 v133, 0xbfb8aa3b, v133
	v_exp_f32_e32 v133, v133
	v_mov_b32_e32 v215, 0
	v_add_f32_e32 v132, 1.0, v132
	v_rcp_f32_e32 v132, v132
	v_add_f32_e32 v133, 1.0, v133
	v_rcp_f32_e32 v133, v133
	v_mov_b32_e32 v207, 0
	v_mov_b32_e32 v211, 0
	v_mov_b32_e32 v201, 0
	v_mul_f32_e32 v128, 0xbfb8aa3b, v128
	v_exp_f32_e32 v128, v128
	v_mul_f32_e32 v129, 0xbfb8aa3b, v129
	v_exp_f32_e32 v129, v129
	v_add_f32_e32 v128, 1.0, v128
	v_rcp_f32_e32 v128, v128
	v_add_f32_e32 v129, 1.0, v129
	v_rcp_f32_e32 v129, v129
	s_waitcnt vmcnt(5)
; __device__ __forceinline__ unsigned cvt_pk_bf16(float lo, float hi) { unsigned r; asm volatile("v_cvt_pk_bf16_f32 %0, %1, %2" : "=v"(r) : "v"(lo), "v"(hi)); return r; }
; __device__ __forceinline__ float bflo(unsigned w) { return __uint_as_float(w << 16); }
; __device__ __forceinline__ float bfhi(unsigned w) { return __uint_as_float(w & 0xffff0000u); }
;     __device__ __forceinline__ void operator()(const f32x4 (&acc)[2][2][4][2], const Unit& u, int wr, int wc, int fr, int fq) const {
;     ...
;                 u32x4 rr[2], ee[2]; load_pair_lines(R, D, row, fr, col0, rr[0], rr[1]); load_pair_lines(E, D, row, fr, col0, ee[0], ee[1]);
; #pragma unroll
;                 for (int bj = 0; bj < 2; ++bj) { const u32x4 rw = rr[bj], ew = ee[bj];
;                     const float r[8] = {bflo(rw.x), bfhi(rw.x), bflo(rw.y), bfhi(rw.y), bflo(rw.z), bfhi(rw.z), bflo(rw.w), bfhi(rw.w)};
;                     const float e[8] = {bflo(ew.x), bfhi(ew.x), bflo(ew.y), bfhi(ew.y), bflo(ew.z), bfhi(ew.z), bflo(ew.w), bfhi(ew.w)};
;                     float o[8];
; #pragma unroll
;                     for (int j = 0; j < 8; ++j) { const float a = acc[ai][bj][m][j >> 2][j & 3]; const float gg = gv[bj][j >> 2][j & 3];
;                         o[j] = r[j] + e[j] * ri * gg * __builtin_amdgcn_rcpf(1.f + __builtin_amdgcn_exp2f(-a * LOG2E)); }
;                     if (OUT) { *(f32x4*)(OUT + off + 8 * bj) = (f32x4){o[0], o[1], o[2], o[3]}; *(f32x4*)(OUT + off + 8 * bj + 4) = (f32x4){o[4], o[5], o[6], o[7]}; }
;                     else { sq += (o[0] * o[0] + o[1] * o[1]) + (o[2] * o[2] + o[3] * o[3]) + (o[4] * o[4] + o[5] * o[5]) + (o[6] * o[6] + o[7] * o[7]);
;                         w[bj].x = cvt_pk_bf16(o[0], o[1]); w[bj].y = cvt_pk_bf16(o[2], o[3]); w[bj].z = cvt_pk_bf16(o[4], o[5]); w[bj].w = cvt_pk_bf16(o[6], o[7]); } }
	v_mov_b32_dpp v198, v182 row_ror:8 row_mask:0xf bank_mask:0xf
	v_mov_b32_dpp v199, v183 row_ror:8 row_mask:0xf bank_mask:0xf
	v_mov_b32_dpp v200, v184 row_ror:8 row_mask:0xf bank_mask:0xf
	v_mov_b32_dpp v201, v185 row_ror:8 row_mask:0xf bank_mask:0xf
	v_fmamk_f32 v181, v181, 0x3a000000, v180
	v_rsq_f32_e32 v181, v181
	v_mov_b32_dpp v204, v190 row_ror:8 row_mask:0xf bank_mask:0xf
	v_cndmask_b32_e64 v182, v204, v182, s[6:7]
	v_cndmask_b32_e64 v190, v190, v198, s[6:7]
	v_lshlrev_b32_e32 v198, 16, v182
	v_mov_b32_dpp v208, v186 row_ror:8 row_mask:0xf bank_mask:0xf
	v_mov_b32_dpp v212, v194 row_ror:8 row_mask:0xf bank_mask:0xf
	v_cndmask_b32_e64 v186, v212, v186, s[6:7]
	v_lshlrev_b32_e32 v204, 16, v186
	v_mul_f32_e32 v204, v181, v204
	v_and_b32_e32 v186, 0xffff0000, v186
	v_mul_f32_e32 v204, v52, v204
	v_fmac_f32_e32 v198, v140, v204
	v_mul_f32_e32 v140, v181, v186
	v_and_b32_e32 v182, 0xffff0000, v182
	v_mul_f32_e32 v140, v53, v140
	v_fmac_f32_e32 v182, v141, v140
	v_mul_f32_e32 v140, 0xbfb8aa3b, v142
	v_exp_f32_e32 v140, v140
	v_mul_f32_e32 v142, 0xbfb8aa3b, v143
	v_exp_f32_e32 v142, v142
	v_mov_b32_dpp v213, v195 row_ror:8 row_mask:0xf bank_mask:0xf
	v_add_f32_e32 v140, 1.0, v140
	v_mov_b32_dpp v209, v187 row_ror:8 row_mask:0xf bank_mask:0xf
	v_mov_b32_dpp v205, v191 row_ror:8 row_mask:0xf bank_mask:0xf
	v_cndmask_b32_e64 v187, v213, v187, s[6:7]
	v_rcp_f32_e32 v140, v140
	v_cndmask_b32_e64 v183, v205, v183, s[6:7]
	v_lshlrev_b32_e32 v205, 16, v187
	v_add_f32_e32 v142, 1.0, v142
	v_mul_f32_e32 v141, v181, v205
	v_rcp_f32_e32 v142, v142
	v_cndmask_b32_e64 v191, v191, v199, s[6:7]
	v_mov_b32_dpp v214, v196 row_ror:8 row_mask:0xf bank_mask:0xf
	v_lshlrev_b32_e32 v199, 16, v183
	v_and_b32_e32 v187, 0xffff0000, v187
	v_mul_f32_e32 v141, v54, v141
	v_mov_b32_dpp v210, v188 row_ror:8 row_mask:0xf bank_mask:0xf
	v_mov_b32_dpp v206, v192 row_ror:8 row_mask:0xf bank_mask:0xf
	v_cndmask_b32_e64 v188, v214, v188, s[6:7]
	v_fmac_f32_e32 v199, v140, v141
	v_mul_f32_e32 v140, v181, v187
	v_cndmask_b32_e64 v184, v206, v184, s[6:7]
	v_and_b32_e32 v183, 0xffff0000, v183
	v_lshlrev_b32_e32 v206, 16, v188
	v_mul_f32_e32 v140, v55, v140
	v_fmac_f32_e32 v183, v142, v140
	v_mul_f32_e32 v140, v181, v206
	v_cndmask_b32_e64 v192, v192, v200, s[6:7]
	v_lshlrev_b32_e32 v200, 16, v184
	v_and_b32_e32 v188, 0xffff0000, v188
	v_mul_f32_e32 v140, v48, v140
	v_fmac_f32_e32 v200, v136, v140
	v_mul_f32_e32 v136, v181, v188
	v_and_b32_e32 v184, 0xffff0000, v184
	v_mul_f32_e32 v136, v49, v136
	v_fmac_f32_e32 v184, v137, v136
	v_mul_f32_e32 v136, 0xbfb8aa3b, v138
	v_cndmask_b32_e64 v194, v194, v208, s[6:7]
	v_exp_f32_e32 v136, v136
	v_mul_f32_e32 v138, 0xbfb8aa3b, v139
	v_lshlrev_b32_e32 v187, 16, v194
	v_exp_f32_e32 v138, v138
	v_mul_f32_e32 v187, v181, v187
	v_lshlrev_b32_e32 v141, 16, v190
	v_and_b32_e32 v188, 0xffff0000, v194
	v_mul_f32_e32 v187, v40, v187
	v_mov_b32_dpp v215, v197 row_ror:8 row_mask:0xf bank_mask:0xf
	v_add_f32_e32 v136, 1.0, v136
	v_fmac_f32_e32 v141, v132, v187
	v_mul_f32_e32 v132, v181, v188
	v_mov_b32_dpp v211, v189 row_ror:8 row_mask:0xf bank_mask:0xf
	v_mov_b32_dpp v207, v193 row_ror:8 row_mask:0xf bank_mask:0xf
	v_cndmask_b32_e64 v189, v215, v189, s[6:7]
	v_rcp_f32_e32 v136, v136
	v_and_b32_e32 v142, 0xffff0000, v190
	v_mul_f32_e32 v132, v41, v132
	v_cndmask_b32_e64 v185, v207, v185, s[6:7]
	v_lshlrev_b32_e32 v207, 16, v189
	v_add_f32_e32 v138, 1.0, v138
	v_fmac_f32_e32 v142, v133, v132
	v_mul_f32_e32 v132, 0xbfb8aa3b, v134
	v_mul_f32_e32 v137, v181, v207
	v_rcp_f32_e32 v138, v138
	v_exp_f32_e32 v132, v132
	v_cndmask_b32_e64 v193, v193, v201, s[6:7]
	v_lshlrev_b32_e32 v201, 16, v185
	v_and_b32_e32 v189, 0xffff0000, v189
	v_mul_f32_e32 v137, v50, v137
	v_mul_f32_e32 v134, 0xbfb8aa3b, v135
	v_fmac_f32_e32 v201, v136, v137
	v_mul_f32_e32 v136, v181, v189
	v_exp_f32_e32 v134, v134
	v_and_b32_e32 v185, 0xffff0000, v185
	v_mul_f32_e32 v136, v51, v136
	v_fmac_f32_e32 v185, v138, v136
	v_mul_f32_e32 v136, v182, v182
	v_mul_f32_e32 v137, v183, v183
	v_add_f32_e32 v132, 1.0, v132
	v_cndmask_b32_e64 v195, v195, v209, s[6:7]
	v_fmac_f32_e32 v136, v198, v198
	v_fmac_f32_e32 v137, v199, v199
	v_rcp_f32_e32 v132, v132
	v_add_f32_e32 v136, v136, v137
	v_mul_f32_e32 v137, v184, v184
	v_lshlrev_b32_e32 v189, 16, v195
	v_add_f32_e32 v134, 1.0, v134
	v_fmac_f32_e32 v137, v200, v200
	v_mul_f32_e32 v133, v181, v189
	v_rcp_f32_e32 v134, v134
	v_add_f32_e32 v136, v137, v136
	v_mul_f32_e32 v137, v185, v185
	v_lshlrev_b32_e32 v143, 16, v191
	v_and_b32_e32 v190, 0xffff0000, v195
	v_mul_f32_e32 v133, v42, v133
	v_cndmask_b32_e64 v196, v196, v210, s[6:7]
	v_fmac_f32_e32 v137, v201, v201
	v_fmac_f32_e32 v143, v132, v133
	v_mul_f32_e32 v132, v181, v190
	v_add_f32_e32 v136, v137, v136
	v_cvt_pk_bf16_f32 v137, v198, v182
	v_and_b32_e32 v182, 0xffff0000, v191
	v_lshlrev_b32_e32 v191, 16, v196
	v_mul_f32_e32 v132, v43, v132
	v_fmac_f32_e32 v182, v134, v132
	v_mul_f32_e32 v132, v181, v191
	v_cvt_pk_bf16_f32 v138, v199, v183
	v_cvt_pk_bf16_f32 v139, v200, v184
	v_lshlrev_b32_e32 v183, 16, v192
	v_and_b32_e32 v184, 0xffff0000, v192
	v_and_b32_e32 v192, 0xffff0000, v196
	v_mul_f32_e32 v132, v32, v132
	v_fmac_f32_e32 v183, v128, v132
	v_mul_f32_e32 v128, v181, v192
	v_mul_f32_e32 v128, v33, v128
	v_fmac_f32_e32 v184, v129, v128
	v_mul_f32_e32 v128, 0xbfb8aa3b, v130
	v_exp_f32_e32 v128, v128
	v_mul_f32_e32 v130, 0xbfb8aa3b, v131
	v_exp_f32_e32 v130, v130
	v_cndmask_b32_e64 v197, v197, v211, s[6:7]
	v_add_f32_e32 v128, 1.0, v128
	v_rcp_f32_e32 v128, v128
	v_cvt_pk_bf16_f32 v140, v201, v185
	v_lshlrev_b32_e32 v185, 16, v193
	v_and_b32_e32 v186, 0xffff0000, v193
	v_lshlrev_b32_e32 v193, 16, v197
; __device__ __forceinline__ unsigned cvt_pk_bf16(float lo, float hi) { unsigned r; asm volatile("v_cvt_pk_bf16_f32 %0, %1, %2" : "=v"(r) : "v"(lo), "v"(hi)); return r; }
;     __device__ __forceinline__ void operator()(const f32x4 (&acc)[2][2][4][2], const Unit& u, int wr, int wc, int fr, int fq) const {
;     ...
;             for (int m = 0; m < 4; ++m) { const int row = row0 + ai * HALF + m * 16; const size_t off = (size_t)row * D + col0; const float ri = __builtin_amdgcn_rsqf(sse[row] * (1.f / D) + EPS); float sq = 0.f; u32x4 w[2];
;                 u32x4 rr[2], ee[2]; load_pair_lines(R, D, row, fr, col0, rr[0], rr[1]); load_pair_lines(E, D, row, fr, col0, ee[0], ee[1]);
;     ...
;                     else { sq += (o[0] * o[0] + o[1] * o[1]) + (o[2] * o[2] + o[3] * o[3]) + (o[4] * o[4] + o[5] * o[5]) + (o[6] * o[6] + o[7] * o[7]);
;                         w[bj].x = cvt_pk_bf16(o[0], o[1]); w[bj].y = cvt_pk_bf16(o[2], o[3]); w[bj].z = cvt_pk_bf16(o[4], o[5]); w[bj].w = cvt_pk_bf16(o[6], o[7]); } }
;                 if (!OUT) { store_pair_lines(O, D, row, fr, col0, w[0], w[1]);
;                     sq += __shfl_xor(sq, 16); sq += __shfl_xor(sq, 32); if (fq == 0) unsafeAtomicAdd(ssout + row, sq); } }
	v_add_f32_e32 v130, 1.0, v130
	v_mul_f32_e32 v129, v181, v193
	v_rcp_f32_e32 v130, v130
	v_and_b32_e32 v194, 0xffff0000, v197
	v_mul_f32_e32 v129, v34, v129
	v_fmac_f32_e32 v185, v128, v129
	v_mul_f32_e32 v128, v181, v194
	v_mul_f32_e32 v128, v35, v128
	v_fmac_f32_e32 v186, v130, v128
	v_mul_f32_e32 v128, v142, v142
	v_mul_f32_e32 v129, v182, v182
	v_fmac_f32_e32 v128, v141, v141
	v_fmac_f32_e32 v129, v143, v143
	v_add_f32_e32 v128, v128, v129
	v_mul_f32_e32 v129, v184, v184
	v_fmac_f32_e32 v129, v183, v183
	v_add_f32_e32 v128, v129, v128
	v_mul_f32_e32 v129, v186, v186
	v_fmac_f32_e32 v129, v185, v185
	v_add_f32_e32 v128, v129, v128
	v_add_f32_e32 v135, v128, v136
	v_cvt_pk_bf16_f32 v128, v141, v142
	v_cvt_pk_bf16_f32 v129, v143, v182
	v_mov_b32_e32 v143, 0
	v_mov_b32_e32 v130, 0
	v_mov_b32_e32 v134, 0
	v_mov_b32_dpp v143, v138 row_ror:8 row_mask:0xf bank_mask:0xf
	v_mov_b32_dpp v130, v128 row_ror:8 row_mask:0xf bank_mask:0xf
	v_mov_b32_e32 v131, 0
	v_mov_b32_dpp v134, v137 row_ror:8 row_mask:0xf bank_mask:0xf
	v_cndmask_b32_e64 v130, v130, v137, s[6:7]
	v_mov_b32_dpp v131, v129 row_ror:8 row_mask:0xf bank_mask:0xf
	v_cndmask_b32_e64 v137, v129, v143, s[6:7]
	v_and_b32_e32 v129, 64, v203
	v_cndmask_b32_e64 v136, v128, v134, s[6:7]
	v_xor_b32_e32 v128, 16, v203
	v_add_u32_e32 v143, 64, v129
	v_cmp_lt_i32_e32 vcc, v128, v143
	v_cvt_pk_bf16_f32 v141, v183, v184
	v_mov_b32_e32 v181, 0
	v_mov_b32_e32 v133, 0
	v_cndmask_b32_e32 v128, v203, v128, vcc
	v_lshlrev_b32_e32 v134, 2, v128
	ds_bpermute_b32 v183, v134, v135
	v_cvt_pk_bf16_f32 v142, v185, v186
	v_mov_b32_dpp v181, v139 row_ror:8 row_mask:0xf bank_mask:0xf
	v_mov_b32_e32 v182, 0
	v_mov_b32_e32 v132, 0
	v_mov_b32_dpp v133, v142 row_ror:8 row_mask:0xf bank_mask:0xf
	v_lshl_add_u64 v[128:129], s[36:37], 0, v[168:169]
	v_mov_b32_dpp v182, v140 row_ror:8 row_mask:0xf bank_mask:0xf
	v_mov_b32_dpp v132, v141 row_ror:8 row_mask:0xf bank_mask:0xf
	v_cndmask_b32_e64 v131, v131, v138, s[6:7]
	v_cndmask_b32_e64 v133, v133, v140, s[6:7]
	v_cndmask_b32_e64 v138, v141, v181, s[6:7]
	v_lshl_add_u64 v[140:141], v[128:129], 0, v[162:163]
	v_xor_b32_e32 v129, 32, v203
	v_cmp_lt_i32_e32 vcc, v129, v143
	s_waitcnt lgkmcnt(0)
	v_add_f32_e32 v128, v135, v183
	v_cndmask_b32_e64 v132, v132, v139, s[6:7]
	v_cndmask_b32_e32 v129, v203, v129, vcc
	v_lshlrev_b32_e32 v135, 2, v129
	ds_bpermute_b32 v129, v135, v128
	global_store_dwordx4 v[140:141], v[130:133], off
	v_cndmask_b32_e64 v139, v142, v182, s[6:7]
	s_nop 0
	v_lshl_add_u64 v[130:131], s[36:37], 0, v[170:171]
	v_lshl_add_u64 v[130:131], v[130:131], 0, v[162:163]
	global_store_dwordx4 v[130:131], v[136:139], off
	s_and_saveexec_b64 s[56:57], s[8:9]
	s_cbranch_execz .LBB0_885
	v_lshl_add_u64 v[130:131], v[164:165], 2, s[18:19]
	s_waitcnt lgkmcnt(0)
	v_add_f32_e32 v128, v128, v129
	global_atomic_add_f32 v[130:131], v128, off
.LBB0_885:
	s_or_b64 exec, exec, s[56:57]
	v_or_b32_e32 v128, 16, v164
	s_waitcnt lgkmcnt(0)
	v_ashrrev_i32_e32 v129, 31, v128
	v_lshl_add_u64 v[130:131], v[128:129], 2, s[40:41]
	s_waitcnt vmcnt(2)
	s_nop 0
	v_mov_b32_e32 v165, v226
	v_sub_u32_e32 v130, v128, v172
	v_add_u32_e32 v130, v130, v174
	v_ashrrev_i32_e32 v131, 31, v130
	v_lshlrev_b64 v[130:131], 12, v[130:131]
	v_lshl_add_u64 v[132:133], s[16:17], 0, v[130:131]
	v_lshl_add_u64 v[132:133], v[132:133], 0, v[162:163]
	v_mov_b64_e32 v[136:137], v[228:229]
	v_mov_b64_e32 v[138:139], v[230:231]
	v_lshl_add_u64 v[132:133], s[38:39], 0, v[130:131]
	v_lshl_add_u64 v[132:133], v[132:133], 0, v[162:163]
	v_mov_b64_e32 v[140:141], v[232:233]
	v_mov_b64_e32 v[142:143], v[234:235]
	v_lshl_add_u64 v[132:133], v[130:131], 0, s[44:45]
	v_lshl_add_u64 v[182:183], s[38:39], 0, v[132:133]
	v_lshl_add_u64 v[168:169], s[16:17], 0, v[132:133]
	v_lshl_add_u64 v[182:183], v[182:183], 0, v[162:163]
	v_lshl_add_u64 v[168:169], v[168:169], 0, v[162:163]
	v_mov_b64_e32 v[182:183], v[236:237]
	v_mov_b64_e32 v[184:185], v[238:239]
	v_mul_f32_e32 v124, 0xbfb8aa3b, v124
	v_mov_b64_e32 v[168:169], v[240:241]
	v_mov_b64_e32 v[170:171], v[242:243]
	s_nop 1
	v_or_b32_e32 v216, 32, v164
	v_ashrrev_i32_e32 v217, 31, v216
	v_lshl_add_u64 v[218:219], v[216:217], 2, s[40:41]
	global_load_dword v226, v[218:219], off
	v_sub_u32_e32 v218, v216, v172
	v_add_u32_e32 v218, v218, v174
	v_ashrrev_i32_e32 v219, 31, v218
	v_lshlrev_b64 v[218:219], 12, v[218:219]
	v_lshl_add_u64 v[220:221], s[16:17], 0, v[218:219]
	v_lshl_add_u64 v[220:221], v[220:221], 0, v[162:163]
	global_load_dwordx4 v[228:231], v[220:221], off
	v_lshl_add_u64 v[220:221], s[38:39], 0, v[218:219]
	v_lshl_add_u64 v[220:221], v[220:221], 0, v[162:163]
	global_load_dwordx4 v[232:235], v[220:221], off
	v_lshl_add_u64 v[220:221], v[218:219], 0, s[44:45]
	v_lshl_add_u64 v[224:225], s[38:39], 0, v[220:221]
	v_lshl_add_u64 v[222:223], s[16:17], 0, v[220:221]
	v_lshl_add_u64 v[224:225], v[224:225], 0, v[162:163]
	v_lshl_add_u64 v[222:223], v[222:223], 0, v[162:163]
	global_load_dwordx4 v[236:239], v[224:225], off
	global_load_dwordx4 v[240:243], v[222:223], off
	v_exp_f32_e32 v124, v124
	v_mul_f32_e32 v125, 0xbfb8aa3b, v125
	v_exp_f32_e32 v125, v125
	v_mov_b32_e32 v197, 0
	v_mov_b32_e32 v189, 0
	v_mov_b32_e32 v193, 0
	v_add_f32_e32 v124, 1.0, v124
	v_mov_b32_e32 v181, 0
	v_rcp_f32_e32 v124, v124
	v_mov_b32_e32 v196, 0
	v_add_f32_e32 v125, 1.0, v125
	v_mov_b32_e32 v200, 0
	v_rcp_f32_e32 v125, v125
	v_mov_b32_e32 v198, 0
	v_mul_f32_e32 v120, 0xbfb8aa3b, v120
	v_mov_b32_e32 v190, 0
	v_mov_b32_e32 v194, 0
	v_exp_f32_e32 v120, v120
	v_mov_b32_e32 v186, 0
	v_mul_f32_e32 v121, 0xbfb8aa3b, v121
	v_exp_f32_e32 v121, v121
	v_mov_b32_e32 v199, 0
	v_mov_b32_e32 v191, 0
; __device__ __forceinline__ unsigned cvt_pk_bf16(float lo, float hi) { unsigned r; asm volatile("v_cvt_pk_bf16_f32 %0, %1, %2" : "=v"(r) : "v"(lo), "v"(hi)); return r; }
; __device__ __forceinline__ float bflo(unsigned w) { return __uint_as_float(w << 16); }
; __device__ __forceinline__ float bfhi(unsigned w) { return __uint_as_float(w & 0xffff0000u); }
;     __device__ __forceinline__ void operator()(const f32x4 (&acc)[2][2][4][2], const Unit& u, int wr, int wc, int fr, int fq) const {
;     ...
;             for (int m = 0; m < 4; ++m) { const int row = row0 + ai * HALF + m * 16; const size_t off = (size_t)row * D + col0; const float ri = __builtin_amdgcn_rsqf(sse[row] * (1.f / D) + EPS); float sq = 0.f; u32x4 w[2];
;                 u32x4 rr[2], ee[2]; load_pair_lines(R, D, row, fr, col0, rr[0], rr[1]); load_pair_lines(E, D, row, fr, col0, ee[0], ee[1]);
; #pragma unroll
;                 for (int bj = 0; bj < 2; ++bj) { const u32x4 rw = rr[bj], ew = ee[bj];
;                     const float r[8] = {bflo(rw.x), bfhi(rw.x), bflo(rw.y), bfhi(rw.y), bflo(rw.z), bfhi(rw.z), bflo(rw.w), bfhi(rw.w)};
;                     const float e[8] = {bflo(ew.x), bfhi(ew.x), bflo(ew.y), bfhi(ew.y), bflo(ew.z), bfhi(ew.z), bflo(ew.w), bfhi(ew.w)};
;                     float o[8];
; #pragma unroll
;                     for (int j = 0; j < 8; ++j) { const float a = acc[ai][bj][m][j >> 2][j & 3]; const float gg = gv[bj][j >> 2][j & 3];
;                         o[j] = r[j] + e[j] * ri * gg * __builtin_amdgcn_rcpf(1.f + __builtin_amdgcn_exp2f(-a * LOG2E)); }
;                     if (OUT) { *(f32x4*)(OUT + off + 8 * bj) = (f32x4){o[0], o[1], o[2], o[3]}; *(f32x4*)(OUT + off + 8 * bj + 4) = (f32x4){o[4], o[5], o[6], o[7]}; }
;                     else { sq += (o[0] * o[0] + o[1] * o[1]) + (o[2] * o[2] + o[3] * o[3]) + (o[4] * o[4] + o[5] * o[5]) + (o[6] * o[6] + o[7] * o[7]);
;                         w[bj].x = cvt_pk_bf16(o[0], o[1]); w[bj].y = cvt_pk_bf16(o[2], o[3]); w[bj].z = cvt_pk_bf16(o[4], o[5]); w[bj].w = cvt_pk_bf16(o[6], o[7]); } }
	v_mov_b32_e32 v195, 0
	v_add_f32_e32 v120, 1.0, v120
	v_mov_b32_e32 v187, 0
	v_rcp_f32_e32 v120, v120
	v_add_f32_e32 v121, 1.0, v121
	v_mul_f32_e32 v116, 0xbfb8aa3b, v116
	v_rcp_f32_e32 v121, v121
	v_exp_f32_e32 v116, v116
	v_mul_f32_e32 v117, 0xbfb8aa3b, v117
	v_exp_f32_e32 v117, v117
	v_mov_b32_e32 v192, 0
	v_add_f32_e32 v116, 1.0, v116
	v_rcp_f32_e32 v116, v116
	v_add_f32_e32 v117, 1.0, v117
	v_rcp_f32_e32 v117, v117
	v_mov_b32_e32 v188, 0
	v_mul_f32_e32 v112, 0xbfb8aa3b, v112
	v_exp_f32_e32 v112, v112
	v_mul_f32_e32 v113, 0xbfb8aa3b, v113
	v_exp_f32_e32 v113, v113
	v_add_f32_e32 v112, 1.0, v112
	v_rcp_f32_e32 v112, v112
	v_add_f32_e32 v113, 1.0, v113
	v_rcp_f32_e32 v113, v113
	v_fmamk_f32 v165, v165, 0x3a000000, v180
	v_rsq_f32_e32 v165, v165
	v_mov_b32_dpp v181, v136 row_ror:8 row_mask:0xf bank_mask:0xf
	v_mov_b32_dpp v186, v137 row_ror:8 row_mask:0xf bank_mask:0xf
	v_mov_b32_dpp v187, v138 row_ror:8 row_mask:0xf bank_mask:0xf
	v_mov_b32_dpp v193, v140 row_ror:8 row_mask:0xf bank_mask:0xf
	v_mov_b32_dpp v196, v143 row_ror:8 row_mask:0xf bank_mask:0xf
	v_mov_b32_dpp v194, v141 row_ror:8 row_mask:0xf bank_mask:0xf
	v_mov_b32_dpp v195, v142 row_ror:8 row_mask:0xf bank_mask:0xf
	v_mov_b32_dpp v188, v139 row_ror:8 row_mask:0xf bank_mask:0xf
	v_mov_b32_dpp v197, v182 row_ror:8 row_mask:0xf bank_mask:0xf
	v_cndmask_b32_e64 v140, v197, v140, s[6:7]
	v_mov_b32_dpp v189, v168 row_ror:8 row_mask:0xf bank_mask:0xf
	v_cndmask_b32_e64 v136, v189, v136, s[6:7]
	v_lshlrev_b32_e32 v189, 16, v140
	v_mul_f32_e32 v189, v165, v189
	v_cndmask_b32_e64 v168, v168, v181, s[6:7]
	v_mov_b32_dpp v200, v185 row_ror:8 row_mask:0xf bank_mask:0xf
	v_cndmask_b32_e64 v181, v185, v196, s[6:7]
	v_lshlrev_b32_e32 v185, 16, v136
	v_and_b32_e32 v140, 0xffff0000, v140
	v_mul_f32_e32 v189, v52, v189
	v_fmac_f32_e32 v185, v124, v189
	v_mul_f32_e32 v124, v165, v140
	v_and_b32_e32 v136, 0xffff0000, v136
	v_mul_f32_e32 v124, v53, v124
	v_fmac_f32_e32 v136, v125, v124
	v_mul_f32_e32 v124, 0xbfb8aa3b, v126
	v_exp_f32_e32 v124, v124
	v_mul_f32_e32 v126, 0xbfb8aa3b, v127
	v_exp_f32_e32 v126, v126
	v_mov_b32_dpp v198, v183 row_ror:8 row_mask:0xf bank_mask:0xf
	v_add_f32_e32 v124, 1.0, v124
	v_mov_b32_dpp v190, v169 row_ror:8 row_mask:0xf bank_mask:0xf
	v_cndmask_b32_e64 v141, v198, v141, s[6:7]
	v_rcp_f32_e32 v124, v124
	v_cndmask_b32_e64 v137, v190, v137, s[6:7]
	v_lshlrev_b32_e32 v190, 16, v141
	v_add_f32_e32 v126, 1.0, v126
	v_mul_f32_e32 v125, v165, v190
	v_rcp_f32_e32 v126, v126
	v_cndmask_b32_e64 v169, v169, v186, s[6:7]
	v_mov_b32_dpp v199, v184 row_ror:8 row_mask:0xf bank_mask:0xf
	v_lshlrev_b32_e32 v186, 16, v137
	v_and_b32_e32 v141, 0xffff0000, v141
	v_mul_f32_e32 v125, v54, v125
	v_mov_b32_dpp v191, v170 row_ror:8 row_mask:0xf bank_mask:0xf
	v_cndmask_b32_e64 v142, v199, v142, s[6:7]
	v_fmac_f32_e32 v186, v124, v125
	v_mul_f32_e32 v124, v165, v141
	v_cndmask_b32_e64 v138, v191, v138, s[6:7]
	v_and_b32_e32 v137, 0xffff0000, v137
	v_lshlrev_b32_e32 v191, 16, v142
	v_mul_f32_e32 v124, v55, v124
	v_fmac_f32_e32 v137, v126, v124
	v_mul_f32_e32 v124, v165, v191
	v_cndmask_b32_e64 v170, v170, v187, s[6:7]
	v_lshlrev_b32_e32 v187, 16, v138
	v_and_b32_e32 v142, 0xffff0000, v142
	v_mul_f32_e32 v124, v48, v124
	v_fmac_f32_e32 v187, v120, v124
	v_mul_f32_e32 v120, v165, v142
	v_and_b32_e32 v138, 0xffff0000, v138
	v_mul_f32_e32 v120, v49, v120
	v_fmac_f32_e32 v138, v121, v120
	v_mul_f32_e32 v120, 0xbfb8aa3b, v122
	v_cndmask_b32_e64 v182, v182, v193, s[6:7]
	v_exp_f32_e32 v120, v120
	v_mul_f32_e32 v122, 0xbfb8aa3b, v123
	v_lshlrev_b32_e32 v141, 16, v182
	v_exp_f32_e32 v122, v122
	v_mul_f32_e32 v141, v165, v141
	v_lshlrev_b32_e32 v125, 16, v168
	v_and_b32_e32 v142, 0xffff0000, v182
	v_mul_f32_e32 v141, v40, v141
	v_add_f32_e32 v120, 1.0, v120
	v_fmac_f32_e32 v125, v116, v141
	v_mul_f32_e32 v116, v165, v142
	v_mov_b32_dpp v192, v171 row_ror:8 row_mask:0xf bank_mask:0xf
	v_cndmask_b32_e64 v143, v200, v143, s[6:7]
	v_rcp_f32_e32 v120, v120
	v_and_b32_e32 v126, 0xffff0000, v168
	v_mul_f32_e32 v116, v41, v116
	v_cndmask_b32_e64 v139, v192, v139, s[6:7]
	v_lshlrev_b32_e32 v192, 16, v143
	v_add_f32_e32 v122, 1.0, v122
	v_fmac_f32_e32 v126, v117, v116
	v_mul_f32_e32 v116, 0xbfb8aa3b, v118
	v_mul_f32_e32 v121, v165, v192
	v_rcp_f32_e32 v122, v122
	v_exp_f32_e32 v116, v116
	v_cndmask_b32_e64 v171, v171, v188, s[6:7]
	v_lshlrev_b32_e32 v188, 16, v139
	v_and_b32_e32 v143, 0xffff0000, v143
	v_mul_f32_e32 v121, v50, v121
	v_mul_f32_e32 v118, 0xbfb8aa3b, v119
	v_fmac_f32_e32 v188, v120, v121
	v_mul_f32_e32 v120, v165, v143
	v_exp_f32_e32 v118, v118
	v_and_b32_e32 v139, 0xffff0000, v139
	v_mul_f32_e32 v120, v51, v120
	v_fmac_f32_e32 v139, v122, v120
	v_mul_f32_e32 v120, v136, v136
	v_mul_f32_e32 v121, v137, v137
	v_add_f32_e32 v116, 1.0, v116
	v_cndmask_b32_e64 v183, v183, v194, s[6:7]
	v_fmac_f32_e32 v120, v185, v185
	v_fmac_f32_e32 v121, v186, v186
	v_rcp_f32_e32 v116, v116
	v_add_f32_e32 v120, v120, v121
	v_mul_f32_e32 v121, v138, v138
	v_lshlrev_b32_e32 v143, 16, v183
	v_add_f32_e32 v118, 1.0, v118
	v_fmac_f32_e32 v121, v187, v187
	v_mul_f32_e32 v117, v165, v143
	v_rcp_f32_e32 v118, v118
	v_add_f32_e32 v120, v121, v120
	v_mul_f32_e32 v121, v139, v139
	v_lshlrev_b32_e32 v127, 16, v169
	v_and_b32_e32 v168, 0xffff0000, v183
	v_mul_f32_e32 v117, v42, v117
	v_cndmask_b32_e64 v184, v184, v195, s[6:7]
	v_fmac_f32_e32 v121, v188, v188
	v_fmac_f32_e32 v127, v116, v117
	v_mul_f32_e32 v116, v165, v168
	v_add_f32_e32 v120, v121, v120
	v_cvt_pk_bf16_f32 v121, v185, v136
	v_and_b32_e32 v136, 0xffff0000, v169
	v_lshlrev_b32_e32 v169, 16, v184
	v_mul_f32_e32 v116, v43, v116
	v_fmac_f32_e32 v136, v118, v116
; __device__ __forceinline__ unsigned cvt_pk_bf16(float lo, float hi) { unsigned r; asm volatile("v_cvt_pk_bf16_f32 %0, %1, %2" : "=v"(r) : "v"(lo), "v"(hi)); return r; }
; __device__ __forceinline__ float bflo(unsigned w) { return __uint_as_float(w << 16); }
; __device__ __forceinline__ float bfhi(unsigned w) { return __uint_as_float(w & 0xffff0000u); }
;     __device__ __forceinline__ void operator()(const f32x4 (&acc)[2][2][4][2], const Unit& u, int wr, int wc, int fr, int fq) const {
;     ...
;                 for (int bj = 0; bj < 2; ++bj) { const u32x4 rw = rr[bj], ew = ee[bj];
;                     const float r[8] = {bflo(rw.x), bfhi(rw.x), bflo(rw.y), bfhi(rw.y), bflo(rw.z), bfhi(rw.z), bflo(rw.w), bfhi(rw.w)};
;                     const float e[8] = {bflo(ew.x), bfhi(ew.x), bflo(ew.y), bfhi(ew.y), bflo(ew.z), bfhi(ew.z), bflo(ew.w), bfhi(ew.w)};
;                     float o[8];
; #pragma unroll
;                     for (int j = 0; j < 8; ++j) { const float a = acc[ai][bj][m][j >> 2][j & 3]; const float gg = gv[bj][j >> 2][j & 3];
;                         o[j] = r[j] + e[j] * ri * gg * __builtin_amdgcn_rcpf(1.f + __builtin_amdgcn_exp2f(-a * LOG2E)); }
;                     if (OUT) { *(f32x4*)(OUT + off + 8 * bj) = (f32x4){o[0], o[1], o[2], o[3]}; *(f32x4*)(OUT + off + 8 * bj + 4) = (f32x4){o[4], o[5], o[6], o[7]}; }
;                     else { sq += (o[0] * o[0] + o[1] * o[1]) + (o[2] * o[2] + o[3] * o[3]) + (o[4] * o[4] + o[5] * o[5]) + (o[6] * o[6] + o[7] * o[7]);
;                         w[bj].x = cvt_pk_bf16(o[0], o[1]); w[bj].y = cvt_pk_bf16(o[2], o[3]); w[bj].z = cvt_pk_bf16(o[4], o[5]); w[bj].w = cvt_pk_bf16(o[6], o[7]); } }
;                 if (!OUT) { store_pair_lines(O, D, row, fr, col0, w[0], w[1]);
;                     sq += __shfl_xor(sq, 16); sq += __shfl_xor(sq, 32); if (fq == 0) unsafeAtomicAdd(ssout + row, sq); } }
	v_mul_f32_e32 v116, v165, v169
	v_cvt_pk_bf16_f32 v122, v186, v137
	v_cvt_pk_bf16_f32 v123, v187, v138
	v_lshlrev_b32_e32 v137, 16, v170
	v_and_b32_e32 v138, 0xffff0000, v170
	v_and_b32_e32 v170, 0xffff0000, v184
	v_mul_f32_e32 v116, v32, v116
	v_fmac_f32_e32 v137, v112, v116
	v_mul_f32_e32 v112, v165, v170
	v_mul_f32_e32 v112, v33, v112
	v_fmac_f32_e32 v138, v113, v112
	v_mul_f32_e32 v112, 0xbfb8aa3b, v114
	v_exp_f32_e32 v112, v112
	v_mul_f32_e32 v114, 0xbfb8aa3b, v115
	v_exp_f32_e32 v114, v114
	v_cvt_pk_bf16_f32 v124, v188, v139
	v_add_f32_e32 v112, 1.0, v112
	v_rcp_f32_e32 v112, v112
	v_lshlrev_b32_e32 v139, 16, v171
	v_and_b32_e32 v140, 0xffff0000, v171
	v_lshlrev_b32_e32 v171, 16, v181
	v_add_f32_e32 v114, 1.0, v114
	v_mul_f32_e32 v113, v165, v171
	v_rcp_f32_e32 v114, v114
	v_and_b32_e32 v181, 0xffff0000, v181
	v_mul_f32_e32 v113, v34, v113
	v_fmac_f32_e32 v139, v112, v113
	v_mul_f32_e32 v112, v165, v181
	v_mul_f32_e32 v112, v35, v112
	v_fmac_f32_e32 v140, v114, v112
	v_mul_f32_e32 v112, v126, v126
	v_mul_f32_e32 v113, v136, v136
	v_fmac_f32_e32 v112, v125, v125
	v_fmac_f32_e32 v113, v127, v127
	v_add_f32_e32 v112, v112, v113
	v_mul_f32_e32 v113, v138, v138
	v_fmac_f32_e32 v113, v137, v137
	v_add_f32_e32 v112, v113, v112
	v_mul_f32_e32 v113, v140, v140
	v_fmac_f32_e32 v113, v139, v139
	v_add_f32_e32 v112, v113, v112
	v_mov_b32_e32 v117, 0
	v_add_f32_e32 v141, v112, v120
	v_cvt_pk_bf16_f32 v112, v125, v126
	v_cvt_pk_bf16_f32 v113, v127, v136
	v_cvt_pk_bf16_f32 v120, v137, v138
	v_cvt_pk_bf16_f32 v125, v139, v140
	v_mov_b32_e32 v127, 0
	v_mov_b32_e32 v118, 0
	v_mov_b32_dpp v117, v125 row_ror:8 row_mask:0xf bank_mask:0xf
	v_mov_b32_dpp v127, v124 row_ror:8 row_mask:0xf bank_mask:0xf
	v_cndmask_b32_e64 v117, v117, v124, s[6:7]
	ds_bpermute_b32 v124, v134, v141
	v_mov_b32_e32 v119, 0
	v_mov_b32_dpp v118, v121 row_ror:8 row_mask:0xf bank_mask:0xf
	v_mov_b32_e32 v114, 0
	v_mov_b32_dpp v119, v122 row_ror:8 row_mask:0xf bank_mask:0xf
	v_mov_b32_e32 v115, 0
	v_mov_b32_e32 v116, 0
	v_mov_b32_e32 v126, 0
	v_mov_b32_dpp v114, v112 row_ror:8 row_mask:0xf bank_mask:0xf
	v_mov_b32_dpp v115, v113 row_ror:8 row_mask:0xf bank_mask:0xf
	v_mov_b32_dpp v116, v120 row_ror:8 row_mask:0xf bank_mask:0xf
	v_cndmask_b32_e64 v118, v112, v118, s[6:7]
	v_cndmask_b32_e64 v119, v113, v119, s[6:7]
	v_lshl_add_u64 v[112:113], s[36:37], 0, v[130:131]
	v_mov_b32_dpp v126, v123 row_ror:8 row_mask:0xf bank_mask:0xf
	v_cndmask_b32_e64 v115, v115, v122, s[6:7]
	v_cndmask_b32_e64 v116, v116, v123, s[6:7]
	v_lshl_add_u64 v[122:123], v[112:113], 0, v[162:163]
	s_waitcnt lgkmcnt(0)
	v_add_f32_e32 v112, v141, v124
	ds_bpermute_b32 v113, v135, v112
	v_cndmask_b32_e64 v114, v114, v121, s[6:7]
	global_store_dwordx4 v[122:123], v[114:117], off
	v_cndmask_b32_e64 v120, v120, v126, s[6:7]
	v_cndmask_b32_e64 v121, v125, v127, s[6:7]
	v_lshl_add_u64 v[114:115], s[36:37], 0, v[132:133]
	v_lshl_add_u64 v[114:115], v[114:115], 0, v[162:163]
	global_store_dwordx4 v[114:115], v[118:121], off
	s_and_saveexec_b64 s[56:57], s[8:9]
	s_cbranch_execz .LBB0_887
	v_lshl_add_u64 v[114:115], v[128:129], 2, s[18:19]
	s_waitcnt lgkmcnt(0)
	v_add_f32_e32 v112, v112, v113
	global_atomic_add_f32 v[114:115], v112, off
.LBB0_887:
	s_or_b64 exec, exec, s[56:57]
	v_or_b32_e32 v112, 32, v164
	s_waitcnt lgkmcnt(0)
	v_ashrrev_i32_e32 v113, 31, v112
	v_lshl_add_u64 v[114:115], v[112:113], 2, s[40:41]
	s_waitcnt vmcnt(2)
	s_nop 0
	v_mov_b32_e32 v136, v226
	v_sub_u32_e32 v114, v112, v172
	v_add_u32_e32 v114, v114, v174
	v_ashrrev_i32_e32 v115, 31, v114
	v_lshlrev_b64 v[114:115], 12, v[114:115]
	v_lshl_add_u64 v[116:117], s[16:17], 0, v[114:115]
	v_lshl_add_u64 v[116:117], v[116:117], 0, v[162:163]
	v_mov_b64_e32 v[118:119], v[228:229]
	v_mov_b64_e32 v[120:121], v[230:231]
	v_lshl_add_u64 v[116:117], s[38:39], 0, v[114:115]
	v_lshl_add_u64 v[116:117], v[116:117], 0, v[162:163]
	v_mov_b64_e32 v[122:123], v[232:233]
	v_mov_b64_e32 v[124:125], v[234:235]
	v_lshl_add_u64 v[116:117], v[114:115], 0, s[44:45]
	v_lshl_add_u64 v[130:131], s[38:39], 0, v[116:117]
	v_lshl_add_u64 v[126:127], s[16:17], 0, v[116:117]
	v_lshl_add_u64 v[130:131], v[130:131], 0, v[162:163]
	v_lshl_add_u64 v[126:127], v[126:127], 0, v[162:163]
	v_mov_b64_e32 v[130:131], v[236:237]
	v_mov_b64_e32 v[132:133], v[238:239]
	v_mul_f32_e32 v108, 0xbfb8aa3b, v108
	v_mov_b64_e32 v[126:127], v[240:241]
	v_mov_b64_e32 v[128:129], v[242:243]
	s_nop 1
	v_or_b32_e32 v216, 48, v164
	v_ashrrev_i32_e32 v217, 31, v216
	v_lshl_add_u64 v[218:219], v[216:217], 2, s[40:41]
	global_load_dword v226, v[218:219], off
	v_sub_u32_e32 v218, v216, v172
	v_add_u32_e32 v218, v218, v174
	v_ashrrev_i32_e32 v219, 31, v218
	v_lshlrev_b64 v[218:219], 12, v[218:219]
	v_lshl_add_u64 v[220:221], s[16:17], 0, v[218:219]
	v_lshl_add_u64 v[220:221], v[220:221], 0, v[162:163]
	global_load_dwordx4 v[228:231], v[220:221], off
	v_lshl_add_u64 v[220:221], s[38:39], 0, v[218:219]
	v_lshl_add_u64 v[220:221], v[220:221], 0, v[162:163]
	global_load_dwordx4 v[232:235], v[220:221], off
	v_lshl_add_u64 v[220:221], v[218:219], 0, s[44:45]
	v_lshl_add_u64 v[224:225], s[38:39], 0, v[220:221]
	v_lshl_add_u64 v[222:223], s[16:17], 0, v[220:221]
	v_lshl_add_u64 v[224:225], v[224:225], 0, v[162:163]
	v_lshl_add_u64 v[222:223], v[222:223], 0, v[162:163]
	global_load_dwordx4 v[236:239], v[224:225], off
	global_load_dwordx4 v[240:243], v[222:223], off
	v_exp_f32_e32 v108, v108
	v_mul_f32_e32 v109, 0xbfb8aa3b, v109
	v_exp_f32_e32 v109, v109
	v_mov_b32_e32 v181, 0
	v_mov_b32_e32 v141, 0
	v_mov_b32_e32 v168, 0
	v_add_f32_e32 v108, 1.0, v108
	v_mov_b32_e32 v137, 0
	v_rcp_f32_e32 v108, v108
	v_add_f32_e32 v109, 1.0, v109
; __device__ __forceinline__ unsigned cvt_pk_bf16(float lo, float hi) { unsigned r; asm volatile("v_cvt_pk_bf16_f32 %0, %1, %2" : "=v"(r) : "v"(lo), "v"(hi)); return r; }
; __device__ __forceinline__ float bflo(unsigned w) { return __uint_as_float(w << 16); }
; __device__ __forceinline__ float bfhi(unsigned w) { return __uint_as_float(w & 0xffff0000u); }
;     __device__ __forceinline__ void operator()(const f32x4 (&acc)[2][2][4][2], const Unit& u, int wr, int wc, int fr, int fq) const {
;     ...
;             for (int m = 0; m < 4; ++m) { const int row = row0 + ai * HALF + m * 16; const size_t off = (size_t)row * D + col0; const float ri = __builtin_amdgcn_rsqf(sse[row] * (1.f / D) + EPS); float sq = 0.f; u32x4 w[2];
;                 u32x4 rr[2], ee[2]; load_pair_lines(R, D, row, fr, col0, rr[0], rr[1]); load_pair_lines(E, D, row, fr, col0, ee[0], ee[1]);
; #pragma unroll
;                 for (int bj = 0; bj < 2; ++bj) { const u32x4 rw = rr[bj], ew = ee[bj];
;                     const float r[8] = {bflo(rw.x), bfhi(rw.x), bflo(rw.y), bfhi(rw.y), bflo(rw.z), bfhi(rw.z), bflo(rw.w), bfhi(rw.w)};
;                     const float e[8] = {bflo(ew.x), bfhi(ew.x), bflo(ew.y), bfhi(ew.y), bflo(ew.z), bfhi(ew.z), bflo(ew.w), bfhi(ew.w)};
;                     float o[8];
; #pragma unroll
;                     for (int j = 0; j < 8; ++j) { const float a = acc[ai][bj][m][j >> 2][j & 3]; const float gg = gv[bj][j >> 2][j & 3];
;                         o[j] = r[j] + e[j] * ri * gg * __builtin_amdgcn_rcpf(1.f + __builtin_amdgcn_exp2f(-a * LOG2E)); }
;                     if (OUT) { *(f32x4*)(OUT + off + 8 * bj) = (f32x4){o[0], o[1], o[2], o[3]}; *(f32x4*)(OUT + off + 8 * bj + 4) = (f32x4){o[4], o[5], o[6], o[7]}; }
;                     else { sq += (o[0] * o[0] + o[1] * o[1]) + (o[2] * o[2] + o[3] * o[3]) + (o[4] * o[4] + o[5] * o[5]) + (o[6] * o[6] + o[7] * o[7]);
;                         w[bj].x = cvt_pk_bf16(o[0], o[1]); w[bj].y = cvt_pk_bf16(o[2], o[3]); w[bj].z = cvt_pk_bf16(o[4], o[5]); w[bj].w = cvt_pk_bf16(o[6], o[7]); } }
	v_rcp_f32_e32 v109, v109
	v_mov_b32_e32 v182, 0
	v_mul_f32_e32 v104, 0xbfb8aa3b, v104
	v_mov_b32_e32 v142, 0
	v_mov_b32_e32 v169, 0
	v_exp_f32_e32 v104, v104
	v_mov_b32_e32 v138, 0
	v_mul_f32_e32 v105, 0xbfb8aa3b, v105
	v_exp_f32_e32 v105, v105
	v_mov_b32_e32 v183, 0
	v_mov_b32_e32 v143, 0
	v_mov_b32_e32 v170, 0
	v_add_f32_e32 v104, 1.0, v104
	v_mov_b32_e32 v139, 0
	v_rcp_f32_e32 v104, v104
	v_add_f32_e32 v105, 1.0, v105
	v_mul_f32_e32 v100, 0xbfb8aa3b, v100
	v_rcp_f32_e32 v105, v105
	v_exp_f32_e32 v100, v100
	v_mul_f32_e32 v101, 0xbfb8aa3b, v101
	v_exp_f32_e32 v101, v101
	v_mov_b32_e32 v184, 0
	v_add_f32_e32 v100, 1.0, v100
	v_rcp_f32_e32 v100, v100
	v_add_f32_e32 v101, 1.0, v101
	v_rcp_f32_e32 v101, v101
	v_mov_b32_e32 v165, 0
	v_mov_b32_e32 v171, 0
	v_mov_b32_e32 v140, 0
	v_mul_f32_e32 v96, 0xbfb8aa3b, v96
	v_exp_f32_e32 v96, v96
	v_mul_f32_e32 v97, 0xbfb8aa3b, v97
	v_exp_f32_e32 v97, v97
	v_add_f32_e32 v96, 1.0, v96
	v_rcp_f32_e32 v96, v96
	v_add_f32_e32 v97, 1.0, v97
	v_rcp_f32_e32 v97, v97
	v_fmamk_f32 v136, v136, 0x3a000000, v180
	v_rsq_f32_e32 v136, v136
	v_mov_b32_dpp v137, v118 row_ror:8 row_mask:0xf bank_mask:0xf
	v_mov_b32_dpp v138, v119 row_ror:8 row_mask:0xf bank_mask:0xf
	v_mov_b32_dpp v139, v120 row_ror:8 row_mask:0xf bank_mask:0xf
	v_mov_b32_dpp v168, v122 row_ror:8 row_mask:0xf bank_mask:0xf
	v_mov_b32_dpp v169, v123 row_ror:8 row_mask:0xf bank_mask:0xf
	v_mov_b32_dpp v170, v124 row_ror:8 row_mask:0xf bank_mask:0xf
	v_mov_b32_dpp v171, v125 row_ror:8 row_mask:0xf bank_mask:0xf
	v_mov_b32_dpp v140, v121 row_ror:8 row_mask:0xf bank_mask:0xf
	v_mov_b32_dpp v181, v130 row_ror:8 row_mask:0xf bank_mask:0xf
	v_cndmask_b32_e64 v122, v181, v122, s[6:7]
	v_mov_b32_dpp v141, v126 row_ror:8 row_mask:0xf bank_mask:0xf
	v_cndmask_b32_e64 v118, v141, v118, s[6:7]
	v_lshlrev_b32_e32 v141, 16, v122
	v_mul_f32_e32 v141, v136, v141
	v_cndmask_b32_e64 v126, v126, v137, s[6:7]
	v_lshlrev_b32_e32 v137, 16, v118
	v_and_b32_e32 v122, 0xffff0000, v122
	v_mul_f32_e32 v141, v52, v141
	v_fmac_f32_e32 v137, v108, v141
	v_mul_f32_e32 v108, v136, v122
	v_and_b32_e32 v118, 0xffff0000, v118
	v_mul_f32_e32 v108, v53, v108
	v_fmac_f32_e32 v118, v109, v108
	v_mul_f32_e32 v108, 0xbfb8aa3b, v110
	v_exp_f32_e32 v108, v108
	v_mul_f32_e32 v110, 0xbfb8aa3b, v111
	v_exp_f32_e32 v110, v110
	v_mov_b32_dpp v182, v131 row_ror:8 row_mask:0xf bank_mask:0xf
	v_add_f32_e32 v108, 1.0, v108
	v_mov_b32_dpp v142, v127 row_ror:8 row_mask:0xf bank_mask:0xf
	v_cndmask_b32_e64 v123, v182, v123, s[6:7]
	v_rcp_f32_e32 v108, v108
	v_cndmask_b32_e64 v119, v142, v119, s[6:7]
	v_lshlrev_b32_e32 v142, 16, v123
	v_add_f32_e32 v110, 1.0, v110
	v_mul_f32_e32 v109, v136, v142
	v_rcp_f32_e32 v110, v110
	v_cndmask_b32_e64 v127, v127, v138, s[6:7]
	v_mov_b32_dpp v183, v132 row_ror:8 row_mask:0xf bank_mask:0xf
	v_lshlrev_b32_e32 v138, 16, v119
	v_and_b32_e32 v123, 0xffff0000, v123
	v_mul_f32_e32 v109, v54, v109
	v_mov_b32_dpp v143, v128 row_ror:8 row_mask:0xf bank_mask:0xf
	v_cndmask_b32_e64 v124, v183, v124, s[6:7]
	v_fmac_f32_e32 v138, v108, v109
	v_mul_f32_e32 v108, v136, v123
	v_cndmask_b32_e64 v120, v143, v120, s[6:7]
	v_and_b32_e32 v119, 0xffff0000, v119
	v_lshlrev_b32_e32 v143, 16, v124
	v_mul_f32_e32 v108, v55, v108
	v_fmac_f32_e32 v119, v110, v108
	v_mul_f32_e32 v108, v136, v143
	v_cndmask_b32_e64 v128, v128, v139, s[6:7]
	v_lshlrev_b32_e32 v139, 16, v120
	v_and_b32_e32 v124, 0xffff0000, v124
	v_mul_f32_e32 v108, v48, v108
	v_fmac_f32_e32 v139, v104, v108
	v_mul_f32_e32 v104, v136, v124
	v_and_b32_e32 v120, 0xffff0000, v120
	v_mul_f32_e32 v104, v49, v104
	v_fmac_f32_e32 v120, v105, v104
	v_mul_f32_e32 v104, 0xbfb8aa3b, v106
	v_cndmask_b32_e64 v130, v130, v168, s[6:7]
	v_exp_f32_e32 v104, v104
	v_mul_f32_e32 v106, 0xbfb8aa3b, v107
	v_lshlrev_b32_e32 v123, 16, v130
	v_exp_f32_e32 v106, v106
	v_mul_f32_e32 v123, v136, v123
	v_lshlrev_b32_e32 v109, 16, v126
	v_and_b32_e32 v124, 0xffff0000, v130
	v_mul_f32_e32 v123, v40, v123
	v_mov_b32_dpp v184, v133 row_ror:8 row_mask:0xf bank_mask:0xf
	v_add_f32_e32 v104, 1.0, v104
	v_fmac_f32_e32 v109, v100, v123
	v_mul_f32_e32 v100, v136, v124
	v_mov_b32_dpp v165, v129 row_ror:8 row_mask:0xf bank_mask:0xf
	v_cndmask_b32_e64 v125, v184, v125, s[6:7]
	v_rcp_f32_e32 v104, v104
	v_and_b32_e32 v110, 0xffff0000, v126
	v_mul_f32_e32 v100, v41, v100
	v_cndmask_b32_e64 v121, v165, v121, s[6:7]
	v_lshlrev_b32_e32 v165, 16, v125
	v_add_f32_e32 v106, 1.0, v106
	v_fmac_f32_e32 v110, v101, v100
	v_mul_f32_e32 v100, 0xbfb8aa3b, v102
	v_mul_f32_e32 v105, v136, v165
	v_rcp_f32_e32 v106, v106
	v_exp_f32_e32 v100, v100
	v_cndmask_b32_e64 v129, v129, v140, s[6:7]
	v_lshlrev_b32_e32 v140, 16, v121
	v_and_b32_e32 v125, 0xffff0000, v125
	v_mul_f32_e32 v105, v50, v105
	v_mul_f32_e32 v102, 0xbfb8aa3b, v103
	v_fmac_f32_e32 v140, v104, v105
	v_mul_f32_e32 v104, v136, v125
	v_exp_f32_e32 v102, v102
	v_and_b32_e32 v121, 0xffff0000, v121
	v_mul_f32_e32 v104, v51, v104
	v_fmac_f32_e32 v121, v106, v104
	v_mul_f32_e32 v104, v118, v118
	v_mul_f32_e32 v105, v119, v119
	v_add_f32_e32 v100, 1.0, v100
	v_cndmask_b32_e64 v131, v131, v169, s[6:7]
	v_fmac_f32_e32 v104, v137, v137
	v_fmac_f32_e32 v105, v138, v138
	v_rcp_f32_e32 v100, v100
	v_add_f32_e32 v104, v104, v105
	v_mul_f32_e32 v105, v120, v120
	v_lshlrev_b32_e32 v125, 16, v131
	v_add_f32_e32 v102, 1.0, v102
	v_fmac_f32_e32 v105, v139, v139
	v_mul_f32_e32 v101, v136, v125
	v_rcp_f32_e32 v102, v102
	v_add_f32_e32 v104, v105, v104
	v_mul_f32_e32 v105, v121, v121
	v_lshlrev_b32_e32 v111, 16, v127
	v_and_b32_e32 v126, 0xffff0000, v131
	v_mul_f32_e32 v101, v42, v101
	v_cndmask_b32_e64 v132, v132, v170, s[6:7]
	v_fmac_f32_e32 v105, v140, v140
; __device__ __forceinline__ unsigned cvt_pk_bf16(float lo, float hi) { unsigned r; asm volatile("v_cvt_pk_bf16_f32 %0, %1, %2" : "=v"(r) : "v"(lo), "v"(hi)); return r; }
; __device__ __forceinline__ float bflo(unsigned w) { return __uint_as_float(w << 16); }
; __device__ __forceinline__ float bfhi(unsigned w) { return __uint_as_float(w & 0xffff0000u); }
;     __device__ __forceinline__ void operator()(const f32x4 (&acc)[2][2][4][2], const Unit& u, int wr, int wc, int fr, int fq) const {
;     ...
;                 for (int bj = 0; bj < 2; ++bj) { const u32x4 rw = rr[bj], ew = ee[bj];
;                     const float r[8] = {bflo(rw.x), bfhi(rw.x), bflo(rw.y), bfhi(rw.y), bflo(rw.z), bfhi(rw.z), bflo(rw.w), bfhi(rw.w)};
;                     const float e[8] = {bflo(ew.x), bfhi(ew.x), bflo(ew.y), bfhi(ew.y), bflo(ew.z), bfhi(ew.z), bflo(ew.w), bfhi(ew.w)};
;                     float o[8];
; #pragma unroll
;                     for (int j = 0; j < 8; ++j) { const float a = acc[ai][bj][m][j >> 2][j & 3]; const float gg = gv[bj][j >> 2][j & 3];
;                         o[j] = r[j] + e[j] * ri * gg * __builtin_amdgcn_rcpf(1.f + __builtin_amdgcn_exp2f(-a * LOG2E)); }
;                     if (OUT) { *(f32x4*)(OUT + off + 8 * bj) = (f32x4){o[0], o[1], o[2], o[3]}; *(f32x4*)(OUT + off + 8 * bj + 4) = (f32x4){o[4], o[5], o[6], o[7]}; }
;                     else { sq += (o[0] * o[0] + o[1] * o[1]) + (o[2] * o[2] + o[3] * o[3]) + (o[4] * o[4] + o[5] * o[5]) + (o[6] * o[6] + o[7] * o[7]);
;                         w[bj].x = cvt_pk_bf16(o[0], o[1]); w[bj].y = cvt_pk_bf16(o[2], o[3]); w[bj].z = cvt_pk_bf16(o[4], o[5]); w[bj].w = cvt_pk_bf16(o[6], o[7]); } }
;                 if (!OUT) { store_pair_lines(O, D, row, fr, col0, w[0], w[1]);
;                     sq += __shfl_xor(sq, 16); sq += __shfl_xor(sq, 32); if (fq == 0) unsafeAtomicAdd(ssout + row, sq); } }
	v_fmac_f32_e32 v111, v100, v101
	v_mul_f32_e32 v100, v136, v126
	v_add_f32_e32 v104, v105, v104
	v_cvt_pk_bf16_f32 v105, v137, v118
	v_and_b32_e32 v118, 0xffff0000, v127
	v_lshlrev_b32_e32 v127, 16, v132
	v_mul_f32_e32 v100, v43, v100
	v_fmac_f32_e32 v118, v102, v100
	v_mul_f32_e32 v100, v136, v127
	v_cvt_pk_bf16_f32 v106, v138, v119
	v_cvt_pk_bf16_f32 v107, v139, v120
	v_lshlrev_b32_e32 v119, 16, v128
	v_and_b32_e32 v120, 0xffff0000, v128
	v_and_b32_e32 v128, 0xffff0000, v132
	v_mul_f32_e32 v100, v32, v100
	v_fmac_f32_e32 v119, v96, v100
	v_mul_f32_e32 v96, v136, v128
	v_mul_f32_e32 v96, v33, v96
	v_fmac_f32_e32 v120, v97, v96
	v_mul_f32_e32 v96, 0xbfb8aa3b, v98
	v_exp_f32_e32 v96, v96
	v_mul_f32_e32 v98, 0xbfb8aa3b, v99
	v_exp_f32_e32 v98, v98
	v_cndmask_b32_e64 v133, v133, v171, s[6:7]
	v_add_f32_e32 v96, 1.0, v96
	v_rcp_f32_e32 v96, v96
	v_cvt_pk_bf16_f32 v108, v140, v121
	v_lshlrev_b32_e32 v121, 16, v129
	v_and_b32_e32 v122, 0xffff0000, v129
	v_lshlrev_b32_e32 v129, 16, v133
	v_add_f32_e32 v98, 1.0, v98
	v_mul_f32_e32 v97, v136, v129
	v_rcp_f32_e32 v98, v98
	v_and_b32_e32 v130, 0xffff0000, v133
	v_mul_f32_e32 v97, v34, v97
	v_fmac_f32_e32 v121, v96, v97
	v_mul_f32_e32 v96, v136, v130
	v_mul_f32_e32 v96, v35, v96
	v_fmac_f32_e32 v122, v98, v96
	v_mul_f32_e32 v96, v110, v110
	v_mul_f32_e32 v97, v118, v118
	v_fmac_f32_e32 v96, v109, v109
	v_fmac_f32_e32 v97, v111, v111
	v_add_f32_e32 v96, v96, v97
	v_mul_f32_e32 v97, v120, v120
	v_fmac_f32_e32 v97, v119, v119
	v_add_f32_e32 v96, v97, v96
	v_mul_f32_e32 v97, v122, v122
	v_fmac_f32_e32 v97, v121, v121
	v_add_f32_e32 v96, v97, v96
	v_mov_b32_e32 v101, 0
	v_add_f32_e32 v123, v96, v104
	v_cvt_pk_bf16_f32 v96, v109, v110
	v_cvt_pk_bf16_f32 v97, v111, v118
	v_cvt_pk_bf16_f32 v104, v119, v120
	v_cvt_pk_bf16_f32 v109, v121, v122
	v_mov_b32_e32 v111, 0
	v_mov_b32_e32 v102, 0
	v_mov_b32_dpp v101, v109 row_ror:8 row_mask:0xf bank_mask:0xf
	v_mov_b32_dpp v111, v108 row_ror:8 row_mask:0xf bank_mask:0xf
	v_cndmask_b32_e64 v101, v101, v108, s[6:7]
	ds_bpermute_b32 v108, v134, v123
	v_mov_b32_e32 v103, 0
	v_mov_b32_dpp v102, v105 row_ror:8 row_mask:0xf bank_mask:0xf
	v_mov_b32_e32 v98, 0
	v_mov_b32_dpp v103, v106 row_ror:8 row_mask:0xf bank_mask:0xf
	v_mov_b32_e32 v99, 0
	v_mov_b32_e32 v100, 0
	v_mov_b32_e32 v110, 0
	v_mov_b32_dpp v98, v96 row_ror:8 row_mask:0xf bank_mask:0xf
	v_mov_b32_dpp v99, v97 row_ror:8 row_mask:0xf bank_mask:0xf
	v_mov_b32_dpp v100, v104 row_ror:8 row_mask:0xf bank_mask:0xf
	v_cndmask_b32_e64 v102, v96, v102, s[6:7]
	v_cndmask_b32_e64 v103, v97, v103, s[6:7]
	v_lshl_add_u64 v[96:97], s[36:37], 0, v[114:115]
	v_mov_b32_dpp v110, v107 row_ror:8 row_mask:0xf bank_mask:0xf
	v_cndmask_b32_e64 v99, v99, v106, s[6:7]
	v_cndmask_b32_e64 v100, v100, v107, s[6:7]
	v_lshl_add_u64 v[106:107], v[96:97], 0, v[162:163]
	s_waitcnt lgkmcnt(0)
	v_add_f32_e32 v96, v123, v108
	ds_bpermute_b32 v97, v135, v96
	v_cndmask_b32_e64 v98, v98, v105, s[6:7]
	global_store_dwordx4 v[106:107], v[98:101], off
	v_cndmask_b32_e64 v104, v104, v110, s[6:7]
	v_cndmask_b32_e64 v105, v109, v111, s[6:7]
	v_lshl_add_u64 v[98:99], s[36:37], 0, v[116:117]
	v_lshl_add_u64 v[98:99], v[98:99], 0, v[162:163]
	global_store_dwordx4 v[98:99], v[102:105], off
	s_and_saveexec_b64 s[56:57], s[8:9]
	s_cbranch_execz .LBB0_889
	v_lshl_add_u64 v[98:99], v[112:113], 2, s[18:19]
	s_waitcnt lgkmcnt(0)
	v_add_f32_e32 v96, v96, v97
	global_atomic_add_f32 v[98:99], v96, off
.LBB0_889:
	s_or_b64 exec, exec, s[56:57]
	v_or_b32_e32 v96, 48, v164
	s_waitcnt lgkmcnt(0)
	v_ashrrev_i32_e32 v97, 31, v96
	v_lshl_add_u64 v[98:99], v[96:97], 2, s[40:41]
	s_waitcnt vmcnt(2)
	s_nop 0
	v_mov_b32_e32 v118, v226
	v_sub_u32_e32 v98, v96, v172
	v_add_u32_e32 v98, v98, v174
	v_ashrrev_i32_e32 v99, 31, v98
	v_lshlrev_b64 v[98:99], 12, v[98:99]
	v_lshl_add_u64 v[100:101], s[16:17], 0, v[98:99]
	v_lshl_add_u64 v[100:101], v[100:101], 0, v[162:163]
	v_mov_b64_e32 v[102:103], v[228:229]
	v_mov_b64_e32 v[104:105], v[230:231]
	v_lshl_add_u64 v[100:101], s[38:39], 0, v[98:99]
	v_lshl_add_u64 v[100:101], v[100:101], 0, v[162:163]
	v_mov_b64_e32 v[106:107], v[232:233]
	v_mov_b64_e32 v[108:109], v[234:235]
	v_lshl_add_u64 v[100:101], v[98:99], 0, s[44:45]
	v_lshl_add_u64 v[114:115], s[38:39], 0, v[100:101]
	v_lshl_add_u64 v[110:111], s[16:17], 0, v[100:101]
	v_lshl_add_u64 v[114:115], v[114:115], 0, v[162:163]
	v_lshl_add_u64 v[110:111], v[110:111], 0, v[162:163]
	v_mov_b64_e32 v[114:115], v[236:237]
	v_mov_b64_e32 v[116:117], v[238:239]
	v_mul_f32_e32 v92, 0xbfb8aa3b, v92
	v_mov_b64_e32 v[110:111], v[240:241]
	v_mov_b64_e32 v[112:113], v[242:243]
	s_nop 1
	v_add_u32_e32 v216, 0x80, v164
	v_sub_u32_e32 v218, v216, v172
	v_add_u32_e32 v218, v218, v174
	v_ashrrev_i32_e32 v219, 31, v218
	v_lshlrev_b64 v[218:219], 12, v[218:219]
	v_lshl_add_u64 v[220:221], s[16:17], 0, v[218:219]
	v_lshl_add_u64 v[220:221], v[220:221], 0, v[162:163]
	global_load_dwordx4 v[228:231], v[220:221], off
	v_lshl_add_u64 v[220:221], s[38:39], 0, v[218:219]
	v_lshl_add_u64 v[220:221], v[220:221], 0, v[162:163]
	global_load_dword v226, v[166:167], off offset:512
	global_load_dwordx4 v[232:235], v[220:221], off
	v_lshl_add_u64 v[220:221], v[218:219], 0, s[44:45]
	v_lshl_add_u64 v[224:225], s[38:39], 0, v[220:221]
	v_lshl_add_u64 v[222:223], s[16:17], 0, v[220:221]
	v_lshl_add_u64 v[224:225], v[224:225], 0, v[162:163]
	v_lshl_add_u64 v[222:223], v[222:223], 0, v[162:163]
	global_load_dwordx4 v[236:239], v[224:225], off
	global_load_dwordx4 v[240:243], v[222:223], off
	v_exp_f32_e32 v92, v92
	v_mul_f32_e32 v93, 0xbfb8aa3b, v93
	v_exp_f32_e32 v93, v93
	v_mov_b32_e32 v131, 0
	v_mov_b32_e32 v123, 0
; __device__ __forceinline__ unsigned cvt_pk_bf16(float lo, float hi) { unsigned r; asm volatile("v_cvt_pk_bf16_f32 %0, %1, %2" : "=v"(r) : "v"(lo), "v"(hi)); return r; }
; __device__ __forceinline__ float bflo(unsigned w) { return __uint_as_float(w << 16); }
; __device__ __forceinline__ float bfhi(unsigned w) { return __uint_as_float(w & 0xffff0000u); }
;     __device__ __forceinline__ void operator()(const f32x4 (&acc)[2][2][4][2], const Unit& u, int wr, int wc, int fr, int fq) const {
;     ...
;             for (int m = 0; m < 4; ++m) { const int row = row0 + ai * HALF + m * 16; const size_t off = (size_t)row * D + col0; const float ri = __builtin_amdgcn_rsqf(sse[row] * (1.f / D) + EPS); float sq = 0.f; u32x4 w[2];
;                 u32x4 rr[2], ee[2]; load_pair_lines(R, D, row, fr, col0, rr[0], rr[1]); load_pair_lines(E, D, row, fr, col0, ee[0], ee[1]);
; #pragma unroll
;                 for (int bj = 0; bj < 2; ++bj) { const u32x4 rw = rr[bj], ew = ee[bj];
;                     const float r[8] = {bflo(rw.x), bfhi(rw.x), bflo(rw.y), bfhi(rw.y), bflo(rw.z), bfhi(rw.z), bflo(rw.w), bfhi(rw.w)};
;                     const float e[8] = {bflo(ew.x), bfhi(ew.x), bflo(ew.y), bfhi(ew.y), bflo(ew.z), bfhi(ew.z), bflo(ew.w), bfhi(ew.w)};
;                     float o[8];
; #pragma unroll
;                     for (int j = 0; j < 8; ++j) { const float a = acc[ai][bj][m][j >> 2][j & 3]; const float gg = gv[bj][j >> 2][j & 3];
;                         o[j] = r[j] + e[j] * ri * gg * __builtin_amdgcn_rcpf(1.f + __builtin_amdgcn_exp2f(-a * LOG2E)); }
;                     if (OUT) { *(f32x4*)(OUT + off + 8 * bj) = (f32x4){o[0], o[1], o[2], o[3]}; *(f32x4*)(OUT + off + 8 * bj + 4) = (f32x4){o[4], o[5], o[6], o[7]}; }
;                     else { sq += (o[0] * o[0] + o[1] * o[1]) + (o[2] * o[2] + o[3] * o[3]) + (o[4] * o[4] + o[5] * o[5]) + (o[6] * o[6] + o[7] * o[7]);
;                         w[bj].x = cvt_pk_bf16(o[0], o[1]); w[bj].y = cvt_pk_bf16(o[2], o[3]); w[bj].z = cvt_pk_bf16(o[4], o[5]); w[bj].w = cvt_pk_bf16(o[6], o[7]); } }
	v_mov_b32_e32 v127, 0
	v_add_f32_e32 v92, 1.0, v92
	v_mov_b32_e32 v119, 0
	v_rcp_f32_e32 v92, v92
	v_add_f32_e32 v93, 1.0, v93
	v_rcp_f32_e32 v93, v93
	v_mov_b32_e32 v132, 0
	v_mul_f32_e32 v88, 0xbfb8aa3b, v88
	v_mov_b32_e32 v124, 0
	v_mov_b32_e32 v128, 0
	v_exp_f32_e32 v88, v88
	v_mov_b32_e32 v120, 0
	v_mul_f32_e32 v89, 0xbfb8aa3b, v89
	v_exp_f32_e32 v89, v89
	v_mov_b32_e32 v133, 0
	v_mov_b32_e32 v125, 0
	v_mov_b32_e32 v129, 0
	v_add_f32_e32 v88, 1.0, v88
	v_mov_b32_e32 v121, 0
	v_rcp_f32_e32 v88, v88
	v_add_f32_e32 v89, 1.0, v89
	v_mul_f32_e32 v84, 0xbfb8aa3b, v84
	v_rcp_f32_e32 v89, v89
	v_exp_f32_e32 v84, v84
	v_mul_f32_e32 v85, 0xbfb8aa3b, v85
	v_exp_f32_e32 v85, v85
	v_mov_b32_e32 v136, 0
	v_add_f32_e32 v84, 1.0, v84
	v_rcp_f32_e32 v84, v84
	v_add_f32_e32 v85, 1.0, v85
	v_rcp_f32_e32 v85, v85
	v_mov_b32_e32 v126, 0
	v_mov_b32_e32 v130, 0
	v_mov_b32_e32 v122, 0
	v_mul_f32_e32 v80, 0xbfb8aa3b, v80
	v_exp_f32_e32 v80, v80
	v_mul_f32_e32 v81, 0xbfb8aa3b, v81
	v_exp_f32_e32 v81, v81
	v_add_f32_e32 v80, 1.0, v80
	v_rcp_f32_e32 v80, v80
	v_add_f32_e32 v81, 1.0, v81
	v_rcp_f32_e32 v81, v81
	v_fmamk_f32 v118, v118, 0x3a000000, v180
	v_rsq_f32_e32 v118, v118
	v_mov_b32_dpp v119, v102 row_ror:8 row_mask:0xf bank_mask:0xf
	v_mov_b32_dpp v120, v103 row_ror:8 row_mask:0xf bank_mask:0xf
	v_mov_b32_dpp v121, v104 row_ror:8 row_mask:0xf bank_mask:0xf
	v_mov_b32_dpp v127, v106 row_ror:8 row_mask:0xf bank_mask:0xf
	v_mov_b32_dpp v128, v107 row_ror:8 row_mask:0xf bank_mask:0xf
	v_mov_b32_dpp v129, v108 row_ror:8 row_mask:0xf bank_mask:0xf
	v_mov_b32_dpp v130, v109 row_ror:8 row_mask:0xf bank_mask:0xf
	v_mov_b32_dpp v122, v105 row_ror:8 row_mask:0xf bank_mask:0xf
	v_mov_b32_dpp v131, v114 row_ror:8 row_mask:0xf bank_mask:0xf
	v_cndmask_b32_e64 v106, v131, v106, s[6:7]
	v_mov_b32_dpp v123, v110 row_ror:8 row_mask:0xf bank_mask:0xf
	v_cndmask_b32_e64 v102, v123, v102, s[6:7]
	v_lshlrev_b32_e32 v123, 16, v106
	v_mul_f32_e32 v123, v118, v123
	v_cndmask_b32_e64 v110, v110, v119, s[6:7]
	v_lshlrev_b32_e32 v119, 16, v102
	v_and_b32_e32 v106, 0xffff0000, v106
	v_mul_f32_e32 v123, v52, v123
	v_fmac_f32_e32 v119, v92, v123
	v_mul_f32_e32 v92, v118, v106
	v_and_b32_e32 v102, 0xffff0000, v102
	v_mul_f32_e32 v92, v53, v92
	v_fmac_f32_e32 v102, v93, v92
	v_mul_f32_e32 v92, 0xbfb8aa3b, v94
	v_exp_f32_e32 v92, v92
	v_mul_f32_e32 v94, 0xbfb8aa3b, v95
	v_exp_f32_e32 v94, v94
	v_mov_b32_dpp v132, v115 row_ror:8 row_mask:0xf bank_mask:0xf
	v_add_f32_e32 v92, 1.0, v92
	v_mov_b32_dpp v124, v111 row_ror:8 row_mask:0xf bank_mask:0xf
	v_cndmask_b32_e64 v107, v132, v107, s[6:7]
	v_rcp_f32_e32 v92, v92
	v_cndmask_b32_e64 v103, v124, v103, s[6:7]
	v_lshlrev_b32_e32 v124, 16, v107
	v_add_f32_e32 v94, 1.0, v94
	v_mul_f32_e32 v93, v118, v124
	v_rcp_f32_e32 v94, v94
	v_cndmask_b32_e64 v111, v111, v120, s[6:7]
	v_mov_b32_dpp v133, v116 row_ror:8 row_mask:0xf bank_mask:0xf
	v_lshlrev_b32_e32 v120, 16, v103
	v_and_b32_e32 v107, 0xffff0000, v107
	v_mul_f32_e32 v93, v54, v93
	v_mov_b32_dpp v125, v112 row_ror:8 row_mask:0xf bank_mask:0xf
	v_cndmask_b32_e64 v108, v133, v108, s[6:7]
	v_fmac_f32_e32 v120, v92, v93
	v_mul_f32_e32 v92, v118, v107
	v_cndmask_b32_e64 v104, v125, v104, s[6:7]
	v_and_b32_e32 v103, 0xffff0000, v103
	v_lshlrev_b32_e32 v125, 16, v108
	v_mul_f32_e32 v92, v55, v92
	v_fmac_f32_e32 v103, v94, v92
	v_mul_f32_e32 v92, v118, v125
	v_cndmask_b32_e64 v112, v112, v121, s[6:7]
	v_lshlrev_b32_e32 v121, 16, v104
	v_and_b32_e32 v108, 0xffff0000, v108
	v_mul_f32_e32 v92, v48, v92
	v_fmac_f32_e32 v121, v88, v92
	v_mul_f32_e32 v88, v118, v108
	v_and_b32_e32 v104, 0xffff0000, v104
	v_mul_f32_e32 v88, v49, v88
	v_fmac_f32_e32 v104, v89, v88
	v_mul_f32_e32 v88, 0xbfb8aa3b, v90
	v_cndmask_b32_e64 v114, v114, v127, s[6:7]
	v_exp_f32_e32 v88, v88
	v_mul_f32_e32 v90, 0xbfb8aa3b, v91
	v_lshlrev_b32_e32 v107, 16, v114
	v_exp_f32_e32 v90, v90
	v_mul_f32_e32 v107, v118, v107
	v_lshlrev_b32_e32 v93, 16, v110
	v_and_b32_e32 v108, 0xffff0000, v114
	v_mul_f32_e32 v107, v40, v107
	v_mov_b32_dpp v136, v117 row_ror:8 row_mask:0xf bank_mask:0xf
	v_add_f32_e32 v88, 1.0, v88
	v_fmac_f32_e32 v93, v84, v107
	v_mul_f32_e32 v84, v118, v108
	v_mov_b32_dpp v126, v113 row_ror:8 row_mask:0xf bank_mask:0xf
	v_cndmask_b32_e64 v109, v136, v109, s[6:7]
	v_rcp_f32_e32 v88, v88
	v_and_b32_e32 v94, 0xffff0000, v110
	v_mul_f32_e32 v84, v41, v84
	v_cndmask_b32_e64 v105, v126, v105, s[6:7]
	v_lshlrev_b32_e32 v126, 16, v109
	v_add_f32_e32 v90, 1.0, v90
	v_fmac_f32_e32 v94, v85, v84
	v_mul_f32_e32 v84, 0xbfb8aa3b, v86
	v_mul_f32_e32 v89, v118, v126
	v_rcp_f32_e32 v90, v90
	v_exp_f32_e32 v84, v84
	v_cndmask_b32_e64 v113, v113, v122, s[6:7]
	v_lshlrev_b32_e32 v122, 16, v105
	v_and_b32_e32 v109, 0xffff0000, v109
	v_mul_f32_e32 v89, v50, v89
	v_mul_f32_e32 v86, 0xbfb8aa3b, v87
	v_fmac_f32_e32 v122, v88, v89
	v_mul_f32_e32 v88, v118, v109
	v_exp_f32_e32 v86, v86
	v_and_b32_e32 v105, 0xffff0000, v105
	v_mul_f32_e32 v88, v51, v88
	v_fmac_f32_e32 v105, v90, v88
	v_mul_f32_e32 v88, v102, v102
	v_mul_f32_e32 v89, v103, v103
	v_add_f32_e32 v84, 1.0, v84
	v_cndmask_b32_e64 v115, v115, v128, s[6:7]
	v_fmac_f32_e32 v88, v119, v119
	v_fmac_f32_e32 v89, v120, v120
	v_rcp_f32_e32 v84, v84
	v_add_f32_e32 v88, v88, v89
	v_mul_f32_e32 v89, v104, v104
	v_lshlrev_b32_e32 v109, 16, v115
	v_add_f32_e32 v86, 1.0, v86
	v_fmac_f32_e32 v89, v121, v121
	v_mul_f32_e32 v85, v118, v109
	v_rcp_f32_e32 v86, v86
	v_add_f32_e32 v88, v89, v88
	v_mul_f32_e32 v89, v105, v105
	v_lshlrev_b32_e32 v95, 16, v111
	v_and_b32_e32 v110, 0xffff0000, v115
	v_mul_f32_e32 v85, v42, v85
	v_cndmask_b32_e64 v116, v116, v129, s[6:7]
	v_fmac_f32_e32 v89, v122, v122
; __device__ __forceinline__ unsigned cvt_pk_bf16(float lo, float hi) { unsigned r; asm volatile("v_cvt_pk_bf16_f32 %0, %1, %2" : "=v"(r) : "v"(lo), "v"(hi)); return r; }
; __device__ __forceinline__ float bflo(unsigned w) { return __uint_as_float(w << 16); }
; __device__ __forceinline__ float bfhi(unsigned w) { return __uint_as_float(w & 0xffff0000u); }
;     __device__ __forceinline__ void operator()(const f32x4 (&acc)[2][2][4][2], const Unit& u, int wr, int wc, int fr, int fq) const {
;     ...
;                 for (int bj = 0; bj < 2; ++bj) { const u32x4 rw = rr[bj], ew = ee[bj];
;                     const float r[8] = {bflo(rw.x), bfhi(rw.x), bflo(rw.y), bfhi(rw.y), bflo(rw.z), bfhi(rw.z), bflo(rw.w), bfhi(rw.w)};
;                     const float e[8] = {bflo(ew.x), bfhi(ew.x), bflo(ew.y), bfhi(ew.y), bflo(ew.z), bfhi(ew.z), bflo(ew.w), bfhi(ew.w)};
;                     float o[8];
; #pragma unroll
;                     for (int j = 0; j < 8; ++j) { const float a = acc[ai][bj][m][j >> 2][j & 3]; const float gg = gv[bj][j >> 2][j & 3];
;                         o[j] = r[j] + e[j] * ri * gg * __builtin_amdgcn_rcpf(1.f + __builtin_amdgcn_exp2f(-a * LOG2E)); }
;                     if (OUT) { *(f32x4*)(OUT + off + 8 * bj) = (f32x4){o[0], o[1], o[2], o[3]}; *(f32x4*)(OUT + off + 8 * bj + 4) = (f32x4){o[4], o[5], o[6], o[7]}; }
;                     else { sq += (o[0] * o[0] + o[1] * o[1]) + (o[2] * o[2] + o[3] * o[3]) + (o[4] * o[4] + o[5] * o[5]) + (o[6] * o[6] + o[7] * o[7]);
;                         w[bj].x = cvt_pk_bf16(o[0], o[1]); w[bj].y = cvt_pk_bf16(o[2], o[3]); w[bj].z = cvt_pk_bf16(o[4], o[5]); w[bj].w = cvt_pk_bf16(o[6], o[7]); } }
;                 if (!OUT) { store_pair_lines(O, D, row, fr, col0, w[0], w[1]);
;                     sq += __shfl_xor(sq, 16); sq += __shfl_xor(sq, 32); if (fq == 0) unsafeAtomicAdd(ssout + row, sq); } }
	v_fmac_f32_e32 v95, v84, v85
	v_mul_f32_e32 v84, v118, v110
	v_add_f32_e32 v88, v89, v88
	v_cvt_pk_bf16_f32 v89, v119, v102
	v_and_b32_e32 v102, 0xffff0000, v111
	v_lshlrev_b32_e32 v111, 16, v116
	v_mul_f32_e32 v84, v43, v84
	v_fmac_f32_e32 v102, v86, v84
	v_mul_f32_e32 v84, v118, v111
	v_cvt_pk_bf16_f32 v90, v120, v103
	v_cvt_pk_bf16_f32 v91, v121, v104
	v_lshlrev_b32_e32 v103, 16, v112
	v_and_b32_e32 v104, 0xffff0000, v112
	v_and_b32_e32 v112, 0xffff0000, v116
	v_mul_f32_e32 v84, v32, v84
	v_fmac_f32_e32 v103, v80, v84
	v_mul_f32_e32 v80, v118, v112
	v_mul_f32_e32 v80, v33, v80
	v_fmac_f32_e32 v104, v81, v80
	v_mul_f32_e32 v80, 0xbfb8aa3b, v82
	v_exp_f32_e32 v80, v80
	v_mul_f32_e32 v82, 0xbfb8aa3b, v83
	v_exp_f32_e32 v82, v82
	v_cndmask_b32_e64 v117, v117, v130, s[6:7]
	v_add_f32_e32 v80, 1.0, v80
	v_rcp_f32_e32 v80, v80
	v_cvt_pk_bf16_f32 v92, v122, v105
	v_lshlrev_b32_e32 v105, 16, v113
	v_and_b32_e32 v106, 0xffff0000, v113
	v_lshlrev_b32_e32 v113, 16, v117
	v_add_f32_e32 v82, 1.0, v82
	v_mul_f32_e32 v81, v118, v113
	v_rcp_f32_e32 v82, v82
	v_and_b32_e32 v114, 0xffff0000, v117
	v_mul_f32_e32 v81, v34, v81
	v_fmac_f32_e32 v105, v80, v81
	v_mul_f32_e32 v80, v118, v114
	v_mul_f32_e32 v80, v35, v80
	v_fmac_f32_e32 v106, v82, v80
	v_mul_f32_e32 v80, v94, v94
	v_mul_f32_e32 v81, v102, v102
	v_fmac_f32_e32 v80, v93, v93
	v_fmac_f32_e32 v81, v95, v95
	v_add_f32_e32 v80, v80, v81
	v_mul_f32_e32 v81, v104, v104
	v_fmac_f32_e32 v81, v103, v103
	v_add_f32_e32 v80, v81, v80
	v_mul_f32_e32 v81, v106, v106
	v_fmac_f32_e32 v81, v105, v105
	v_add_f32_e32 v80, v81, v80
	v_mov_b32_e32 v85, 0
	v_add_f32_e32 v107, v80, v88
	v_cvt_pk_bf16_f32 v80, v93, v94
	v_cvt_pk_bf16_f32 v81, v95, v102
	v_cvt_pk_bf16_f32 v88, v103, v104
	v_cvt_pk_bf16_f32 v93, v105, v106
	v_mov_b32_e32 v95, 0
	v_mov_b32_e32 v86, 0
	v_mov_b32_dpp v85, v93 row_ror:8 row_mask:0xf bank_mask:0xf
	v_mov_b32_dpp v95, v92 row_ror:8 row_mask:0xf bank_mask:0xf
	v_cndmask_b32_e64 v85, v85, v92, s[6:7]
	ds_bpermute_b32 v92, v134, v107
	v_mov_b32_e32 v87, 0
	v_mov_b32_dpp v86, v89 row_ror:8 row_mask:0xf bank_mask:0xf
	v_mov_b32_e32 v82, 0
	v_mov_b32_dpp v87, v90 row_ror:8 row_mask:0xf bank_mask:0xf
	v_mov_b32_e32 v83, 0
	v_mov_b32_e32 v84, 0
	v_mov_b32_e32 v94, 0
	v_mov_b32_dpp v82, v80 row_ror:8 row_mask:0xf bank_mask:0xf
	v_mov_b32_dpp v83, v81 row_ror:8 row_mask:0xf bank_mask:0xf
	v_mov_b32_dpp v84, v88 row_ror:8 row_mask:0xf bank_mask:0xf
	v_cndmask_b32_e64 v86, v80, v86, s[6:7]
	v_cndmask_b32_e64 v87, v81, v87, s[6:7]
	v_lshl_add_u64 v[80:81], s[36:37], 0, v[98:99]
	v_mov_b32_dpp v94, v91 row_ror:8 row_mask:0xf bank_mask:0xf
	v_cndmask_b32_e64 v83, v83, v90, s[6:7]
	v_cndmask_b32_e64 v84, v84, v91, s[6:7]
	v_lshl_add_u64 v[90:91], v[80:81], 0, v[162:163]
	s_waitcnt lgkmcnt(0)
	v_add_f32_e32 v80, v107, v92
	ds_bpermute_b32 v81, v135, v80
	v_cndmask_b32_e64 v82, v82, v89, s[6:7]
	global_store_dwordx4 v[90:91], v[82:85], off
	v_cndmask_b32_e64 v88, v88, v94, s[6:7]
	v_cndmask_b32_e64 v89, v93, v95, s[6:7]
	v_lshl_add_u64 v[82:83], s[36:37], 0, v[100:101]
	v_lshl_add_u64 v[82:83], v[82:83], 0, v[162:163]
	global_store_dwordx4 v[82:83], v[86:89], off
	s_and_saveexec_b64 s[56:57], s[8:9]
	s_cbranch_execz .LBB0_891
	v_lshl_add_u64 v[82:83], v[96:97], 2, s[18:19]
	s_waitcnt lgkmcnt(0)
	v_add_f32_e32 v80, v80, v81
	global_atomic_add_f32 v[82:83], v80, off
.LBB0_891:
	s_or_b64 exec, exec, s[56:57]
	v_add_u32_e32 v80, 0x80, v164
	v_sub_u32_e32 v82, v80, v172
	v_add_u32_e32 v82, v82, v174
	v_ashrrev_i32_e32 v83, 31, v82
	v_lshlrev_b64 v[82:83], 12, v[82:83]
	v_lshl_add_u64 v[84:85], s[16:17], 0, v[82:83]
	v_lshl_add_u64 v[84:85], v[84:85], 0, v[162:163]
	s_waitcnt vmcnt(2)
	s_nop 0
	v_mov_b64_e32 v[86:87], v[228:229]
	v_mov_b64_e32 v[88:89], v[230:231]
	v_lshl_add_u64 v[84:85], s[38:39], 0, v[82:83]
	v_lshl_add_u64 v[84:85], v[84:85], 0, v[162:163]
	s_waitcnt lgkmcnt(0)
	v_mov_b32_e32 v81, v226
	v_mov_b64_e32 v[90:91], v[232:233]
	v_mov_b64_e32 v[92:93], v[234:235]
	v_lshl_add_u64 v[84:85], v[82:83], 0, s[44:45]
	v_lshl_add_u64 v[98:99], s[38:39], 0, v[84:85]
	v_lshl_add_u64 v[94:95], s[16:17], 0, v[84:85]
	v_lshl_add_u64 v[98:99], v[98:99], 0, v[162:163]
	v_lshl_add_u64 v[94:95], v[94:95], 0, v[162:163]
	v_mov_b64_e32 v[98:99], v[236:237]
	v_mov_b64_e32 v[100:101], v[238:239]
	v_mul_f32_e32 v76, 0xbfb8aa3b, v76
	v_mov_b64_e32 v[94:95], v[240:241]
	v_mov_b64_e32 v[96:97], v[242:243]
	s_nop 1
	v_add_u32_e32 v216, 0x90, v164
	v_sub_u32_e32 v218, v216, v172
	v_add_u32_e32 v218, v218, v174
	v_ashrrev_i32_e32 v219, 31, v218
	v_lshlrev_b64 v[218:219], 12, v[218:219]
	v_lshl_add_u64 v[220:221], s[16:17], 0, v[218:219]
	v_lshl_add_u64 v[220:221], v[220:221], 0, v[162:163]
	global_load_dwordx4 v[228:231], v[220:221], off
	v_lshl_add_u64 v[220:221], s[38:39], 0, v[218:219]
	v_lshl_add_u64 v[220:221], v[220:221], 0, v[162:163]
	global_load_dword v226, v[166:167], off offset:576
	global_load_dwordx4 v[232:235], v[220:221], off
	v_lshl_add_u64 v[220:221], v[218:219], 0, s[44:45]
	v_lshl_add_u64 v[224:225], s[38:39], 0, v[220:221]
	v_lshl_add_u64 v[222:223], s[16:17], 0, v[220:221]
	v_lshl_add_u64 v[224:225], v[224:225], 0, v[162:163]
	v_lshl_add_u64 v[222:223], v[222:223], 0, v[162:163]
	global_load_dwordx4 v[236:239], v[224:225], off
	global_load_dwordx4 v[240:243], v[222:223], off
	v_exp_f32_e32 v76, v76
	v_mul_f32_e32 v77, 0xbfb8aa3b, v77
	v_exp_f32_e32 v77, v77
	v_mov_b32_e32 v114, 0
	v_mov_b32_e32 v106, 0
	v_mov_b32_e32 v110, 0
	v_add_f32_e32 v76, 1.0, v76
	v_mov_b32_e32 v102, 0
	v_rcp_f32_e32 v76, v76
	v_add_f32_e32 v77, 1.0, v77
	v_rcp_f32_e32 v77, v77
	v_mov_b32_e32 v115, 0
	v_mul_f32_e32 v72, 0xbfb8aa3b, v72
; __device__ __forceinline__ unsigned cvt_pk_bf16(float lo, float hi) { unsigned r; asm volatile("v_cvt_pk_bf16_f32 %0, %1, %2" : "=v"(r) : "v"(lo), "v"(hi)); return r; }
; __device__ __forceinline__ float bflo(unsigned w) { return __uint_as_float(w << 16); }
; __device__ __forceinline__ float bfhi(unsigned w) { return __uint_as_float(w & 0xffff0000u); }
;     __device__ __forceinline__ void operator()(const f32x4 (&acc)[2][2][4][2], const Unit& u, int wr, int wc, int fr, int fq) const {
;     ...
;             for (int m = 0; m < 4; ++m) { const int row = row0 + ai * HALF + m * 16; const size_t off = (size_t)row * D + col0; const float ri = __builtin_amdgcn_rsqf(sse[row] * (1.f / D) + EPS); float sq = 0.f; u32x4 w[2];
;                 u32x4 rr[2], ee[2]; load_pair_lines(R, D, row, fr, col0, rr[0], rr[1]); load_pair_lines(E, D, row, fr, col0, ee[0], ee[1]);
; #pragma unroll
;                 for (int bj = 0; bj < 2; ++bj) { const u32x4 rw = rr[bj], ew = ee[bj];
;                     const float r[8] = {bflo(rw.x), bfhi(rw.x), bflo(rw.y), bfhi(rw.y), bflo(rw.z), bfhi(rw.z), bflo(rw.w), bfhi(rw.w)};
;                     const float e[8] = {bflo(ew.x), bfhi(ew.x), bflo(ew.y), bfhi(ew.y), bflo(ew.z), bfhi(ew.z), bflo(ew.w), bfhi(ew.w)};
;                     float o[8];
; #pragma unroll
;                     for (int j = 0; j < 8; ++j) { const float a = acc[ai][bj][m][j >> 2][j & 3]; const float gg = gv[bj][j >> 2][j & 3];
;                         o[j] = r[j] + e[j] * ri * gg * __builtin_amdgcn_rcpf(1.f + __builtin_amdgcn_exp2f(-a * LOG2E)); }
;                     if (OUT) { *(f32x4*)(OUT + off + 8 * bj) = (f32x4){o[0], o[1], o[2], o[3]}; *(f32x4*)(OUT + off + 8 * bj + 4) = (f32x4){o[4], o[5], o[6], o[7]}; }
;                     else { sq += (o[0] * o[0] + o[1] * o[1]) + (o[2] * o[2] + o[3] * o[3]) + (o[4] * o[4] + o[5] * o[5]) + (o[6] * o[6] + o[7] * o[7]);
;                         w[bj].x = cvt_pk_bf16(o[0], o[1]); w[bj].y = cvt_pk_bf16(o[2], o[3]); w[bj].z = cvt_pk_bf16(o[4], o[5]); w[bj].w = cvt_pk_bf16(o[6], o[7]); } }
	v_mov_b32_e32 v107, 0
	v_mov_b32_e32 v111, 0
	v_exp_f32_e32 v72, v72
	v_mov_b32_e32 v103, 0
	v_mul_f32_e32 v73, 0xbfb8aa3b, v73
	v_exp_f32_e32 v73, v73
	v_mov_b32_e32 v116, 0
	v_mov_b32_e32 v108, 0
	v_mov_b32_e32 v112, 0
	v_add_f32_e32 v72, 1.0, v72
	v_mov_b32_e32 v104, 0
	v_rcp_f32_e32 v72, v72
	v_add_f32_e32 v73, 1.0, v73
	v_mul_f32_e32 v68, 0xbfb8aa3b, v68
	v_rcp_f32_e32 v73, v73
	v_exp_f32_e32 v68, v68
	v_mul_f32_e32 v69, 0xbfb8aa3b, v69
	v_exp_f32_e32 v69, v69
	v_mov_b32_e32 v117, 0
	v_add_f32_e32 v68, 1.0, v68
	v_rcp_f32_e32 v68, v68
	v_add_f32_e32 v69, 1.0, v69
	v_rcp_f32_e32 v69, v69
	v_mov_b32_e32 v109, 0
	v_mov_b32_e32 v113, 0
	v_mov_b32_e32 v105, 0
	v_mul_f32_e32 v64, 0xbfb8aa3b, v64
	v_exp_f32_e32 v64, v64
	v_mul_f32_e32 v65, 0xbfb8aa3b, v65
	v_exp_f32_e32 v65, v65
	v_add_f32_e32 v64, 1.0, v64
	v_rcp_f32_e32 v64, v64
	v_add_f32_e32 v65, 1.0, v65
	v_rcp_f32_e32 v65, v65
	v_mov_b32_dpp v102, v86 row_ror:8 row_mask:0xf bank_mask:0xf
	v_mov_b32_dpp v103, v87 row_ror:8 row_mask:0xf bank_mask:0xf
	v_mov_b32_dpp v104, v88 row_ror:8 row_mask:0xf bank_mask:0xf
	v_fmamk_f32 v81, v81, 0x3a000000, v180
	v_rsq_f32_e32 v81, v81
	v_mov_b32_dpp v110, v90 row_ror:8 row_mask:0xf bank_mask:0xf
	v_mov_b32_dpp v111, v91 row_ror:8 row_mask:0xf bank_mask:0xf
	v_mov_b32_dpp v112, v92 row_ror:8 row_mask:0xf bank_mask:0xf
	v_mov_b32_dpp v113, v93 row_ror:8 row_mask:0xf bank_mask:0xf
	v_mov_b32_dpp v105, v89 row_ror:8 row_mask:0xf bank_mask:0xf
	v_mov_b32_dpp v114, v98 row_ror:8 row_mask:0xf bank_mask:0xf
	v_cndmask_b32_e64 v90, v114, v90, s[6:7]
	v_mov_b32_dpp v106, v94 row_ror:8 row_mask:0xf bank_mask:0xf
	v_cndmask_b32_e64 v86, v106, v86, s[6:7]
	v_lshlrev_b32_e32 v106, 16, v90
	v_mul_f32_e32 v106, v81, v106
	v_cndmask_b32_e64 v94, v94, v102, s[6:7]
	v_lshlrev_b32_e32 v102, 16, v86
	v_and_b32_e32 v90, 0xffff0000, v90
	v_mul_f32_e32 v106, v52, v106
	v_fmac_f32_e32 v102, v76, v106
	v_mul_f32_e32 v76, v81, v90
	v_and_b32_e32 v86, 0xffff0000, v86
	v_mul_f32_e32 v76, v53, v76
	v_fmac_f32_e32 v86, v77, v76
	v_mul_f32_e32 v76, 0xbfb8aa3b, v78
	v_exp_f32_e32 v76, v76
	v_mul_f32_e32 v78, 0xbfb8aa3b, v79
	v_exp_f32_e32 v78, v78
	v_mov_b32_dpp v115, v99 row_ror:8 row_mask:0xf bank_mask:0xf
	v_add_f32_e32 v76, 1.0, v76
	v_mov_b32_dpp v107, v95 row_ror:8 row_mask:0xf bank_mask:0xf
	v_cndmask_b32_e64 v91, v115, v91, s[6:7]
	v_rcp_f32_e32 v76, v76
	v_cndmask_b32_e64 v87, v107, v87, s[6:7]
	v_lshlrev_b32_e32 v107, 16, v91
	v_add_f32_e32 v78, 1.0, v78
	v_mul_f32_e32 v77, v81, v107
	v_rcp_f32_e32 v78, v78
	v_cndmask_b32_e64 v95, v95, v103, s[6:7]
	v_mov_b32_dpp v116, v100 row_ror:8 row_mask:0xf bank_mask:0xf
	v_lshlrev_b32_e32 v103, 16, v87
	v_and_b32_e32 v91, 0xffff0000, v91
	v_mul_f32_e32 v77, v54, v77
	v_mov_b32_dpp v108, v96 row_ror:8 row_mask:0xf bank_mask:0xf
	v_cndmask_b32_e64 v92, v116, v92, s[6:7]
	v_fmac_f32_e32 v103, v76, v77
	v_mul_f32_e32 v76, v81, v91
	v_cndmask_b32_e64 v88, v108, v88, s[6:7]
	v_and_b32_e32 v87, 0xffff0000, v87
	v_lshlrev_b32_e32 v108, 16, v92
	v_mul_f32_e32 v76, v55, v76
	v_fmac_f32_e32 v87, v78, v76
	v_mul_f32_e32 v76, v81, v108
	v_cndmask_b32_e64 v96, v96, v104, s[6:7]
	v_lshlrev_b32_e32 v104, 16, v88
	v_and_b32_e32 v92, 0xffff0000, v92
	v_mul_f32_e32 v76, v48, v76
	v_fmac_f32_e32 v104, v72, v76
	v_mul_f32_e32 v72, v81, v92
	v_and_b32_e32 v88, 0xffff0000, v88
	v_mul_f32_e32 v72, v49, v72
	v_fmac_f32_e32 v88, v73, v72
	v_mul_f32_e32 v72, 0xbfb8aa3b, v74
	v_cndmask_b32_e64 v98, v98, v110, s[6:7]
	v_exp_f32_e32 v72, v72
	v_mul_f32_e32 v74, 0xbfb8aa3b, v75
	v_lshlrev_b32_e32 v91, 16, v98
	v_exp_f32_e32 v74, v74
	v_mul_f32_e32 v91, v81, v91
	v_lshlrev_b32_e32 v77, 16, v94
	v_and_b32_e32 v92, 0xffff0000, v98
	v_mul_f32_e32 v91, v40, v91
	v_mov_b32_dpp v117, v101 row_ror:8 row_mask:0xf bank_mask:0xf
	v_add_f32_e32 v72, 1.0, v72
	v_fmac_f32_e32 v77, v68, v91
	v_mul_f32_e32 v68, v81, v92
	v_mov_b32_dpp v109, v97 row_ror:8 row_mask:0xf bank_mask:0xf
	v_cndmask_b32_e64 v93, v117, v93, s[6:7]
	v_rcp_f32_e32 v72, v72
	v_and_b32_e32 v78, 0xffff0000, v94
	v_mul_f32_e32 v68, v41, v68
	v_cndmask_b32_e64 v89, v109, v89, s[6:7]
	v_lshlrev_b32_e32 v109, 16, v93
	v_add_f32_e32 v74, 1.0, v74
	v_fmac_f32_e32 v78, v69, v68
	v_mul_f32_e32 v68, 0xbfb8aa3b, v70
	v_mul_f32_e32 v73, v81, v109
	v_rcp_f32_e32 v74, v74
	v_exp_f32_e32 v68, v68
	v_cndmask_b32_e64 v97, v97, v105, s[6:7]
	v_lshlrev_b32_e32 v105, 16, v89
	v_and_b32_e32 v93, 0xffff0000, v93
	v_mul_f32_e32 v73, v50, v73
	v_mul_f32_e32 v70, 0xbfb8aa3b, v71
	v_fmac_f32_e32 v105, v72, v73
	v_mul_f32_e32 v72, v81, v93
	v_exp_f32_e32 v70, v70
	v_and_b32_e32 v89, 0xffff0000, v89
	v_mul_f32_e32 v72, v51, v72
	v_fmac_f32_e32 v89, v74, v72
	v_mul_f32_e32 v72, v86, v86
	v_mul_f32_e32 v73, v87, v87
	v_add_f32_e32 v68, 1.0, v68
	v_cndmask_b32_e64 v99, v99, v111, s[6:7]
	v_fmac_f32_e32 v72, v102, v102
	v_fmac_f32_e32 v73, v103, v103
	v_rcp_f32_e32 v68, v68
	v_add_f32_e32 v72, v72, v73
	v_mul_f32_e32 v73, v88, v88
	v_lshlrev_b32_e32 v93, 16, v99
	v_add_f32_e32 v70, 1.0, v70
	v_fmac_f32_e32 v73, v104, v104
	v_mul_f32_e32 v69, v81, v93
	v_rcp_f32_e32 v70, v70
	v_add_f32_e32 v72, v73, v72
	v_mul_f32_e32 v73, v89, v89
	v_lshlrev_b32_e32 v79, 16, v95
	v_and_b32_e32 v94, 0xffff0000, v99
	v_mul_f32_e32 v69, v42, v69
	v_cndmask_b32_e64 v100, v100, v112, s[6:7]
	v_fmac_f32_e32 v73, v105, v105
	v_fmac_f32_e32 v79, v68, v69
	v_mul_f32_e32 v68, v81, v94
	v_add_f32_e32 v72, v73, v72
	v_cvt_pk_bf16_f32 v73, v102, v86
	v_and_b32_e32 v86, 0xffff0000, v95
	v_lshlrev_b32_e32 v95, 16, v100
	v_mul_f32_e32 v68, v43, v68
	v_fmac_f32_e32 v86, v70, v68
	v_mul_f32_e32 v68, v81, v95
	v_cvt_pk_bf16_f32 v74, v103, v87
	v_cvt_pk_bf16_f32 v75, v104, v88
; __device__ __forceinline__ unsigned cvt_pk_bf16(float lo, float hi) { unsigned r; asm volatile("v_cvt_pk_bf16_f32 %0, %1, %2" : "=v"(r) : "v"(lo), "v"(hi)); return r; }
; __device__ __forceinline__ float bflo(unsigned w) { return __uint_as_float(w << 16); }
; __device__ __forceinline__ float bfhi(unsigned w) { return __uint_as_float(w & 0xffff0000u); }
;     __device__ __forceinline__ void operator()(const f32x4 (&acc)[2][2][4][2], const Unit& u, int wr, int wc, int fr, int fq) const {
;     ...
;                 for (int bj = 0; bj < 2; ++bj) { const u32x4 rw = rr[bj], ew = ee[bj];
;                     const float r[8] = {bflo(rw.x), bfhi(rw.x), bflo(rw.y), bfhi(rw.y), bflo(rw.z), bfhi(rw.z), bflo(rw.w), bfhi(rw.w)};
;                     const float e[8] = {bflo(ew.x), bfhi(ew.x), bflo(ew.y), bfhi(ew.y), bflo(ew.z), bfhi(ew.z), bflo(ew.w), bfhi(ew.w)};
;                     float o[8];
; #pragma unroll
;                     for (int j = 0; j < 8; ++j) { const float a = acc[ai][bj][m][j >> 2][j & 3]; const float gg = gv[bj][j >> 2][j & 3];
;                         o[j] = r[j] + e[j] * ri * gg * __builtin_amdgcn_rcpf(1.f + __builtin_amdgcn_exp2f(-a * LOG2E)); }
;                     if (OUT) { *(f32x4*)(OUT + off + 8 * bj) = (f32x4){o[0], o[1], o[2], o[3]}; *(f32x4*)(OUT + off + 8 * bj + 4) = (f32x4){o[4], o[5], o[6], o[7]}; }
;                     else { sq += (o[0] * o[0] + o[1] * o[1]) + (o[2] * o[2] + o[3] * o[3]) + (o[4] * o[4] + o[5] * o[5]) + (o[6] * o[6] + o[7] * o[7]);
;                         w[bj].x = cvt_pk_bf16(o[0], o[1]); w[bj].y = cvt_pk_bf16(o[2], o[3]); w[bj].z = cvt_pk_bf16(o[4], o[5]); w[bj].w = cvt_pk_bf16(o[6], o[7]); } }
;                 if (!OUT) { store_pair_lines(O, D, row, fr, col0, w[0], w[1]);
;                     sq += __shfl_xor(sq, 16); sq += __shfl_xor(sq, 32); if (fq == 0) unsafeAtomicAdd(ssout + row, sq); } }
	v_lshlrev_b32_e32 v87, 16, v96
	v_and_b32_e32 v88, 0xffff0000, v96
	v_and_b32_e32 v96, 0xffff0000, v100
	v_mul_f32_e32 v68, v32, v68
	v_fmac_f32_e32 v87, v64, v68
	v_mul_f32_e32 v64, v81, v96
	v_mul_f32_e32 v64, v33, v64
	v_fmac_f32_e32 v88, v65, v64
	v_mul_f32_e32 v64, 0xbfb8aa3b, v66
	v_exp_f32_e32 v64, v64
	v_mul_f32_e32 v66, 0xbfb8aa3b, v67
	v_exp_f32_e32 v66, v66
	v_cndmask_b32_e64 v101, v101, v113, s[6:7]
	v_add_f32_e32 v64, 1.0, v64
	v_rcp_f32_e32 v64, v64
	v_cvt_pk_bf16_f32 v76, v105, v89
	v_lshlrev_b32_e32 v89, 16, v97
	v_and_b32_e32 v90, 0xffff0000, v97
	v_lshlrev_b32_e32 v97, 16, v101
	v_add_f32_e32 v66, 1.0, v66
	v_mul_f32_e32 v65, v81, v97
	v_rcp_f32_e32 v66, v66
	v_and_b32_e32 v98, 0xffff0000, v101
	v_mul_f32_e32 v65, v34, v65
	v_fmac_f32_e32 v89, v64, v65
	v_mul_f32_e32 v64, v81, v98
	v_mul_f32_e32 v64, v35, v64
	v_fmac_f32_e32 v90, v66, v64
	v_mul_f32_e32 v64, v78, v78
	v_mul_f32_e32 v65, v86, v86
	v_fmac_f32_e32 v64, v77, v77
	v_fmac_f32_e32 v65, v79, v79
	v_add_f32_e32 v64, v64, v65
	v_mul_f32_e32 v65, v88, v88
	v_fmac_f32_e32 v65, v87, v87
	v_add_f32_e32 v64, v65, v64
	v_mul_f32_e32 v65, v90, v90
	v_fmac_f32_e32 v65, v89, v89
	v_add_f32_e32 v64, v65, v64
	v_mov_b32_e32 v69, 0
	v_add_f32_e32 v81, v64, v72
	v_cvt_pk_bf16_f32 v64, v77, v78
	v_cvt_pk_bf16_f32 v65, v79, v86
	v_cvt_pk_bf16_f32 v72, v87, v88
	v_cvt_pk_bf16_f32 v77, v89, v90
	v_mov_b32_e32 v79, 0
	v_mov_b32_e32 v70, 0
	v_mov_b32_dpp v69, v77 row_ror:8 row_mask:0xf bank_mask:0xf
	v_mov_b32_dpp v79, v76 row_ror:8 row_mask:0xf bank_mask:0xf
	v_cndmask_b32_e64 v69, v69, v76, s[6:7]
	ds_bpermute_b32 v76, v134, v81
	v_mov_b32_e32 v71, 0
	v_mov_b32_dpp v70, v73 row_ror:8 row_mask:0xf bank_mask:0xf
	v_mov_b32_e32 v66, 0
	v_mov_b32_dpp v71, v74 row_ror:8 row_mask:0xf bank_mask:0xf
	v_mov_b32_e32 v67, 0
	v_mov_b32_e32 v68, 0
	v_mov_b32_e32 v78, 0
	v_mov_b32_dpp v66, v64 row_ror:8 row_mask:0xf bank_mask:0xf
	v_mov_b32_dpp v67, v65 row_ror:8 row_mask:0xf bank_mask:0xf
	v_mov_b32_dpp v68, v72 row_ror:8 row_mask:0xf bank_mask:0xf
	v_cndmask_b32_e64 v70, v64, v70, s[6:7]
	v_cndmask_b32_e64 v71, v65, v71, s[6:7]
	v_lshl_add_u64 v[64:65], s[36:37], 0, v[82:83]
	v_mov_b32_dpp v78, v75 row_ror:8 row_mask:0xf bank_mask:0xf
	v_cndmask_b32_e64 v67, v67, v74, s[6:7]
	v_cndmask_b32_e64 v68, v68, v75, s[6:7]
	v_lshl_add_u64 v[74:75], v[64:65], 0, v[162:163]
	s_waitcnt lgkmcnt(0)
	v_add_f32_e32 v64, v81, v76
	ds_bpermute_b32 v65, v135, v64
	v_cndmask_b32_e64 v66, v66, v73, s[6:7]
	global_store_dwordx4 v[74:75], v[66:69], off
	v_cndmask_b32_e64 v72, v72, v78, s[6:7]
	v_cndmask_b32_e64 v73, v77, v79, s[6:7]
	v_lshl_add_u64 v[66:67], s[36:37], 0, v[84:85]
	v_lshl_add_u64 v[66:67], v[66:67], 0, v[162:163]
	global_store_dwordx4 v[66:67], v[70:73], off
	s_and_saveexec_b64 s[56:57], s[8:9]
	s_cbranch_execz .LBB0_893
	v_ashrrev_i32_e32 v81, 31, v80
	v_lshl_add_u64 v[66:67], v[80:81], 2, s[18:19]
	s_waitcnt lgkmcnt(0)
	v_add_f32_e32 v64, v64, v65
	global_atomic_add_f32 v[66:67], v64, off
.LBB0_893:
	s_or_b64 exec, exec, s[56:57]
	v_add_u32_e32 v64, 0x90, v164
	v_sub_u32_e32 v66, v64, v172
	v_add_u32_e32 v66, v66, v174
	v_ashrrev_i32_e32 v67, 31, v66
	v_lshlrev_b64 v[66:67], 12, v[66:67]
	v_lshl_add_u64 v[68:69], s[16:17], 0, v[66:67]
	v_lshl_add_u64 v[68:69], v[68:69], 0, v[162:163]
	s_waitcnt vmcnt(2)
	s_nop 0
	v_mov_b64_e32 v[70:71], v[228:229]
	v_mov_b64_e32 v[72:73], v[230:231]
	v_lshl_add_u64 v[68:69], s[38:39], 0, v[66:67]
	v_lshl_add_u64 v[68:69], v[68:69], 0, v[162:163]
	s_waitcnt lgkmcnt(0)
	v_mov_b32_e32 v65, v226
	v_mov_b64_e32 v[74:75], v[232:233]
	v_mov_b64_e32 v[76:77], v[234:235]
	v_lshl_add_u64 v[68:69], v[66:67], 0, s[44:45]
	v_lshl_add_u64 v[82:83], s[38:39], 0, v[68:69]
	v_lshl_add_u64 v[78:79], s[16:17], 0, v[68:69]
	v_lshl_add_u64 v[82:83], v[82:83], 0, v[162:163]
	v_lshl_add_u64 v[78:79], v[78:79], 0, v[162:163]
	v_mov_b64_e32 v[82:83], v[236:237]
	v_mov_b64_e32 v[84:85], v[238:239]
	v_mul_f32_e32 v60, 0xbfb8aa3b, v60
	v_mov_b64_e32 v[78:79], v[240:241]
	v_mov_b64_e32 v[80:81], v[242:243]
	s_nop 1
	v_add_u32_e32 v216, 0xa0, v164
	v_sub_u32_e32 v218, v216, v172
	v_add_u32_e32 v218, v218, v174
	v_ashrrev_i32_e32 v219, 31, v218
	v_lshlrev_b64 v[218:219], 12, v[218:219]
	v_lshl_add_u64 v[220:221], s[16:17], 0, v[218:219]
	v_lshl_add_u64 v[220:221], v[220:221], 0, v[162:163]
	global_load_dwordx4 v[228:231], v[220:221], off
	v_lshl_add_u64 v[220:221], s[38:39], 0, v[218:219]
	v_lshl_add_u64 v[220:221], v[220:221], 0, v[162:163]
	global_load_dword v226, v[166:167], off offset:640
	global_load_dwordx4 v[232:235], v[220:221], off
	v_lshl_add_u64 v[220:221], v[218:219], 0, s[44:45]
	v_lshl_add_u64 v[222:223], s[16:17], 0, v[220:221]
	v_lshl_add_u64 v[222:223], v[222:223], 0, v[162:163]
	global_load_dwordx4 v[236:239], v[222:223], off
	v_lshl_add_u64 v[222:223], s[38:39], 0, v[220:221]
	v_lshl_add_u64 v[222:223], v[222:223], 0, v[162:163]
	global_load_dwordx4 v[240:243], v[222:223], off
	v_exp_f32_e32 v60, v60
	v_mul_f32_e32 v61, 0xbfb8aa3b, v61
	v_exp_f32_e32 v61, v61
	v_mov_b32_e32 v98, 0
	v_mov_b32_e32 v90, 0
	v_mov_b32_e32 v94, 0
	v_add_f32_e32 v60, 1.0, v60
	v_mov_b32_e32 v86, 0
	v_rcp_f32_e32 v60, v60
	v_add_f32_e32 v61, 1.0, v61
	v_rcp_f32_e32 v61, v61
	v_mov_b32_e32 v99, 0
	v_mul_f32_e32 v56, 0xbfb8aa3b, v56
	v_mov_b32_e32 v91, 0
	v_mov_b32_e32 v95, 0
	v_exp_f32_e32 v56, v56
	v_mov_b32_e32 v87, 0
	v_mul_f32_e32 v57, 0xbfb8aa3b, v57
	v_exp_f32_e32 v57, v57
	v_mov_b32_e32 v100, 0
	v_mov_b32_e32 v92, 0
	v_mov_b32_e32 v96, 0
	v_add_f32_e32 v56, 1.0, v56
	v_mov_b32_e32 v88, 0
	v_rcp_f32_e32 v56, v56
	v_add_f32_e32 v57, 1.0, v57
	v_mul_f32_e32 v44, 0xbfb8aa3b, v44
	v_rcp_f32_e32 v57, v57
; __device__ __forceinline__ unsigned cvt_pk_bf16(float lo, float hi) { unsigned r; asm volatile("v_cvt_pk_bf16_f32 %0, %1, %2" : "=v"(r) : "v"(lo), "v"(hi)); return r; }
; __device__ __forceinline__ float bflo(unsigned w) { return __uint_as_float(w << 16); }
; __device__ __forceinline__ float bfhi(unsigned w) { return __uint_as_float(w & 0xffff0000u); }
;     __device__ __forceinline__ void operator()(const f32x4 (&acc)[2][2][4][2], const Unit& u, int wr, int wc, int fr, int fq) const {
;     ...
;             for (int m = 0; m < 4; ++m) { const int row = row0 + ai * HALF + m * 16; const size_t off = (size_t)row * D + col0; const float ri = __builtin_amdgcn_rsqf(sse[row] * (1.f / D) + EPS); float sq = 0.f; u32x4 w[2];
;                 u32x4 rr[2], ee[2]; load_pair_lines(R, D, row, fr, col0, rr[0], rr[1]); load_pair_lines(E, D, row, fr, col0, ee[0], ee[1]);
; #pragma unroll
;                 for (int bj = 0; bj < 2; ++bj) { const u32x4 rw = rr[bj], ew = ee[bj];
;                     const float r[8] = {bflo(rw.x), bfhi(rw.x), bflo(rw.y), bfhi(rw.y), bflo(rw.z), bfhi(rw.z), bflo(rw.w), bfhi(rw.w)};
;                     const float e[8] = {bflo(ew.x), bfhi(ew.x), bflo(ew.y), bfhi(ew.y), bflo(ew.z), bfhi(ew.z), bflo(ew.w), bfhi(ew.w)};
;                     float o[8];
; #pragma unroll
;                     for (int j = 0; j < 8; ++j) { const float a = acc[ai][bj][m][j >> 2][j & 3]; const float gg = gv[bj][j >> 2][j & 3];
;                         o[j] = r[j] + e[j] * ri * gg * __builtin_amdgcn_rcpf(1.f + __builtin_amdgcn_exp2f(-a * LOG2E)); }
;                     if (OUT) { *(f32x4*)(OUT + off + 8 * bj) = (f32x4){o[0], o[1], o[2], o[3]}; *(f32x4*)(OUT + off + 8 * bj + 4) = (f32x4){o[4], o[5], o[6], o[7]}; }
;                     else { sq += (o[0] * o[0] + o[1] * o[1]) + (o[2] * o[2] + o[3] * o[3]) + (o[4] * o[4] + o[5] * o[5]) + (o[6] * o[6] + o[7] * o[7]);
;                         w[bj].x = cvt_pk_bf16(o[0], o[1]); w[bj].y = cvt_pk_bf16(o[2], o[3]); w[bj].z = cvt_pk_bf16(o[4], o[5]); w[bj].w = cvt_pk_bf16(o[6], o[7]); } }
;                 if (!OUT) { store_pair_lines(O, D, row, fr, col0, w[0], w[1]);
;                     sq += __shfl_xor(sq, 16); sq += __shfl_xor(sq, 32); if (fq == 0) unsafeAtomicAdd(ssout + row, sq); } }
	v_exp_f32_e32 v44, v44
	v_mul_f32_e32 v45, 0xbfb8aa3b, v45
	v_exp_f32_e32 v45, v45
	v_mov_b32_e32 v101, 0
	v_add_f32_e32 v44, 1.0, v44
	v_rcp_f32_e32 v44, v44
	v_add_f32_e32 v45, 1.0, v45
	v_rcp_f32_e32 v45, v45
	v_mov_b32_e32 v93, 0
	v_mov_b32_e32 v97, 0
	v_mov_b32_e32 v89, 0
	v_mul_f32_e32 v36, 0xbfb8aa3b, v36
	v_exp_f32_e32 v36, v36
	v_mul_f32_e32 v37, 0xbfb8aa3b, v37
	v_exp_f32_e32 v37, v37
	v_add_f32_e32 v36, 1.0, v36
	v_rcp_f32_e32 v36, v36
	v_add_f32_e32 v37, 1.0, v37
	v_rcp_f32_e32 v37, v37
	v_mov_b32_dpp v86, v70 row_ror:8 row_mask:0xf bank_mask:0xf
	v_mov_b32_dpp v87, v71 row_ror:8 row_mask:0xf bank_mask:0xf
	v_mov_b32_dpp v88, v72 row_ror:8 row_mask:0xf bank_mask:0xf
	v_fmamk_f32 v65, v65, 0x3a000000, v180
	v_rsq_f32_e32 v65, v65
	v_mov_b32_dpp v94, v74 row_ror:8 row_mask:0xf bank_mask:0xf
	v_mov_b32_dpp v95, v75 row_ror:8 row_mask:0xf bank_mask:0xf
	v_mov_b32_dpp v96, v76 row_ror:8 row_mask:0xf bank_mask:0xf
	v_mov_b32_dpp v97, v77 row_ror:8 row_mask:0xf bank_mask:0xf
	v_mov_b32_dpp v89, v73 row_ror:8 row_mask:0xf bank_mask:0xf
	v_mov_b32_dpp v98, v82 row_ror:8 row_mask:0xf bank_mask:0xf
	v_cndmask_b32_e64 v74, v98, v74, s[6:7]
	v_mov_b32_dpp v90, v78 row_ror:8 row_mask:0xf bank_mask:0xf
	v_cndmask_b32_e64 v70, v90, v70, s[6:7]
	v_lshlrev_b32_e32 v90, 16, v74
	v_mul_f32_e32 v90, v65, v90
	v_cndmask_b32_e64 v78, v78, v86, s[6:7]
	v_lshlrev_b32_e32 v86, 16, v70
	v_and_b32_e32 v74, 0xffff0000, v74
	v_mul_f32_e32 v90, v52, v90
	v_fmac_f32_e32 v86, v60, v90
	v_mul_f32_e32 v60, v65, v74
	v_and_b32_e32 v70, 0xffff0000, v70
	v_mul_f32_e32 v60, v53, v60
	v_fmac_f32_e32 v70, v61, v60
	v_mul_f32_e32 v60, 0xbfb8aa3b, v62
	v_exp_f32_e32 v60, v60
	v_mul_f32_e32 v62, 0xbfb8aa3b, v63
	v_exp_f32_e32 v62, v62
	v_mov_b32_dpp v99, v83 row_ror:8 row_mask:0xf bank_mask:0xf
	v_add_f32_e32 v60, 1.0, v60
	v_mov_b32_dpp v91, v79 row_ror:8 row_mask:0xf bank_mask:0xf
	v_cndmask_b32_e64 v75, v99, v75, s[6:7]
	v_rcp_f32_e32 v60, v60
	v_cndmask_b32_e64 v71, v91, v71, s[6:7]
	v_lshlrev_b32_e32 v91, 16, v75
	v_add_f32_e32 v62, 1.0, v62
	v_mul_f32_e32 v61, v65, v91
	v_rcp_f32_e32 v62, v62
	v_cndmask_b32_e64 v79, v79, v87, s[6:7]
	v_mov_b32_dpp v100, v84 row_ror:8 row_mask:0xf bank_mask:0xf
	v_lshlrev_b32_e32 v87, 16, v71
	v_and_b32_e32 v75, 0xffff0000, v75
	v_mul_f32_e32 v61, v54, v61
	v_mov_b32_dpp v92, v80 row_ror:8 row_mask:0xf bank_mask:0xf
	v_cndmask_b32_e64 v76, v100, v76, s[6:7]
	v_fmac_f32_e32 v87, v60, v61
	v_mul_f32_e32 v60, v65, v75
	v_cndmask_b32_e64 v72, v92, v72, s[6:7]
	v_and_b32_e32 v71, 0xffff0000, v71
	v_lshlrev_b32_e32 v92, 16, v76
	v_mul_f32_e32 v60, v55, v60
	v_fmac_f32_e32 v71, v62, v60
	v_mul_f32_e32 v60, v65, v92
	v_cndmask_b32_e64 v80, v80, v88, s[6:7]
	v_lshlrev_b32_e32 v88, 16, v72
	v_and_b32_e32 v76, 0xffff0000, v76
	v_mul_f32_e32 v60, v48, v60
	v_fmac_f32_e32 v88, v56, v60
	v_mul_f32_e32 v56, v65, v76
	v_and_b32_e32 v72, 0xffff0000, v72
	v_mul_f32_e32 v56, v49, v56
	v_fmac_f32_e32 v72, v57, v56
	v_mul_f32_e32 v56, 0xbfb8aa3b, v58
	v_cndmask_b32_e64 v82, v82, v94, s[6:7]
	v_exp_f32_e32 v56, v56
	v_mul_f32_e32 v58, 0xbfb8aa3b, v59
	v_lshlrev_b32_e32 v75, 16, v82
	v_exp_f32_e32 v58, v58
	v_mul_f32_e32 v75, v65, v75
	v_lshlrev_b32_e32 v61, 16, v78
	v_and_b32_e32 v76, 0xffff0000, v82
	v_mul_f32_e32 v75, v40, v75
	v_mov_b32_dpp v101, v85 row_ror:8 row_mask:0xf bank_mask:0xf
	v_add_f32_e32 v56, 1.0, v56
	v_fmac_f32_e32 v61, v44, v75
	v_mul_f32_e32 v44, v65, v76
	v_mov_b32_dpp v93, v81 row_ror:8 row_mask:0xf bank_mask:0xf
	v_cndmask_b32_e64 v77, v101, v77, s[6:7]
	v_rcp_f32_e32 v56, v56
	v_and_b32_e32 v62, 0xffff0000, v78
	v_mul_f32_e32 v44, v41, v44
	v_cndmask_b32_e64 v73, v93, v73, s[6:7]
	v_lshlrev_b32_e32 v93, 16, v77
	v_add_f32_e32 v58, 1.0, v58
	v_fmac_f32_e32 v62, v45, v44
	v_mul_f32_e32 v44, 0xbfb8aa3b, v46
	v_mul_f32_e32 v57, v65, v93
	v_rcp_f32_e32 v58, v58
	v_exp_f32_e32 v44, v44
	v_cndmask_b32_e64 v81, v81, v89, s[6:7]
	v_lshlrev_b32_e32 v89, 16, v73
	v_and_b32_e32 v77, 0xffff0000, v77
	v_mul_f32_e32 v57, v50, v57
	v_mul_f32_e32 v46, 0xbfb8aa3b, v47
	v_fmac_f32_e32 v89, v56, v57
	v_mul_f32_e32 v56, v65, v77
	v_exp_f32_e32 v46, v46
	v_and_b32_e32 v73, 0xffff0000, v73
	v_mul_f32_e32 v56, v51, v56
	v_fmac_f32_e32 v73, v58, v56
	v_mul_f32_e32 v56, v70, v70
	v_mul_f32_e32 v57, v71, v71
	v_add_f32_e32 v44, 1.0, v44
	v_cndmask_b32_e64 v83, v83, v95, s[6:7]
	v_fmac_f32_e32 v56, v86, v86
	v_fmac_f32_e32 v57, v87, v87
	v_rcp_f32_e32 v44, v44
	v_add_f32_e32 v56, v56, v57
	v_mul_f32_e32 v57, v72, v72
	v_lshlrev_b32_e32 v77, 16, v83
	v_add_f32_e32 v46, 1.0, v46
	v_fmac_f32_e32 v57, v88, v88
	v_mul_f32_e32 v45, v65, v77
	v_rcp_f32_e32 v46, v46
	v_add_f32_e32 v56, v57, v56
	v_mul_f32_e32 v57, v73, v73
	v_lshlrev_b32_e32 v63, 16, v79
	v_and_b32_e32 v78, 0xffff0000, v83
	v_mul_f32_e32 v45, v42, v45
	v_cndmask_b32_e64 v84, v84, v96, s[6:7]
	v_fmac_f32_e32 v57, v89, v89
	v_fmac_f32_e32 v63, v44, v45
	v_mul_f32_e32 v44, v65, v78
	v_add_f32_e32 v56, v57, v56
	v_cvt_pk_bf16_f32 v57, v86, v70
	v_and_b32_e32 v70, 0xffff0000, v79
	v_lshlrev_b32_e32 v79, 16, v84
	v_mul_f32_e32 v44, v43, v44
	v_fmac_f32_e32 v70, v46, v44
	v_mul_f32_e32 v44, v65, v79
	v_cvt_pk_bf16_f32 v58, v87, v71
	v_cvt_pk_bf16_f32 v59, v88, v72
	v_lshlrev_b32_e32 v71, 16, v80
	v_and_b32_e32 v72, 0xffff0000, v80
	v_and_b32_e32 v80, 0xffff0000, v84
	v_mul_f32_e32 v44, v32, v44
	v_fmac_f32_e32 v71, v36, v44
	v_mul_f32_e32 v36, v65, v80
	v_mul_f32_e32 v36, v33, v36
	v_fmac_f32_e32 v72, v37, v36
	v_mul_f32_e32 v36, 0xbfb8aa3b, v38
	v_exp_f32_e32 v36, v36
	v_mul_f32_e32 v38, 0xbfb8aa3b, v39
	v_exp_f32_e32 v38, v38
	v_cndmask_b32_e64 v85, v85, v97, s[6:7]
	v_add_f32_e32 v36, 1.0, v36
;     const bool lo = fr < 8;
;     const int r1 = row - fr + (fr & 7), cb = col0 + (lo ? 0 : boff);
;     const u32x4 l1 = *(const u32x4*)(P + (size_t)r1 * ld + cb), l2 = *(const u32x4*)(P + (size_t)(r1 + 8) * ld + cb);
;     const u32x4 s1 = {dpp_ror8(l1.x), dpp_ror8(l1.y), dpp_ror8(l1.z), dpp_ror8(l1.w)}, s2 = {dpp_ror8(l2.x), dpp_ror8(l2.y), dpp_ror8(l2.z), dpp_ror8(l2.w)};
;     wA = lo ? l1 : s2; wB = lo ? s1 : l2;
; }
;     __device__ __forceinline__ void operator()(const f32x4 (&acc)[2][2][4][2], const Unit& u, int wr, int wc, int fr, int fq) const {
;     ...
;             for (int m = 0; m < 4; ++m) { const int row = row0 + ai * HALF + m * 16; const size_t off = (size_t)row * D + col0; const float ri = __builtin_amdgcn_rsqf(sse[row] * (1.f / D) + EPS); float sq = 0.f; u32x4 w[2];
;                 u32x4 rr[2], ee[2]; load_pair_lines(R, D, row, fr, col0, rr[0], rr[1]); load_pair_lines(E, D, row, fr, col0, ee[0], ee[1]);
; #pragma unroll
;                 for (int bj = 0; bj < 2; ++bj) { const u32x4 rw = rr[bj], ew = ee[bj];
;                     const float r[8] = {bflo(rw.x), bfhi(rw.x), bflo(rw.y), bfhi(rw.y), bflo(rw.z), bfhi(rw.z), bflo(rw.w), bfhi(rw.w)};
;                     const float e[8] = {bflo(ew.x), bfhi(ew.x), bflo(ew.y), bfhi(ew.y), bflo(ew.z), bfhi(ew.z), bflo(ew.w), bfhi(ew.w)};
;                     float o[8];
; #pragma unroll
;                     for (int j = 0; j < 8; ++j) { const float a = acc[ai][bj][m][j >> 2][j & 3]; const float gg = gv[bj][j >> 2][j & 3];
;                         o[j] = r[j] + e[j] * ri * gg * __builtin_amdgcn_rcpf(1.f + __builtin_amdgcn_exp2f(-a * LOG2E)); }
;                     if (OUT) { *(f32x4*)(OUT + off + 8 * bj) = (f32x4){o[0], o[1], o[2], o[3]}; *(f32x4*)(OUT + off + 8 * bj + 4) = (f32x4){o[4], o[5], o[6], o[7]}; }
;                     else { sq += (o[0] * o[0] + o[1] * o[1]) + (o[2] * o[2] + o[3] * o[3]) + (o[4] * o[4] + o[5] * o[5]) + (o[6] * o[6] + o[7] * o[7]);
;                         w[bj].x = cvt_pk_bf16(o[0], o[1]); w[bj].y = cvt_pk_bf16(o[2], o[3]); w[bj].z = cvt_pk_bf16(o[4], o[5]); w[bj].w = cvt_pk_bf16(o[6], o[7]); } }
;                 if (!OUT) { store_pair_lines(O, D, row, fr, col0, w[0], w[1]);
;                     sq += __shfl_xor(sq, 16); sq += __shfl_xor(sq, 32); if (fq == 0) unsafeAtomicAdd(ssout + row, sq); } }
	v_rcp_f32_e32 v36, v36
	v_cvt_pk_bf16_f32 v60, v89, v73
	v_lshlrev_b32_e32 v73, 16, v81
	v_and_b32_e32 v74, 0xffff0000, v81
	v_lshlrev_b32_e32 v81, 16, v85
	v_add_f32_e32 v38, 1.0, v38
	v_mul_f32_e32 v37, v65, v81
	v_rcp_f32_e32 v38, v38
	v_and_b32_e32 v82, 0xffff0000, v85
	v_mul_f32_e32 v37, v34, v37
	v_fmac_f32_e32 v73, v36, v37
	v_mul_f32_e32 v36, v65, v82
	v_mul_f32_e32 v36, v35, v36
	v_fmac_f32_e32 v74, v38, v36
	v_mul_f32_e32 v36, v62, v62
	v_mul_f32_e32 v37, v70, v70
	v_fmac_f32_e32 v36, v61, v61
	v_fmac_f32_e32 v37, v63, v63
	v_add_f32_e32 v36, v36, v37
	v_mul_f32_e32 v37, v72, v72
	v_fmac_f32_e32 v37, v71, v71
	v_add_f32_e32 v36, v37, v36
	v_mul_f32_e32 v37, v74, v74
	v_fmac_f32_e32 v37, v73, v73
	v_add_f32_e32 v36, v37, v36
	v_mov_b32_e32 v47, 0
	v_add_f32_e32 v65, v36, v56
	v_cvt_pk_bf16_f32 v36, v61, v62
	v_cvt_pk_bf16_f32 v37, v63, v70
	v_cvt_pk_bf16_f32 v38, v71, v72
	v_cvt_pk_bf16_f32 v39, v73, v74
	v_mov_b32_e32 v63, 0
	v_mov_b32_e32 v56, 0
	v_mov_b32_dpp v47, v39 row_ror:8 row_mask:0xf bank_mask:0xf
	v_mov_b32_dpp v63, v60 row_ror:8 row_mask:0xf bank_mask:0xf
	v_cndmask_b32_e64 v47, v47, v60, s[6:7]
	ds_bpermute_b32 v60, v134, v65
	v_mov_b32_e32 v61, 0
	v_mov_b32_e32 v44, 0
	v_mov_b32_dpp v56, v57 row_ror:8 row_mask:0xf bank_mask:0xf
	v_mov_b32_dpp v61, v58 row_ror:8 row_mask:0xf bank_mask:0xf
	v_mov_b32_e32 v62, 0
	v_mov_b32_dpp v44, v36 row_ror:8 row_mask:0xf bank_mask:0xf
	v_mov_b32_e32 v45, 0
	v_mov_b32_e32 v46, 0
	v_mov_b32_dpp v62, v59 row_ror:8 row_mask:0xf bank_mask:0xf
	v_mov_b32_dpp v45, v37 row_ror:8 row_mask:0xf bank_mask:0xf
	v_mov_b32_dpp v46, v38 row_ror:8 row_mask:0xf bank_mask:0xf
	v_cndmask_b32_e64 v44, v44, v57, s[6:7]
	v_cndmask_b32_e64 v56, v36, v56, s[6:7]
	v_cndmask_b32_e64 v57, v37, v61, s[6:7]
	v_lshl_add_u64 v[36:37], s[36:37], 0, v[66:67]
	v_cndmask_b32_e64 v45, v45, v58, s[6:7]
	v_cndmask_b32_e64 v46, v46, v59, s[6:7]
	v_cndmask_b32_e64 v58, v38, v62, s[6:7]
	v_cndmask_b32_e64 v59, v39, v63, s[6:7]
	v_lshl_add_u64 v[38:39], v[36:37], 0, v[162:163]
	s_waitcnt lgkmcnt(0)
	v_add_f32_e32 v36, v65, v60
	ds_bpermute_b32 v37, v135, v36
	global_store_dwordx4 v[38:39], v[44:47], off
	v_lshl_add_u64 v[38:39], s[36:37], 0, v[68:69]
	v_lshl_add_u64 v[38:39], v[38:39], 0, v[162:163]
	global_store_dwordx4 v[38:39], v[56:59], off
	s_and_saveexec_b64 s[56:57], s[8:9]
	s_cbranch_execz .LBB0_895
	v_ashrrev_i32_e32 v65, 31, v64
	v_lshl_add_u64 v[38:39], v[64:65], 2, s[18:19]
	s_waitcnt lgkmcnt(0)
	v_add_f32_e32 v36, v36, v37
	global_atomic_add_f32 v[38:39], v36, off
.LBB0_895:
	s_or_b64 exec, exec, s[56:57]
	v_add_u32_e32 v36, 0xa0, v164
	v_sub_u32_e32 v38, v36, v172
	v_add_u32_e32 v38, v38, v174
	v_ashrrev_i32_e32 v39, 31, v38
	v_lshlrev_b64 v[38:39], 12, v[38:39]
	v_lshl_add_u64 v[44:45], s[16:17], 0, v[38:39]
	v_lshl_add_u64 v[44:45], v[44:45], 0, v[162:163]
	s_waitcnt vmcnt(2)
	s_nop 0
	v_mov_b64_e32 v[56:57], v[228:229]
	v_mov_b64_e32 v[58:59], v[230:231]
	v_lshl_add_u64 v[44:45], s[38:39], 0, v[38:39]
	v_lshl_add_u64 v[44:45], v[44:45], 0, v[162:163]
	s_waitcnt lgkmcnt(0)
	v_mov_b32_e32 v37, v226
	v_mov_b64_e32 v[60:61], v[232:233]
	v_mov_b64_e32 v[62:63], v[234:235]
	v_lshl_add_u64 v[44:45], v[38:39], 0, s[44:45]
	v_lshl_add_u64 v[46:47], s[16:17], 0, v[44:45]
	v_lshl_add_u64 v[46:47], v[46:47], 0, v[162:163]
	v_mov_b64_e32 v[64:65], v[236:237]
	v_mov_b64_e32 v[66:67], v[238:239]
	v_lshl_add_u64 v[46:47], s[38:39], 0, v[44:45]
	v_lshl_add_u64 v[46:47], v[46:47], 0, v[162:163]
	v_mov_b64_e32 v[68:69], v[240:241]
	v_mov_b64_e32 v[70:71], v[242:243]
	s_nop 1
	v_add_u32_e32 v216, 0xb0, v164
	v_sub_u32_e32 v218, v216, v172
	v_add_u32_e32 v218, v218, v174
	v_ashrrev_i32_e32 v219, 31, v218
	v_lshlrev_b64 v[218:219], 12, v[218:219]
	v_lshl_add_u64 v[220:221], s[16:17], 0, v[218:219]
	v_lshl_add_u64 v[220:221], v[220:221], 0, v[162:163]
	global_load_dwordx4 v[228:231], v[220:221], off
	v_lshl_add_u64 v[220:221], s[38:39], 0, v[218:219]
	v_lshl_add_u64 v[220:221], v[220:221], 0, v[162:163]
	global_load_dword v226, v[166:167], off offset:704
	global_load_dwordx4 v[232:235], v[220:221], off
	v_lshl_add_u64 v[220:221], v[218:219], 0, s[44:45]
	v_lshl_add_u64 v[222:223], s[16:17], 0, v[220:221]
	v_lshl_add_u64 v[222:223], v[222:223], 0, v[162:163]
	global_load_dwordx4 v[236:239], v[222:223], off
	v_lshl_add_u64 v[222:223], s[38:39], 0, v[220:221]
	v_lshl_add_u64 v[222:223], v[222:223], 0, v[162:163]
	global_load_dwordx4 v[240:243], v[222:223], off
	v_mul_f32_e32 v28, 0xbfb8aa3b, v28
	v_exp_f32_e32 v28, v28
	v_mul_f32_e32 v29, 0xbfb8aa3b, v29
	v_exp_f32_e32 v29, v29
	v_mov_b32_e32 v82, 0
	v_mov_b32_e32 v74, 0
	v_mov_b32_e32 v78, 0
	v_add_f32_e32 v28, 1.0, v28
	v_mov_b32_e32 v46, 0
	v_rcp_f32_e32 v28, v28
	v_mov_b32_e32 v47, 0
	v_mov_b32_e32 v80, 0
	v_add_f32_e32 v29, 1.0, v29
	v_mov_b32_e32 v75, 0
	v_mov_b32_e32 v84, 0
	v_rcp_f32_e32 v29, v29
	v_mov_b32_e32 v83, 0
	v_mul_f32_e32 v24, 0xbfb8aa3b, v24
	v_mov_b32_e32 v79, 0
	v_exp_f32_e32 v24, v24
	v_mul_f32_e32 v25, 0xbfb8aa3b, v25
	v_mov_b32_e32 v81, 0
	v_exp_f32_e32 v25, v25
	v_mov_b32_e32 v85, 0
	v_mov_b32_e32 v76, 0
	v_add_f32_e32 v24, 1.0, v24
	v_mov_b32_e32 v72, 0
	v_rcp_f32_e32 v24, v24
	v_add_f32_e32 v25, 1.0, v25
	v_rcp_f32_e32 v25, v25
	v_mov_b32_e32 v77, 0
	v_mov_b32_e32 v73, 0
	v_mul_f32_e32 v20, 0xbfb8aa3b, v20
	v_exp_f32_e32 v20, v20
	v_mul_f32_e32 v21, 0xbfb8aa3b, v21
	v_exp_f32_e32 v21, v21
	v_mul_f32_e32 v16, 0xbfb8aa3b, v16
	v_add_f32_e32 v20, 1.0, v20
	v_rcp_f32_e32 v20, v20
	v_add_f32_e32 v21, 1.0, v21
	v_rcp_f32_e32 v21, v21
	v_exp_f32_e32 v16, v16
	v_mul_f32_e32 v17, 0xbfb8aa3b, v17
	v_exp_f32_e32 v17, v17
	v_add_f32_e32 v16, 1.0, v16
; __device__ __forceinline__ unsigned cvt_pk_bf16(float lo, float hi) { unsigned r; asm volatile("v_cvt_pk_bf16_f32 %0, %1, %2" : "=v"(r) : "v"(lo), "v"(hi)); return r; }
; __device__ __forceinline__ float bflo(unsigned w) { return __uint_as_float(w << 16); }
; __device__ __forceinline__ float bfhi(unsigned w) { return __uint_as_float(w & 0xffff0000u); }
;     __device__ __forceinline__ void operator()(const f32x4 (&acc)[2][2][4][2], const Unit& u, int wr, int wc, int fr, int fq) const {
;     ...
;             for (int m = 0; m < 4; ++m) { const int row = row0 + ai * HALF + m * 16; const size_t off = (size_t)row * D + col0; const float ri = __builtin_amdgcn_rsqf(sse[row] * (1.f / D) + EPS); float sq = 0.f; u32x4 w[2];
;                 u32x4 rr[2], ee[2]; load_pair_lines(R, D, row, fr, col0, rr[0], rr[1]); load_pair_lines(E, D, row, fr, col0, ee[0], ee[1]);
; #pragma unroll
;                 for (int bj = 0; bj < 2; ++bj) { const u32x4 rw = rr[bj], ew = ee[bj];
;                     const float r[8] = {bflo(rw.x), bfhi(rw.x), bflo(rw.y), bfhi(rw.y), bflo(rw.z), bfhi(rw.z), bflo(rw.w), bfhi(rw.w)};
;                     const float e[8] = {bflo(ew.x), bfhi(ew.x), bflo(ew.y), bfhi(ew.y), bflo(ew.z), bfhi(ew.z), bflo(ew.w), bfhi(ew.w)};
;                     float o[8];
; #pragma unroll
;                     for (int j = 0; j < 8; ++j) { const float a = acc[ai][bj][m][j >> 2][j & 3]; const float gg = gv[bj][j >> 2][j & 3];
;                         o[j] = r[j] + e[j] * ri * gg * __builtin_amdgcn_rcpf(1.f + __builtin_amdgcn_exp2f(-a * LOG2E)); }
;                     if (OUT) { *(f32x4*)(OUT + off + 8 * bj) = (f32x4){o[0], o[1], o[2], o[3]}; *(f32x4*)(OUT + off + 8 * bj + 4) = (f32x4){o[4], o[5], o[6], o[7]}; }
;                     else { sq += (o[0] * o[0] + o[1] * o[1]) + (o[2] * o[2] + o[3] * o[3]) + (o[4] * o[4] + o[5] * o[5]) + (o[6] * o[6] + o[7] * o[7]);
;                         w[bj].x = cvt_pk_bf16(o[0], o[1]); w[bj].y = cvt_pk_bf16(o[2], o[3]); w[bj].z = cvt_pk_bf16(o[4], o[5]); w[bj].w = cvt_pk_bf16(o[6], o[7]); } }
;                 if (!OUT) { store_pair_lines(O, D, row, fr, col0, w[0], w[1]);
;                     sq += __shfl_xor(sq, 16); sq += __shfl_xor(sq, 32); if (fq == 0) unsafeAtomicAdd(ssout + row, sq); } }
	v_rcp_f32_e32 v16, v16
	v_add_f32_e32 v17, 1.0, v17
	v_rcp_f32_e32 v17, v17
	v_mov_b32_dpp v46, v56 row_ror:8 row_mask:0xf bank_mask:0xf
	v_mov_b32_dpp v47, v57 row_ror:8 row_mask:0xf bank_mask:0xf
	v_mov_b32_dpp v72, v58 row_ror:8 row_mask:0xf bank_mask:0xf
	v_fmamk_f32 v37, v37, 0x3a000000, v180
	v_rsq_f32_e32 v37, v37
	v_mov_b32_dpp v78, v60 row_ror:8 row_mask:0xf bank_mask:0xf
	v_mov_b32_dpp v80, v62 row_ror:8 row_mask:0xf bank_mask:0xf
	v_mov_b32_dpp v79, v61 row_ror:8 row_mask:0xf bank_mask:0xf
	v_mov_b32_dpp v74, v64 row_ror:8 row_mask:0xf bank_mask:0xf
	v_cndmask_b32_e64 v56, v74, v56, s[6:7]
	v_mov_b32_dpp v75, v65 row_ror:8 row_mask:0xf bank_mask:0xf
	v_mov_b32_dpp v82, v68 row_ror:8 row_mask:0xf bank_mask:0xf
	v_cndmask_b32_e64 v60, v82, v60, s[6:7]
	v_lshlrev_b32_e32 v74, 16, v60
	v_mul_f32_e32 v74, v37, v74
	v_cndmask_b32_e64 v47, v65, v47, s[6:7]
	v_mov_b32_dpp v84, v70 row_ror:8 row_mask:0xf bank_mask:0xf
	v_cndmask_b32_e64 v65, v70, v80, s[6:7]
	v_lshlrev_b32_e32 v70, 16, v56
	v_and_b32_e32 v60, 0xffff0000, v60
	v_mul_f32_e32 v74, v52, v74
	v_fmac_f32_e32 v70, v28, v74
	v_mul_f32_e32 v28, v37, v60
	v_and_b32_e32 v56, 0xffff0000, v56
	v_mul_f32_e32 v28, v53, v28
	v_fmac_f32_e32 v56, v29, v28
	v_mul_f32_e32 v28, 0xbfb8aa3b, v30
	v_exp_f32_e32 v28, v28
	v_mul_f32_e32 v30, 0xbfb8aa3b, v31
	v_exp_f32_e32 v30, v30
	v_mov_b32_dpp v83, v69 row_ror:8 row_mask:0xf bank_mask:0xf
	v_add_f32_e32 v28, 1.0, v28
	v_cndmask_b32_e64 v61, v83, v61, s[6:7]
	v_rcp_f32_e32 v28, v28
	v_cndmask_b32_e64 v57, v75, v57, s[6:7]
	v_lshlrev_b32_e32 v75, 16, v61
	v_add_f32_e32 v30, 1.0, v30
	v_mov_b32_dpp v81, v63 row_ror:8 row_mask:0xf bank_mask:0xf
	v_mul_f32_e32 v29, v37, v75
	v_rcp_f32_e32 v30, v30
	v_cndmask_b32_e64 v46, v64, v46, s[6:7]
	v_mov_b32_dpp v85, v71 row_ror:8 row_mask:0xf bank_mask:0xf
	v_cndmask_b32_e64 v64, v71, v81, s[6:7]
	v_lshlrev_b32_e32 v71, 16, v57
	v_and_b32_e32 v61, 0xffff0000, v61
	v_mul_f32_e32 v29, v54, v29
	v_mov_b32_dpp v76, v66 row_ror:8 row_mask:0xf bank_mask:0xf
	v_cndmask_b32_e64 v62, v84, v62, s[6:7]
	v_fmac_f32_e32 v71, v28, v29
	v_mul_f32_e32 v28, v37, v61
	v_cndmask_b32_e64 v58, v76, v58, s[6:7]
	v_and_b32_e32 v57, 0xffff0000, v57
	v_lshlrev_b32_e32 v76, 16, v62
	v_mul_f32_e32 v28, v55, v28
	v_fmac_f32_e32 v57, v30, v28
	v_mul_f32_e32 v28, v37, v76
	v_cndmask_b32_e64 v66, v66, v72, s[6:7]
	v_lshlrev_b32_e32 v72, 16, v58
	v_and_b32_e32 v62, 0xffff0000, v62
	v_mul_f32_e32 v28, v48, v28
	v_fmac_f32_e32 v72, v24, v28
	v_mul_f32_e32 v24, v37, v62
	v_and_b32_e32 v58, 0xffff0000, v58
	v_mul_f32_e32 v24, v49, v24
	v_fmac_f32_e32 v58, v25, v24
	v_mul_f32_e32 v24, 0xbfb8aa3b, v26
	v_exp_f32_e32 v24, v24
	v_mul_f32_e32 v26, 0xbfb8aa3b, v27
	v_exp_f32_e32 v26, v26
	v_mov_b32_dpp v77, v67 row_ror:8 row_mask:0xf bank_mask:0xf
	v_add_f32_e32 v24, 1.0, v24
	v_cndmask_b32_e64 v63, v85, v63, s[6:7]
	v_rcp_f32_e32 v24, v24
	v_mov_b32_dpp v73, v59 row_ror:8 row_mask:0xf bank_mask:0xf
	v_cndmask_b32_e64 v59, v77, v59, s[6:7]
	v_lshlrev_b32_e32 v77, 16, v63
	v_add_f32_e32 v26, 1.0, v26
	v_mul_f32_e32 v25, v37, v77
	v_rcp_f32_e32 v26, v26
	v_cndmask_b32_e64 v67, v67, v73, s[6:7]
	v_lshlrev_b32_e32 v73, 16, v59
	v_and_b32_e32 v63, 0xffff0000, v63
	v_mul_f32_e32 v25, v50, v25
	v_fmac_f32_e32 v73, v24, v25
	v_mul_f32_e32 v24, v37, v63
	v_and_b32_e32 v59, 0xffff0000, v59
	v_mul_f32_e32 v24, v51, v24
	v_fmac_f32_e32 v59, v26, v24
	v_mul_f32_e32 v24, v56, v56
	v_mul_f32_e32 v25, v57, v57
	v_fmac_f32_e32 v24, v70, v70
	v_fmac_f32_e32 v25, v71, v71
	v_add_f32_e32 v24, v24, v25
	v_mul_f32_e32 v25, v58, v58
	v_fmac_f32_e32 v25, v72, v72
	v_add_f32_e32 v24, v25, v24
	v_mul_f32_e32 v25, v59, v59
	v_cndmask_b32_e64 v68, v68, v78, s[6:7]
	v_fmac_f32_e32 v25, v73, v73
	v_add_f32_e32 v24, v25, v24
	v_cvt_pk_bf16_f32 v25, v70, v56
	v_cvt_pk_bf16_f32 v26, v71, v57
	v_cvt_pk_bf16_f32 v27, v72, v58
	v_cvt_pk_bf16_f32 v28, v73, v59
	v_lshlrev_b32_e32 v59, 16, v68
	v_mul_f32_e32 v59, v37, v59
	v_lshlrev_b32_e32 v29, 16, v46
	v_and_b32_e32 v60, 0xffff0000, v68
	v_mul_f32_e32 v59, v40, v59
	v_fmac_f32_e32 v29, v20, v59
	v_mul_f32_e32 v20, v37, v60
	v_and_b32_e32 v30, 0xffff0000, v46
	v_mul_f32_e32 v20, v41, v20
	v_fmac_f32_e32 v30, v21, v20
	v_mul_f32_e32 v20, 0xbfb8aa3b, v22
	v_exp_f32_e32 v20, v20
	v_mul_f32_e32 v22, 0xbfb8aa3b, v23
	v_exp_f32_e32 v22, v22
	v_cndmask_b32_e64 v69, v69, v79, s[6:7]
	v_add_f32_e32 v20, 1.0, v20
	v_rcp_f32_e32 v20, v20
	v_lshlrev_b32_e32 v61, 16, v69
	v_add_f32_e32 v22, 1.0, v22
	v_mul_f32_e32 v21, v37, v61
	v_rcp_f32_e32 v22, v22
	v_lshlrev_b32_e32 v31, 16, v47
	v_and_b32_e32 v62, 0xffff0000, v69
	v_mul_f32_e32 v21, v42, v21
	v_fmac_f32_e32 v31, v20, v21
	v_mul_f32_e32 v20, v37, v62
	v_and_b32_e32 v46, 0xffff0000, v47
	v_lshlrev_b32_e32 v63, 16, v65
	v_mul_f32_e32 v20, v43, v20
	v_fmac_f32_e32 v46, v22, v20
	v_mul_f32_e32 v20, v37, v63
	v_lshlrev_b32_e32 v47, 16, v66
	v_and_b32_e32 v65, 0xffff0000, v65
	v_mul_f32_e32 v20, v32, v20
	v_fmac_f32_e32 v47, v16, v20
	v_mul_f32_e32 v16, v37, v65
	v_and_b32_e32 v56, 0xffff0000, v66
	v_mul_f32_e32 v16, v33, v16
	v_fmac_f32_e32 v56, v17, v16
	v_mul_f32_e32 v16, 0xbfb8aa3b, v18
	v_exp_f32_e32 v16, v16
	v_mul_f32_e32 v18, 0xbfb8aa3b, v19
	v_exp_f32_e32 v18, v18
	v_lshlrev_b32_e32 v66, 16, v64
	v_add_f32_e32 v16, 1.0, v16
	v_rcp_f32_e32 v16, v16
	v_add_f32_e32 v18, 1.0, v18
	v_mul_f32_e32 v17, v37, v66
	v_rcp_f32_e32 v18, v18
	v_lshlrev_b32_e32 v57, 16, v67
	v_and_b32_e32 v64, 0xffff0000, v64
	v_mul_f32_e32 v17, v34, v17
	v_fmac_f32_e32 v57, v16, v17
	v_mul_f32_e32 v16, v37, v64
	v_and_b32_e32 v58, 0xffff0000, v67
	v_mul_f32_e32 v16, v35, v16
	v_fmac_f32_e32 v58, v18, v16
;     const bool lo = fr < 8;
;     const int r1 = row - fr + (fr & 7), cb = col0 + (lo ? 0 : boff);
;     const u32x4 l1 = *(const u32x4*)(P + (size_t)r1 * ld + cb), l2 = *(const u32x4*)(P + (size_t)(r1 + 8) * ld + cb);
;     const u32x4 s1 = {dpp_ror8(l1.x), dpp_ror8(l1.y), dpp_ror8(l1.z), dpp_ror8(l1.w)}, s2 = {dpp_ror8(l2.x), dpp_ror8(l2.y), dpp_ror8(l2.z), dpp_ror8(l2.w)};
;     wA = lo ? l1 : s2; wB = lo ? s1 : l2;
; }
;     __device__ __forceinline__ void operator()(const f32x4 (&acc)[2][2][4][2], const Unit& u, int wr, int wc, int fr, int fq) const {
;     ...
;             for (int m = 0; m < 4; ++m) { const int row = row0 + ai * HALF + m * 16; const size_t off = (size_t)row * D + col0; const float ri = __builtin_amdgcn_rsqf(sse[row] * (1.f / D) + EPS); float sq = 0.f; u32x4 w[2];
;                 u32x4 rr[2], ee[2]; load_pair_lines(R, D, row, fr, col0, rr[0], rr[1]); load_pair_lines(E, D, row, fr, col0, ee[0], ee[1]);
; #pragma unroll
;                 for (int bj = 0; bj < 2; ++bj) { const u32x4 rw = rr[bj], ew = ee[bj];
;                     const float r[8] = {bflo(rw.x), bfhi(rw.x), bflo(rw.y), bfhi(rw.y), bflo(rw.z), bfhi(rw.z), bflo(rw.w), bfhi(rw.w)};
;                     const float e[8] = {bflo(ew.x), bfhi(ew.x), bflo(ew.y), bfhi(ew.y), bflo(ew.z), bfhi(ew.z), bflo(ew.w), bfhi(ew.w)};
;                     float o[8];
; #pragma unroll
;                     for (int j = 0; j < 8; ++j) { const float a = acc[ai][bj][m][j >> 2][j & 3]; const float gg = gv[bj][j >> 2][j & 3];
;                         o[j] = r[j] + e[j] * ri * gg * __builtin_amdgcn_rcpf(1.f + __builtin_amdgcn_exp2f(-a * LOG2E)); }
;                     if (OUT) { *(f32x4*)(OUT + off + 8 * bj) = (f32x4){o[0], o[1], o[2], o[3]}; *(f32x4*)(OUT + off + 8 * bj + 4) = (f32x4){o[4], o[5], o[6], o[7]}; }
;                     else { sq += (o[0] * o[0] + o[1] * o[1]) + (o[2] * o[2] + o[3] * o[3]) + (o[4] * o[4] + o[5] * o[5]) + (o[6] * o[6] + o[7] * o[7]);
;                         w[bj].x = cvt_pk_bf16(o[0], o[1]); w[bj].y = cvt_pk_bf16(o[2], o[3]); w[bj].z = cvt_pk_bf16(o[4], o[5]); w[bj].w = cvt_pk_bf16(o[6], o[7]); } }
;                 if (!OUT) { store_pair_lines(O, D, row, fr, col0, w[0], w[1]);
;                     sq += __shfl_xor(sq, 16); sq += __shfl_xor(sq, 32); if (fq == 0) unsafeAtomicAdd(ssout + row, sq); } }
	v_mul_f32_e32 v16, v30, v30
	v_mul_f32_e32 v17, v46, v46
	v_fmac_f32_e32 v16, v29, v29
	v_fmac_f32_e32 v17, v31, v31
	v_add_f32_e32 v16, v16, v17
	v_mul_f32_e32 v17, v56, v56
	v_fmac_f32_e32 v17, v47, v47
	v_add_f32_e32 v16, v17, v16
	v_mul_f32_e32 v17, v58, v58
	v_fmac_f32_e32 v17, v57, v57
	v_add_f32_e32 v16, v17, v16
	v_mov_b32_e32 v21, 0
	v_add_f32_e32 v37, v16, v24
	v_cvt_pk_bf16_f32 v16, v29, v30
	v_cvt_pk_bf16_f32 v17, v31, v46
	v_cvt_pk_bf16_f32 v24, v47, v56
	v_cvt_pk_bf16_f32 v29, v57, v58
	v_mov_b32_e32 v31, 0
	v_mov_b32_e32 v22, 0
	v_mov_b32_dpp v21, v29 row_ror:8 row_mask:0xf bank_mask:0xf
	v_mov_b32_dpp v31, v28 row_ror:8 row_mask:0xf bank_mask:0xf
	v_cndmask_b32_e64 v21, v21, v28, s[6:7]
	ds_bpermute_b32 v28, v134, v37
	v_mov_b32_e32 v23, 0
	v_mov_b32_dpp v22, v25 row_ror:8 row_mask:0xf bank_mask:0xf
	v_mov_b32_e32 v18, 0
	v_mov_b32_dpp v23, v26 row_ror:8 row_mask:0xf bank_mask:0xf
	v_mov_b32_e32 v19, 0
	v_mov_b32_e32 v20, 0
	v_mov_b32_e32 v30, 0
	v_mov_b32_dpp v18, v16 row_ror:8 row_mask:0xf bank_mask:0xf
	v_mov_b32_dpp v19, v17 row_ror:8 row_mask:0xf bank_mask:0xf
	v_mov_b32_dpp v20, v24 row_ror:8 row_mask:0xf bank_mask:0xf
	v_cndmask_b32_e64 v22, v16, v22, s[6:7]
	v_cndmask_b32_e64 v23, v17, v23, s[6:7]
	v_lshl_add_u64 v[16:17], s[36:37], 0, v[38:39]
	v_mov_b32_dpp v30, v27 row_ror:8 row_mask:0xf bank_mask:0xf
	v_cndmask_b32_e64 v19, v19, v26, s[6:7]
	v_cndmask_b32_e64 v20, v20, v27, s[6:7]
	v_lshl_add_u64 v[26:27], v[16:17], 0, v[162:163]
	s_waitcnt lgkmcnt(0)
	v_add_f32_e32 v16, v37, v28
	ds_bpermute_b32 v17, v135, v16
	v_cndmask_b32_e64 v18, v18, v25, s[6:7]
	global_store_dwordx4 v[26:27], v[18:21], off
	v_cndmask_b32_e64 v24, v24, v30, s[6:7]
	v_cndmask_b32_e64 v25, v29, v31, s[6:7]
	v_lshl_add_u64 v[18:19], s[36:37], 0, v[44:45]
	v_lshl_add_u64 v[18:19], v[18:19], 0, v[162:163]
	global_store_dwordx4 v[18:19], v[22:25], off
	s_and_saveexec_b64 s[56:57], s[8:9]
	s_cbranch_execz .LBB0_897
	v_ashrrev_i32_e32 v37, 31, v36
	v_lshl_add_u64 v[18:19], v[36:37], 2, s[18:19]
	s_waitcnt lgkmcnt(0)
	v_add_f32_e32 v16, v16, v17
	global_atomic_add_f32 v[18:19], v16, off
.LBB0_897:
	s_or_b64 exec, exec, s[56:57]
	v_add_u32_e32 v16, 0xb0, v164
	v_sub_u32_e32 v18, v16, v172
	v_add_u32_e32 v18, v18, v174
	v_ashrrev_i32_e32 v19, 31, v18
	v_lshlrev_b64 v[18:19], 12, v[18:19]
	v_lshl_add_u64 v[20:21], s[16:17], 0, v[18:19]
	v_lshl_add_u64 v[20:21], v[20:21], 0, v[162:163]
	s_waitcnt vmcnt(2)
	s_nop 0
	v_mov_b64_e32 v[22:23], v[228:229]
	v_mov_b64_e32 v[24:25], v[230:231]
	v_lshl_add_u64 v[20:21], s[38:39], 0, v[18:19]
	v_lshl_add_u64 v[20:21], v[20:21], 0, v[162:163]
	s_waitcnt lgkmcnt(0)
	v_mov_b32_e32 v17, v226
	v_mov_b64_e32 v[26:27], v[232:233]
	v_mov_b64_e32 v[28:29], v[234:235]
	v_lshl_add_u64 v[20:21], v[18:19], 0, s[44:45]
	v_lshl_add_u64 v[30:31], s[16:17], 0, v[20:21]
	v_lshl_add_u64 v[30:31], v[30:31], 0, v[162:163]
	v_mov_b64_e32 v[36:37], v[236:237]
	v_mov_b64_e32 v[38:39], v[238:239]
	v_lshl_add_u64 v[30:31], s[38:39], 0, v[20:21]
	v_lshl_add_u64 v[30:31], v[30:31], 0, v[162:163]
	v_mov_b64_e32 v[44:45], v[240:241]
	v_mov_b64_e32 v[46:47], v[242:243]
	s_nop 1
	v_mul_f32_e32 v12, 0xbfb8aa3b, v12
	v_exp_f32_e32 v12, v12
	v_mul_f32_e32 v13, 0xbfb8aa3b, v13
	v_exp_f32_e32 v13, v13
	v_mov_b32_e32 v66, 0
	v_mov_b32_e32 v58, 0
	v_mov_b32_e32 v62, 0
	v_add_f32_e32 v12, 1.0, v12
	v_mov_b32_e32 v30, 0
	v_rcp_f32_e32 v12, v12
	v_mov_b32_e32 v31, 0
	v_mov_b32_e32 v64, 0
	v_add_f32_e32 v13, 1.0, v13
	v_mov_b32_e32 v59, 0
	v_mov_b32_e32 v68, 0
	v_rcp_f32_e32 v13, v13
	v_mov_b32_e32 v67, 0
	v_mul_f32_e32 v8, 0xbfb8aa3b, v8
	v_mov_b32_e32 v63, 0
	v_exp_f32_e32 v8, v8
	v_mul_f32_e32 v9, 0xbfb8aa3b, v9
	v_mov_b32_e32 v65, 0
	v_exp_f32_e32 v9, v9
	v_mov_b32_e32 v69, 0
	v_mov_b32_e32 v60, 0
	v_add_f32_e32 v8, 1.0, v8
	v_mov_b32_e32 v56, 0
	v_rcp_f32_e32 v8, v8
	v_add_f32_e32 v9, 1.0, v9
	v_mul_f32_e32 v4, 0xbfb8aa3b, v4
	v_rcp_f32_e32 v9, v9
	v_exp_f32_e32 v4, v4
	v_mul_f32_e32 v5, 0xbfb8aa3b, v5
	v_exp_f32_e32 v5, v5
	v_mov_b32_e32 v61, 0
	v_add_f32_e32 v4, 1.0, v4
	v_rcp_f32_e32 v4, v4
	v_add_f32_e32 v5, 1.0, v5
	v_rcp_f32_e32 v5, v5
	v_mov_b32_e32 v57, 0
	v_mul_f32_e32 v0, 0xbfb8aa3b, v0
	v_exp_f32_e32 v0, v0
	v_mul_f32_e32 v1, 0xbfb8aa3b, v1
	v_exp_f32_e32 v1, v1
	v_add_f32_e32 v0, 1.0, v0
	v_rcp_f32_e32 v0, v0
	v_add_f32_e32 v1, 1.0, v1
	v_rcp_f32_e32 v1, v1
	v_mov_b32_dpp v30, v22 row_ror:8 row_mask:0xf bank_mask:0xf
	v_mov_b32_dpp v31, v23 row_ror:8 row_mask:0xf bank_mask:0xf
	v_mov_b32_dpp v56, v24 row_ror:8 row_mask:0xf bank_mask:0xf
	v_fmamk_f32 v17, v17, 0x3a000000, v180
	v_rsq_f32_e32 v17, v17
	v_mov_b32_dpp v62, v26 row_ror:8 row_mask:0xf bank_mask:0xf
	v_mov_b32_dpp v64, v28 row_ror:8 row_mask:0xf bank_mask:0xf
	v_mov_b32_dpp v63, v27 row_ror:8 row_mask:0xf bank_mask:0xf
	v_mov_b32_dpp v58, v36 row_ror:8 row_mask:0xf bank_mask:0xf
	v_cndmask_b32_e64 v22, v58, v22, s[6:7]
	v_mov_b32_dpp v59, v37 row_ror:8 row_mask:0xf bank_mask:0xf
	v_mov_b32_dpp v66, v44 row_ror:8 row_mask:0xf bank_mask:0xf
	v_cndmask_b32_e64 v26, v66, v26, s[6:7]
	v_lshlrev_b32_e32 v58, 16, v26
	v_mul_f32_e32 v58, v17, v58
	v_cndmask_b32_e64 v31, v37, v31, s[6:7]
	v_mov_b32_dpp v68, v46 row_ror:8 row_mask:0xf bank_mask:0xf
	v_cndmask_b32_e64 v37, v46, v64, s[6:7]
	v_lshlrev_b32_e32 v46, 16, v22
	v_and_b32_e32 v26, 0xffff0000, v26
	v_mul_f32_e32 v52, v52, v58
	v_fmac_f32_e32 v46, v12, v52
	v_mul_f32_e32 v12, v17, v26
	v_and_b32_e32 v22, 0xffff0000, v22
	v_mul_f32_e32 v12, v53, v12
	v_fmac_f32_e32 v22, v13, v12
	v_mul_f32_e32 v12, 0xbfb8aa3b, v14
	v_exp_f32_e32 v12, v12
	v_mul_f32_e32 v14, 0xbfb8aa3b, v15
	v_exp_f32_e32 v14, v14
; __device__ __forceinline__ unsigned cvt_pk_bf16(float lo, float hi) { unsigned r; asm volatile("v_cvt_pk_bf16_f32 %0, %1, %2" : "=v"(r) : "v"(lo), "v"(hi)); return r; }
; __device__ __forceinline__ float bflo(unsigned w) { return __uint_as_float(w << 16); }
; __device__ __forceinline__ float bfhi(unsigned w) { return __uint_as_float(w & 0xffff0000u); }
;     __device__ __forceinline__ void operator()(const f32x4 (&acc)[2][2][4][2], const Unit& u, int wr, int wc, int fr, int fq) const {
;     ...
;             for (int m = 0; m < 4; ++m) { const int row = row0 + ai * HALF + m * 16; const size_t off = (size_t)row * D + col0; const float ri = __builtin_amdgcn_rsqf(sse[row] * (1.f / D) + EPS); float sq = 0.f; u32x4 w[2];
;                 u32x4 rr[2], ee[2]; load_pair_lines(R, D, row, fr, col0, rr[0], rr[1]); load_pair_lines(E, D, row, fr, col0, ee[0], ee[1]);
; #pragma unroll
;                 for (int bj = 0; bj < 2; ++bj) { const u32x4 rw = rr[bj], ew = ee[bj];
;                     const float r[8] = {bflo(rw.x), bfhi(rw.x), bflo(rw.y), bfhi(rw.y), bflo(rw.z), bfhi(rw.z), bflo(rw.w), bfhi(rw.w)};
;                     const float e[8] = {bflo(ew.x), bfhi(ew.x), bflo(ew.y), bfhi(ew.y), bflo(ew.z), bfhi(ew.z), bflo(ew.w), bfhi(ew.w)};
;                     float o[8];
; #pragma unroll
;                     for (int j = 0; j < 8; ++j) { const float a = acc[ai][bj][m][j >> 2][j & 3]; const float gg = gv[bj][j >> 2][j & 3];
;                         o[j] = r[j] + e[j] * ri * gg * __builtin_amdgcn_rcpf(1.f + __builtin_amdgcn_exp2f(-a * LOG2E)); }
;                     if (OUT) { *(f32x4*)(OUT + off + 8 * bj) = (f32x4){o[0], o[1], o[2], o[3]}; *(f32x4*)(OUT + off + 8 * bj + 4) = (f32x4){o[4], o[5], o[6], o[7]}; }
;                     else { sq += (o[0] * o[0] + o[1] * o[1]) + (o[2] * o[2] + o[3] * o[3]) + (o[4] * o[4] + o[5] * o[5]) + (o[6] * o[6] + o[7] * o[7]);
;                         w[bj].x = cvt_pk_bf16(o[0], o[1]); w[bj].y = cvt_pk_bf16(o[2], o[3]); w[bj].z = cvt_pk_bf16(o[4], o[5]); w[bj].w = cvt_pk_bf16(o[6], o[7]); } }
;                 if (!OUT) { store_pair_lines(O, D, row, fr, col0, w[0], w[1]);
;                     sq += __shfl_xor(sq, 16); sq += __shfl_xor(sq, 32); if (fq == 0) unsafeAtomicAdd(ssout + row, sq); } }
	v_mov_b32_dpp v67, v45 row_ror:8 row_mask:0xf bank_mask:0xf
	v_add_f32_e32 v12, 1.0, v12
	v_cndmask_b32_e64 v27, v67, v27, s[6:7]
	v_rcp_f32_e32 v12, v12
	v_cndmask_b32_e64 v23, v59, v23, s[6:7]
	v_lshlrev_b32_e32 v59, 16, v27
	v_add_f32_e32 v14, 1.0, v14
	v_mov_b32_dpp v65, v29 row_ror:8 row_mask:0xf bank_mask:0xf
	v_mul_f32_e32 v13, v17, v59
	v_rcp_f32_e32 v14, v14
	v_cndmask_b32_e64 v30, v36, v30, s[6:7]
	v_mov_b32_dpp v69, v47 row_ror:8 row_mask:0xf bank_mask:0xf
	v_cndmask_b32_e64 v36, v47, v65, s[6:7]
	v_lshlrev_b32_e32 v47, 16, v23
	v_and_b32_e32 v27, 0xffff0000, v27
	v_mul_f32_e32 v13, v54, v13
	v_mov_b32_dpp v60, v38 row_ror:8 row_mask:0xf bank_mask:0xf
	v_cndmask_b32_e64 v28, v68, v28, s[6:7]
	v_fmac_f32_e32 v47, v12, v13
	v_mul_f32_e32 v12, v17, v27
	v_cndmask_b32_e64 v24, v60, v24, s[6:7]
	v_and_b32_e32 v23, 0xffff0000, v23
	v_lshlrev_b32_e32 v60, 16, v28
	v_mul_f32_e32 v12, v55, v12
	v_fmac_f32_e32 v23, v14, v12
	v_mul_f32_e32 v12, v17, v60
	v_cndmask_b32_e64 v38, v38, v56, s[6:7]
	v_lshlrev_b32_e32 v56, 16, v24
	v_and_b32_e32 v28, 0xffff0000, v28
	v_mul_f32_e32 v12, v48, v12
	v_fmac_f32_e32 v56, v8, v12
	v_mul_f32_e32 v8, v17, v28
	v_and_b32_e32 v24, 0xffff0000, v24
	v_mul_f32_e32 v8, v49, v8
	v_fmac_f32_e32 v24, v9, v8
	v_mul_f32_e32 v8, 0xbfb8aa3b, v10
	v_cndmask_b32_e64 v44, v44, v62, s[6:7]
	v_exp_f32_e32 v8, v8
	v_mul_f32_e32 v10, 0xbfb8aa3b, v11
	v_lshlrev_b32_e32 v27, 16, v44
	v_exp_f32_e32 v10, v10
	v_mul_f32_e32 v27, v17, v27
	v_lshlrev_b32_e32 v13, 16, v30
	v_and_b32_e32 v28, 0xffff0000, v44
	v_mul_f32_e32 v27, v40, v27
	v_add_f32_e32 v8, 1.0, v8
	v_fmac_f32_e32 v13, v4, v27
	v_mul_f32_e32 v4, v17, v28
	v_mov_b32_dpp v61, v39 row_ror:8 row_mask:0xf bank_mask:0xf
	v_cndmask_b32_e64 v29, v69, v29, s[6:7]
	v_rcp_f32_e32 v8, v8
	v_and_b32_e32 v14, 0xffff0000, v30
	v_mul_f32_e32 v4, v41, v4
	v_mov_b32_dpp v57, v25 row_ror:8 row_mask:0xf bank_mask:0xf
	v_cndmask_b32_e64 v25, v61, v25, s[6:7]
	v_lshlrev_b32_e32 v61, 16, v29
	v_add_f32_e32 v10, 1.0, v10
	v_fmac_f32_e32 v14, v5, v4
	v_mul_f32_e32 v4, 0xbfb8aa3b, v6
	v_mul_f32_e32 v9, v17, v61
	v_rcp_f32_e32 v10, v10
	v_exp_f32_e32 v4, v4
	v_cndmask_b32_e64 v39, v39, v57, s[6:7]
	v_lshlrev_b32_e32 v57, 16, v25
	v_and_b32_e32 v29, 0xffff0000, v29
	v_mul_f32_e32 v9, v50, v9
	v_mul_f32_e32 v6, 0xbfb8aa3b, v7
	v_fmac_f32_e32 v57, v8, v9
	v_mul_f32_e32 v8, v17, v29
	v_exp_f32_e32 v6, v6
	v_and_b32_e32 v25, 0xffff0000, v25
	v_mul_f32_e32 v8, v51, v8
	v_fmac_f32_e32 v25, v10, v8
	v_mul_f32_e32 v8, v22, v22
	v_mul_f32_e32 v9, v23, v23
	v_add_f32_e32 v4, 1.0, v4
	v_cndmask_b32_e64 v45, v45, v63, s[6:7]
	v_fmac_f32_e32 v8, v46, v46
	v_fmac_f32_e32 v9, v47, v47
	v_rcp_f32_e32 v4, v4
	v_add_f32_e32 v8, v8, v9
	v_mul_f32_e32 v9, v24, v24
	v_lshlrev_b32_e32 v29, 16, v45
	v_add_f32_e32 v6, 1.0, v6
	v_fmac_f32_e32 v9, v56, v56
	v_mul_f32_e32 v5, v17, v29
	v_rcp_f32_e32 v6, v6
	v_add_f32_e32 v8, v9, v8
	v_mul_f32_e32 v9, v25, v25
	v_lshlrev_b32_e32 v15, 16, v31
	v_and_b32_e32 v30, 0xffff0000, v45
	v_mul_f32_e32 v5, v42, v5
	v_fmac_f32_e32 v9, v57, v57
	v_fmac_f32_e32 v15, v4, v5
	v_mul_f32_e32 v4, v17, v30
	v_add_f32_e32 v8, v9, v8
	v_cvt_pk_bf16_f32 v9, v46, v22
	v_and_b32_e32 v22, 0xffff0000, v31
	v_lshlrev_b32_e32 v31, 16, v37
	v_mul_f32_e32 v4, v43, v4
	v_fmac_f32_e32 v22, v6, v4
	v_mul_f32_e32 v4, v17, v31
	v_cvt_pk_bf16_f32 v10, v47, v23
	v_lshlrev_b32_e32 v23, 16, v38
	v_and_b32_e32 v37, 0xffff0000, v37
	v_mul_f32_e32 v4, v32, v4
	v_fmac_f32_e32 v23, v0, v4
	v_mul_f32_e32 v0, v17, v37
	v_cvt_pk_bf16_f32 v11, v56, v24
	v_and_b32_e32 v24, 0xffff0000, v38
	v_mul_f32_e32 v0, v33, v0
	v_fmac_f32_e32 v24, v1, v0
	v_mul_f32_e32 v0, 0xbfb8aa3b, v2
	v_exp_f32_e32 v0, v0
	v_mul_f32_e32 v2, 0xbfb8aa3b, v3
	v_exp_f32_e32 v2, v2
	v_lshlrev_b32_e32 v38, 16, v36
	v_add_f32_e32 v0, 1.0, v0
	v_rcp_f32_e32 v0, v0
	v_add_f32_e32 v2, 1.0, v2
	v_mul_f32_e32 v1, v17, v38
	v_rcp_f32_e32 v2, v2
	v_cvt_pk_bf16_f32 v12, v57, v25
	v_lshlrev_b32_e32 v25, 16, v39
	v_and_b32_e32 v36, 0xffff0000, v36
	v_mul_f32_e32 v1, v34, v1
	v_fmac_f32_e32 v25, v0, v1
	v_mul_f32_e32 v0, v17, v36
	v_and_b32_e32 v26, 0xffff0000, v39
	v_mul_f32_e32 v0, v35, v0
	v_fmac_f32_e32 v26, v2, v0
	v_mul_f32_e32 v0, v14, v14
	v_mul_f32_e32 v1, v22, v22
	v_fmac_f32_e32 v0, v13, v13
	v_fmac_f32_e32 v1, v15, v15
	v_add_f32_e32 v0, v0, v1
	v_mul_f32_e32 v1, v24, v24
	v_fmac_f32_e32 v1, v23, v23
	v_add_f32_e32 v0, v1, v0
	v_mul_f32_e32 v1, v26, v26
	v_fmac_f32_e32 v1, v25, v25
	v_add_f32_e32 v0, v1, v0
	v_mov_b32_e32 v5, 0
	v_add_f32_e32 v17, v0, v8
	v_cvt_pk_bf16_f32 v0, v13, v14
	v_cvt_pk_bf16_f32 v1, v15, v22
	v_cvt_pk_bf16_f32 v8, v23, v24
	v_cvt_pk_bf16_f32 v13, v25, v26
	v_mov_b32_e32 v15, 0
	v_mov_b32_e32 v6, 0
	v_mov_b32_dpp v5, v13 row_ror:8 row_mask:0xf bank_mask:0xf
	v_mov_b32_dpp v15, v12 row_ror:8 row_mask:0xf bank_mask:0xf
	v_cndmask_b32_e64 v5, v5, v12, s[6:7]
	ds_bpermute_b32 v12, v134, v17
	v_mov_b32_e32 v7, 0
	v_mov_b32_dpp v6, v9 row_ror:8 row_mask:0xf bank_mask:0xf
	v_mov_b32_e32 v2, 0
	v_mov_b32_dpp v7, v10 row_ror:8 row_mask:0xf bank_mask:0xf
	v_mov_b32_e32 v3, 0
	v_mov_b32_e32 v4, 0
	v_mov_b32_e32 v14, 0
	v_mov_b32_dpp v2, v0 row_ror:8 row_mask:0xf bank_mask:0xf
	v_mov_b32_dpp v3, v1 row_ror:8 row_mask:0xf bank_mask:0xf
	v_mov_b32_dpp v4, v8 row_ror:8 row_mask:0xf bank_mask:0xf
	v_cndmask_b32_e64 v6, v0, v6, s[6:7]
	v_cndmask_b32_e64 v7, v1, v7, s[6:7]
	v_lshl_add_u64 v[0:1], s[36:37], 0, v[18:19]
	v_mov_b32_dpp v14, v11 row_ror:8 row_mask:0xf bank_mask:0xf
	v_cndmask_b32_e64 v3, v3, v10, s[6:7]
	v_cndmask_b32_e64 v4, v4, v11, s[6:7]
	v_lshl_add_u64 v[10:11], v[0:1], 0, v[162:163]
	s_waitcnt lgkmcnt(0)
	v_add_f32_e32 v0, v17, v12
	ds_bpermute_b32 v1, v135, v0
	v_cndmask_b32_e64 v2, v2, v9, s[6:7]
	global_store_dwordx4 v[10:11], v[2:5], off
	v_cndmask_b32_e64 v8, v8, v14, s[6:7]
	v_cndmask_b32_e64 v9, v13, v15, s[6:7]
	v_lshl_add_u64 v[2:3], s[36:37], 0, v[20:21]
	v_lshl_add_u64 v[2:3], v[2:3], 0, v[162:163]
	global_store_dwordx4 v[2:3], v[6:9], off
	s_and_saveexec_b64 s[56:57], s[8:9]
	s_cbranch_execz .LBB0_873
	v_ashrrev_i32_e32 v17, 31, v16
	v_lshl_add_u64 v[2:3], v[16:17], 2, s[18:19]
	s_waitcnt lgkmcnt(0)
	v_add_f32_e32 v0, v0, v1
	global_atomic_add_f32 v[2:3], v0, off
	s_branch .LBB0_873

; #define PG8_STAGE(bufoff, gbase, voff) do { _Pragma("unroll") for (int _i = 0; _i < 2; ++_i) \
;         __builtin_amdgcn_global_load_lds((const unsigned*)((const char*)(gbase) + (voff)[_i]), (LAS unsigned*)(lds + (bufoff) + ldsw + _i * 8192), 16, 0, 0); } while (0)
; #define PG8_LDA(dst, b, h) do { _Pragma("unroll") for (int m = 0; m < 4; ++m) _Pragma("unroll") for (int k = 0; k < 2; ++k) dst[m][k] = *(const LAS bf16x8*)(lds + PG8_SA(b, h) + aoff + m * 2048 + k * 1024); } while (0)
; #define PG8_LDB(dst, b, h) do { _Pragma("unroll") for (int n = 0; n < 2; ++n) _Pragma("unroll") for (int k = 0; k < 2; ++k) dst[n][k] = *(const LAS bf16x8*)(lds + PG8_SB(b, h) + boff + n * 2048 + k * 1024); } while (0)
; #define PG8_WAIT_V(n) asm volatile("s_waitcnt vmcnt(" #n ")" ::: "memory")
; #define PG8_WAIT_L(n) asm volatile("s_waitcnt lgkmcnt(" #n ")" ::: "memory")
; #define PG8_BAR __builtin_amdgcn_s_barrier()
; #define PG8_SCHED __builtin_amdgcn_sched_barrier(0)
; template <class Epi>
; __device__ __forceinline__ void gemm_phase(LAS unsigned char* lds, const Gemm g, const StaticOrder& S, const Epi& E) {
;     ...
;             PG8_LDB(B0, 0, 0); PG8_SCHED; PG8_LDA(At, 0, 0); PG8_STAGE(PG8_SA(1, 1), a1 + hstep, voffA);
;             PG8_WAIT_L(8); PG8_BAR; PG8_WAIT_L(0); PG8_MMA(0, 0, At, B0); PG8_BAR; PG8_SCHED;
;             PG8_LDB(B1, 0, 1); PG8_STAGE(PG8_SB(0, 0), b2, voffB0);
;             PG8_BAR; PG8_WAIT_L(0); PG8_MMA(0, 1, At, B1); PG8_BAR;
;             PG8_LDA(At, 0, 1); PG8_STAGE(PG8_SA(0, 0), a2, voffA);
;             PG8_BAR; PG8_WAIT_L(0); PG8_MMA(1, 0, At, B0); PG8_BAR; PG8_SCHED;
;             PG8_STAGE(PG8_SB(0, 1), b2, voffB1);
;             PG8_WAIT_V(6); PG8_BAR; PG8_MMA(1, 1, At, B1); PG8_BAR;
;             PG8_LDB(B0, 1, 0); PG8_SCHED; PG8_LDA(At, 1, 0); PG8_STAGE(PG8_SA(0, 1), a2 + hstep, voffA);
;             PG8_WAIT_L(8); PG8_BAR; PG8_WAIT_L(0); PG8_MMA(0, 0, At, B0); PG8_BAR; PG8_SCHED;
;             PG8_LDB(B1, 1, 1); PG8_STAGE(PG8_SB(1, 0), b3, voffB0);
;             PG8_BAR; PG8_WAIT_L(0); PG8_MMA(0, 1, At, B1); PG8_BAR;
;             PG8_LDA(At, 1, 1); PG8_STAGE(PG8_SA(1, 0), a3, voffA);
;             PG8_BAR; PG8_WAIT_L(0); PG8_MMA(1, 0, At, B0); PG8_BAR; PG8_SCHED;
;             PG8_STAGE(PG8_SB(1, 1), b3, voffB1);
;             PG8_WAIT_V(6); PG8_BAR; PG8_MMA(1, 1, At, B1); PG8_BAR;
.LBB0_962:
	ds_read_b128 v[146:149], v158
	ds_read_b128 v[150:153], v158 offset:1024
	ds_read_b128 v[162:165], v158 offset:2048
	ds_read_b128 v[166:169], v158 offset:3072
	s_add_u32 s33, s46, 0xfff80080
	s_addc_u32 s48, s47, -1
	s_cmp_eq_u32 s77, 28
	s_cselect_b32 s49, s37, s48
	s_cselect_b32 s48, s72, s33
	s_cselect_b32 s51, s19, s75
	s_cselect_b32 s50, s73, s74
	v_lshl_add_u64 v[204:205], s[46:47], 0, v[140:141]
	s_add_i32 m0, s45, 0xc000
	ds_read_b128 v[170:173], v159
	ds_read_b128 v[174:177], v159 offset:1024
	ds_read_b128 v[178:181], v159 offset:2048
	ds_read_b128 v[182:185], v159 offset:3072
	ds_read_b128 v[186:189], v159 offset:4096
	ds_read_b128 v[190:193], v159 offset:5120
	ds_read_b128 v[194:197], v159 offset:6144
	ds_read_b128 v[198:201], v159 offset:7168
	global_load_lds_dwordx4 v[204:205], off
	v_lshl_add_u64 v[204:205], s[46:47], 0, v[142:143]
	s_add_i32 m0, s45, 0xe000
	s_nop 0
	global_load_lds_dwordx4 v[204:205], off
	s_waitcnt lgkmcnt(8)
	s_barrier
	s_waitcnt lgkmcnt(0)
	s_setprio 1
	s_waitcnt lgkmcnt(0)
	v_mfma_f32_16x16x32_bf16 v[124:127], v[146:149], v[170:173], v[124:127]
	v_mfma_f32_16x16x32_bf16 v[120:123], v[162:165], v[170:173], v[120:123]
	v_mfma_f32_16x16x32_bf16 v[108:111], v[146:149], v[178:181], v[108:111]
	v_mfma_f32_16x16x32_bf16 v[104:107], v[162:165], v[178:181], v[104:107]
	v_mfma_f32_16x16x32_bf16 v[92:95], v[146:149], v[186:189], v[92:95]
	v_mfma_f32_16x16x32_bf16 v[88:91], v[162:165], v[186:189], v[88:91]
	v_mfma_f32_16x16x32_bf16 v[76:79], v[146:149], v[194:197], v[76:79]
	v_mfma_f32_16x16x32_bf16 v[72:75], v[162:165], v[194:197], v[72:75]
	v_mfma_f32_16x16x32_bf16 v[124:127], v[150:153], v[174:177], v[124:127]
	v_mfma_f32_16x16x32_bf16 v[120:123], v[166:169], v[174:177], v[120:123]
	v_mfma_f32_16x16x32_bf16 v[108:111], v[150:153], v[182:185], v[108:111]
	v_mfma_f32_16x16x32_bf16 v[104:107], v[166:169], v[182:185], v[104:107]
	v_mfma_f32_16x16x32_bf16 v[92:95], v[150:153], v[190:193], v[92:95]
	v_mfma_f32_16x16x32_bf16 v[88:91], v[166:169], v[190:193], v[88:91]
	v_mfma_f32_16x16x32_bf16 v[76:79], v[150:153], v[198:201], v[76:79]
	v_mfma_f32_16x16x32_bf16 v[72:75], v[166:169], v[198:201], v[72:75]
	s_setprio 0
	s_barrier
	s_add_i32 s33, s68, s57
	v_lshl_add_u64 v[220:221], s[50:51], 0, v[134:135]
	s_mov_b32 m0, s33
	ds_read_b128 v[204:207], v160
	ds_read_b128 v[208:211], v160 offset:1024
	ds_read_b128 v[212:215], v160 offset:2048
	ds_read_b128 v[216:219], v160 offset:3072
	global_load_lds_dwordx4 v[220:221], off
	v_lshl_add_u64 v[222:223], s[50:51], 0, v[128:129]
	s_add_i32 m0, s33, 0x2000
	s_nop 0
	global_load_lds_dwordx4 v[222:223], off
	s_barrier
	s_waitcnt lgkmcnt(0)
	s_setprio 1
	s_waitcnt lgkmcnt(0)
	v_mfma_f32_16x16x32_bf16 v[116:119], v[204:207], v[170:173], v[116:119]
	v_mfma_f32_16x16x32_bf16 v[112:115], v[212:215], v[170:173], v[112:115]
	v_mfma_f32_16x16x32_bf16 v[100:103], v[204:207], v[178:181], v[100:103]
	v_mfma_f32_16x16x32_bf16 v[96:99], v[212:215], v[178:181], v[96:99]
	v_mfma_f32_16x16x32_bf16 v[84:87], v[204:207], v[186:189], v[84:87]
	v_mfma_f32_16x16x32_bf16 v[80:83], v[212:215], v[186:189], v[80:83]
	v_mfma_f32_16x16x32_bf16 v[68:71], v[204:207], v[194:197], v[68:71]
	v_mfma_f32_16x16x32_bf16 v[64:67], v[212:215], v[194:197], v[64:67]
	v_mfma_f32_16x16x32_bf16 v[116:119], v[208:211], v[174:177], v[116:119]
	v_mfma_f32_16x16x32_bf16 v[112:115], v[216:219], v[174:177], v[112:115]
	v_mfma_f32_16x16x32_bf16 v[100:103], v[208:211], v[182:185], v[100:103]
	v_mfma_f32_16x16x32_bf16 v[96:99], v[216:219], v[182:185], v[96:99]
	v_mfma_f32_16x16x32_bf16 v[84:87], v[208:211], v[190:193], v[84:87]
	v_mfma_f32_16x16x32_bf16 v[80:83], v[216:219], v[190:193], v[80:83]
	v_mfma_f32_16x16x32_bf16 v[68:71], v[208:211], v[198:201], v[68:71]
	v_mfma_f32_16x16x32_bf16 v[64:67], v[216:219], v[198:201], v[64:67]
	s_setprio 0
	s_mov_b32 m0, s45
	v_lshl_add_u64 v[224:225], s[48:49], 0, v[138:139]
	s_barrier
	ds_read_b128 v[170:173], v159 offset:16384
	ds_read_b128 v[174:177], v159 offset:17408
	ds_read_b128 v[178:181], v159 offset:18432
	ds_read_b128 v[182:185], v159 offset:19456
	ds_read_b128 v[186:189], v159 offset:20480
	ds_read_b128 v[190:193], v159 offset:21504
	ds_read_b128 v[194:197], v159 offset:22528
	ds_read_b128 v[198:201], v159 offset:23552
	global_load_lds_dwordx4 v[224:225], off
	v_lshl_add_u64 v[226:227], s[48:49], 0, v[132:133]
	s_mov_b32 m0, s59
	s_nop 0
	global_load_lds_dwordx4 v[226:227], off
	s_barrier
	s_waitcnt lgkmcnt(0)
	s_setprio 1
	s_waitcnt lgkmcnt(0)
	v_mfma_f32_16x16x32_bf16 v[60:63], v[146:149], v[170:173], v[60:63]
	v_mfma_f32_16x16x32_bf16 v[56:59], v[162:165], v[170:173], v[56:59]
	v_mfma_f32_16x16x32_bf16 v[44:47], v[146:149], v[178:181], v[44:47]
	v_mfma_f32_16x16x32_bf16 v[40:43], v[162:165], v[178:181], v[40:43]
	v_mfma_f32_16x16x32_bf16 v[28:31], v[146:149], v[186:189], v[28:31]
	v_mfma_f32_16x16x32_bf16 v[24:27], v[162:165], v[186:189], v[24:27]
	v_mfma_f32_16x16x32_bf16 v[12:15], v[146:149], v[194:197], v[12:15]
	v_mfma_f32_16x16x32_bf16 v[8:11], v[162:165], v[194:197], v[8:11]
	v_mfma_f32_16x16x32_bf16 v[60:63], v[150:153], v[174:177], v[60:63]
	v_mfma_f32_16x16x32_bf16 v[56:59], v[166:169], v[174:177], v[56:59]
	v_mfma_f32_16x16x32_bf16 v[44:47], v[150:153], v[182:185], v[44:47]
	v_mfma_f32_16x16x32_bf16 v[40:43], v[166:169], v[182:185], v[40:43]
	v_mfma_f32_16x16x32_bf16 v[28:31], v[150:153], v[190:193], v[28:31]
	v_mfma_f32_16x16x32_bf16 v[24:27], v[166:169], v[190:193], v[24:27]
	v_mfma_f32_16x16x32_bf16 v[12:15], v[150:153], v[198:201], v[12:15]
	v_mfma_f32_16x16x32_bf16 v[8:11], v[166:169], v[198:201], v[8:11]
	s_setprio 0
	s_barrier
; #define PG8_STAGE(bufoff, gbase, voff) do { _Pragma("unroll") for (int _i = 0; _i < 2; ++_i) \
;         __builtin_amdgcn_global_load_lds((const unsigned*)((const char*)(gbase) + (voff)[_i]), (LAS unsigned*)(lds + (bufoff) + ldsw + _i * 8192), 16, 0, 0); } while (0)
; #define PG8_LDA(dst, b, h) do { _Pragma("unroll") for (int m = 0; m < 4; ++m) _Pragma("unroll") for (int k = 0; k < 2; ++k) dst[m][k] = *(const LAS bf16x8*)(lds + PG8_SA(b, h) + aoff + m * 2048 + k * 1024); } while (0)
; #define PG8_LDB(dst, b, h) do { _Pragma("unroll") for (int n = 0; n < 2; ++n) _Pragma("unroll") for (int k = 0; k < 2; ++k) dst[n][k] = *(const LAS bf16x8*)(lds + PG8_SB(b, h) + boff + n * 2048 + k * 1024); } while (0)
; #define PG8_WAIT_V(n) asm volatile("s_waitcnt vmcnt(" #n ")" ::: "memory")
; #define PG8_WAIT_L(n) asm volatile("s_waitcnt lgkmcnt(" #n ")" ::: "memory")
; #define PG8_BAR __builtin_amdgcn_s_barrier()
; #define PG8_SCHED __builtin_amdgcn_sched_barrier(0)
; template <class Epi>
; __device__ __forceinline__ void gemm_phase(LAS unsigned char* lds, const Gemm g, const StaticOrder& S, const Epi& E) {
;     ...
;             PG8_LDB(B0, 0, 0); PG8_SCHED; PG8_LDA(At, 0, 0); PG8_STAGE(PG8_SA(1, 1), a1 + hstep, voffA);
;             PG8_WAIT_L(8); PG8_BAR; PG8_WAIT_L(0); PG8_MMA(0, 0, At, B0); PG8_BAR; PG8_SCHED;
;             PG8_LDB(B1, 0, 1); PG8_STAGE(PG8_SB(0, 0), b2, voffB0);
;             PG8_BAR; PG8_WAIT_L(0); PG8_MMA(0, 1, At, B1); PG8_BAR;
;             PG8_LDA(At, 0, 1); PG8_STAGE(PG8_SA(0, 0), a2, voffA);
;             PG8_BAR; PG8_WAIT_L(0); PG8_MMA(1, 0, At, B0); PG8_BAR; PG8_SCHED;
;             PG8_STAGE(PG8_SB(0, 1), b2, voffB1);
;             PG8_WAIT_V(6); PG8_BAR; PG8_MMA(1, 1, At, B1); PG8_BAR;
;             PG8_LDB(B0, 1, 0); PG8_SCHED; PG8_LDA(At, 1, 0); PG8_STAGE(PG8_SA(0, 1), a2 + hstep, voffA);
;             PG8_WAIT_L(8); PG8_BAR; PG8_WAIT_L(0); PG8_MMA(0, 0, At, B0); PG8_BAR; PG8_SCHED;
;             PG8_LDB(B1, 1, 1); PG8_STAGE(PG8_SB(1, 0), b3, voffB0);
;             PG8_BAR; PG8_WAIT_L(0); PG8_MMA(0, 1, At, B1); PG8_BAR;
;             PG8_LDA(At, 1, 1); PG8_STAGE(PG8_SA(1, 0), a3, voffA);
;             PG8_BAR; PG8_WAIT_L(0); PG8_MMA(1, 0, At, B0); PG8_BAR; PG8_SCHED;
;             PG8_STAGE(PG8_SB(1, 1), b3, voffB1);
;             PG8_WAIT_V(6); PG8_BAR; PG8_MMA(1, 1, At, B1); PG8_BAR;
	s_add_i32 s33, s69, s57
	v_lshl_add_u64 v[228:229], s[50:51], 0, v[136:137]
	s_mov_b32 m0, s33
	v_lshl_add_u64 v[230:231], s[50:51], 0, v[130:131]
	global_load_lds_dwordx4 v[228:229], off
	s_add_i32 m0, s33, 0x2000
	s_nop 0
	global_load_lds_dwordx4 v[230:231], off
	s_waitcnt vmcnt(6)
	s_barrier
	s_setprio 1
	v_mfma_f32_16x16x32_bf16 v[52:55], v[204:207], v[170:173], v[52:55]
	v_mfma_f32_16x16x32_bf16 v[48:51], v[212:215], v[170:173], v[48:51]
	v_mfma_f32_16x16x32_bf16 v[36:39], v[204:207], v[178:181], v[36:39]
	v_mfma_f32_16x16x32_bf16 v[32:35], v[212:215], v[178:181], v[32:35]
	v_mfma_f32_16x16x32_bf16 v[20:23], v[204:207], v[186:189], v[20:23]
	v_mfma_f32_16x16x32_bf16 v[16:19], v[212:215], v[186:189], v[16:19]
	v_mfma_f32_16x16x32_bf16 v[4:7], v[204:207], v[194:197], v[4:7]
	v_mfma_f32_16x16x32_bf16 v[0:3], v[212:215], v[194:197], v[0:3]
	v_mfma_f32_16x16x32_bf16 v[52:55], v[208:211], v[174:177], v[52:55]
	v_mfma_f32_16x16x32_bf16 v[48:51], v[216:219], v[174:177], v[48:51]
	v_mfma_f32_16x16x32_bf16 v[36:39], v[208:211], v[182:185], v[36:39]
	v_mfma_f32_16x16x32_bf16 v[32:35], v[216:219], v[182:185], v[32:35]
	v_mfma_f32_16x16x32_bf16 v[20:23], v[208:211], v[190:193], v[20:23]
	v_mfma_f32_16x16x32_bf16 v[16:19], v[216:219], v[190:193], v[16:19]
	v_mfma_f32_16x16x32_bf16 v[4:7], v[208:211], v[198:201], v[4:7]
	v_mfma_f32_16x16x32_bf16 v[0:3], v[216:219], v[198:201], v[0:3]
	s_setprio 0
	s_add_i32 s33, 0, 0x18000
	v_add_u32_e32 v166, s33, v155
	s_barrier
	ds_read_b128 v[146:149], v166
	ds_read_b128 v[150:153], v166 offset:1024
	ds_read_b128 v[162:165], v166 offset:2048
	ds_read_b128 v[166:169], v166 offset:3072
	s_add_u32 s48, s48, 0x80000
	s_addc_u32 s49, s49, 0
	s_mov_b32 m0, s60
	v_lshl_add_u64 v[204:205], s[48:49], 0, v[138:139]
	ds_read_b128 v[170:173], v159 offset:32768
	ds_read_b128 v[174:177], v159 offset:33792
	ds_read_b128 v[178:181], v159 offset:34816
	ds_read_b128 v[182:185], v159 offset:35840
	ds_read_b128 v[186:189], v159 offset:36864
	ds_read_b128 v[190:193], v159 offset:37888
	ds_read_b128 v[194:197], v159 offset:38912
	ds_read_b128 v[198:201], v159 offset:39936
	global_load_lds_dwordx4 v[204:205], off
	v_lshl_add_u64 v[204:205], s[48:49], 0, v[132:133]
	s_mov_b32 m0, s61
	s_nop 0
	global_load_lds_dwordx4 v[204:205], off
	s_waitcnt lgkmcnt(8)
	s_barrier
	s_waitcnt lgkmcnt(0)
	s_setprio 1
	s_waitcnt lgkmcnt(0)
	v_mfma_f32_16x16x32_bf16 v[124:127], v[146:149], v[170:173], v[124:127]
	v_mfma_f32_16x16x32_bf16 v[120:123], v[162:165], v[170:173], v[120:123]
	v_mfma_f32_16x16x32_bf16 v[108:111], v[146:149], v[178:181], v[108:111]
	v_mfma_f32_16x16x32_bf16 v[104:107], v[162:165], v[178:181], v[104:107]
	v_mfma_f32_16x16x32_bf16 v[92:95], v[146:149], v[186:189], v[92:95]
	v_mfma_f32_16x16x32_bf16 v[88:91], v[162:165], v[186:189], v[88:91]
	v_mfma_f32_16x16x32_bf16 v[76:79], v[146:149], v[194:197], v[76:79]
	v_mfma_f32_16x16x32_bf16 v[72:75], v[162:165], v[194:197], v[72:75]
	v_mfma_f32_16x16x32_bf16 v[124:127], v[150:153], v[174:177], v[124:127]
	v_mfma_f32_16x16x32_bf16 v[120:123], v[166:169], v[174:177], v[120:123]
	v_mfma_f32_16x16x32_bf16 v[108:111], v[150:153], v[182:185], v[108:111]
	v_mfma_f32_16x16x32_bf16 v[104:107], v[166:169], v[182:185], v[104:107]
	v_mfma_f32_16x16x32_bf16 v[92:95], v[150:153], v[190:193], v[92:95]
	v_mfma_f32_16x16x32_bf16 v[88:91], v[166:169], v[190:193], v[88:91]
	v_mfma_f32_16x16x32_bf16 v[76:79], v[150:153], v[198:201], v[76:79]
	v_mfma_f32_16x16x32_bf16 v[72:75], v[166:169], v[198:201], v[72:75]
	s_setprio 0
	s_barrier
	s_add_i32 s48, 0, 0x1c000
	s_add_i32 s33, s33, s57
	v_add_u32_e32 v216, s48, v155
	v_lshl_add_u64 v[220:221], v[220:221], 0, s[16:17]
	s_mov_b32 m0, s33
	ds_read_b128 v[204:207], v216
	ds_read_b128 v[208:211], v216 offset:1024
	ds_read_b128 v[212:215], v216 offset:2048
	ds_read_b128 v[216:219], v216 offset:3072
	global_load_lds_dwordx4 v[220:221], off
	v_lshl_add_u64 v[220:221], v[222:223], 0, s[16:17]
	s_add_i32 m0, s33, 0x2000
	s_nop 0
	global_load_lds_dwordx4 v[220:221], off
	s_barrier
	s_waitcnt lgkmcnt(0)
	s_setprio 1
	s_waitcnt lgkmcnt(0)
	v_mfma_f32_16x16x32_bf16 v[116:119], v[204:207], v[170:173], v[116:119]
	v_mfma_f32_16x16x32_bf16 v[112:115], v[212:215], v[170:173], v[112:115]
	v_mfma_f32_16x16x32_bf16 v[100:103], v[204:207], v[178:181], v[100:103]
	v_mfma_f32_16x16x32_bf16 v[96:99], v[212:215], v[178:181], v[96:99]
	v_mfma_f32_16x16x32_bf16 v[84:87], v[204:207], v[186:189], v[84:87]
	v_mfma_f32_16x16x32_bf16 v[80:83], v[212:215], v[186:189], v[80:83]
	v_mfma_f32_16x16x32_bf16 v[68:71], v[204:207], v[194:197], v[68:71]
	v_mfma_f32_16x16x32_bf16 v[64:67], v[212:215], v[194:197], v[64:67]
	v_mfma_f32_16x16x32_bf16 v[116:119], v[208:211], v[174:177], v[116:119]
	v_mfma_f32_16x16x32_bf16 v[112:115], v[216:219], v[174:177], v[112:115]
	v_mfma_f32_16x16x32_bf16 v[100:103], v[208:211], v[182:185], v[100:103]
	v_mfma_f32_16x16x32_bf16 v[96:99], v[216:219], v[182:185], v[96:99]
	v_mfma_f32_16x16x32_bf16 v[84:87], v[208:211], v[190:193], v[84:87]
	v_mfma_f32_16x16x32_bf16 v[80:83], v[216:219], v[190:193], v[80:83]
	v_mfma_f32_16x16x32_bf16 v[68:71], v[208:211], v[198:201], v[68:71]
	v_mfma_f32_16x16x32_bf16 v[64:67], v[216:219], v[198:201], v[64:67]
	s_setprio 0
	s_mov_b32 m0, s63
	v_lshl_add_u64 v[220:221], v[224:225], 0, s[16:17]
	s_barrier
	ds_read_b128 v[170:173], v159 offset:49152
	ds_read_b128 v[174:177], v159 offset:50176
	ds_read_b128 v[178:181], v159 offset:51200
	ds_read_b128 v[182:185], v159 offset:52224
	ds_read_b128 v[186:189], v159 offset:53248
	ds_read_b128 v[190:193], v159 offset:54272
	ds_read_b128 v[194:197], v159 offset:55296
	ds_read_b128 v[198:201], v159 offset:56320
	global_load_lds_dwordx4 v[220:221], off
	v_lshl_add_u64 v[220:221], v[226:227], 0, s[16:17]
	s_mov_b32 m0, s64
	s_nop 0
	global_load_lds_dwordx4 v[220:221], off
	s_barrier
; #define PG8_WAIT_V(n) asm volatile("s_waitcnt vmcnt(" #n ")" ::: "memory")
; #define PG8_WAIT_L(n) asm volatile("s_waitcnt lgkmcnt(" #n ")" ::: "memory")
;     __device__ __forceinline__ void operator()(const f32x4 (&acc)[2][2][4][2], const Unit& u, int wr, int wc, int fr, int fq) const {
;         const int row0 = u.pm * BM + wr * 64 + fr; const int col0 = u.pn * BM + wc * 64 + 16 * fq;
; #pragma unroll
;         for (int ai = 0; ai < 2; ++ai)
; #pragma unroll
;             for (int m = 0; m < 4; ++m) { const int row = row0 + ai * HALF + m * 16;
;                 const float rs = ssin ? __builtin_amdgcn_rsqf(ssin[row] * (1.f / D) + EPS) : 1.0f; float sq = 0.f; u32x4 w[2];
; #pragma unroll
;                 for (int bj = 0; bj < 2; ++bj) { f32x4 v0 = acc[ai][bj][m][0] * rs, v1 = acc[ai][bj][m][1] * rs;
;                     if (ACT == 1) {
; #pragma unroll
;                         for (int j = 0; j < 4; ++j) { const float a = fmaxf(v0[j], 0.f), b = fmaxf(v1[j], 0.f); v0[j] = a * a; v1[j] = b * b; } }
;                     sq += (v0[0] * v0[0] + v0[1] * v0[1]) + (v0[2] * v0[2] + v0[3] * v0[3]) + (v1[0] * v1[0] + v1[1] * v1[1]) + (v1[2] * v1[2] + v1[3] * v1[3]);
;                     w[bj].x = cvt_pk_bf16(v0[0], v0[1]); w[bj].y = cvt_pk_bf16(v0[2], v0[3]); w[bj].z = cvt_pk_bf16(v1[0], v1[1]); w[bj].w = cvt_pk_bf16(v1[2], v1[3]); }
;                 store_pair_lines(O, ldc, row, fr, col0, w[0], w[1]);
;                 if (ssout) { sq += __shfl_xor(sq, 16); sq += __shfl_xor(sq, 32); if (fq == 0) unsafeAtomicAdd(ssout + row, sq); } }
; template <class Epi>
; __device__ __forceinline__ void gemm_phase(LAS unsigned char* lds, const Gemm g, const StaticOrder& S, const Epi& E) {
;     ...
;             PG8_WAIT_V(6); PG8_BAR; PG8_MMA(1, 1, At, B1); PG8_BAR;
;             PG8_LDB(B0, 1, 0); PG8_SCHED; PG8_LDA(At, 1, 0); PG8_STAGE(PG8_SA(0, 1), a2 + hstep, voffA);
;             PG8_WAIT_L(8); PG8_BAR; PG8_WAIT_L(0); PG8_MMA(0, 0, At, B0); PG8_BAR; PG8_SCHED;
;             PG8_LDB(B1, 1, 1); PG8_STAGE(PG8_SB(1, 0), b3, voffB0);
;             PG8_BAR; PG8_WAIT_L(0); PG8_MMA(0, 1, At, B1); PG8_BAR;
;             PG8_LDA(At, 1, 1); PG8_STAGE(PG8_SA(1, 0), a3, voffA);
;             PG8_BAR; PG8_WAIT_L(0); PG8_MMA(1, 0, At, B0); PG8_BAR; PG8_SCHED;
;             PG8_STAGE(PG8_SB(1, 1), b3, voffB1);
;             PG8_WAIT_V(6); PG8_BAR; PG8_MMA(1, 1, At, B1); PG8_BAR;
	s_waitcnt lgkmcnt(0)
	s_setprio 1
	s_waitcnt lgkmcnt(0)
	v_mfma_f32_16x16x32_bf16 v[60:63], v[146:149], v[170:173], v[60:63]
	v_mfma_f32_16x16x32_bf16 v[56:59], v[162:165], v[170:173], v[56:59]
	v_mfma_f32_16x16x32_bf16 v[44:47], v[146:149], v[178:181], v[44:47]
	v_mfma_f32_16x16x32_bf16 v[40:43], v[162:165], v[178:181], v[40:43]
	v_mfma_f32_16x16x32_bf16 v[28:31], v[146:149], v[186:189], v[28:31]
	v_mfma_f32_16x16x32_bf16 v[24:27], v[162:165], v[186:189], v[24:27]
	v_mfma_f32_16x16x32_bf16 v[12:15], v[146:149], v[194:197], v[12:15]
	v_mfma_f32_16x16x32_bf16 v[8:11], v[162:165], v[194:197], v[8:11]
	v_mfma_f32_16x16x32_bf16 v[60:63], v[150:153], v[174:177], v[60:63]
	v_mfma_f32_16x16x32_bf16 v[56:59], v[166:169], v[174:177], v[56:59]
	v_mfma_f32_16x16x32_bf16 v[44:47], v[150:153], v[182:185], v[44:47]
	v_mfma_f32_16x16x32_bf16 v[40:43], v[166:169], v[182:185], v[40:43]
	v_mfma_f32_16x16x32_bf16 v[28:31], v[150:153], v[190:193], v[28:31]
	v_mfma_f32_16x16x32_bf16 v[24:27], v[166:169], v[190:193], v[24:27]
	v_mfma_f32_16x16x32_bf16 v[12:15], v[150:153], v[198:201], v[12:15]
	v_mfma_f32_16x16x32_bf16 v[8:11], v[166:169], v[198:201], v[8:11]
	s_setprio 0
	s_barrier
	s_add_i32 s33, s48, s57
	v_lshl_add_u64 v[146:147], v[228:229], 0, s[16:17]
	s_mov_b32 m0, s33
	s_nop 0
	global_load_lds_dwordx4 v[146:147], off
	v_lshl_add_u64 v[146:147], v[230:231], 0, s[16:17]
	s_add_i32 m0, s33, 0x2000
	s_nop 0
	global_load_lds_dwordx4 v[146:147], off
	s_waitcnt vmcnt(6)
	s_barrier
	s_setprio 1
	v_mfma_f32_16x16x32_bf16 v[52:55], v[204:207], v[170:173], v[52:55]
	v_mfma_f32_16x16x32_bf16 v[48:51], v[212:215], v[170:173], v[48:51]
	v_mfma_f32_16x16x32_bf16 v[36:39], v[204:207], v[178:181], v[36:39]
	v_mfma_f32_16x16x32_bf16 v[32:35], v[212:215], v[178:181], v[32:35]
	v_mfma_f32_16x16x32_bf16 v[20:23], v[204:207], v[186:189], v[20:23]
	v_mfma_f32_16x16x32_bf16 v[16:19], v[212:215], v[186:189], v[16:19]
	v_mfma_f32_16x16x32_bf16 v[4:7], v[204:207], v[194:197], v[4:7]
	v_mfma_f32_16x16x32_bf16 v[0:3], v[212:215], v[194:197], v[0:3]
	v_mfma_f32_16x16x32_bf16 v[52:55], v[208:211], v[174:177], v[52:55]
	v_mfma_f32_16x16x32_bf16 v[48:51], v[216:219], v[174:177], v[48:51]
	v_mfma_f32_16x16x32_bf16 v[36:39], v[208:211], v[182:185], v[36:39]
	v_mfma_f32_16x16x32_bf16 v[32:35], v[216:219], v[182:185], v[32:35]
	v_mfma_f32_16x16x32_bf16 v[20:23], v[208:211], v[190:193], v[20:23]
	v_mfma_f32_16x16x32_bf16 v[16:19], v[216:219], v[190:193], v[16:19]
	v_mfma_f32_16x16x32_bf16 v[4:7], v[208:211], v[198:201], v[4:7]
	v_mfma_f32_16x16x32_bf16 v[0:3], v[216:219], v[198:201], v[0:3]
	s_setprio 0
	s_add_i32 s77, s77, 2
	s_add_u32 s46, s46, 0x100
	s_addc_u32 s47, s47, 0
	s_add_u32 s74, s74, 0x100
	s_addc_u32 s75, s75, 0
	s_cmp_gt_u32 s77, 29
	s_barrier
	s_cbranch_scc0 .LBB0_962
	s_lshl_b32 s19, s44, 8
	s_add_i32 s19, s19, s65
	v_or_b32_e32 v152, s19, v154
	v_ashrrev_i32_e32 v153, 31, v152
	v_lshl_add_u64 v[150:151], v[152:153], 2, s[10:11]
	global_load_dword v153, v[150:151], off
	v_or_b32_e32 v180, 16, v152
	v_ashrrev_i32_e32 v181, 31, v180
	v_lshl_add_u64 v[182:183], v[180:181], 2, s[10:11]
	global_load_dword v179, v[182:183], off
	v_or_b32_e32 v180, 32, v152
	v_ashrrev_i32_e32 v181, 31, v180
	v_lshl_add_u64 v[182:183], v[180:181], 2, s[10:11]
	global_load_dword v184, v[182:183], off
	v_or_b32_e32 v180, 48, v152
	v_ashrrev_i32_e32 v181, 31, v180
	v_lshl_add_u64 v[182:183], v[180:181], 2, s[10:11]
	global_load_dword v185, v[182:183], off
	global_load_dword v186, v[150:151], off offset:512
	global_load_dword v187, v[150:151], off offset:576
	global_load_dword v188, v[150:151], off offset:640
	global_load_dword v189, v[150:151], off offset:704
	v_lshl_or_b32 v148, s71, 8, v157
	v_mov_b32_e32 v169, 0
	v_mov_b32_e32 v175, 0
	v_mov_b32_e32 v176, 0
	v_mov_b32_e32 v177, 0
	v_mov_b32_e32 v178, 0
	v_mov_b64_e32 v[146:147], s[8:9]
	v_ashrrev_i32_e32 v149, 31, v148
	v_or_b32_e32 v164, s19, v156
	v_mov_b32_e32 v172, 0
	v_mov_b32_e32 v173, 0
	v_mov_b32_e32 v174, 0
	v_lshlrev_b64 v[148:149], 1, v[148:149]
	v_mad_i64_i32 v[162:163], s[46:47], v164, s70, v[146:147]
	v_or_b32_e32 v165, 8, v164
	v_or_b32_e32 v164, 16, v152
	v_lshl_add_u64 v[162:163], v[162:163], 0, v[148:149]
	v_mad_i64_i32 v[166:167], s[46:47], v165, s70, v[146:147]
	v_ashrrev_i32_e32 v165, 31, v164
	v_lshl_add_u64 v[166:167], v[166:167], 0, v[148:149]
	v_lshl_add_u64 v[170:171], v[164:165], 2, s[10:11]
	s_and_b64 vcc, exec, s[40:41]
	s_mov_b32 s71, s18
	s_mov_b32 s44, s36
	s_mov_b64 s[48:49], s[42:43]
	s_waitcnt vmcnt(7)
	v_fmamk_f32 v153, v153, 0x3a000000, v161
	v_rsq_f32_e32 v168, v153
	v_mov_b32_e32 v153, 0
	v_pk_mul_f32 v[124:125], v[124:125], v[168:169] op_sel_hi:[1,0]
	v_pk_mul_f32 v[120:121], v[120:121], v[168:169] op_sel_hi:[1,0]
	v_pk_mul_f32 v[118:119], v[118:119], v[168:169] op_sel_hi:[1,0]
	v_pk_mul_f32 v[116:117], v[116:117], v[168:169] op_sel_hi:[1,0]
	v_pk_mul_f32 v[126:127], v[126:127], v[168:169] op_sel_hi:[1,0]
	v_pk_mul_f32 v[122:123], v[122:123], v[168:169] op_sel_hi:[1,0]
	v_pk_mul_f32 v[114:115], v[114:115], v[168:169] op_sel_hi:[1,0]
	v_pk_mul_f32 v[112:113], v[112:113], v[168:169] op_sel_hi:[1,0]
	v_cvt_pk_bf16_f32 v124, v124, v125
	v_cvt_pk_bf16_f32 v125, v126, v127
	v_cvt_pk_bf16_f32 v120, v120, v121
	v_cvt_pk_bf16_f32 v121, v122, v123
	v_cvt_pk_bf16_f32 v116, v116, v117
	v_cvt_pk_bf16_f32 v117, v118, v119
	s_nop 0
	v_cvt_pk_bf16_f32 v118, v112, v113
	v_cvt_pk_bf16_f32 v119, v114, v115
	s_nop 0
	v_mov_b32_dpp v169, v124 row_ror:8 row_mask:0xf bank_mask:0xf
	v_mov_b32_dpp v172, v125 row_ror:8 row_mask:0xf bank_mask:0xf
	v_mov_b32_dpp v175, v116 row_ror:8 row_mask:0xf bank_mask:0xf
	v_mov_b32_dpp v176, v117 row_ror:8 row_mask:0xf bank_mask:0xf
	v_mov_b32_dpp v177, v118 row_ror:8 row_mask:0xf bank_mask:0xf
	v_mov_b32_dpp v178, v119 row_ror:8 row_mask:0xf bank_mask:0xf
	v_mov_b32_dpp v173, v120 row_ror:8 row_mask:0xf bank_mask:0xf
	v_mov_b32_dpp v174, v121 row_ror:8 row_mask:0xf bank_mask:0xf
	v_cndmask_b32_e64 v112, v175, v124, s[6:7]
	v_cndmask_b32_e64 v113, v176, v125, s[6:7]
	v_cndmask_b32_e64 v114, v177, v120, s[6:7]
	v_cndmask_b32_e64 v115, v178, v121, s[6:7]
	v_cndmask_b32_e64 v116, v116, v169, s[6:7]
	v_cndmask_b32_e64 v117, v117, v172, s[6:7]
	v_cndmask_b32_e64 v118, v118, v173, s[6:7]
	v_cndmask_b32_e64 v119, v119, v174, s[6:7]
	global_store_dwordx4 v[162:163], v[112:115], off
	global_store_dwordx4 v[166:167], v[116:119], off
	s_waitcnt vmcnt(8)
; __device__ __forceinline__ unsigned cvt_pk_bf16(float lo, float hi) { unsigned r; asm volatile("v_cvt_pk_bf16_f32 %0, %1, %2" : "=v"(r) : "v"(lo), "v"(hi)); return r; }
; __device__ __forceinline__ unsigned dpp_ror8(unsigned x) { return (unsigned)__builtin_amdgcn_update_dpp(0, (int)x, 0x128, 0xf, 0xf, false); }
; __device__ __forceinline__ void store_pair_lines(bf16_t* O, int ldc, int row, int fr, int col0, u32x4 wA, u32x4 wB) {
;     const u32x4 sA = {dpp_ror8(wA.x), dpp_ror8(wA.y), dpp_ror8(wA.z), dpp_ror8(wA.w)}, sB = {dpp_ror8(wB.x), dpp_ror8(wB.y), dpp_ror8(wB.z), dpp_ror8(wB.w)};
;     const bool lo = fr < 8;
;     const u32x4 o1 = lo ? wA : sB, o2 = lo ? sA : wB;
;     const int r1 = row - fr + (fr & 7), cb = col0 + (lo ? 0 : 8);
;     *(u32x4*)(O + (size_t)r1 * ldc + cb) = o1;
;     *(u32x4*)(O + (size_t)(r1 + 8) * ldc + cb) = o2;
; }
;     __device__ __forceinline__ void operator()(const f32x4 (&acc)[2][2][4][2], const Unit& u, int wr, int wc, int fr, int fq) const {
;         const int row0 = u.pm * BM + wr * 64 + fr; const int col0 = u.pn * BM + wc * 64 + 16 * fq;
; #pragma unroll
;         for (int ai = 0; ai < 2; ++ai)
; #pragma unroll
;             for (int m = 0; m < 4; ++m) { const int row = row0 + ai * HALF + m * 16;
;                 const float rs = ssin ? __builtin_amdgcn_rsqf(ssin[row] * (1.f / D) + EPS) : 1.0f; float sq = 0.f; u32x4 w[2];
; #pragma unroll
;                 for (int bj = 0; bj < 2; ++bj) { f32x4 v0 = acc[ai][bj][m][0] * rs, v1 = acc[ai][bj][m][1] * rs;
;                     if (ACT == 1) {
; #pragma unroll
;                         for (int j = 0; j < 4; ++j) { const float a = fmaxf(v0[j], 0.f), b = fmaxf(v1[j], 0.f); v0[j] = a * a; v1[j] = b * b; } }
;                     sq += (v0[0] * v0[0] + v0[1] * v0[1]) + (v0[2] * v0[2] + v0[3] * v0[3]) + (v1[0] * v1[0] + v1[1] * v1[1]) + (v1[2] * v1[2] + v1[3] * v1[3]);
;                     w[bj].x = cvt_pk_bf16(v0[0], v0[1]); w[bj].y = cvt_pk_bf16(v0[2], v0[3]); w[bj].z = cvt_pk_bf16(v1[0], v1[1]); w[bj].w = cvt_pk_bf16(v1[2], v1[3]); }
;                 store_pair_lines(O, ldc, row, fr, col0, w[0], w[1]);
;                 if (ssout) { sq += __shfl_xor(sq, 16); sq += __shfl_xor(sq, 32); if (fq == 0) unsafeAtomicAdd(ssout + row, sq); } }
	s_nop 0
	v_mov_b32_e32 v118, v179
	s_nop 1
	v_or_b32_e32 v112, 32, v152
	v_mov_b32_e32 v119, 0
	v_sub_u32_e32 v114, v164, v154
	v_mov_b32_e32 v125, 0
	v_mov_b32_e32 v126, 0
	v_mov_b32_e32 v127, 0
	v_ashrrev_i32_e32 v113, 31, v112
	v_add_u32_e32 v120, v114, v156
	v_mov_b32_e32 v122, 0
	v_mov_b32_e32 v123, 0
	v_mov_b32_e32 v124, 0
	v_lshl_add_u64 v[114:115], v[112:113], 2, s[10:11]
	v_mad_i64_i32 v[116:117], s[46:47], v120, s70, v[146:147]
	v_add_u32_e32 v113, 8, v120
	v_lshl_add_u64 v[116:117], v[116:117], 0, v[148:149]
	v_mad_i64_i32 v[120:121], s[46:47], v113, s70, v[146:147]
	v_lshl_add_u64 v[120:121], v[120:121], 0, v[148:149]
	v_mov_b32_e32 v113, 0
	v_fmamk_f32 v118, v118, 0x3a000000, v161
	v_rsq_f32_e32 v118, v118
	s_nop 0
	v_pk_mul_f32 v[108:109], v[108:109], v[118:119] op_sel_hi:[1,0]
	v_pk_mul_f32 v[104:105], v[104:105], v[118:119] op_sel_hi:[1,0]
	v_pk_mul_f32 v[102:103], v[102:103], v[118:119] op_sel_hi:[1,0]
	v_pk_mul_f32 v[100:101], v[100:101], v[118:119] op_sel_hi:[1,0]
	v_pk_mul_f32 v[110:111], v[110:111], v[118:119] op_sel_hi:[1,0]
	v_pk_mul_f32 v[106:107], v[106:107], v[118:119] op_sel_hi:[1,0]
	v_pk_mul_f32 v[98:99], v[98:99], v[118:119] op_sel_hi:[1,0]
	v_pk_mul_f32 v[96:97], v[96:97], v[118:119] op_sel_hi:[1,0]
	v_cvt_pk_bf16_f32 v108, v108, v109
	v_cvt_pk_bf16_f32 v109, v110, v111
	v_cvt_pk_bf16_f32 v104, v104, v105
	v_cvt_pk_bf16_f32 v105, v106, v107
	v_cvt_pk_bf16_f32 v100, v100, v101
	v_cvt_pk_bf16_f32 v101, v102, v103
	s_nop 0
	v_cvt_pk_bf16_f32 v102, v96, v97
	v_cvt_pk_bf16_f32 v103, v98, v99
	s_nop 0
	v_mov_b32_dpp v119, v108 row_ror:8 row_mask:0xf bank_mask:0xf
	v_mov_b32_dpp v122, v109 row_ror:8 row_mask:0xf bank_mask:0xf
	v_mov_b32_dpp v125, v100 row_ror:8 row_mask:0xf bank_mask:0xf
	v_mov_b32_dpp v126, v101 row_ror:8 row_mask:0xf bank_mask:0xf
	v_mov_b32_dpp v127, v102 row_ror:8 row_mask:0xf bank_mask:0xf
	v_mov_b32_dpp v153, v103 row_ror:8 row_mask:0xf bank_mask:0xf
	v_mov_b32_dpp v123, v104 row_ror:8 row_mask:0xf bank_mask:0xf
	v_mov_b32_dpp v124, v105 row_ror:8 row_mask:0xf bank_mask:0xf
	v_cndmask_b32_e64 v96, v125, v108, s[6:7]
	v_cndmask_b32_e64 v97, v126, v109, s[6:7]
	v_cndmask_b32_e64 v98, v127, v104, s[6:7]
	v_cndmask_b32_e64 v99, v153, v105, s[6:7]
	v_cndmask_b32_e64 v100, v100, v119, s[6:7]
	v_cndmask_b32_e64 v101, v101, v122, s[6:7]
	v_cndmask_b32_e64 v102, v102, v123, s[6:7]
	v_cndmask_b32_e64 v103, v103, v124, s[6:7]
	global_store_dwordx4 v[116:117], v[96:99], off
	global_store_dwordx4 v[120:121], v[100:103], off
	s_waitcnt vmcnt(9)
	s_nop 0
	v_mov_b32_e32 v102, v184
	s_nop 1
	v_or_b32_e32 v96, 48, v152
	v_mov_b32_e32 v103, 0
	v_sub_u32_e32 v98, v112, v154
	v_mov_b32_e32 v109, 0
	v_mov_b32_e32 v110, 0
	v_mov_b32_e32 v111, 0
	v_ashrrev_i32_e32 v97, 31, v96
	v_add_u32_e32 v104, v98, v156
	v_mov_b32_e32 v106, 0
	v_mov_b32_e32 v107, 0
	v_mov_b32_e32 v108, 0
	v_lshl_add_u64 v[98:99], v[96:97], 2, s[10:11]
	v_mad_i64_i32 v[100:101], s[46:47], v104, s70, v[146:147]
	v_add_u32_e32 v97, 8, v104
	v_lshl_add_u64 v[100:101], v[100:101], 0, v[148:149]
	v_mad_i64_i32 v[104:105], s[46:47], v97, s70, v[146:147]
	v_lshl_add_u64 v[104:105], v[104:105], 0, v[148:149]
	v_fmamk_f32 v102, v102, 0x3a000000, v161
	v_rsq_f32_e32 v102, v102
	s_nop 0
	v_pk_mul_f32 v[92:93], v[92:93], v[102:103] op_sel_hi:[1,0]
	v_pk_mul_f32 v[88:89], v[88:89], v[102:103] op_sel_hi:[1,0]
	v_pk_mul_f32 v[86:87], v[86:87], v[102:103] op_sel_hi:[1,0]
	v_pk_mul_f32 v[84:85], v[84:85], v[102:103] op_sel_hi:[1,0]
	v_pk_mul_f32 v[94:95], v[94:95], v[102:103] op_sel_hi:[1,0]
	v_pk_mul_f32 v[90:91], v[90:91], v[102:103] op_sel_hi:[1,0]
	v_pk_mul_f32 v[82:83], v[82:83], v[102:103] op_sel_hi:[1,0]
	v_pk_mul_f32 v[80:81], v[80:81], v[102:103] op_sel_hi:[1,0]
	v_cvt_pk_bf16_f32 v92, v92, v93
	v_cvt_pk_bf16_f32 v93, v94, v95
	v_cvt_pk_bf16_f32 v88, v88, v89
	v_cvt_pk_bf16_f32 v89, v90, v91
	v_cvt_pk_bf16_f32 v84, v84, v85
	v_cvt_pk_bf16_f32 v85, v86, v87
	s_nop 0
	v_cvt_pk_bf16_f32 v86, v80, v81
	v_cvt_pk_bf16_f32 v87, v82, v83
	s_nop 0
	v_mov_b32_dpp v103, v92 row_ror:8 row_mask:0xf bank_mask:0xf
	v_mov_b32_dpp v106, v93 row_ror:8 row_mask:0xf bank_mask:0xf
	v_mov_b32_dpp v109, v84 row_ror:8 row_mask:0xf bank_mask:0xf
	v_mov_b32_dpp v110, v85 row_ror:8 row_mask:0xf bank_mask:0xf
	v_mov_b32_dpp v111, v86 row_ror:8 row_mask:0xf bank_mask:0xf
	v_mov_b32_dpp v113, v87 row_ror:8 row_mask:0xf bank_mask:0xf
	v_mov_b32_dpp v107, v88 row_ror:8 row_mask:0xf bank_mask:0xf
	v_mov_b32_dpp v108, v89 row_ror:8 row_mask:0xf bank_mask:0xf
	v_cndmask_b32_e64 v80, v109, v92, s[6:7]
	v_cndmask_b32_e64 v81, v110, v93, s[6:7]
	v_cndmask_b32_e64 v82, v111, v88, s[6:7]
	v_cndmask_b32_e64 v83, v113, v89, s[6:7]
	v_cndmask_b32_e64 v84, v84, v103, s[6:7]
	v_cndmask_b32_e64 v85, v85, v106, s[6:7]
	v_cndmask_b32_e64 v86, v86, v107, s[6:7]
	v_cndmask_b32_e64 v87, v87, v108, s[6:7]
	global_store_dwordx4 v[100:101], v[80:83], off
	global_store_dwordx4 v[104:105], v[84:87], off
	s_waitcnt vmcnt(10)
; __device__ __forceinline__ unsigned cvt_pk_bf16(float lo, float hi) { unsigned r; asm volatile("v_cvt_pk_bf16_f32 %0, %1, %2" : "=v"(r) : "v"(lo), "v"(hi)); return r; }
; __device__ __forceinline__ unsigned dpp_ror8(unsigned x) { return (unsigned)__builtin_amdgcn_update_dpp(0, (int)x, 0x128, 0xf, 0xf, false); }
; __device__ __forceinline__ void store_pair_lines(bf16_t* O, int ldc, int row, int fr, int col0, u32x4 wA, u32x4 wB) {
;     const u32x4 sA = {dpp_ror8(wA.x), dpp_ror8(wA.y), dpp_ror8(wA.z), dpp_ror8(wA.w)}, sB = {dpp_ror8(wB.x), dpp_ror8(wB.y), dpp_ror8(wB.z), dpp_ror8(wB.w)};
;     const bool lo = fr < 8;
;     const u32x4 o1 = lo ? wA : sB, o2 = lo ? sA : wB;
;     const int r1 = row - fr + (fr & 7), cb = col0 + (lo ? 0 : 8);
;     *(u32x4*)(O + (size_t)r1 * ldc + cb) = o1;
;     *(u32x4*)(O + (size_t)(r1 + 8) * ldc + cb) = o2;
; }
;     __device__ __forceinline__ void operator()(const f32x4 (&acc)[2][2][4][2], const Unit& u, int wr, int wc, int fr, int fq) const {
;         const int row0 = u.pm * BM + wr * 64 + fr; const int col0 = u.pn * BM + wc * 64 + 16 * fq;
; #pragma unroll
;         for (int ai = 0; ai < 2; ++ai)
; #pragma unroll
;             for (int m = 0; m < 4; ++m) { const int row = row0 + ai * HALF + m * 16;
;                 const float rs = ssin ? __builtin_amdgcn_rsqf(ssin[row] * (1.f / D) + EPS) : 1.0f; float sq = 0.f; u32x4 w[2];
; #pragma unroll
;                 for (int bj = 0; bj < 2; ++bj) { f32x4 v0 = acc[ai][bj][m][0] * rs, v1 = acc[ai][bj][m][1] * rs;
;                     if (ACT == 1) {
; #pragma unroll
;                         for (int j = 0; j < 4; ++j) { const float a = fmaxf(v0[j], 0.f), b = fmaxf(v1[j], 0.f); v0[j] = a * a; v1[j] = b * b; } }
;                     sq += (v0[0] * v0[0] + v0[1] * v0[1]) + (v0[2] * v0[2] + v0[3] * v0[3]) + (v1[0] * v1[0] + v1[1] * v1[1]) + (v1[2] * v1[2] + v1[3] * v1[3]);
;                     w[bj].x = cvt_pk_bf16(v0[0], v0[1]); w[bj].y = cvt_pk_bf16(v0[2], v0[3]); w[bj].z = cvt_pk_bf16(v1[0], v1[1]); w[bj].w = cvt_pk_bf16(v1[2], v1[3]); }
;                 store_pair_lines(O, ldc, row, fr, col0, w[0], w[1]);
;                 if (ssout) { sq += __shfl_xor(sq, 16); sq += __shfl_xor(sq, 32); if (fq == 0) unsafeAtomicAdd(ssout + row, sq); } }
	s_nop 0
	v_mov_b32_e32 v82, v185
	s_nop 1
	v_mov_b32_e32 v83, 0
	v_sub_u32_e32 v80, v96, v154
	v_mov_b32_e32 v89, 0
	v_mov_b32_e32 v90, 0
	v_mov_b32_e32 v91, 0
	v_mov_b32_e32 v92, 0
	v_add_u32_e32 v84, v80, v156
	v_mov_b32_e32 v86, 0
	v_mov_b32_e32 v87, 0
	v_mov_b32_e32 v88, 0
	v_mad_i64_i32 v[80:81], s[46:47], v84, s70, v[146:147]
	v_add_u32_e32 v84, 8, v84
	v_lshl_add_u64 v[80:81], v[80:81], 0, v[148:149]
	v_mad_i64_i32 v[84:85], s[46:47], v84, s70, v[146:147]
	v_lshl_add_u64 v[84:85], v[84:85], 0, v[148:149]
	v_fmamk_f32 v82, v82, 0x3a000000, v161
	v_rsq_f32_e32 v82, v82
	s_nop 0
	v_pk_mul_f32 v[76:77], v[76:77], v[82:83] op_sel_hi:[1,0]
	v_pk_mul_f32 v[72:73], v[72:73], v[82:83] op_sel_hi:[1,0]
	v_pk_mul_f32 v[70:71], v[70:71], v[82:83] op_sel_hi:[1,0]
	v_pk_mul_f32 v[68:69], v[68:69], v[82:83] op_sel_hi:[1,0]
	v_pk_mul_f32 v[78:79], v[78:79], v[82:83] op_sel_hi:[1,0]
	v_pk_mul_f32 v[74:75], v[74:75], v[82:83] op_sel_hi:[1,0]
	v_pk_mul_f32 v[66:67], v[66:67], v[82:83] op_sel_hi:[1,0]
	v_pk_mul_f32 v[64:65], v[64:65], v[82:83] op_sel_hi:[1,0]
	v_cvt_pk_bf16_f32 v76, v76, v77
	v_cvt_pk_bf16_f32 v77, v78, v79
	v_cvt_pk_bf16_f32 v72, v72, v73
	v_cvt_pk_bf16_f32 v73, v74, v75
	v_cvt_pk_bf16_f32 v68, v68, v69
	v_cvt_pk_bf16_f32 v69, v70, v71
	s_nop 0
	v_cvt_pk_bf16_f32 v70, v64, v65
	v_cvt_pk_bf16_f32 v71, v66, v67
	s_nop 0
	v_mov_b32_dpp v83, v76 row_ror:8 row_mask:0xf bank_mask:0xf
	v_mov_b32_dpp v86, v77 row_ror:8 row_mask:0xf bank_mask:0xf
	v_mov_b32_dpp v89, v68 row_ror:8 row_mask:0xf bank_mask:0xf
	v_mov_b32_dpp v90, v69 row_ror:8 row_mask:0xf bank_mask:0xf
	v_mov_b32_dpp v91, v70 row_ror:8 row_mask:0xf bank_mask:0xf
	v_mov_b32_dpp v92, v71 row_ror:8 row_mask:0xf bank_mask:0xf
	v_mov_b32_dpp v87, v72 row_ror:8 row_mask:0xf bank_mask:0xf
	v_mov_b32_dpp v88, v73 row_ror:8 row_mask:0xf bank_mask:0xf
	v_cndmask_b32_e64 v64, v89, v76, s[6:7]
	v_cndmask_b32_e64 v65, v90, v77, s[6:7]
	v_cndmask_b32_e64 v66, v91, v72, s[6:7]
	v_cndmask_b32_e64 v67, v92, v73, s[6:7]
	v_cndmask_b32_e64 v68, v68, v83, s[6:7]
	v_cndmask_b32_e64 v69, v69, v86, s[6:7]
	v_cndmask_b32_e64 v70, v70, v87, s[6:7]
	v_cndmask_b32_e64 v71, v71, v88, s[6:7]
	global_store_dwordx4 v[80:81], v[64:67], off
	global_store_dwordx4 v[84:85], v[68:71], off
	s_waitcnt vmcnt(11)
	s_nop 0
	v_mov_b32_e32 v66, v186
	s_nop 1
	v_sub_u32_e32 v64, v152, v154
	v_mov_b32_e32 v67, 0
	v_add_u32_e32 v77, v64, v156
	v_mov_b32_e32 v73, 0
	v_mov_b32_e32 v74, 0
	v_mov_b32_e32 v75, 0
	v_mov_b32_e32 v76, 0
	v_add_u32_e32 v64, 0x80, v77
	v_mov_b32_e32 v70, 0
	v_mov_b32_e32 v71, 0
	v_mov_b32_e32 v72, 0
	v_add_u32_e32 v68, 0x88, v77
	v_mad_i64_i32 v[64:65], s[46:47], v64, s70, v[146:147]
	v_mad_i64_i32 v[68:69], s[46:47], v68, s70, v[146:147]
	v_lshl_add_u64 v[64:65], v[64:65], 0, v[148:149]
	v_lshl_add_u64 v[68:69], v[68:69], 0, v[148:149]
	v_fmamk_f32 v66, v66, 0x3a000000, v161
	v_rsq_f32_e32 v66, v66
	s_nop 0
	v_pk_mul_f32 v[60:61], v[60:61], v[66:67] op_sel_hi:[1,0]
	v_pk_mul_f32 v[56:57], v[56:57], v[66:67] op_sel_hi:[1,0]
	v_pk_mul_f32 v[54:55], v[54:55], v[66:67] op_sel_hi:[1,0]
	v_pk_mul_f32 v[52:53], v[52:53], v[66:67] op_sel_hi:[1,0]
	v_pk_mul_f32 v[62:63], v[62:63], v[66:67] op_sel_hi:[1,0]
	v_pk_mul_f32 v[58:59], v[58:59], v[66:67] op_sel_hi:[1,0]
	v_pk_mul_f32 v[50:51], v[50:51], v[66:67] op_sel_hi:[1,0]
	v_pk_mul_f32 v[48:49], v[48:49], v[66:67] op_sel_hi:[1,0]
	v_cvt_pk_bf16_f32 v60, v60, v61
	v_cvt_pk_bf16_f32 v61, v62, v63
	v_cvt_pk_bf16_f32 v56, v56, v57
	v_cvt_pk_bf16_f32 v57, v58, v59
	v_cvt_pk_bf16_f32 v52, v52, v53
	v_cvt_pk_bf16_f32 v53, v54, v55
	s_nop 0
	v_cvt_pk_bf16_f32 v54, v48, v49
	v_cvt_pk_bf16_f32 v55, v50, v51
	s_nop 0
	v_mov_b32_dpp v67, v60 row_ror:8 row_mask:0xf bank_mask:0xf
	v_mov_b32_dpp v70, v61 row_ror:8 row_mask:0xf bank_mask:0xf
	v_mov_b32_dpp v73, v52 row_ror:8 row_mask:0xf bank_mask:0xf
	v_mov_b32_dpp v74, v53 row_ror:8 row_mask:0xf bank_mask:0xf
	v_mov_b32_dpp v75, v54 row_ror:8 row_mask:0xf bank_mask:0xf
	v_mov_b32_dpp v76, v55 row_ror:8 row_mask:0xf bank_mask:0xf
	v_mov_b32_dpp v71, v56 row_ror:8 row_mask:0xf bank_mask:0xf
	v_mov_b32_dpp v72, v57 row_ror:8 row_mask:0xf bank_mask:0xf
	v_cndmask_b32_e64 v48, v73, v60, s[6:7]
	v_cndmask_b32_e64 v49, v74, v61, s[6:7]
	v_cndmask_b32_e64 v50, v75, v56, s[6:7]
	v_cndmask_b32_e64 v51, v76, v57, s[6:7]
	v_cndmask_b32_e64 v52, v52, v67, s[6:7]
	v_cndmask_b32_e64 v53, v53, v70, s[6:7]
	v_cndmask_b32_e64 v54, v54, v71, s[6:7]
	v_cndmask_b32_e64 v55, v55, v72, s[6:7]
	global_store_dwordx4 v[64:65], v[48:51], off
	global_store_dwordx4 v[68:69], v[52:55], off
	s_waitcnt vmcnt(12)
; __device__ __forceinline__ unsigned cvt_pk_bf16(float lo, float hi) { unsigned r; asm volatile("v_cvt_pk_bf16_f32 %0, %1, %2" : "=v"(r) : "v"(lo), "v"(hi)); return r; }
; #define PG8_WAIT_V(n) asm volatile("s_waitcnt vmcnt(" #n ")" ::: "memory")
; #define PG8_BAR __builtin_amdgcn_s_barrier()
;     __device__ __forceinline__ void operator()(const f32x4 (&acc)[2][2][4][2], const Unit& u, int wr, int wc, int fr, int fq) const {
;     ...
;             for (int m = 0; m < 4; ++m) { const int row = row0 + ai * HALF + m * 16;
;                 const float rs = ssin ? __builtin_amdgcn_rsqf(ssin[row] * (1.f / D) + EPS) : 1.0f; float sq = 0.f; u32x4 w[2];
; #pragma unroll
;                 for (int bj = 0; bj < 2; ++bj) { f32x4 v0 = acc[ai][bj][m][0] * rs, v1 = acc[ai][bj][m][1] * rs;
;                     if (ACT == 1) {
; #pragma unroll
;                         for (int j = 0; j < 4; ++j) { const float a = fmaxf(v0[j], 0.f), b = fmaxf(v1[j], 0.f); v0[j] = a * a; v1[j] = b * b; } }
;                     sq += (v0[0] * v0[0] + v0[1] * v0[1]) + (v0[2] * v0[2] + v0[3] * v0[3]) + (v1[0] * v1[0] + v1[1] * v1[1]) + (v1[2] * v1[2] + v1[3] * v1[3]);
;                     w[bj].x = cvt_pk_bf16(v0[0], v0[1]); w[bj].y = cvt_pk_bf16(v0[2], v0[3]); w[bj].z = cvt_pk_bf16(v1[0], v1[1]); w[bj].w = cvt_pk_bf16(v1[2], v1[3]); }
;                 store_pair_lines(O, ldc, row, fr, col0, w[0], w[1]);
;                 if (ssout) { sq += __shfl_xor(sq, 16); sq += __shfl_xor(sq, 32); if (fq == 0) unsafeAtomicAdd(ssout + row, sq); } }
; template <class Epi>
; __device__ __forceinline__ void gemm_phase(LAS unsigned char* lds, const Gemm g, const StaticOrder& S, const Epi& E) {
;     ...
;         E(acc, cur, wr, wc, fr, fq);
;         if (!has_next) break;
; #pragma unroll
;         for (int a = 0; a < 2; ++a)
; #pragma unroll
;             for (int b = 0; b < 2; ++b)
; #pragma unroll
;                 for (int m = 0; m < 4; ++m)
; #pragma unroll
;                     for (int n = 0; n < 2; ++n) acc[a][b][m][n] = (f32x4){0.f, 0.f, 0.f, 0.f};
;         cur = nxt; cA = nA; cB = nB; ++ui;
;     }
;     PG8_WAIT_V(0);
;     if (wr == 0) PG8_BAR;
;     PG8_BAR;
	s_nop 0
	v_mov_b32_e32 v50, v187
	s_nop 1
	v_mov_b32_e32 v51, 0
	v_mov_b32_e32 v57, 0
	v_mov_b32_e32 v58, 0
	v_mov_b32_e32 v59, 0
	v_mov_b32_e32 v60, 0
	v_add_u32_e32 v48, 0x90, v77
	v_mov_b32_e32 v54, 0
	v_mov_b32_e32 v55, 0
	v_mov_b32_e32 v56, 0
	v_add_u32_e32 v52, 0x98, v77
	v_mad_i64_i32 v[48:49], s[46:47], v48, s70, v[146:147]
	v_mad_i64_i32 v[52:53], s[46:47], v52, s70, v[146:147]
	v_lshl_add_u64 v[48:49], v[48:49], 0, v[148:149]
	v_lshl_add_u64 v[52:53], v[52:53], 0, v[148:149]
	v_fmamk_f32 v50, v50, 0x3a000000, v161
	v_rsq_f32_e32 v50, v50
	s_nop 0
	v_pk_mul_f32 v[44:45], v[44:45], v[50:51] op_sel_hi:[1,0]
	v_pk_mul_f32 v[40:41], v[40:41], v[50:51] op_sel_hi:[1,0]
	v_pk_mul_f32 v[38:39], v[38:39], v[50:51] op_sel_hi:[1,0]
	v_pk_mul_f32 v[36:37], v[36:37], v[50:51] op_sel_hi:[1,0]
	v_pk_mul_f32 v[46:47], v[46:47], v[50:51] op_sel_hi:[1,0]
	v_pk_mul_f32 v[42:43], v[42:43], v[50:51] op_sel_hi:[1,0]
	v_pk_mul_f32 v[34:35], v[34:35], v[50:51] op_sel_hi:[1,0]
	v_pk_mul_f32 v[32:33], v[32:33], v[50:51] op_sel_hi:[1,0]
	v_cvt_pk_bf16_f32 v44, v44, v45
	v_cvt_pk_bf16_f32 v45, v46, v47
	v_cvt_pk_bf16_f32 v40, v40, v41
	v_cvt_pk_bf16_f32 v41, v42, v43
	v_cvt_pk_bf16_f32 v36, v36, v37
	v_cvt_pk_bf16_f32 v37, v38, v39
	s_nop 0
	v_cvt_pk_bf16_f32 v38, v32, v33
	v_cvt_pk_bf16_f32 v39, v34, v35
	s_nop 0
	v_mov_b32_dpp v51, v44 row_ror:8 row_mask:0xf bank_mask:0xf
	v_mov_b32_dpp v54, v45 row_ror:8 row_mask:0xf bank_mask:0xf
	v_mov_b32_dpp v57, v36 row_ror:8 row_mask:0xf bank_mask:0xf
	v_mov_b32_dpp v58, v37 row_ror:8 row_mask:0xf bank_mask:0xf
	v_mov_b32_dpp v59, v38 row_ror:8 row_mask:0xf bank_mask:0xf
	v_mov_b32_dpp v60, v39 row_ror:8 row_mask:0xf bank_mask:0xf
	v_mov_b32_dpp v55, v40 row_ror:8 row_mask:0xf bank_mask:0xf
	v_mov_b32_dpp v56, v41 row_ror:8 row_mask:0xf bank_mask:0xf
	v_cndmask_b32_e64 v32, v57, v44, s[6:7]
	v_cndmask_b32_e64 v33, v58, v45, s[6:7]
	v_cndmask_b32_e64 v34, v59, v40, s[6:7]
	v_cndmask_b32_e64 v35, v60, v41, s[6:7]
	v_cndmask_b32_e64 v36, v36, v51, s[6:7]
	v_cndmask_b32_e64 v37, v37, v54, s[6:7]
	v_cndmask_b32_e64 v38, v38, v55, s[6:7]
	v_cndmask_b32_e64 v39, v39, v56, s[6:7]
	global_store_dwordx4 v[48:49], v[32:35], off
	global_store_dwordx4 v[52:53], v[36:39], off
	s_waitcnt vmcnt(13)
	s_nop 0
	v_mov_b32_e32 v34, v188
	s_nop 1
	v_mov_b32_e32 v35, 0
	v_mov_b32_e32 v41, 0
	v_mov_b32_e32 v42, 0
	v_mov_b32_e32 v43, 0
	v_mov_b32_e32 v44, 0
	v_add_u32_e32 v32, 0xa0, v77
	v_mov_b32_e32 v38, 0
	v_mov_b32_e32 v39, 0
	v_mov_b32_e32 v40, 0
	v_add_u32_e32 v36, 0xa8, v77
	v_mad_i64_i32 v[32:33], s[46:47], v32, s70, v[146:147]
	v_mad_i64_i32 v[36:37], s[46:47], v36, s70, v[146:147]
	v_lshl_add_u64 v[32:33], v[32:33], 0, v[148:149]
	v_lshl_add_u64 v[36:37], v[36:37], 0, v[148:149]
	s_mov_b64 s[46:47], s[38:39]
	v_fmamk_f32 v34, v34, 0x3a000000, v161
	v_rsq_f32_e32 v34, v34
	s_nop 0
	v_pk_mul_f32 v[28:29], v[28:29], v[34:35] op_sel_hi:[1,0]
	v_pk_mul_f32 v[24:25], v[24:25], v[34:35] op_sel_hi:[1,0]
	v_pk_mul_f32 v[22:23], v[22:23], v[34:35] op_sel_hi:[1,0]
	v_pk_mul_f32 v[20:21], v[20:21], v[34:35] op_sel_hi:[1,0]
	v_pk_mul_f32 v[30:31], v[30:31], v[34:35] op_sel_hi:[1,0]
	v_pk_mul_f32 v[26:27], v[26:27], v[34:35] op_sel_hi:[1,0]
	v_pk_mul_f32 v[18:19], v[18:19], v[34:35] op_sel_hi:[1,0]
	v_pk_mul_f32 v[16:17], v[16:17], v[34:35] op_sel_hi:[1,0]
	v_cvt_pk_bf16_f32 v28, v28, v29
	v_cvt_pk_bf16_f32 v29, v30, v31
	v_cvt_pk_bf16_f32 v24, v24, v25
	v_cvt_pk_bf16_f32 v25, v26, v27
	v_cvt_pk_bf16_f32 v20, v20, v21
	v_cvt_pk_bf16_f32 v21, v22, v23
	s_nop 0
	v_cvt_pk_bf16_f32 v22, v16, v17
	v_cvt_pk_bf16_f32 v23, v18, v19
	s_nop 0
	v_mov_b32_dpp v35, v28 row_ror:8 row_mask:0xf bank_mask:0xf
	v_mov_b32_dpp v38, v29 row_ror:8 row_mask:0xf bank_mask:0xf
	v_mov_b32_dpp v41, v20 row_ror:8 row_mask:0xf bank_mask:0xf
	v_mov_b32_dpp v42, v21 row_ror:8 row_mask:0xf bank_mask:0xf
	v_mov_b32_dpp v43, v22 row_ror:8 row_mask:0xf bank_mask:0xf
	v_mov_b32_dpp v44, v23 row_ror:8 row_mask:0xf bank_mask:0xf
	v_mov_b32_dpp v39, v24 row_ror:8 row_mask:0xf bank_mask:0xf
	v_mov_b32_dpp v40, v25 row_ror:8 row_mask:0xf bank_mask:0xf
	v_cndmask_b32_e64 v16, v41, v28, s[6:7]
	v_cndmask_b32_e64 v17, v42, v29, s[6:7]
	v_cndmask_b32_e64 v18, v43, v24, s[6:7]
	v_cndmask_b32_e64 v19, v44, v25, s[6:7]
	v_cndmask_b32_e64 v20, v20, v35, s[6:7]
	v_cndmask_b32_e64 v21, v21, v38, s[6:7]
	v_cndmask_b32_e64 v22, v22, v39, s[6:7]
	v_cndmask_b32_e64 v23, v23, v40, s[6:7]
	global_store_dwordx4 v[32:33], v[16:19], off
	global_store_dwordx4 v[36:37], v[20:23], off
	s_waitcnt vmcnt(14)
	s_nop 0
	v_mov_b32_e32 v18, v189
	s_nop 1
	v_mov_b32_e32 v19, 0
	v_mov_b32_e32 v25, 0
	v_mov_b32_e32 v26, 0
	v_mov_b32_e32 v27, 0
	v_mov_b32_e32 v28, 0
	v_add_u32_e32 v16, 0xb0, v77
	v_mov_b32_e32 v22, 0
	v_mov_b32_e32 v23, 0
	v_mov_b32_e32 v24, 0
	v_add_u32_e32 v20, 0xb8, v77
	v_mad_i64_i32 v[16:17], s[38:39], v16, s70, v[146:147]
	v_mad_i64_i32 v[20:21], s[38:39], v20, s70, v[146:147]
	v_lshl_add_u64 v[16:17], v[16:17], 0, v[148:149]
	v_lshl_add_u64 v[20:21], v[20:21], 0, v[148:149]
	v_fmamk_f32 v18, v18, 0x3a000000, v161
	v_rsq_f32_e32 v18, v18
	s_nop 0
	v_pk_mul_f32 v[12:13], v[12:13], v[18:19] op_sel_hi:[1,0]
	v_pk_mul_f32 v[8:9], v[8:9], v[18:19] op_sel_hi:[1,0]
	v_pk_mul_f32 v[6:7], v[6:7], v[18:19] op_sel_hi:[1,0]
	v_pk_mul_f32 v[4:5], v[4:5], v[18:19] op_sel_hi:[1,0]
	v_pk_mul_f32 v[14:15], v[14:15], v[18:19] op_sel_hi:[1,0]
	v_pk_mul_f32 v[10:11], v[10:11], v[18:19] op_sel_hi:[1,0]
	v_pk_mul_f32 v[2:3], v[2:3], v[18:19] op_sel_hi:[1,0]
	v_pk_mul_f32 v[0:1], v[0:1], v[18:19] op_sel_hi:[1,0]
	v_cvt_pk_bf16_f32 v12, v12, v13
	v_cvt_pk_bf16_f32 v13, v14, v15
	v_cvt_pk_bf16_f32 v8, v8, v9
	v_cvt_pk_bf16_f32 v9, v10, v11
	v_cvt_pk_bf16_f32 v4, v4, v5
	v_cvt_pk_bf16_f32 v5, v6, v7
	s_nop 0
	v_cvt_pk_bf16_f32 v6, v0, v1
	v_cvt_pk_bf16_f32 v7, v2, v3
	s_nop 0
	v_mov_b32_dpp v19, v12 row_ror:8 row_mask:0xf bank_mask:0xf
	v_mov_b32_dpp v22, v13 row_ror:8 row_mask:0xf bank_mask:0xf
	v_mov_b32_dpp v25, v4 row_ror:8 row_mask:0xf bank_mask:0xf
	v_mov_b32_dpp v26, v5 row_ror:8 row_mask:0xf bank_mask:0xf
	v_mov_b32_dpp v27, v6 row_ror:8 row_mask:0xf bank_mask:0xf
	v_mov_b32_dpp v28, v7 row_ror:8 row_mask:0xf bank_mask:0xf
	v_mov_b32_dpp v23, v8 row_ror:8 row_mask:0xf bank_mask:0xf
	v_mov_b32_dpp v24, v9 row_ror:8 row_mask:0xf bank_mask:0xf
	v_cndmask_b32_e64 v0, v25, v12, s[6:7]
	v_cndmask_b32_e64 v1, v26, v13, s[6:7]
	v_cndmask_b32_e64 v2, v27, v8, s[6:7]
	v_cndmask_b32_e64 v3, v28, v9, s[6:7]
	v_cndmask_b32_e64 v4, v4, v19, s[6:7]
	v_cndmask_b32_e64 v5, v5, v22, s[6:7]
	v_cndmask_b32_e64 v6, v6, v23, s[6:7]
	v_cndmask_b32_e64 v7, v7, v24, s[6:7]
	global_store_dwordx4 v[16:17], v[0:3], off
	global_store_dwordx4 v[20:21], v[4:7], off
	s_cbranch_vccz .LBB0_958
	s_waitcnt vmcnt(0)
	s_cmpk_gt_u32 s52, 0xff
	s_cbranch_scc1 .LBB0_966
	s_barrier

; __device__ __forceinline__ float bflo(unsigned w) { return __uint_as_float(w << 16); }
; __device__ __forceinline__ float bfhi(unsigned w) { return __uint_as_float(w & 0xffff0000u); }
; __global__ void __launch_bounds__(NTHREADS, 2) fwd_megakernel(Params P) {
;     ...
;                 _Pragma("unroll 1") for (int rp_ = 0; rp_ < REP_PREP; ++rp_) for (int tok = gw; tok < M; tok += ngw) {
;                     const int pos = tok_pos(tok);
;                     const f32x4 c0 = *(const f32x4*)(ROPE128 + pos * 64 + j8), c1 = *(const f32x4*)(ROPE128 + pos * 64 + j8 + 4);
;                     const f32x4 s0 = *(const f32x4*)(ROPE128 + 4096 * 64 + pos * 64 + j8), s1 = *(const f32x4*)(ROPE128 + 4096 * 64 + pos * 64 + j8 + 4);
;                     const float cc[8] = {c0[0], c0[1], c0[2], c0[3], c1[0], c1[1], c1[2], c1[3]}, sn[8] = {s0[0], s0[1], s0[2], s0[3], s1[0], s1[1], s1[2], s1[3]};
;                     const bf16_t* z = Z3 + (size_t)tok * OD_IN;
; #pragma unroll
;                     for (int p = 0; p < 3; ++p) {
;                         const int head = 8 * p + hs; const bool act = head < 20; const int hc = act ? head : 19;
;                         const bf16_t* src = z + hc * 128;
;                         const u32x4 w1 = *(const u32x4*)(src + j8), w2 = *(const u32x4*)(src + 64 + j8);
;                         const float a[8] = {bflo(w1.x), bfhi(w1.x), bflo(w1.y), bfhi(w1.y), bflo(w1.z), bfhi(w1.z), bflo(w1.w), bfhi(w1.w)};
;                         const float b[8] = {bflo(w2.x), bfhi(w2.x), bflo(w2.y), bfhi(w2.y), bflo(w2.z), bfhi(w2.z), bflo(w2.w), bfhi(w2.w)};
;                         float ss = 0.f;
; #pragma unroll
;                         for (int j = 0; j < 8; ++j) ss += a[j] * a[j] + b[j] * b[j];
;                         const bool isq = hc < 16;
;                         const float ri = (isq ? CS : 1.0f) / sqrtf(group_sum<8>(ss) * (1.f / 128.f) + EPS);
;                         float o1[8], o2[8];
; #pragma unroll
;                         for (int j = 0; j < 8; ++j) { const float y1 = a[j] * ri * (isq ? gq[j] : gk[j]), y2 = b[j] * ri * (isq ? gq[8 + j] : gk[8 + j]); o1[j] = y1 * cc[j] - y2 * sn[j]; o2[j] = y2 * cc[j] + y1 * sn[j]; }
.LBB0_1029:
	v_lshl_add_u64 v[150:151], v[70:71], 0, v[42:43]
	global_load_dwordx4 v[152:155], v[150:151], off offset:-1920
	global_load_dwordx4 v[156:159], v[150:151], off offset:-2048
	s_cmpk_lt_i32 s59, 0x2000
	s_nop 0
	s_cselect_b32 s8, s55, 0x7ff
	s_nop 0
	s_and_b32 s8, s8, s59
	s_nop 0
	s_lshl_b32 s16, s8, 8
	s_nop 0
	v_lshl_add_u64 v[142:143], v[44:45], 0, s[16:17]
	v_lshl_add_u64 v[144:145], v[46:47], 0, s[16:17]
	global_load_dwordx4 v[160:163], v[142:143], off offset:16
	global_load_dwordx4 v[164:167], v[144:145], off offset:16
	global_load_dwordx4 v[168:171], v[142:143], off
	global_load_dwordx4 v[172:175], v[144:145], off
	global_load_dwordx4 v[176:179], v[150:151], off offset:128
	global_load_dwordx4 v[180:183], v[150:151], off
	v_lshl_add_u64 v[146:147], v[68:69], 0, v[42:43]
	v_add_co_u32_e32 v148, vcc, s58, v146
	s_nop 1
	v_addc_co_u32_e32 v149, vcc, 0, v147, vcc
	s_nop 1
	global_load_dwordx4 v[184:187], v[148:149], off
	global_load_dwordx4 v[188:191], v[148:149], off offset:128
	v_lshl_add_u64 v[80:81], v[70:71], 0, v[42:43]
	s_waitcnt vmcnt(9)
	s_nop 0
	v_mov_b64_e32 v[72:73], v[152:153]
	v_mov_b64_e32 v[74:75], v[154:155]
	s_nop 1
	s_waitcnt vmcnt(8)
	s_nop 0
	v_mov_b64_e32 v[76:77], v[156:157]
	v_mov_b64_e32 v[78:79], v[158:159]
	s_nop 1
	s_cmpk_lt_i32 s59, 0x2000
	s_cselect_b32 s8, s55, 0x7ff
	s_and_b32 s8, s8, s59
	s_lshl_b32 s16, s8, 8
	v_lshl_add_u64 v[32:33], v[44:45], 0, s[16:17]
	v_lshl_add_u64 v[36:37], v[46:47], 0, s[16:17]
	s_waitcnt vmcnt(7)
	s_nop 0
	v_mov_b64_e32 v[24:25], v[160:161]
	v_mov_b64_e32 v[26:27], v[162:163]
	s_nop 1
	s_waitcnt vmcnt(6)
	s_nop 0
	v_mov_b64_e32 v[28:29], v[164:165]
	v_mov_b64_e32 v[30:31], v[166:167]
	s_nop 1
	s_nop 0
	s_waitcnt vmcnt(5)
	s_nop 0
	v_mov_b64_e32 v[32:33], v[168:169]
	v_mov_b64_e32 v[34:35], v[170:171]
	s_nop 1
	s_nop 0
	s_waitcnt vmcnt(4)
	s_nop 0
	v_mov_b64_e32 v[36:37], v[172:173]
	v_mov_b64_e32 v[38:39], v[174:175]
	s_nop 1
	v_lshlrev_b32_e32 v103, 16, v74
	v_and_b32_e32 v105, 0xffff0000, v74
	v_and_b32_e32 v109, 0xffff0000, v73
	v_and_b32_e32 v108, 0xffff0000, v77
	v_lshlrev_b32_e32 v111, 16, v72
	v_lshlrev_b32_e32 v110, 16, v76
	v_and_b32_e32 v113, 0xffff0000, v72
	v_and_b32_e32 v112, 0xffff0000, v76
	v_lshlrev_b32_e32 v98, 16, v79
	v_and_b32_e32 v100, 0xffff0000, v79
	v_lshlrev_b32_e32 v102, 16, v78
	v_and_b32_e32 v104, 0xffff0000, v78
	v_lshlrev_b32_e32 v107, 16, v73
	v_lshlrev_b32_e32 v106, 16, v77
	v_mov_b32_e32 v78, v103
	v_mov_b32_e32 v79, v105
	v_pk_mul_f32 v[84:85], v[108:109], v[108:109]
	v_pk_mul_f32 v[86:87], v[110:111], v[110:111]
	v_pk_mul_f32 v[88:89], v[112:113], v[112:113]
	v_mov_b32_e32 v76, v102
	v_mov_b32_e32 v77, v104
	v_pk_mul_f32 v[82:83], v[106:107], v[106:107]
	v_pk_mul_f32 v[78:79], v[78:79], v[78:79]
	v_add_f32_e32 v84, v84, v85
	v_add_f32_e32 v85, v88, v89
	v_add_f32_e32 v86, v86, v87
	v_add_f32_e32 v87, v82, v83
	v_pk_fma_f32 v[76:77], v[76:77], v[76:77], v[78:79]
	v_add_f32_e32 v78, v86, v85
	v_lshlrev_b32_e32 v99, 16, v75
	v_and_b32_e32 v101, 0xffff0000, v75
	v_add_f32_e32 v78, v78, v87
	v_mov_b32_e32 v74, v99
	v_mov_b32_e32 v75, v101
	v_add_f32_e32 v78, v78, v84
	v_mov_b32_e32 v72, v98
	v_mov_b32_e32 v73, v100
	v_pk_mul_f32 v[74:75], v[74:75], v[74:75]
	v_add_f32_e32 v76, v78, v76
	v_pk_fma_f32 v[82:83], v[72:73], v[72:73], v[74:75]
	v_add_f32_e32 v76, v76, v77
	v_add_f32_e32 v76, v76, v82
	v_add_f32_e32 v82, v76, v83
	ds_bpermute_b32 v83, v40, v82
	v_mov_b32_e32 v76, v34
	v_mov_b32_e32 v77, v38
	v_mov_b32_e32 v88, v38
	v_mov_b32_e32 v89, v34
	s_waitcnt lgkmcnt(0)
	v_add_f32_e32 v86, v82, v83
	ds_bpermute_b32 v87, v96, v86
	v_mov_b32_e32 v74, v24
	v_mov_b32_e32 v75, v28
	v_mov_b32_e32 v78, v32
	v_mov_b32_e32 v79, v36
	s_waitcnt lgkmcnt(0)
	v_add_f32_e32 v90, v86, v87
	ds_bpermute_b32 v91, v97, v90
	v_mov_b32_e32 v82, v36
	v_mov_b32_e32 v83, v32
	v_mov_b32_e32 v92, v39
	v_mov_b32_e32 v84, v33
	s_waitcnt lgkmcnt(0)
	v_add_f32_e32 v90, v90, v91
	v_fmamk_f32 v90, v90, 0x3c000000, v94
	v_mul_f32_e32 v91, 0x4f800000, v90
	v_cmp_gt_f32_e32 vcc, s56, v90
	v_mov_b32_e32 v85, v37
	v_mov_b32_e32 v86, v37
	v_cndmask_b32_e32 v93, v90, v91, vcc
	v_sqrt_f32_e32 v114, v93
	v_mov_b32_e32 v90, v35
	v_mov_b32_e32 v91, v39
	v_mov_b32_e32 v87, v33
	v_add_u32_e32 v115, -1, v114
	v_add_u32_e32 v116, 1, v114
	v_fma_f32 v117, -v115, v114, v93
	v_fma_f32 v118, -v116, v114, v93
	v_cmp_ge_f32_e64 s[8:9], 0, v117
	v_mov_b32_e32 v72, v26
	v_mov_b32_e32 v73, v30
	v_cndmask_b32_e64 v114, v114, v115, s[8:9]
	v_cmp_lt_f32_e64 s[8:9], 0, v118
	s_nop 1
	v_cndmask_b32_e64 v114, v114, v116, s[8:9]
	v_mul_f32_e32 v115, 0x37800000, v114
	v_cndmask_b32_e32 v114, v114, v115, vcc
	v_cmp_class_f32_e32 vcc, v93, v95
	s_nop 1
	v_cndmask_b32_e32 v114, v114, v93, vcc
	v_div_scale_f32 v115, s[8:9], v114, v114, s57
	v_rcp_f32_e32 v116, v115
	v_div_scale_f32 v117, vcc, s57, v114, s57
	v_mov_b32_e32 v93, v35
	v_fma_f32 v118, -v115, v116, 1.0
	v_fmac_f32_e32 v116, v118, v116
	v_mul_f32_e32 v118, v117, v116
	v_fma_f32 v119, -v115, v118, v117
	v_fmac_f32_e32 v118, v119, v116
	v_fma_f32 v115, -v115, v118, v117
	v_div_fmas_f32 v115, v115, v116, v118
	v_div_fixup_f32 v114, v115, v114, s57
	v_pk_mul_f32 v[106:107], v[114:115], v[106:107] op_sel_hi:[0,1]
	v_pk_mul_f32 v[106:107], v[106:107], v[56:57]
	v_pk_mul_f32 v[102:103], v[114:115], v[102:103] op_sel_hi:[0,1]
	v_pk_mul_f32 v[120:121], v[106:107], v[76:77]
	v_pk_mul_f32 v[106:107], v[106:107], v[88:89]
	v_pk_mul_f32 v[110:111], v[114:115], v[110:111] op_sel_hi:[0,1]
	v_pk_mul_f32 v[108:109], v[114:115], v[108:109] op_sel_hi:[0,1]
	v_pk_mul_f32 v[102:103], v[102:103], v[54:55]
	v_sub_f32_e32 v120, v120, v121
	v_add_f32_e32 v121, v107, v106
; __device__ __forceinline__ unsigned cvt_pk_bf16(float lo, float hi) { unsigned r; asm volatile("v_cvt_pk_bf16_f32 %0, %1, %2" : "=v"(r) : "v"(lo), "v"(hi)); return r; }
; __device__ __forceinline__ float bflo(unsigned w) { return __uint_as_float(w << 16); }
; __device__ __forceinline__ float bfhi(unsigned w) { return __uint_as_float(w & 0xffff0000u); }
; __global__ void __launch_bounds__(NTHREADS, 2) fwd_megakernel(Params P) {
;     ...
;                     for (int p = 0; p < 3; ++p) {
;                         const int head = 8 * p + hs; const bool act = head < 20; const int hc = act ? head : 19;
;                         const bf16_t* src = z + hc * 128;
;                         const u32x4 w1 = *(const u32x4*)(src + j8), w2 = *(const u32x4*)(src + 64 + j8);
;                         const float a[8] = {bflo(w1.x), bfhi(w1.x), bflo(w1.y), bfhi(w1.y), bflo(w1.z), bfhi(w1.z), bflo(w1.w), bfhi(w1.w)};
;                         const float b[8] = {bflo(w2.x), bfhi(w2.x), bflo(w2.y), bfhi(w2.y), bflo(w2.z), bfhi(w2.z), bflo(w2.w), bfhi(w2.w)};
;                         float ss = 0.f;
; #pragma unroll
;                         for (int j = 0; j < 8; ++j) ss += a[j] * a[j] + b[j] * b[j];
;                         const bool isq = hc < 16;
;                         const float ri = (isq ? CS : 1.0f) / sqrtf(group_sum<8>(ss) * (1.f / 128.f) + EPS);
;                         float o1[8], o2[8];
; #pragma unroll
;                         for (int j = 0; j < 8; ++j) { const float y1 = a[j] * ri * (isq ? gq[j] : gk[j]), y2 = b[j] * ri * (isq ? gq[8 + j] : gk[8 + j]); o1[j] = y1 * cc[j] - y2 * sn[j]; o2[j] = y2 * cc[j] + y1 * sn[j]; }
;                         u32x4 v1, v2;
;                         v1.x = cvt_pk_bf16(o1[0], o1[1]); v1.y = cvt_pk_bf16(o1[2], o1[3]); v1.z = cvt_pk_bf16(o1[4], o1[5]); v1.w = cvt_pk_bf16(o1[6], o1[7]);
;                         v2.x = cvt_pk_bf16(o2[0], o2[1]); v2.y = cvt_pk_bf16(o2[2], o2[3]); v2.z = cvt_pk_bf16(o2[4], o2[5]); v2.w = cvt_pk_bf16(o2[6], o2[7]);
;                         bf16_t* dst = isq ? SQ + (size_t)tok * 2048 + hc * 128 : SK + (size_t)tok * 512 + (hc - 16) * 128;
;                         if (act) { *(u32x4*)(dst + j8) = v1; *(u32x4*)(dst + 64 + j8) = v2; }
;                     }
	v_mov_b32_e32 v106, v28
	v_mov_b32_e32 v107, v24
	v_pk_mul_f32 v[112:113], v[114:115], v[112:113] op_sel_hi:[0,1]
	v_pk_mul_f32 v[110:111], v[110:111], v[58:59]
	v_pk_mul_f32 v[108:109], v[108:109], v[6:7]
	v_pk_mul_f32 v[124:125], v[102:103], v[74:75]
	v_pk_mul_f32 v[102:103], v[102:103], v[106:107]
	v_pk_mul_f32 v[112:113], v[112:113], v[4:5]
	v_pk_mul_f32 v[116:117], v[110:111], v[78:79]
	v_pk_mul_f32 v[110:111], v[110:111], v[82:83]
	v_pk_mul_f32 v[122:123], v[108:109], v[90:91]
	v_pk_mul_f32 v[108:109], v[108:109], v[92:93]
	v_sub_f32_e32 v124, v124, v125
	v_add_f32_e32 v125, v103, v102
	v_pk_mul_f32 v[102:103], v[114:115], v[104:105] op_sel_hi:[0,1]
	v_pk_mul_f32 v[118:119], v[112:113], v[84:85]
	v_pk_mul_f32 v[112:113], v[112:113], v[86:87]
	v_add_f32_e32 v127, v111, v110
	v_sub_f32_e32 v122, v122, v123
	v_add_f32_e32 v123, v109, v108
	v_pk_mul_f32 v[102:103], v[102:103], v[0:1]
	v_mov_b32_e32 v108, v25
	v_mov_b32_e32 v109, v29
	v_mov_b32_e32 v110, v29
	v_mov_b32_e32 v111, v25
	v_pk_mul_f32 v[98:99], v[114:115], v[98:99] op_sel_hi:[0,1]
	v_sub_f32_e32 v118, v118, v119
	v_add_f32_e32 v119, v113, v112
	v_pk_mul_f32 v[104:105], v[102:103], v[108:109]
	v_pk_mul_f32 v[102:103], v[102:103], v[110:111]
	v_pk_mul_f32 v[98:99], v[98:99], v[52:53]
	v_mov_b32_e32 v112, v30
	v_mov_b32_e32 v113, v26
	v_sub_f32_e32 v104, v104, v105
	v_add_f32_e32 v105, v103, v102
	v_pk_mul_f32 v[102:103], v[98:99], v[72:73]
	v_pk_mul_f32 v[98:99], v[98:99], v[112:113]
	v_sub_f32_e32 v126, v116, v117
	v_add_f32_e32 v128, v99, v98
	v_pk_mul_f32 v[98:99], v[114:115], v[100:101] op_sel_hi:[0,1]
	v_pk_mul_f32 v[98:99], v[98:99], v[2:3]
	v_mov_b32_e32 v114, v27
	v_mov_b32_e32 v115, v31
	v_pk_mul_f32 v[100:101], v[98:99], v[114:115]
	v_mov_b32_e32 v116, v31
	v_mov_b32_e32 v117, v27
	v_sub_f32_e32 v102, v102, v103
	v_sub_f32_e32 v101, v100, v101
	v_pk_mul_f32 v[98:99], v[98:99], v[116:117]
	s_nop 0
	v_add_f32_e32 v129, v99, v98
	v_cvt_pk_bf16_f32 v98, v126, v118
	v_cvt_pk_bf16_f32 v99, v120, v122
	v_cvt_pk_bf16_f32 v100, v124, v104
	v_cvt_pk_bf16_f32 v101, v102, v101
	v_cvt_pk_bf16_f32 v102, v127, v119
	v_lshl_add_u64 v[118:119], v[66:67], 0, v[42:43]
	v_cvt_pk_bf16_f32 v103, v121, v123
	v_cvt_pk_bf16_f32 v104, v125, v105
	v_cvt_pk_bf16_f32 v105, v128, v129
	global_store_dwordx4 v[118:119], v[98:101], off offset:-2048
	global_store_dwordx4 v[118:119], v[102:105], off offset:-1920
	s_waitcnt vmcnt(5)
	s_nop 0
	v_mov_b64_e32 v[98:99], v[176:177]
	v_mov_b64_e32 v[100:101], v[178:179]
	s_nop 1
	s_nop 0
	s_waitcnt vmcnt(4)
	s_nop 0
	v_mov_b64_e32 v[102:103], v[180:181]
	v_mov_b64_e32 v[104:105], v[182:183]
	s_nop 1
	v_lshlrev_b32_e32 v81, 16, v101
	v_lshlrev_b32_e32 v80, 16, v105
	v_and_b32_e32 v121, 0xffff0000, v101
	v_and_b32_e32 v120, 0xffff0000, v105
	v_lshlrev_b32_e32 v123, 16, v100
	v_and_b32_e32 v101, 0xffff0000, v100
	v_lshlrev_b32_e32 v105, 16, v99
	v_and_b32_e32 v125, 0xffff0000, v99
	v_and_b32_e32 v124, 0xffff0000, v103
	v_lshlrev_b32_e32 v127, 16, v98
	v_lshlrev_b32_e32 v126, 16, v102
	v_and_b32_e32 v99, 0xffff0000, v98
	v_and_b32_e32 v98, 0xffff0000, v102
	v_lshlrev_b32_e32 v122, 16, v104
	v_and_b32_e32 v100, 0xffff0000, v104
	v_lshlrev_b32_e32 v104, 16, v103
	v_mov_b32_e32 v128, v81
	v_mov_b32_e32 v129, v121
	v_mov_b32_e32 v132, v123
	v_mov_b32_e32 v133, v101
	v_pk_mul_f32 v[136:137], v[124:125], v[124:125]
	v_pk_mul_f32 v[138:139], v[126:127], v[126:127]
	v_pk_mul_f32 v[140:141], v[98:99], v[98:99]
	v_mov_b32_e32 v102, v80
	v_mov_b32_e32 v103, v120
	v_mov_b32_e32 v130, v122
	v_mov_b32_e32 v131, v100
	v_pk_mul_f32 v[134:135], v[104:105], v[104:105]
	v_pk_mul_f32 v[128:129], v[128:129], v[128:129]
	v_pk_mul_f32 v[132:133], v[132:133], v[132:133]
	v_add_f32_e32 v136, v136, v137
	v_add_f32_e32 v137, v140, v141
	v_add_f32_e32 v138, v138, v139
	v_add_f32_e32 v134, v134, v135
	v_pk_fma_f32 v[102:103], v[102:103], v[102:103], v[128:129]
	v_pk_fma_f32 v[128:129], v[130:131], v[130:131], v[132:133]
	v_add_f32_e32 v130, v138, v137
	v_add_f32_e32 v130, v130, v134
	v_add_f32_e32 v130, v130, v136
	v_add_f32_e32 v128, v130, v128
	v_add_f32_e32 v128, v128, v129
	v_add_f32_e32 v102, v128, v102
	v_add_f32_e32 v102, v102, v103
	ds_bpermute_b32 v103, v40, v102
	s_waitcnt lgkmcnt(0)
	v_add_f32_e32 v102, v102, v103
	ds_bpermute_b32 v103, v96, v102
	s_waitcnt lgkmcnt(0)
	v_add_f32_e32 v102, v102, v103
	ds_bpermute_b32 v103, v97, v102
	s_waitcnt lgkmcnt(0)
; __device__ __forceinline__ unsigned cvt_pk_bf16(float lo, float hi) { unsigned r; asm volatile("v_cvt_pk_bf16_f32 %0, %1, %2" : "=v"(r) : "v"(lo), "v"(hi)); return r; }
; __device__ __forceinline__ float bflo(unsigned w) { return __uint_as_float(w << 16); }
; __device__ __forceinline__ float bfhi(unsigned w) { return __uint_as_float(w & 0xffff0000u); }
; __global__ void __launch_bounds__(NTHREADS, 2) fwd_megakernel(Params P) {
;     ...
;                     for (int p = 0; p < 3; ++p) {
;                         const int head = 8 * p + hs; const bool act = head < 20; const int hc = act ? head : 19;
;                         const bf16_t* src = z + hc * 128;
;                         const u32x4 w1 = *(const u32x4*)(src + j8), w2 = *(const u32x4*)(src + 64 + j8);
;                         const float a[8] = {bflo(w1.x), bfhi(w1.x), bflo(w1.y), bfhi(w1.y), bflo(w1.z), bfhi(w1.z), bflo(w1.w), bfhi(w1.w)};
;                         const float b[8] = {bflo(w2.x), bfhi(w2.x), bflo(w2.y), bfhi(w2.y), bflo(w2.z), bfhi(w2.z), bflo(w2.w), bfhi(w2.w)};
;                         float ss = 0.f;
; #pragma unroll
;                         for (int j = 0; j < 8; ++j) ss += a[j] * a[j] + b[j] * b[j];
;                         const bool isq = hc < 16;
;                         const float ri = (isq ? CS : 1.0f) / sqrtf(group_sum<8>(ss) * (1.f / 128.f) + EPS);
;                         float o1[8], o2[8];
; #pragma unroll
;                         for (int j = 0; j < 8; ++j) { const float y1 = a[j] * ri * (isq ? gq[j] : gk[j]), y2 = b[j] * ri * (isq ? gq[8 + j] : gk[8 + j]); o1[j] = y1 * cc[j] - y2 * sn[j]; o2[j] = y2 * cc[j] + y1 * sn[j]; }
;                         u32x4 v1, v2;
;                         v1.x = cvt_pk_bf16(o1[0], o1[1]); v1.y = cvt_pk_bf16(o1[2], o1[3]); v1.z = cvt_pk_bf16(o1[4], o1[5]); v1.w = cvt_pk_bf16(o1[6], o1[7]);
;                         v2.x = cvt_pk_bf16(o2[0], o2[1]); v2.y = cvt_pk_bf16(o2[2], o2[3]); v2.z = cvt_pk_bf16(o2[4], o2[5]); v2.w = cvt_pk_bf16(o2[6], o2[7]);
;                         bf16_t* dst = isq ? SQ + (size_t)tok * 2048 + hc * 128 : SK + (size_t)tok * 512 + (hc - 16) * 128;
;                         if (act) { *(u32x4*)(dst + j8) = v1; *(u32x4*)(dst + 64 + j8) = v2; }
;                     }
	v_add_f32_e32 v102, v102, v103
	v_fmamk_f32 v102, v102, 0x3c000000, v94
	v_mul_f32_e32 v103, 0x4f800000, v102
	v_cmp_gt_f32_e32 vcc, s56, v102
	s_nop 1
	v_cndmask_b32_e32 v102, v102, v103, vcc
	v_sqrt_f32_e32 v103, v102
	s_nop 0
	v_add_u32_e32 v128, -1, v103
	v_add_u32_e32 v129, 1, v103
	v_fma_f32 v130, -v128, v103, v102
	v_fma_f32 v131, -v129, v103, v102
	v_cmp_ge_f32_e64 s[8:9], 0, v130
	s_nop 1
	v_cndmask_b32_e64 v103, v103, v128, s[8:9]
	v_cmp_lt_f32_e64 s[8:9], 0, v131
	s_nop 1
	v_cndmask_b32_e64 v103, v103, v129, s[8:9]
	v_mul_f32_e32 v128, 0x37800000, v103
	v_cndmask_b32_e32 v103, v103, v128, vcc
	v_cmp_class_f32_e32 vcc, v102, v95
	s_nop 1
	v_cndmask_b32_e32 v102, v103, v102, vcc
	v_div_scale_f32 v103, s[8:9], v102, v102, s57
	v_rcp_f32_e32 v128, v103
	v_div_scale_f32 v129, vcc, s57, v102, s57
	v_fma_f32 v130, -v103, v128, 1.0
	v_fmac_f32_e32 v128, v130, v128
	v_mul_f32_e32 v130, v129, v128
	v_fma_f32 v131, -v103, v130, v129
	v_fmac_f32_e32 v130, v131, v128
	v_fma_f32 v103, -v103, v130, v129
	v_div_fmas_f32 v103, v103, v128, v130
	v_div_fixup_f32 v102, v103, v102, s57
	v_pk_mul_f32 v[126:127], v[102:103], v[126:127] op_sel_hi:[0,1]
	v_pk_mul_f32 v[98:99], v[102:103], v[98:99] op_sel_hi:[0,1]
	v_pk_mul_f32 v[104:105], v[102:103], v[104:105] op_sel_hi:[0,1]
	v_pk_mul_f32 v[126:127], v[126:127], v[58:59]
	v_pk_mul_f32 v[98:99], v[98:99], v[4:5]
	v_pk_mul_f32 v[104:105], v[104:105], v[56:57]
	v_pk_mul_f32 v[82:83], v[126:127], v[82:83]
	v_pk_mul_f32 v[84:85], v[98:99], v[84:85]
	v_pk_mul_f32 v[76:77], v[104:105], v[76:77]
	v_pk_mul_f32 v[86:87], v[98:99], v[86:87]
	v_add_f32_e32 v82, v83, v82
	v_sub_f32_e32 v83, v84, v85
	v_sub_f32_e32 v85, v76, v77
	v_pk_mul_f32 v[76:77], v[104:105], v[88:89]
	v_add_f32_e32 v84, v87, v86
	v_add_f32_e32 v86, v77, v76
	v_pk_mul_f32 v[76:77], v[102:103], v[124:125] op_sel_hi:[0,1]
	v_pk_mul_f32 v[78:79], v[126:127], v[78:79]
	v_pk_mul_f32 v[76:77], v[76:77], v[6:7]
	v_sub_f32_e32 v98, v78, v79
	v_pk_mul_f32 v[78:79], v[76:77], v[90:91]
	v_pk_mul_f32 v[76:77], v[76:77], v[92:93]
	v_sub_f32_e32 v78, v78, v79
	v_add_f32_e32 v79, v77, v76
	v_pk_mul_f32 v[76:77], v[102:103], v[122:123] op_sel_hi:[0,1]
	v_pk_mul_f32 v[76:77], v[76:77], v[54:55]
	s_nop 0
	v_pk_mul_f32 v[74:75], v[76:77], v[74:75]
	s_nop 0
	v_sub_f32_e32 v87, v74, v75
	v_pk_mul_f32 v[74:75], v[76:77], v[106:107]
	s_nop 0
	v_add_f32_e32 v88, v75, v74
	v_pk_mul_f32 v[74:75], v[102:103], v[100:101] op_sel_hi:[0,1]
	v_pk_mul_f32 v[74:75], v[74:75], v[0:1]
	s_nop 0
	v_pk_mul_f32 v[76:77], v[74:75], v[108:109]
	v_pk_mul_f32 v[74:75], v[74:75], v[110:111]
	v_sub_f32_e32 v76, v76, v77
	v_add_f32_e32 v89, v75, v74
	v_pk_mul_f32 v[74:75], v[102:103], v[80:81] op_sel_hi:[0,1]
	v_pk_mul_f32 v[74:75], v[74:75], v[52:53]
	s_nop 0
	v_pk_mul_f32 v[72:73], v[74:75], v[72:73]
	s_nop 0
	v_sub_f32_e32 v77, v72, v73
	v_pk_mul_f32 v[72:73], v[74:75], v[112:113]
	s_nop 0
	v_add_f32_e32 v80, v73, v72
	v_pk_mul_f32 v[72:73], v[102:103], v[120:121] op_sel_hi:[0,1]
	v_pk_mul_f32 v[72:73], v[72:73], v[2:3]
	s_nop 0
	v_pk_mul_f32 v[74:75], v[72:73], v[114:115]
	v_pk_mul_f32 v[72:73], v[72:73], v[116:117]
	v_sub_f32_e32 v75, v74, v75
	v_add_f32_e32 v81, v73, v72
	v_cvt_pk_bf16_f32 v72, v98, v83
	v_cvt_pk_bf16_f32 v73, v85, v78
	v_cvt_pk_bf16_f32 v74, v87, v76
	v_cvt_pk_bf16_f32 v75, v77, v75
	v_cvt_pk_bf16_f32 v76, v82, v84
	v_cvt_pk_bf16_f32 v77, v86, v79
	v_cvt_pk_bf16_f32 v78, v88, v89
	v_cvt_pk_bf16_f32 v79, v80, v81
	global_store_dwordx4 v[118:119], v[72:75], off
	global_store_dwordx4 v[118:119], v[76:79], off offset:128
	s_nop 0
	v_lshl_add_u64 v[72:73], v[68:69], 0, v[42:43]
	v_add_co_u32_e32 v76, vcc, s58, v72
	s_nop 1
	v_addc_co_u32_e32 v77, vcc, 0, v73, vcc
	s_waitcnt vmcnt(5)
	s_nop 0
	v_mov_b64_e32 v[72:73], v[184:185]
	v_mov_b64_e32 v[74:75], v[186:187]
	s_nop 1
	s_nop 0
	s_waitcnt vmcnt(4)
; __device__ __forceinline__ unsigned cvt_pk_bf16(float lo, float hi) { unsigned r; asm volatile("v_cvt_pk_bf16_f32 %0, %1, %2" : "=v"(r) : "v"(lo), "v"(hi)); return r; }
; __device__ __forceinline__ float bflo(unsigned w) { return __uint_as_float(w << 16); }
; __device__ __forceinline__ float bfhi(unsigned w) { return __uint_as_float(w & 0xffff0000u); }
; __global__ void __launch_bounds__(NTHREADS, 2) fwd_megakernel(Params P) {
;     ...
;                     for (int p = 0; p < 3; ++p) {
;                         const int head = 8 * p + hs; const bool act = head < 20; const int hc = act ? head : 19;
;                         const bf16_t* src = z + hc * 128;
;                         const u32x4 w1 = *(const u32x4*)(src + j8), w2 = *(const u32x4*)(src + 64 + j8);
;                         const float a[8] = {bflo(w1.x), bfhi(w1.x), bflo(w1.y), bfhi(w1.y), bflo(w1.z), bfhi(w1.z), bflo(w1.w), bfhi(w1.w)};
;                         const float b[8] = {bflo(w2.x), bfhi(w2.x), bflo(w2.y), bfhi(w2.y), bflo(w2.z), bfhi(w2.z), bflo(w2.w), bfhi(w2.w)};
;                         float ss = 0.f;
; #pragma unroll
;                         for (int j = 0; j < 8; ++j) ss += a[j] * a[j] + b[j] * b[j];
;                         const bool isq = hc < 16;
;                         const float ri = (isq ? CS : 1.0f) / sqrtf(group_sum<8>(ss) * (1.f / 128.f) + EPS);
;                         float o1[8], o2[8];
; #pragma unroll
;                         for (int j = 0; j < 8; ++j) { const float y1 = a[j] * ri * (isq ? gq[j] : gk[j]), y2 = b[j] * ri * (isq ? gq[8 + j] : gk[8 + j]); o1[j] = y1 * cc[j] - y2 * sn[j]; o2[j] = y2 * cc[j] + y1 * sn[j]; }
;                         u32x4 v1, v2;
;                         v1.x = cvt_pk_bf16(o1[0], o1[1]); v1.y = cvt_pk_bf16(o1[2], o1[3]); v1.z = cvt_pk_bf16(o1[4], o1[5]); v1.w = cvt_pk_bf16(o1[6], o1[7]);
;                         v2.x = cvt_pk_bf16(o2[0], o2[1]); v2.y = cvt_pk_bf16(o2[2], o2[3]); v2.z = cvt_pk_bf16(o2[4], o2[5]); v2.w = cvt_pk_bf16(o2[6], o2[7]);
;                         bf16_t* dst = isq ? SQ + (size_t)tok * 2048 + hc * 128 : SK + (size_t)tok * 512 + (hc - 16) * 128;
;                         if (act) { *(u32x4*)(dst + j8) = v1; *(u32x4*)(dst + 64 + j8) = v2; }
;                     }
	s_nop 0
	v_mov_b64_e32 v[76:77], v[188:189]
	v_mov_b64_e32 v[78:79], v[190:191]
	s_nop 1
	v_lshlrev_b32_e32 v80, 16, v72
	v_lshlrev_b32_e32 v84, 16, v76
	v_and_b32_e32 v76, 0xffff0000, v76
	v_and_b32_e32 v72, 0xffff0000, v72
	v_lshlrev_b32_e32 v85, 16, v77
	v_mul_f32_e32 v88, v84, v84
	v_mul_f32_e32 v89, v76, v76
	v_lshlrev_b32_e32 v81, 16, v73
	v_and_b32_e32 v77, 0xffff0000, v77
	v_mul_f32_e32 v90, v85, v85
	v_fmac_f32_e32 v88, v80, v80
	v_fmac_f32_e32 v89, v72, v72
	v_and_b32_e32 v73, 0xffff0000, v73
	v_lshlrev_b32_e32 v86, 16, v78
	v_mul_f32_e32 v91, v77, v77
	v_fmac_f32_e32 v90, v81, v81
	v_add_f32_e32 v88, v88, v89
	v_lshlrev_b32_e32 v82, 16, v74
	v_and_b32_e32 v78, 0xffff0000, v78
	v_mul_f32_e32 v92, v86, v86
	v_fmac_f32_e32 v91, v73, v73
	v_add_f32_e32 v88, v88, v90
	v_and_b32_e32 v74, 0xffff0000, v74
	v_lshlrev_b32_e32 v87, 16, v79
	v_mul_f32_e32 v93, v78, v78
	v_fmac_f32_e32 v92, v82, v82
	v_add_f32_e32 v88, v88, v91
	v_lshlrev_b32_e32 v83, 16, v75
	v_and_b32_e32 v79, 0xffff0000, v79
	v_mul_f32_e32 v98, v87, v87
	v_fmac_f32_e32 v93, v74, v74
	v_add_f32_e32 v88, v88, v92
	v_and_b32_e32 v75, 0xffff0000, v75
	v_mul_f32_e32 v99, v79, v79
	v_fmac_f32_e32 v98, v83, v83
	v_add_f32_e32 v88, v88, v93
	v_fmac_f32_e32 v99, v75, v75
	v_add_f32_e32 v88, v88, v98
	v_add_f32_e32 v88, v88, v99
	ds_bpermute_b32 v89, v40, v88
	s_waitcnt lgkmcnt(0)
	v_add_f32_e32 v88, v88, v89
	ds_bpermute_b32 v89, v96, v88
	s_waitcnt lgkmcnt(0)
	v_add_f32_e32 v88, v88, v89
	ds_bpermute_b32 v89, v97, v88
	s_waitcnt lgkmcnt(0)
	v_add_f32_e32 v88, v88, v89
	v_fmamk_f32 v88, v88, 0x3c000000, v94
	v_mul_f32_e32 v89, 0x4f800000, v88
	v_cmp_gt_f32_e32 vcc, s56, v88
	s_nop 1
	v_cndmask_b32_e32 v88, v88, v89, vcc
	v_sqrt_f32_e32 v89, v88
	s_nop 0
	v_add_u32_e32 v90, -1, v89
	v_add_u32_e32 v91, 1, v89
	v_fma_f32 v92, -v90, v89, v88
	v_fma_f32 v93, -v91, v89, v88
	v_cmp_ge_f32_e64 s[8:9], 0, v92
	s_nop 1
	v_cndmask_b32_e64 v89, v89, v90, s[8:9]
	v_cmp_lt_f32_e64 s[8:9], 0, v93
	s_nop 1
	v_cndmask_b32_e64 v89, v89, v91, s[8:9]
	v_mul_f32_e32 v90, 0x37800000, v89
	v_cndmask_b32_e32 v89, v89, v90, vcc
	v_cmp_class_f32_e32 vcc, v88, v95
	s_nop 1
	v_cndmask_b32_e32 v88, v89, v88, vcc
	v_div_scale_f32 v89, s[8:9], v88, v88, 1.0
	v_rcp_f32_e32 v90, v89
	v_div_scale_f32 v91, vcc, 1.0, v88, 1.0
	v_fma_f32 v92, -v89, v90, 1.0
	v_fmac_f32_e32 v90, v92, v90
	v_mul_f32_e32 v92, v91, v90
	v_fma_f32 v93, -v89, v92, v91
	v_fmac_f32_e32 v92, v93, v90
	v_fma_f32 v89, -v89, v92, v91
	v_div_fmas_f32 v89, v89, v90, v92
	v_div_fixup_f32 v88, v89, v88, 1.0
	v_mul_f32_e32 v80, v88, v80
	v_mul_f32_e32 v84, v88, v84
	v_mul_f32_e32 v76, v88, v76
	v_mul_f32_e32 v72, v88, v72
	v_mul_f32_e32 v80, v80, v8
	v_mul_f32_e32 v84, v84, v16
	v_mul_f32_e32 v76, v76, v17
	v_mul_f32_e32 v72, v72, v9
	v_mul_f32_e32 v89, v84, v36
	v_mul_f32_e32 v36, v80, v36
	v_mul_f32_e32 v90, v76, v37
	v_mul_f32_e32 v37, v72, v37
	v_fma_f32 v80, v80, v32, -v89
	v_fmac_f32_e32 v36, v84, v32
	v_fma_f32 v32, v72, v33, -v90
	v_mul_f32_e32 v72, v88, v85
	v_fmac_f32_e32 v37, v76, v33
	v_mul_f32_e32 v33, v88, v81
	v_mul_f32_e32 v72, v72, v18
	v_mul_f32_e32 v33, v33, v10
	v_mul_f32_e32 v76, v72, v38
	v_fma_f32 v76, v33, v34, -v76
	v_mul_f32_e32 v33, v33, v38
	v_mul_f32_e32 v38, v88, v77
	v_fmac_f32_e32 v33, v72, v34
	v_mul_f32_e32 v34, v88, v73
	v_mul_f32_e32 v38, v38, v19
	v_mul_f32_e32 v34, v34, v11
	v_mul_f32_e32 v72, v38, v39
	v_fma_f32 v72, v34, v35, -v72
	v_mul_f32_e32 v34, v34, v39
	v_fmac_f32_e32 v34, v38, v35
	v_mul_f32_e32 v38, v88, v86
	v_mul_f32_e32 v35, v88, v82
	v_mul_f32_e32 v38, v38, v20
	v_mul_f32_e32 v35, v35, v12
	v_mul_f32_e32 v39, v38, v28
	v_fma_f32 v39, v35, v24, -v39
	v_mul_f32_e32 v35, v35, v28
	v_fmac_f32_e32 v35, v38, v24
	v_mul_f32_e32 v24, v88, v74
	v_mul_f32_e32 v28, v88, v78
	v_mul_f32_e32 v24, v24, v13
	v_mul_f32_e32 v28, v28, v21
	v_mul_f32_e32 v38, v28, v29
	v_mul_f32_e32 v73, v24, v29
	v_fma_f32 v38, v24, v25, -v38
	v_fmac_f32_e32 v73, v28, v25
	v_mul_f32_e32 v24, v88, v83
	v_mul_f32_e32 v25, v88, v87
	v_mul_f32_e32 v24, v24, v14
	v_mul_f32_e32 v25, v25, v22
	v_mul_f32_e32 v28, v25, v30
	v_mul_f32_e32 v74, v24, v30
	v_fma_f32 v28, v24, v26, -v28
	v_fmac_f32_e32 v74, v25, v26
	v_mul_f32_e32 v24, v88, v75
	v_mul_f32_e32 v25, v88, v79
	v_mul_f32_e32 v24, v24, v15
	v_mul_f32_e32 v25, v25, v23
	v_mul_f32_e32 v26, v25, v31
	v_mul_f32_e32 v31, v24, v31
	v_fma_f32 v29, v24, v27, -v26
	v_fmac_f32_e32 v31, v25, v27
	v_cvt_pk_bf16_f32 v24, v80, v32
	v_cvt_pk_bf16_f32 v25, v76, v72
	v_cvt_pk_bf16_f32 v26, v39, v38
	v_cvt_pk_bf16_f32 v27, v28, v29
	v_cvt_pk_bf16_f32 v28, v36, v37
	v_cvt_pk_bf16_f32 v29, v33, v34
	v_cvt_pk_bf16_f32 v30, v35, v73
	v_cvt_pk_bf16_f32 v31, v74, v31
	s_and_saveexec_b64 s[8:9], s[6:7]
	s_cbranch_execz .LBB0_1028
	v_lshl_add_u64 v[32:33], v[64:65], 0, v[42:43]
	v_add_co_u32_e32 v32, vcc, 0x18bff000, v32
	s_nop 1
	v_addc_co_u32_e32 v33, vcc, 0, v33, vcc
	global_store_dwordx4 v[32:33], v[24:27], off
	global_store_dwordx4 v[32:33], v[28:31], off offset:128
	s_branch .LBB0_1028

; #define PG8_STAGE(bufoff, gbase, voff) do { _Pragma("unroll") for (int _i = 0; _i < 2; ++_i) \
;         __builtin_amdgcn_global_load_lds((const unsigned*)((const char*)(gbase) + (voff)[_i]), (LAS unsigned*)(lds + (bufoff) + ldsw + _i * 8192), 16, 0, 0); } while (0)
; #define PG8_LDA(dst, b, h) do { _Pragma("unroll") for (int m = 0; m < 4; ++m) _Pragma("unroll") for (int k = 0; k < 2; ++k) dst[m][k] = *(const LAS bf16x8*)(lds + PG8_SA(b, h) + aoff + m * 2048 + k * 1024); } while (0)
; #define PG8_LDB(dst, b, h) do { _Pragma("unroll") for (int n = 0; n < 2; ++n) _Pragma("unroll") for (int k = 0; k < 2; ++k) dst[n][k] = *(const LAS bf16x8*)(lds + PG8_SB(b, h) + boff + n * 2048 + k * 1024); } while (0)
; #define PG8_WAIT_V(n) asm volatile("s_waitcnt vmcnt(" #n ")" ::: "memory")
; #define PG8_WAIT_L(n) asm volatile("s_waitcnt lgkmcnt(" #n ")" ::: "memory")
; #define PG8_BAR __builtin_amdgcn_s_barrier()
; #define PG8_SCHED __builtin_amdgcn_sched_barrier(0)
; template <class Epi>
; __device__ __forceinline__ void gemm_phase(LAS unsigned char* lds, const Gemm g, const StaticOrder& S, const Epi& E) {
;     ...
;             PG8_LDB(B0, 0, 0); PG8_SCHED; PG8_LDA(At, 0, 0); PG8_STAGE(PG8_SA(1, 1), a1 + hstep, voffA);
;             PG8_WAIT_L(8); PG8_BAR; PG8_WAIT_L(0); PG8_MMA(0, 0, At, B0); PG8_BAR; PG8_SCHED;
;             PG8_LDB(B1, 0, 1); PG8_STAGE(PG8_SB(0, 0), b2, voffB0);
;             PG8_BAR; PG8_WAIT_L(0); PG8_MMA(0, 1, At, B1); PG8_BAR;
;             PG8_LDA(At, 0, 1); PG8_STAGE(PG8_SA(0, 0), a2, voffA);
;             PG8_BAR; PG8_WAIT_L(0); PG8_MMA(1, 0, At, B0); PG8_BAR; PG8_SCHED;
;             PG8_STAGE(PG8_SB(0, 1), b2, voffB1);
;             PG8_WAIT_V(6); PG8_BAR; PG8_MMA(1, 1, At, B1); PG8_BAR;
;             PG8_LDB(B0, 1, 0); PG8_SCHED; PG8_LDA(At, 1, 0); PG8_STAGE(PG8_SA(0, 1), a2 + hstep, voffA);
;             PG8_WAIT_L(8); PG8_BAR; PG8_WAIT_L(0); PG8_MMA(0, 0, At, B0); PG8_BAR; PG8_SCHED;
;             PG8_LDB(B1, 1, 1); PG8_STAGE(PG8_SB(1, 0), b3, voffB0);
;             PG8_BAR; PG8_WAIT_L(0); PG8_MMA(0, 1, At, B1); PG8_BAR;
;             PG8_LDA(At, 1, 1); PG8_STAGE(PG8_SA(1, 0), a3, voffA);
;             PG8_BAR; PG8_WAIT_L(0); PG8_MMA(1, 0, At, B0); PG8_BAR; PG8_SCHED;
;             PG8_STAGE(PG8_SB(1, 1), b3, voffB1);
;             PG8_WAIT_V(6); PG8_BAR; PG8_MMA(1, 1, At, B1); PG8_BAR;
.LBB0_1603:
	ds_read_b128 v[40:43], v179
	ds_read_b128 v[44:47], v179 offset:1024
	ds_read_b128 v[56:59], v179 offset:2048
	ds_read_b128 v[60:63], v179 offset:3072
	s_add_u32 s36, s34, 0xfff80080
	s_addc_u32 s37, s35, -1
	s_cmp_eq_u32 s58, 28
	s_cselect_b32 s37, s23, s37
	s_cselect_b32 s36, s54, s36
	s_cselect_b32 s39, s19, s57
	s_cselect_b32 s38, s55, s56
	v_lshl_add_u64 v[172:173], s[34:35], 0, v[158:159]
	s_add_i32 m0, s31, 0xc000
	ds_read_b128 v[164:167], v180
	ds_read_b128 v[168:171], v180 offset:1024
	ds_read_b128 v[184:187], v180 offset:2048
	ds_read_b128 v[188:191], v180 offset:3072
	ds_read_b128 v[192:195], v180 offset:4096
	ds_read_b128 v[196:199], v180 offset:5120
	ds_read_b128 v[200:203], v180 offset:6144
	ds_read_b128 v[204:207], v180 offset:7168
	global_load_lds_dwordx4 v[172:173], off
	v_lshl_add_u64 v[172:173], s[34:35], 0, v[160:161]
	s_add_i32 m0, s31, 0xe000
	s_nop 0
	global_load_lds_dwordx4 v[172:173], off
	s_waitcnt lgkmcnt(8)
	s_barrier
	s_waitcnt lgkmcnt(0)
	s_setprio 1
	s_waitcnt lgkmcnt(0)
	v_mfma_f32_16x16x32_bf16 v[140:143], v[40:43], v[164:167], v[140:143]
	v_mfma_f32_16x16x32_bf16 v[136:139], v[56:59], v[164:167], v[136:139]
	v_mfma_f32_16x16x32_bf16 v[124:127], v[40:43], v[184:187], v[124:127]
	v_mfma_f32_16x16x32_bf16 v[120:123], v[56:59], v[184:187], v[120:123]
	v_mfma_f32_16x16x32_bf16 v[108:111], v[40:43], v[192:195], v[108:111]
	v_mfma_f32_16x16x32_bf16 v[104:107], v[56:59], v[192:195], v[104:107]
	v_mfma_f32_16x16x32_bf16 v[92:95], v[40:43], v[200:203], v[92:95]
	v_mfma_f32_16x16x32_bf16 v[88:91], v[56:59], v[200:203], v[88:91]
	v_mfma_f32_16x16x32_bf16 v[140:143], v[44:47], v[168:171], v[140:143]
	v_mfma_f32_16x16x32_bf16 v[136:139], v[60:63], v[168:171], v[136:139]
	v_mfma_f32_16x16x32_bf16 v[124:127], v[44:47], v[188:191], v[124:127]
	v_mfma_f32_16x16x32_bf16 v[120:123], v[60:63], v[188:191], v[120:123]
	v_mfma_f32_16x16x32_bf16 v[108:111], v[44:47], v[196:199], v[108:111]
	v_mfma_f32_16x16x32_bf16 v[104:107], v[60:63], v[196:199], v[104:107]
	v_mfma_f32_16x16x32_bf16 v[92:95], v[44:47], v[204:207], v[92:95]
	v_mfma_f32_16x16x32_bf16 v[88:91], v[60:63], v[204:207], v[88:91]
	s_setprio 0
	s_barrier
	s_add_i32 s59, s51, s41
	v_lshl_add_u64 v[172:173], s[38:39], 0, v[146:147]
	s_mov_b32 m0, s59
	ds_read_b128 v[208:211], v181
	ds_read_b128 v[212:215], v181 offset:1024
	ds_read_b128 v[216:219], v181 offset:2048
	ds_read_b128 v[220:223], v181 offset:3072
	global_load_lds_dwordx4 v[172:173], off
	v_lshl_add_u64 v[224:225], s[38:39], 0, v[152:153]
	s_add_i32 m0, s59, 0x2000
	s_nop 0
	global_load_lds_dwordx4 v[224:225], off
	s_barrier
	s_waitcnt lgkmcnt(0)
	s_setprio 1
	s_waitcnt lgkmcnt(0)
	v_mfma_f32_16x16x32_bf16 v[132:135], v[208:211], v[164:167], v[132:135]
	v_mfma_f32_16x16x32_bf16 v[128:131], v[216:219], v[164:167], v[128:131]
	v_mfma_f32_16x16x32_bf16 v[116:119], v[208:211], v[184:187], v[116:119]
	v_mfma_f32_16x16x32_bf16 v[112:115], v[216:219], v[184:187], v[112:115]
	v_mfma_f32_16x16x32_bf16 v[100:103], v[208:211], v[192:195], v[100:103]
	v_mfma_f32_16x16x32_bf16 v[96:99], v[216:219], v[192:195], v[96:99]
	v_mfma_f32_16x16x32_bf16 v[84:87], v[208:211], v[200:203], v[84:87]
	v_mfma_f32_16x16x32_bf16 v[80:83], v[216:219], v[200:203], v[80:83]
	v_mfma_f32_16x16x32_bf16 v[132:135], v[212:215], v[168:171], v[132:135]
	v_mfma_f32_16x16x32_bf16 v[128:131], v[220:223], v[168:171], v[128:131]
	v_mfma_f32_16x16x32_bf16 v[116:119], v[212:215], v[188:191], v[116:119]
	v_mfma_f32_16x16x32_bf16 v[112:115], v[220:223], v[188:191], v[112:115]
	v_mfma_f32_16x16x32_bf16 v[100:103], v[212:215], v[196:199], v[100:103]
	v_mfma_f32_16x16x32_bf16 v[96:99], v[220:223], v[196:199], v[96:99]
	v_mfma_f32_16x16x32_bf16 v[84:87], v[212:215], v[204:207], v[84:87]
	v_mfma_f32_16x16x32_bf16 v[80:83], v[220:223], v[204:207], v[80:83]
	s_setprio 0
	s_mov_b32 m0, s31
	v_lshl_add_u64 v[226:227], s[36:37], 0, v[144:145]
	s_barrier
	ds_read_b128 v[164:167], v180 offset:16384
	ds_read_b128 v[168:171], v180 offset:17408
	ds_read_b128 v[184:187], v180 offset:18432
	ds_read_b128 v[188:191], v180 offset:19456
	ds_read_b128 v[192:195], v180 offset:20480
	ds_read_b128 v[196:199], v180 offset:21504
	ds_read_b128 v[200:203], v180 offset:22528
	ds_read_b128 v[204:207], v180 offset:23552
	global_load_lds_dwordx4 v[226:227], off
	v_lshl_add_u64 v[228:229], s[36:37], 0, v[150:151]
	s_mov_b32 m0, s42
	s_nop 0
	global_load_lds_dwordx4 v[228:229], off
	s_barrier
	s_waitcnt lgkmcnt(0)
	s_setprio 1
	s_waitcnt lgkmcnt(0)
	v_mfma_f32_16x16x32_bf16 v[76:79], v[40:43], v[164:167], v[76:79]
	v_mfma_f32_16x16x32_bf16 v[72:75], v[56:59], v[164:167], v[72:75]
	v_mfma_f32_16x16x32_bf16 v[52:55], v[40:43], v[184:187], v[52:55]
	v_mfma_f32_16x16x32_bf16 v[48:51], v[56:59], v[184:187], v[48:51]
	v_mfma_f32_16x16x32_bf16 v[28:31], v[40:43], v[192:195], v[28:31]
	v_mfma_f32_16x16x32_bf16 v[24:27], v[56:59], v[192:195], v[24:27]
	v_mfma_f32_16x16x32_bf16 v[12:15], v[40:43], v[200:203], v[12:15]
	v_mfma_f32_16x16x32_bf16 v[8:11], v[56:59], v[200:203], v[8:11]
	v_mfma_f32_16x16x32_bf16 v[76:79], v[44:47], v[168:171], v[76:79]
	v_mfma_f32_16x16x32_bf16 v[72:75], v[60:63], v[168:171], v[72:75]
	v_mfma_f32_16x16x32_bf16 v[52:55], v[44:47], v[188:191], v[52:55]
	v_mfma_f32_16x16x32_bf16 v[48:51], v[60:63], v[188:191], v[48:51]
	v_mfma_f32_16x16x32_bf16 v[28:31], v[44:47], v[196:199], v[28:31]
	v_mfma_f32_16x16x32_bf16 v[24:27], v[60:63], v[196:199], v[24:27]
	v_mfma_f32_16x16x32_bf16 v[12:15], v[44:47], v[204:207], v[12:15]
	v_mfma_f32_16x16x32_bf16 v[8:11], v[60:63], v[204:207], v[8:11]
	s_setprio 0
	s_barrier
; #define PG8_STAGE(bufoff, gbase, voff) do { _Pragma("unroll") for (int _i = 0; _i < 2; ++_i) \
;         __builtin_amdgcn_global_load_lds((const unsigned*)((const char*)(gbase) + (voff)[_i]), (LAS unsigned*)(lds + (bufoff) + ldsw + _i * 8192), 16, 0, 0); } while (0)
; #define PG8_LDA(dst, b, h) do { _Pragma("unroll") for (int m = 0; m < 4; ++m) _Pragma("unroll") for (int k = 0; k < 2; ++k) dst[m][k] = *(const LAS bf16x8*)(lds + PG8_SA(b, h) + aoff + m * 2048 + k * 1024); } while (0)
; #define PG8_LDB(dst, b, h) do { _Pragma("unroll") for (int n = 0; n < 2; ++n) _Pragma("unroll") for (int k = 0; k < 2; ++k) dst[n][k] = *(const LAS bf16x8*)(lds + PG8_SB(b, h) + boff + n * 2048 + k * 1024); } while (0)
; #define PG8_WAIT_V(n) asm volatile("s_waitcnt vmcnt(" #n ")" ::: "memory")
; #define PG8_WAIT_L(n) asm volatile("s_waitcnt lgkmcnt(" #n ")" ::: "memory")
; #define PG8_BAR __builtin_amdgcn_s_barrier()
; #define PG8_SCHED __builtin_amdgcn_sched_barrier(0)
; template <class Epi>
; __device__ __forceinline__ void gemm_phase(LAS unsigned char* lds, const Gemm g, const StaticOrder& S, const Epi& E) {
;     ...
;             PG8_LDB(B0, 0, 0); PG8_SCHED; PG8_LDA(At, 0, 0); PG8_STAGE(PG8_SA(1, 1), a1 + hstep, voffA);
;             PG8_WAIT_L(8); PG8_BAR; PG8_WAIT_L(0); PG8_MMA(0, 0, At, B0); PG8_BAR; PG8_SCHED;
;             PG8_LDB(B1, 0, 1); PG8_STAGE(PG8_SB(0, 0), b2, voffB0);
;             PG8_BAR; PG8_WAIT_L(0); PG8_MMA(0, 1, At, B1); PG8_BAR;
;             PG8_LDA(At, 0, 1); PG8_STAGE(PG8_SA(0, 0), a2, voffA);
;             PG8_BAR; PG8_WAIT_L(0); PG8_MMA(1, 0, At, B0); PG8_BAR; PG8_SCHED;
;             PG8_STAGE(PG8_SB(0, 1), b2, voffB1);
;             PG8_WAIT_V(6); PG8_BAR; PG8_MMA(1, 1, At, B1); PG8_BAR;
;             PG8_LDB(B0, 1, 0); PG8_SCHED; PG8_LDA(At, 1, 0); PG8_STAGE(PG8_SA(0, 1), a2 + hstep, voffA);
;             PG8_WAIT_L(8); PG8_BAR; PG8_WAIT_L(0); PG8_MMA(0, 0, At, B0); PG8_BAR; PG8_SCHED;
;             PG8_LDB(B1, 1, 1); PG8_STAGE(PG8_SB(1, 0), b3, voffB0);
;             PG8_BAR; PG8_WAIT_L(0); PG8_MMA(0, 1, At, B1); PG8_BAR;
;             PG8_LDA(At, 1, 1); PG8_STAGE(PG8_SA(1, 0), a3, voffA);
;             PG8_BAR; PG8_WAIT_L(0); PG8_MMA(1, 0, At, B0); PG8_BAR; PG8_SCHED;
;             PG8_STAGE(PG8_SB(1, 1), b3, voffB1);
;             PG8_WAIT_V(6); PG8_BAR; PG8_MMA(1, 1, At, B1); PG8_BAR;
	s_add_i32 s59, s52, s41
	v_lshl_add_u64 v[230:231], s[38:39], 0, v[148:149]
	s_mov_b32 m0, s59
	v_lshl_add_u64 v[232:233], s[38:39], 0, v[154:155]
	global_load_lds_dwordx4 v[230:231], off
	s_add_i32 m0, s59, 0x2000
	s_nop 0
	global_load_lds_dwordx4 v[232:233], off
	s_waitcnt vmcnt(6)
	s_barrier
	s_setprio 1
	v_mfma_f32_16x16x32_bf16 v[36:39], v[208:211], v[184:187], v[36:39]
	v_mfma_f32_16x16x32_bf16 v[32:35], v[216:219], v[184:187], v[32:35]
	v_mfma_f32_16x16x32_bf16 v[20:23], v[208:211], v[192:195], v[20:23]
	v_mfma_f32_16x16x32_bf16 v[16:19], v[216:219], v[192:195], v[16:19]
	v_mfma_f32_16x16x32_bf16 v[4:7], v[208:211], v[200:203], v[4:7]
	v_mfma_f32_16x16x32_bf16 v[0:3], v[216:219], v[200:203], v[0:3]
	v_mfma_f32_16x16x32_bf16 v[40:43], v[208:211], v[164:167], v[68:71]
	v_mfma_f32_16x16x32_bf16 v[44:47], v[216:219], v[164:167], v[64:67]
	v_mfma_f32_16x16x32_bf16 v[36:39], v[212:215], v[188:191], v[36:39]
	v_mfma_f32_16x16x32_bf16 v[32:35], v[220:223], v[188:191], v[32:35]
	v_mfma_f32_16x16x32_bf16 v[20:23], v[212:215], v[196:199], v[20:23]
	v_mfma_f32_16x16x32_bf16 v[16:19], v[220:223], v[196:199], v[16:19]
	v_mfma_f32_16x16x32_bf16 v[4:7], v[212:215], v[204:207], v[4:7]
	v_mfma_f32_16x16x32_bf16 v[0:3], v[220:223], v[204:207], v[0:3]
	v_mfma_f32_16x16x32_bf16 v[40:43], v[212:215], v[168:171], v[40:43]
	v_mfma_f32_16x16x32_bf16 v[44:47], v[220:223], v[168:171], v[44:47]
	s_setprio 0
	s_add_i32 s38, 0, 0x18000
	v_add_u32_e32 v68, s38, v175
	s_barrier
	ds_read_b128 v[56:59], v68
	ds_read_b128 v[60:63], v68 offset:1024
	ds_read_b128 v[64:67], v68 offset:2048
	ds_read_b128 v[68:71], v68 offset:3072
	s_add_u32 s36, s36, 0x80000
	s_addc_u32 s37, s37, 0
	s_mov_b32 m0, s43
	v_lshl_add_u64 v[208:209], s[36:37], 0, v[144:145]
	ds_read_b128 v[164:167], v180 offset:32768
	ds_read_b128 v[168:171], v180 offset:33792
	ds_read_b128 v[184:187], v180 offset:34816
	ds_read_b128 v[188:191], v180 offset:35840
	ds_read_b128 v[192:195], v180 offset:36864
	ds_read_b128 v[196:199], v180 offset:37888
	ds_read_b128 v[200:203], v180 offset:38912
	ds_read_b128 v[204:207], v180 offset:39936
	global_load_lds_dwordx4 v[208:209], off
	v_lshl_add_u64 v[208:209], s[36:37], 0, v[150:151]
	s_mov_b32 m0, s44
	s_nop 0
	global_load_lds_dwordx4 v[208:209], off
	s_waitcnt lgkmcnt(8)
	s_barrier
	s_waitcnt lgkmcnt(0)
	s_setprio 1
	s_waitcnt lgkmcnt(0)
	v_mfma_f32_16x16x32_bf16 v[140:143], v[56:59], v[164:167], v[140:143]
	v_mfma_f32_16x16x32_bf16 v[136:139], v[64:67], v[164:167], v[136:139]
	v_mfma_f32_16x16x32_bf16 v[124:127], v[56:59], v[184:187], v[124:127]
	v_mfma_f32_16x16x32_bf16 v[120:123], v[64:67], v[184:187], v[120:123]
	v_mfma_f32_16x16x32_bf16 v[108:111], v[56:59], v[192:195], v[108:111]
	v_mfma_f32_16x16x32_bf16 v[104:107], v[64:67], v[192:195], v[104:107]
	v_mfma_f32_16x16x32_bf16 v[92:95], v[56:59], v[200:203], v[92:95]
	v_mfma_f32_16x16x32_bf16 v[88:91], v[64:67], v[200:203], v[88:91]
	v_mfma_f32_16x16x32_bf16 v[140:143], v[60:63], v[168:171], v[140:143]
	v_mfma_f32_16x16x32_bf16 v[136:139], v[68:71], v[168:171], v[136:139]
	v_mfma_f32_16x16x32_bf16 v[124:127], v[60:63], v[188:191], v[124:127]
	v_mfma_f32_16x16x32_bf16 v[120:123], v[68:71], v[188:191], v[120:123]
	v_mfma_f32_16x16x32_bf16 v[108:111], v[60:63], v[196:199], v[108:111]
	v_mfma_f32_16x16x32_bf16 v[104:107], v[68:71], v[196:199], v[104:107]
	v_mfma_f32_16x16x32_bf16 v[92:95], v[60:63], v[204:207], v[92:95]
	v_mfma_f32_16x16x32_bf16 v[88:91], v[68:71], v[204:207], v[88:91]
	s_setprio 0
	s_barrier
	s_add_i32 s36, 0, 0x1c000
	s_add_i32 s37, s38, s41
	v_add_u32_e32 v183, s36, v175
	v_lshl_add_u64 v[172:173], v[172:173], 0, s[14:15]
	s_mov_b32 m0, s37
	ds_read_b128 v[208:211], v183
	ds_read_b128 v[212:215], v183 offset:1024
	ds_read_b128 v[216:219], v183 offset:2048
	ds_read_b128 v[220:223], v183 offset:3072
	global_load_lds_dwordx4 v[172:173], off
	v_lshl_add_u64 v[172:173], v[224:225], 0, s[14:15]
	s_add_i32 m0, s37, 0x2000
	s_nop 0
	global_load_lds_dwordx4 v[172:173], off
	s_barrier
	s_waitcnt lgkmcnt(0)
	s_setprio 1
	s_waitcnt lgkmcnt(0)
	v_mfma_f32_16x16x32_bf16 v[132:135], v[208:211], v[164:167], v[132:135]
	v_mfma_f32_16x16x32_bf16 v[128:131], v[216:219], v[164:167], v[128:131]
	v_mfma_f32_16x16x32_bf16 v[116:119], v[208:211], v[184:187], v[116:119]
	v_mfma_f32_16x16x32_bf16 v[112:115], v[216:219], v[184:187], v[112:115]
	v_mfma_f32_16x16x32_bf16 v[100:103], v[208:211], v[192:195], v[100:103]
	v_mfma_f32_16x16x32_bf16 v[96:99], v[216:219], v[192:195], v[96:99]
	v_mfma_f32_16x16x32_bf16 v[84:87], v[208:211], v[200:203], v[84:87]
	v_mfma_f32_16x16x32_bf16 v[80:83], v[216:219], v[200:203], v[80:83]
	v_mfma_f32_16x16x32_bf16 v[132:135], v[212:215], v[168:171], v[132:135]
	v_mfma_f32_16x16x32_bf16 v[128:131], v[220:223], v[168:171], v[128:131]
	v_mfma_f32_16x16x32_bf16 v[116:119], v[212:215], v[188:191], v[116:119]
	v_mfma_f32_16x16x32_bf16 v[112:115], v[220:223], v[188:191], v[112:115]
	v_mfma_f32_16x16x32_bf16 v[100:103], v[212:215], v[196:199], v[100:103]
	v_mfma_f32_16x16x32_bf16 v[96:99], v[220:223], v[196:199], v[96:99]
	v_mfma_f32_16x16x32_bf16 v[84:87], v[212:215], v[204:207], v[84:87]
	v_mfma_f32_16x16x32_bf16 v[80:83], v[220:223], v[204:207], v[80:83]
	s_setprio 0
	s_mov_b32 m0, s47
	v_lshl_add_u64 v[172:173], v[226:227], 0, s[14:15]
	s_barrier
	ds_read_b128 v[164:167], v180 offset:49152
	ds_read_b128 v[168:171], v180 offset:50176
	ds_read_b128 v[184:187], v180 offset:51200
	ds_read_b128 v[188:191], v180 offset:52224
	ds_read_b128 v[192:195], v180 offset:53248
	ds_read_b128 v[196:199], v180 offset:54272
	ds_read_b128 v[200:203], v180 offset:55296
	ds_read_b128 v[204:207], v180 offset:56320
	global_load_lds_dwordx4 v[172:173], off
	v_lshl_add_u64 v[172:173], v[228:229], 0, s[14:15]
	s_mov_b32 m0, s48
	s_nop 0
	global_load_lds_dwordx4 v[172:173], off
	s_barrier
; #define PG8_STAGE(bufoff, gbase, voff) do { _Pragma("unroll") for (int _i = 0; _i < 2; ++_i) \
;         __builtin_amdgcn_global_load_lds((const unsigned*)((const char*)(gbase) + (voff)[_i]), (LAS unsigned*)(lds + (bufoff) + ldsw + _i * 8192), 16, 0, 0); } while (0)
; #define PG8_LDA(dst, b, h) do { _Pragma("unroll") for (int m = 0; m < 4; ++m) _Pragma("unroll") for (int k = 0; k < 2; ++k) dst[m][k] = *(const LAS bf16x8*)(lds + PG8_SA(b, h) + aoff + m * 2048 + k * 1024); } while (0)
; #define PG8_LDB(dst, b, h) do { _Pragma("unroll") for (int n = 0; n < 2; ++n) _Pragma("unroll") for (int k = 0; k < 2; ++k) dst[n][k] = *(const LAS bf16x8*)(lds + PG8_SB(b, h) + boff + n * 2048 + k * 1024); } while (0)
;     __device__ __forceinline__ void operator()(const f32x4 (&acc)[2][2][4][2], const Unit& u, int wr, int wc, int fr, int fq) const {
;         const int row0 = u.pm * BM + wr * 64 + fr, col0 = u.pn * BM + wc * 64 + 8 * fq;
;         f32x4 gv[2][2];
; #pragma unroll
;         for (int bj = 0; bj < 2; ++bj) { gv[bj][0] = *(const f32x4*)(g + col0 + 32 * bj); gv[bj][1] = *(const f32x4*)(g + col0 + 32 * bj + 4); }
;         const bool lo = fr < 8;
; #pragma unroll
;         for (int ai = 0; ai < 2; ++ai)
; #pragma unroll
;             for (int m = 0; m < 4; ++m) { const int row = row0 + ai * HALF + m * 16; const float ri = __builtin_amdgcn_rsqf(sse[row] * (1.f / D) + EPS);
;                 u32x4 rr[2], ee[2]; load_pair_lines(R, D, row, fr, col0, rr[0], rr[1], 32); load_pair_lines(E, D, row, fr, col0, ee[0], ee[1], 32);
; template <class Epi>
; __device__ __forceinline__ void gemm_phase(LAS unsigned char* lds, const Gemm g, const StaticOrder& S, const Epi& E) {
;     ...
;             PG8_WAIT_V(6); PG8_BAR; PG8_MMA(1, 1, At, B1); PG8_BAR;
;             PG8_LDB(B0, 1, 0); PG8_SCHED; PG8_LDA(At, 1, 0); PG8_STAGE(PG8_SA(0, 1), a2 + hstep, voffA);
;             PG8_WAIT_L(8); PG8_BAR; PG8_WAIT_L(0); PG8_MMA(0, 0, At, B0); PG8_BAR; PG8_SCHED;
;             PG8_LDB(B1, 1, 1); PG8_STAGE(PG8_SB(1, 0), b3, voffB0);
;             PG8_BAR; PG8_WAIT_L(0); PG8_MMA(0, 1, At, B1); PG8_BAR;
;             PG8_LDA(At, 1, 1); PG8_STAGE(PG8_SA(1, 0), a3, voffA);
;             PG8_BAR; PG8_WAIT_L(0); PG8_MMA(1, 0, At, B0); PG8_BAR; PG8_SCHED;
;             PG8_STAGE(PG8_SB(1, 1), b3, voffB1);
;             PG8_WAIT_V(6); PG8_BAR; PG8_MMA(1, 1, At, B1); PG8_BAR;
	s_waitcnt lgkmcnt(0)
	s_setprio 1
	s_waitcnt lgkmcnt(0)
	v_mfma_f32_16x16x32_bf16 v[76:79], v[56:59], v[164:167], v[76:79]
	v_mfma_f32_16x16x32_bf16 v[72:75], v[64:67], v[164:167], v[72:75]
	v_mfma_f32_16x16x32_bf16 v[52:55], v[56:59], v[184:187], v[52:55]
	v_mfma_f32_16x16x32_bf16 v[48:51], v[64:67], v[184:187], v[48:51]
	v_mfma_f32_16x16x32_bf16 v[28:31], v[56:59], v[192:195], v[28:31]
	v_mfma_f32_16x16x32_bf16 v[24:27], v[64:67], v[192:195], v[24:27]
	v_mfma_f32_16x16x32_bf16 v[12:15], v[56:59], v[200:203], v[12:15]
	v_mfma_f32_16x16x32_bf16 v[8:11], v[64:67], v[200:203], v[8:11]
	v_mfma_f32_16x16x32_bf16 v[76:79], v[60:63], v[168:171], v[76:79]
	v_mfma_f32_16x16x32_bf16 v[72:75], v[68:71], v[168:171], v[72:75]
	v_mfma_f32_16x16x32_bf16 v[52:55], v[60:63], v[188:191], v[52:55]
	v_mfma_f32_16x16x32_bf16 v[48:51], v[68:71], v[188:191], v[48:51]
	v_mfma_f32_16x16x32_bf16 v[28:31], v[60:63], v[196:199], v[28:31]
	v_mfma_f32_16x16x32_bf16 v[24:27], v[68:71], v[196:199], v[24:27]
	v_mfma_f32_16x16x32_bf16 v[12:15], v[60:63], v[204:207], v[12:15]
	v_mfma_f32_16x16x32_bf16 v[8:11], v[68:71], v[204:207], v[8:11]
	s_setprio 0
	s_barrier
	s_add_i32 s36, s36, s41
	v_lshl_add_u64 v[56:57], v[230:231], 0, s[14:15]
	s_mov_b32 m0, s36
	s_nop 0
	global_load_lds_dwordx4 v[56:57], off
	v_lshl_add_u64 v[56:57], v[232:233], 0, s[14:15]
	s_add_i32 m0, s36, 0x2000
	s_nop 0
	global_load_lds_dwordx4 v[56:57], off
	s_waitcnt vmcnt(6)
	s_barrier
	s_setprio 1
	v_mfma_f32_16x16x32_bf16 v[40:43], v[208:211], v[164:167], v[40:43]
	v_mfma_f32_16x16x32_bf16 v[68:71], v[212:215], v[168:171], v[40:43]
	v_mfma_f32_16x16x32_bf16 v[40:43], v[216:219], v[164:167], v[44:47]
	v_mfma_f32_16x16x32_bf16 v[36:39], v[208:211], v[184:187], v[36:39]
	v_mfma_f32_16x16x32_bf16 v[32:35], v[216:219], v[184:187], v[32:35]
	v_mfma_f32_16x16x32_bf16 v[20:23], v[208:211], v[192:195], v[20:23]
	v_mfma_f32_16x16x32_bf16 v[16:19], v[216:219], v[192:195], v[16:19]
	v_mfma_f32_16x16x32_bf16 v[4:7], v[208:211], v[200:203], v[4:7]
	v_mfma_f32_16x16x32_bf16 v[0:3], v[216:219], v[200:203], v[0:3]
	v_mfma_f32_16x16x32_bf16 v[64:67], v[220:223], v[168:171], v[40:43]
	v_mfma_f32_16x16x32_bf16 v[36:39], v[212:215], v[188:191], v[36:39]
	v_mfma_f32_16x16x32_bf16 v[32:35], v[220:223], v[188:191], v[32:35]
	v_mfma_f32_16x16x32_bf16 v[20:23], v[212:215], v[196:199], v[20:23]
	v_mfma_f32_16x16x32_bf16 v[16:19], v[220:223], v[196:199], v[16:19]
	v_mfma_f32_16x16x32_bf16 v[4:7], v[212:215], v[204:207], v[4:7]
	v_mfma_f32_16x16x32_bf16 v[0:3], v[220:223], v[204:207], v[0:3]
	s_setprio 0
	s_add_i32 s58, s58, 2
	s_add_u32 s34, s34, 0x100
	s_addc_u32 s35, s35, 0
	s_add_u32 s56, s56, 0x100
	s_addc_u32 s57, s57, 0
	s_cmp_gt_u32 s58, 29
	s_barrier
	s_cbranch_scc0 .LBB0_1603
	s_lshl_b32 s19, s30, 8
	s_add_i32 s19, s19, s49
	v_lshl_or_b32 v40, s53, 8, v178
	v_or_b32_e32 v172, s19, v176
	v_or_b32_e32 v42, v40, v177
	v_ashrrev_i32_e32 v173, 31, v172
	v_or_b32_e32 v170, s19, v174
	v_ashrrev_i32_e32 v43, 31, v42
	v_lshlrev_b64 v[44:45], 12, v[172:173]
	v_ashrrev_i32_e32 v171, 31, v170
	v_lshl_add_u64 v[46:47], s[8:9], 0, v[44:45]
	v_lshlrev_b64 v[164:165], 1, v[42:43]
	v_lshl_add_u64 v[168:169], v[170:171], 2, s[6:7]
	v_lshl_add_u64 v[42:43], v[46:47], 0, v[164:165]
	global_load_dword v171, v[168:169], off
	global_load_dwordx4 v[184:187], v[42:43], off
	v_or_b32_e32 v42, 8, v172
	v_ashrrev_i32_e32 v43, 31, v42
	v_lshlrev_b64 v[42:43], 12, v[42:43]
	v_lshl_add_u64 v[46:47], s[8:9], 0, v[42:43]
	v_lshl_add_u64 v[44:45], s[10:11], 0, v[44:45]
	v_lshl_add_u64 v[42:43], s[10:11], 0, v[42:43]
	v_lshl_add_u64 v[46:47], v[46:47], 0, v[164:165]
	v_lshl_add_u64 v[44:45], v[44:45], 0, v[164:165]
	v_lshl_add_u64 v[42:43], v[42:43], 0, v[164:165]
	global_load_dwordx4 v[188:191], v[46:47], off
	global_load_dwordx4 v[192:195], v[44:45], off
	global_load_dwordx4 v[196:199], v[42:43], off
	v_ashrrev_i32_e32 v41, 31, v40
	v_lshlrev_b64 v[166:167], 2, v[40:41]
	v_lshl_add_u64 v[44:45], s[12:13], 0, v[166:167]
	global_load_dwordx4 v[56:59], v[44:45], off
	global_load_dwordx4 v[60:63], v[44:45], off offset:16
	v_mul_f32_e32 v40, 0xbfb8aa3b, v140
	v_exp_f32_e32 v215, v40
	global_load_dwordx4 v[40:43], v[44:45], off offset:128
	s_nop 0
	global_load_dwordx4 v[44:47], v[44:45], off offset:144
	v_or_b32_e32 v216, 16, v170
	v_ashrrev_i32_e32 v217, 31, v216
	v_lshl_add_u64 v[218:219], v[216:217], 2, s[6:7]
	v_sub_u32_e32 v216, v216, v174
	v_add_u32_e32 v222, v216, v176
	v_ashrrev_i32_e32 v223, 31, v222
	v_lshlrev_b64 v[216:217], 12, v[222:223]
	v_lshl_add_u64 v[224:225], v[216:217], 0, s[16:17]
	global_load_dword v228, v[218:219], off
	v_lshl_add_u64 v[218:219], s[8:9], 0, v[216:217]
	v_lshl_add_u64 v[220:221], s[8:9], 0, v[224:225]
	v_lshl_add_u64 v[216:217], s[10:11], 0, v[216:217]
	v_lshl_add_u64 v[218:219], v[218:219], 0, v[164:165]
	v_lshl_add_u64 v[220:221], v[220:221], 0, v[164:165]
	v_lshl_add_u64 v[216:217], v[216:217], 0, v[164:165]
	global_load_dwordx4 v[232:235], v[218:219], off
	global_load_dwordx4 v[236:239], v[220:221], off
	global_load_dwordx4 v[240:243], v[216:217], off
	v_lshl_add_u64 v[216:217], s[10:11], 0, v[224:225]
	v_lshl_add_u64 v[216:217], v[216:217], 0, v[164:165]
	global_load_dwordx4 v[244:247], v[216:217], off
	v_mul_f32_e32 v141, 0xbfb8aa3b, v141
	v_mul_f32_e32 v136, 0xbfb8aa3b, v136
	v_mul_f32_e32 v137, 0xbfb8aa3b, v137
	v_exp_f32_e32 v141, v141
	v_mul_f32_e32 v142, 0xbfb8aa3b, v142
	v_exp_f32_e32 v136, v136
	v_exp_f32_e32 v137, v137
	v_exp_f32_e32 v142, v142
	v_mul_f32_e32 v143, 0xbfb8aa3b, v143
	v_exp_f32_e32 v143, v143
	v_mov_b32_e32 v200, 0
	v_mov_b32_e32 v204, 0
	v_mov_b32_e32 v213, 0
	v_mov_b32_e32 v183, 0
	v_add_f32_e32 v141, 1.0, v141
	v_add_f32_e32 v136, 1.0, v136
	v_add_f32_e32 v137, 1.0, v137
	v_mov_b32_e32 v201, 0
	v_mov_b32_e32 v203, 0
	v_mov_b32_e32 v205, 0
	v_mov_b32_e32 v206, 0
	v_rcp_f32_e32 v136, v136
	v_rcp_f32_e32 v137, v137
	v_mov_b32_e32 v202, 0
	v_mul_f32_e32 v138, 0xbfb8aa3b, v138
	v_mul_f32_e32 v139, 0xbfb8aa3b, v139
	v_mov_b32_e32 v211, 0
	v_exp_f32_e32 v138, v138
	v_exp_f32_e32 v139, v139
	v_mov_b32_e32 v207, 0
	v_mov_b32_e32 v214, 0
	v_mov_b32_e32 v210, 0
	v_add_f32_e32 v138, 1.0, v138
	v_add_f32_e32 v139, 1.0, v139
	v_rcp_f32_e32 v138, v138
	v_rcp_f32_e32 v139, v139
	v_mov_b32_e32 v212, 0
	v_mov_b32_e32 v208, 0
	v_mul_f32_e32 v128, 0xbfb8aa3b, v128
	v_mul_f32_e32 v129, 0xbfb8aa3b, v129
	v_exp_f32_e32 v128, v128
	v_exp_f32_e32 v129, v129
	v_mul_f32_e32 v132, 0xbfb8aa3b, v132
	v_mul_f32_e32 v133, 0xbfb8aa3b, v133
	v_mov_b32_e32 v209, 0
	v_exp_f32_e32 v132, v132
	v_exp_f32_e32 v133, v133
	v_lshlrev_b64 v[172:173], 13, v[172:173]
	v_add_f32_e32 v128, 1.0, v128
	v_add_f32_e32 v129, 1.0, v129
	v_lshl_add_u64 v[172:173], s[4:5], 0, v[172:173]
	v_rcp_f32_e32 v128, v128
	v_mul_f32_e32 v130, 0xbfb8aa3b, v130
	v_mul_f32_e32 v131, 0xbfb8aa3b, v131
	v_rcp_f32_e32 v129, v129
	v_lshl_add_u64 v[172:173], v[172:173], 0, v[166:167]
	v_exp_f32_e32 v130, v130
	v_exp_f32_e32 v131, v131
	v_lshl_add_u64 v[172:173], v[172:173], 0, v[156:157]
	s_waitcnt vmcnt(5)
; __device__ __forceinline__ float bflo(unsigned w) { return __uint_as_float(w << 16); }
; __device__ __forceinline__ float bfhi(unsigned w) { return __uint_as_float(w & 0xffff0000u); }
; __device__ __forceinline__ unsigned dpp_ror8(unsigned x) { return (unsigned)__builtin_amdgcn_update_dpp(0, (int)x, 0x128, 0xf, 0xf, false); }
;     __device__ __forceinline__ void operator()(const f32x4 (&acc)[2][2][4][2], const Unit& u, int wr, int wc, int fr, int fq) const {
;     ...
;             for (int m = 0; m < 4; ++m) { const int row = row0 + ai * HALF + m * 16; const float ri = __builtin_amdgcn_rsqf(sse[row] * (1.f / D) + EPS);
;                 u32x4 rr[2], ee[2]; load_pair_lines(R, D, row, fr, col0, rr[0], rr[1], 32); load_pair_lines(E, D, row, fr, col0, ee[0], ee[1], 32);
;                 float* orow = OUT + (size_t)(row - fr + (fr & 7)) * D + col0 + (lo ? 0 : 4);
; #pragma unroll
;                 for (int bj = 0; bj < 2; ++bj) { const u32x4 rw = rr[bj], ew = ee[bj];
;                     const float r[8] = {bflo(rw.x), bfhi(rw.x), bflo(rw.y), bfhi(rw.y), bflo(rw.z), bfhi(rw.z), bflo(rw.w), bfhi(rw.w)};
;                     const float e[8] = {bflo(ew.x), bfhi(ew.x), bflo(ew.y), bfhi(ew.y), bflo(ew.z), bfhi(ew.z), bflo(ew.w), bfhi(ew.w)};
;                     float o[8];
; #pragma unroll
;                     for (int j = 0; j < 8; ++j) { const float a = acc[ai][bj][m][j >> 2][j & 3]; const float gg = gv[bj][j >> 2][j & 3];
;                         o[j] = r[j] + e[j] * ri * gg * __builtin_amdgcn_rcpf(1.f + __builtin_amdgcn_exp2f(-a * LOG2E)); }
;                     f32x4 o1, o2;
; #pragma unroll
;                     for (int j = 0; j < 4; ++j) { const unsigned a = __float_as_uint(o[j]), b = __float_as_uint(o[4 + j]); const unsigned sa = dpp_ror8(a), sb = dpp_ror8(b);
;                         o1[j] = __uint_as_float(lo ? a : sb); o2[j] = __uint_as_float(lo ? sa : b); }
;                     *(f32x4*)(orow + 32 * bj) = o1; *(f32x4*)(orow + (size_t)8 * D + 32 * bj) = o2; } }
	v_fmamk_f32 v140, v171, 0x3a000000, v182
	v_rsq_f32_e32 v140, v140
	v_mov_b32_dpp v200, v185 row_ror:8 row_mask:0xf bank_mask:0xf
	v_mov_b32_dpp v183, v184 row_ror:8 row_mask:0xf bank_mask:0xf
	v_mov_b32_dpp v201, v186 row_ror:8 row_mask:0xf bank_mask:0xf
	v_mov_b32_dpp v202, v187 row_ror:8 row_mask:0xf bank_mask:0xf
	v_add_f32_e32 v132, 1.0, v132
	v_add_f32_e32 v133, 1.0, v133
	v_rcp_f32_e32 v132, v132
	v_mul_f32_e32 v134, 0xbfb8aa3b, v134
	v_mul_f32_e32 v135, 0xbfb8aa3b, v135
	v_mov_b32_dpp v204, v189 row_ror:8 row_mask:0xf bank_mask:0xf
	v_cndmask_b32_e64 v171, v189, v200, s[0:1]
	v_mov_b32_dpp v213, v198 row_ror:8 row_mask:0xf bank_mask:0xf
	v_cndmask_b32_e64 v200, v204, v185, s[0:1]
	v_cndmask_b32_e64 v189, v213, v194, s[0:1]
	v_rcp_f32_e32 v185, v141
	v_add_f32_e32 v141, 1.0, v142
	v_mov_b32_dpp v203, v188 row_ror:8 row_mask:0xf bank_mask:0xf
	v_mov_b32_dpp v205, v190 row_ror:8 row_mask:0xf bank_mask:0xf
	v_mov_b32_dpp v206, v191 row_ror:8 row_mask:0xf bank_mask:0xf
	v_cndmask_b32_e64 v183, v188, v183, s[0:1]
	v_rcp_f32_e32 v142, v141
	v_add_f32_e32 v141, 1.0, v143
	v_lshlrev_b32_e32 v188, 16, v189
	v_and_b32_e32 v189, 0xffff0000, v189
	v_cndmask_b32_e64 v190, v190, v201, s[0:1]
	v_cndmask_b32_e64 v201, v206, v187, s[0:1]
	v_cndmask_b32_e64 v187, v205, v186, s[0:1]
	v_pk_mul_f32 v[188:189], v[140:141], v[188:189] op_sel_hi:[0,1]
	v_cndmask_b32_e64 v191, v191, v202, s[0:1]
	v_mov_b32_dpp v211, v196 row_ror:8 row_mask:0xf bank_mask:0xf
	v_cndmask_b32_e64 v202, v203, v184, s[0:1]
	v_add_f32_e32 v184, 1.0, v215
	v_lshlrev_b32_e32 v186, 16, v187
	v_and_b32_e32 v187, 0xffff0000, v187
	v_pk_mul_f32 v[188:189], v[60:61], v[188:189]
	v_mov_b32_dpp v207, v192 row_ror:8 row_mask:0xf bank_mask:0xf
	v_cndmask_b32_e64 v192, v211, v192, s[0:1]
	v_rcp_f32_e32 v184, v184
	v_rcp_f32_e32 v143, v141
	v_pk_fma_f32 v[188:189], v[136:137], v[188:189], v[186:187]
	v_mov_b32_e32 v141, v157
	v_lshlrev_b32_e32 v186, 16, v192
	v_and_b32_e32 v187, 0xffff0000, v192
	v_mov_b32_dpp v141, v188 row_ror:8 row_mask:0xf bank_mask:0xf
	v_mov_b32_dpp v214, v199 row_ror:8 row_mask:0xf bank_mask:0xf
	v_pk_mul_f32 v[186:187], v[140:141], v[186:187] op_sel_hi:[0,1]
	v_mov_b32_dpp v210, v195 row_ror:8 row_mask:0xf bank_mask:0xf
	v_cndmask_b32_e64 v195, v214, v195, s[0:1]
	v_lshlrev_b32_e32 v136, 16, v202
	v_and_b32_e32 v137, 0xffff0000, v202
	v_pk_mul_f32 v[186:187], v[56:57], v[186:187]
	v_mov_b32_dpp v212, v197 row_ror:8 row_mask:0xf bank_mask:0xf
	v_pk_fma_f32 v[136:137], v[184:185], v[186:187], v[136:137]
	v_lshlrev_b32_e32 v186, 16, v195
	v_and_b32_e32 v187, 0xffff0000, v195
	v_pk_mul_f32 v[186:187], v[140:141], v[186:187] op_sel_hi:[0,1]
	v_mov_b32_dpp v208, v193 row_ror:8 row_mask:0xf bank_mask:0xf
	v_cndmask_b32_e64 v193, v212, v193, s[0:1]
	v_lshlrev_b32_e32 v184, 16, v201
	v_and_b32_e32 v185, 0xffff0000, v201
	v_pk_mul_f32 v[186:187], v[62:63], v[186:187]
	v_mov_b32_dpp v209, v194 row_ror:8 row_mask:0xf bank_mask:0xf
	v_pk_fma_f32 v[184:185], v[138:139], v[186:187], v[184:185]
	v_lshlrev_b32_e32 v186, 16, v193
	v_and_b32_e32 v187, 0xffff0000, v193
	v_pk_mul_f32 v[186:187], v[140:141], v[186:187] op_sel_hi:[0,1]
	v_lshlrev_b32_e32 v138, 16, v200
	v_and_b32_e32 v139, 0xffff0000, v200
	v_pk_mul_f32 v[186:187], v[58:59], v[186:187]
	v_cndmask_b32_e64 v194, v197, v208, s[0:1]
	v_pk_fma_f32 v[138:139], v[142:143], v[186:187], v[138:139]
	v_mov_b32_e32 v142, v157
	v_mov_b32_e32 v143, v157
	v_cndmask_b32_e64 v197, v199, v210, s[0:1]
	v_cndmask_b32_e64 v198, v198, v209, s[0:1]
	v_mov_b32_e32 v199, v157
	v_mov_b32_e32 v195, v157
	v_mov_b32_e32 v201, v157
	v_mov_b32_dpp v142, v138 row_ror:8 row_mask:0xf bank_mask:0xf
	v_mov_b32_dpp v143, v139 row_ror:8 row_mask:0xf bank_mask:0xf
	v_mov_b32_dpp v199, v189 row_ror:8 row_mask:0xf bank_mask:0xf
	v_mov_b32_e32 v192, v157
	v_mov_b32_e32 v202, v157
	v_mov_b32_dpp v195, v184 row_ror:8 row_mask:0xf bank_mask:0xf
	v_mov_b32_dpp v201, v185 row_ror:8 row_mask:0xf bank_mask:0xf
	v_cndmask_b32_e64 v187, v185, v143, s[0:1]
	v_cndmask_b32_e64 v186, v184, v142, s[0:1]
	v_lshlrev_b32_e32 v142, 16, v198
	v_and_b32_e32 v143, 0xffff0000, v198
	v_mov_b32_dpp v192, v136 row_ror:8 row_mask:0xf bank_mask:0xf
	v_mov_b32_dpp v202, v137 row_ror:8 row_mask:0xf bank_mask:0xf
	v_cndmask_b32_e64 v139, v201, v139, s[0:1]
	v_cndmask_b32_e64 v138, v195, v138, s[0:1]
	v_cndmask_b32_e64 v137, v199, v137, s[0:1]
	v_cndmask_b32_e64 v136, v141, v136, s[0:1]
	v_pk_mul_f32 v[142:143], v[140:141], v[142:143] op_sel_hi:[0,1]
	v_cndmask_b32_e64 v196, v196, v207, s[0:1]
	global_store_dwordx4 v[172:173], v[136:139], off
	v_rcp_f32_e32 v133, v133
	v_pk_mul_f32 v[142:143], v[44:45], v[142:143]
	v_lshlrev_b32_e32 v138, 16, v190
	v_and_b32_e32 v139, 0xffff0000, v190
	v_exp_f32_e32 v134, v134
	v_exp_f32_e32 v135, v135
	v_pk_fma_f32 v[138:139], v[128:129], v[142:143], v[138:139]
	v_lshlrev_b32_e32 v142, 16, v196
	v_and_b32_e32 v143, 0xffff0000, v196
	v_add_f32_e32 v130, 1.0, v130
	v_add_f32_e32 v131, 1.0, v131
	v_pk_mul_f32 v[142:143], v[140:141], v[142:143] op_sel_hi:[0,1]
	v_rcp_f32_e32 v130, v130
	v_rcp_f32_e32 v131, v131
	v_lshlrev_b32_e32 v128, 16, v183
	v_and_b32_e32 v129, 0xffff0000, v183
	v_pk_mul_f32 v[142:143], v[40:41], v[142:143]
	v_add_f32_e32 v134, 1.0, v134
	v_pk_fma_f32 v[128:129], v[132:133], v[142:143], v[128:129]
	v_lshlrev_b32_e32 v142, 16, v197
	v_and_b32_e32 v143, 0xffff0000, v197
	v_add_f32_e32 v135, 1.0, v135
	v_pk_mul_f32 v[142:143], v[140:141], v[142:143] op_sel_hi:[0,1]
	v_rcp_f32_e32 v134, v134
	v_rcp_f32_e32 v135, v135
	v_lshlrev_b32_e32 v132, 16, v191
	v_and_b32_e32 v133, 0xffff0000, v191
	v_pk_mul_f32 v[142:143], v[46:47], v[142:143]
; __device__ __forceinline__ float bflo(unsigned w) { return __uint_as_float(w << 16); }
; __device__ __forceinline__ float bfhi(unsigned w) { return __uint_as_float(w & 0xffff0000u); }
; __device__ __forceinline__ unsigned dpp_ror8(unsigned x) { return (unsigned)__builtin_amdgcn_update_dpp(0, (int)x, 0x128, 0xf, 0xf, false); }
;     __device__ __forceinline__ void operator()(const f32x4 (&acc)[2][2][4][2], const Unit& u, int wr, int wc, int fr, int fq) const {
;     ...
;             for (int m = 0; m < 4; ++m) { const int row = row0 + ai * HALF + m * 16; const float ri = __builtin_amdgcn_rsqf(sse[row] * (1.f / D) + EPS);
;                 u32x4 rr[2], ee[2]; load_pair_lines(R, D, row, fr, col0, rr[0], rr[1], 32); load_pair_lines(E, D, row, fr, col0, ee[0], ee[1], 32);
;                 float* orow = OUT + (size_t)(row - fr + (fr & 7)) * D + col0 + (lo ? 0 : 4);
; #pragma unroll
;                 for (int bj = 0; bj < 2; ++bj) { const u32x4 rw = rr[bj], ew = ee[bj];
;                     const float r[8] = {bflo(rw.x), bfhi(rw.x), bflo(rw.y), bfhi(rw.y), bflo(rw.z), bfhi(rw.z), bflo(rw.w), bfhi(rw.w)};
;                     const float e[8] = {bflo(ew.x), bfhi(ew.x), bflo(ew.y), bfhi(ew.y), bflo(ew.z), bfhi(ew.z), bflo(ew.w), bfhi(ew.w)};
;                     float o[8];
; #pragma unroll
;                     for (int j = 0; j < 8; ++j) { const float a = acc[ai][bj][m][j >> 2][j & 3]; const float gg = gv[bj][j >> 2][j & 3];
;                         o[j] = r[j] + e[j] * ri * gg * __builtin_amdgcn_rcpf(1.f + __builtin_amdgcn_exp2f(-a * LOG2E)); }
;                     f32x4 o1, o2;
; #pragma unroll
;                     for (int j = 0; j < 4; ++j) { const unsigned a = __float_as_uint(o[j]), b = __float_as_uint(o[4 + j]); const unsigned sa = dpp_ror8(a), sb = dpp_ror8(b);
;                         o1[j] = __uint_as_float(lo ? a : sb); o2[j] = __uint_as_float(lo ? sa : b); }
;                     *(f32x4*)(orow + 32 * bj) = o1; *(f32x4*)(orow + (size_t)8 * D + 32 * bj) = o2; } }
	v_add_co_u32_e32 v136, vcc, s45, v172
	v_pk_fma_f32 v[132:133], v[130:131], v[142:143], v[132:133]
	v_lshlrev_b32_e32 v142, 16, v194
	v_and_b32_e32 v143, 0xffff0000, v194
	v_cndmask_b32_e64 v185, v189, v202, s[0:1]
	v_cndmask_b32_e64 v184, v188, v192, s[0:1]
	v_addc_co_u32_e32 v137, vcc, 0, v173, vcc
	v_pk_mul_f32 v[140:141], v[140:141], v[142:143] op_sel_hi:[0,1]
	global_store_dwordx4 v[136:137], v[184:187], off
	v_mov_b32_e32 v188, v157
	v_lshlrev_b32_e32 v130, 16, v171
	v_mov_b32_e32 v184, v157
	v_mov_b32_e32 v185, v157
	v_mov_b32_e32 v187, v157
	v_and_b32_e32 v131, 0xffff0000, v171
	v_pk_mul_f32 v[140:141], v[42:43], v[140:141]
	v_mov_b32_dpp v184, v138 row_ror:8 row_mask:0xf bank_mask:0xf
	v_mov_b32_dpp v185, v139 row_ror:8 row_mask:0xf bank_mask:0xf
	v_mov_b32_e32 v183, v157
	v_mov_b32_e32 v186, v157
	v_mov_b32_dpp v187, v132 row_ror:8 row_mask:0xf bank_mask:0xf
	v_mov_b32_dpp v188, v133 row_ror:8 row_mask:0xf bank_mask:0xf
	v_pk_fma_f32 v[130:131], v[134:135], v[140:141], v[130:131]
	v_mov_b32_e32 v134, v157
	v_mov_b32_e32 v135, v157
	v_mov_b32_dpp v183, v128 row_ror:8 row_mask:0xf bank_mask:0xf
	v_mov_b32_dpp v186, v129 row_ror:8 row_mask:0xf bank_mask:0xf
	v_mov_b32_dpp v134, v130 row_ror:8 row_mask:0xf bank_mask:0xf
	v_mov_b32_dpp v135, v131 row_ror:8 row_mask:0xf bank_mask:0xf
	v_cndmask_b32_e64 v131, v188, v131, s[0:1]
	v_cndmask_b32_e64 v130, v187, v130, s[0:1]
	v_cndmask_b32_e64 v129, v185, v129, s[0:1]
	v_cndmask_b32_e64 v128, v184, v128, s[0:1]
	v_cndmask_b32_e64 v135, v133, v135, s[0:1]
	v_cndmask_b32_e64 v134, v132, v134, s[0:1]
	v_cndmask_b32_e64 v133, v139, v186, s[0:1]
	v_cndmask_b32_e64 v132, v138, v183, s[0:1]
	global_store_dwordx4 v[172:173], v[128:131], off offset:128
	global_store_dwordx4 v[136:137], v[132:135], off offset:128
	v_mov_b32_e32 v183, v157
	v_or_b32_e32 v128, 16, v170
	v_ashrrev_i32_e32 v129, 31, v128
	v_lshl_add_u64 v[130:131], v[128:129], 2, s[6:7]
	v_sub_u32_e32 v128, v128, v174
	v_add_u32_e32 v142, v128, v176
	v_ashrrev_i32_e32 v143, 31, v142
	v_lshlrev_b64 v[128:129], 12, v[142:143]
	v_lshl_add_u64 v[172:173], v[128:129], 0, s[16:17]
	s_waitcnt vmcnt(4)
	s_nop 0
	v_mov_b32_e32 v171, v228
	v_lshl_add_u64 v[130:131], s[8:9], 0, v[128:129]
	v_lshl_add_u64 v[134:135], s[8:9], 0, v[172:173]
	v_lshl_add_u64 v[128:129], s[10:11], 0, v[128:129]
	v_lshl_add_u64 v[130:131], v[130:131], 0, v[164:165]
	v_lshl_add_u64 v[134:135], v[134:135], 0, v[164:165]
	v_lshl_add_u64 v[128:129], v[128:129], 0, v[164:165]
	v_mov_b64_e32 v[130:131], v[232:233]
	v_mov_b64_e32 v[132:133], v[234:235]
	v_mov_b32_e32 v189, v157
	v_mov_b64_e32 v[134:135], v[236:237]
	v_mov_b64_e32 v[136:137], v[238:239]
	v_mov_b32_e32 v190, v157
	v_mov_b64_e32 v[138:139], v[240:241]
	v_mov_b64_e32 v[140:141], v[242:243]
	v_lshl_add_u64 v[128:129], s[10:11], 0, v[172:173]
	v_lshl_add_u64 v[128:129], v[128:129], 0, v[164:165]
	v_mov_b64_e32 v[184:185], v[244:245]
	v_mov_b64_e32 v[186:187], v[246:247]
	s_nop 1
	v_or_b32_e32 v216, 32, v170
	v_ashrrev_i32_e32 v217, 31, v216
	v_lshl_add_u64 v[218:219], v[216:217], 2, s[6:7]
	v_sub_u32_e32 v216, v216, v174
	v_add_u32_e32 v224, v216, v176
	v_ashrrev_i32_e32 v225, 31, v224
	v_lshlrev_b64 v[216:217], 12, v[224:225]
	v_lshl_add_u64 v[222:223], v[216:217], 0, s[16:17]
	v_lshl_add_u64 v[220:221], s[8:9], 0, v[222:223]
	global_load_dword v228, v[218:219], off
	v_lshl_add_u64 v[218:219], s[8:9], 0, v[216:217]
	v_lshl_add_u64 v[220:221], v[220:221], 0, v[164:165]
	v_lshl_add_u64 v[216:217], s[10:11], 0, v[216:217]
	v_lshl_add_u64 v[218:219], v[218:219], 0, v[164:165]
	global_load_dwordx4 v[232:235], v[220:221], off
	v_lshl_add_u64 v[216:217], v[216:217], 0, v[164:165]
	global_load_dwordx4 v[236:239], v[218:219], off
	global_load_dwordx4 v[240:243], v[216:217], off
	v_lshl_add_u64 v[216:217], s[10:11], 0, v[222:223]
	v_lshl_add_u64 v[216:217], v[216:217], 0, v[164:165]
	global_load_dwordx4 v[244:247], v[216:217], off
	v_mov_b32_e32 v173, v157
	v_mov_b32_e32 v129, v157
	v_mov_b32_e32 v172, v157
	v_mov_b32_e32 v188, v157
	v_mul_f32_e32 v120, 0xbfb8aa3b, v120
	v_mul_f32_e32 v121, 0xbfb8aa3b, v121
	v_mul_f32_e32 v124, 0xbfb8aa3b, v124
	v_exp_f32_e32 v120, v120
	v_exp_f32_e32 v121, v121
	v_mul_f32_e32 v122, 0xbfb8aa3b, v122
	v_mul_f32_e32 v123, 0xbfb8aa3b, v123
	v_add_f32_e32 v120, 1.0, v120
	v_add_f32_e32 v121, 1.0, v121
	v_rcp_f32_e32 v120, v120
	v_rcp_f32_e32 v121, v121
	v_exp_f32_e32 v122, v122
	v_exp_f32_e32 v123, v123
	v_mul_f32_e32 v126, 0xbfb8aa3b, v126
	v_mul_f32_e32 v127, 0xbfb8aa3b, v127
	v_exp_f32_e32 v126, v126
	v_exp_f32_e32 v127, v127
	v_add_f32_e32 v122, 1.0, v122
	v_add_f32_e32 v123, 1.0, v123
	v_rcp_f32_e32 v122, v122
	v_rcp_f32_e32 v123, v123
	v_add_f32_e32 v126, 1.0, v126
	v_add_f32_e32 v127, 1.0, v127
	v_mul_f32_e32 v112, 0xbfb8aa3b, v112
	v_mul_f32_e32 v113, 0xbfb8aa3b, v113
	v_rcp_f32_e32 v126, v126
	v_rcp_f32_e32 v127, v127
	v_exp_f32_e32 v112, v112
	v_exp_f32_e32 v113, v113
	v_mul_f32_e32 v116, 0xbfb8aa3b, v116
	v_mul_f32_e32 v117, 0xbfb8aa3b, v117
	v_exp_f32_e32 v116, v116
	v_exp_f32_e32 v117, v117
	v_add_f32_e32 v112, 1.0, v112
	v_add_f32_e32 v113, 1.0, v113
	v_rcp_f32_e32 v112, v112
	v_rcp_f32_e32 v113, v113
	v_mul_f32_e32 v114, 0xbfb8aa3b, v114
	v_mul_f32_e32 v115, 0xbfb8aa3b, v115
	v_add_f32_e32 v116, 1.0, v116
	v_add_f32_e32 v117, 1.0, v117
	v_exp_f32_e32 v114, v114
	v_exp_f32_e32 v115, v115
	v_rcp_f32_e32 v116, v116
	v_rcp_f32_e32 v117, v117
	v_mul_f32_e32 v118, 0xbfb8aa3b, v118
	v_mul_f32_e32 v119, 0xbfb8aa3b, v119
	v_exp_f32_e32 v118, v118
	v_exp_f32_e32 v119, v119
	v_add_f32_e32 v114, 1.0, v114
	v_add_f32_e32 v115, 1.0, v115
	v_rcp_f32_e32 v114, v114
	v_rcp_f32_e32 v115, v115
; __device__ __forceinline__ float bflo(unsigned w) { return __uint_as_float(w << 16); }
; __device__ __forceinline__ float bfhi(unsigned w) { return __uint_as_float(w & 0xffff0000u); }
; __device__ __forceinline__ unsigned dpp_ror8(unsigned x) { return (unsigned)__builtin_amdgcn_update_dpp(0, (int)x, 0x128, 0xf, 0xf, false); }
;     __device__ __forceinline__ void operator()(const f32x4 (&acc)[2][2][4][2], const Unit& u, int wr, int wc, int fr, int fq) const {
;     ...
;             for (int m = 0; m < 4; ++m) { const int row = row0 + ai * HALF + m * 16; const float ri = __builtin_amdgcn_rsqf(sse[row] * (1.f / D) + EPS);
;                 u32x4 rr[2], ee[2]; load_pair_lines(R, D, row, fr, col0, rr[0], rr[1], 32); load_pair_lines(E, D, row, fr, col0, ee[0], ee[1], 32);
;                 float* orow = OUT + (size_t)(row - fr + (fr & 7)) * D + col0 + (lo ? 0 : 4);
; #pragma unroll
;                 for (int bj = 0; bj < 2; ++bj) { const u32x4 rw = rr[bj], ew = ee[bj];
;                     const float r[8] = {bflo(rw.x), bfhi(rw.x), bflo(rw.y), bfhi(rw.y), bflo(rw.z), bfhi(rw.z), bflo(rw.w), bfhi(rw.w)};
;                     const float e[8] = {bflo(ew.x), bfhi(ew.x), bflo(ew.y), bfhi(ew.y), bflo(ew.z), bfhi(ew.z), bflo(ew.w), bfhi(ew.w)};
;                     float o[8];
; #pragma unroll
;                     for (int j = 0; j < 8; ++j) { const float a = acc[ai][bj][m][j >> 2][j & 3]; const float gg = gv[bj][j >> 2][j & 3];
;                         o[j] = r[j] + e[j] * ri * gg * __builtin_amdgcn_rcpf(1.f + __builtin_amdgcn_exp2f(-a * LOG2E)); }
;                     f32x4 o1, o2;
; #pragma unroll
;                     for (int j = 0; j < 4; ++j) { const unsigned a = __float_as_uint(o[j]), b = __float_as_uint(o[4 + j]); const unsigned sa = dpp_ror8(a), sb = dpp_ror8(b);
;                         o1[j] = __uint_as_float(lo ? a : sb); o2[j] = __uint_as_float(lo ? sa : b); }
;                     *(f32x4*)(orow + 32 * bj) = o1; *(f32x4*)(orow + (size_t)8 * D + 32 * bj) = o2; } }
	v_add_f32_e32 v118, 1.0, v118
	v_add_f32_e32 v119, 1.0, v119
	v_rcp_f32_e32 v118, v118
	v_rcp_f32_e32 v119, v119
	v_mul_f32_e32 v104, 0xbfb8aa3b, v104
	v_mul_f32_e32 v105, 0xbfb8aa3b, v105
	v_mul_f32_e32 v108, 0xbfb8aa3b, v108
	v_exp_f32_e32 v104, v104
	v_fmamk_f32 v128, v171, 0x3a000000, v182
	v_mov_b32_e32 v171, v157
	v_rsq_f32_e32 v128, v128
	v_exp_f32_e32 v105, v105
	v_add_f32_e32 v104, 1.0, v104
	v_rcp_f32_e32 v104, v104
	v_mul_f32_e32 v106, 0xbfb8aa3b, v106
	v_mov_b32_dpp v171, v131 row_ror:8 row_mask:0xf bank_mask:0xf
	v_mov_b32_dpp v173, v133 row_ror:8 row_mask:0xf bank_mask:0xf
	v_mov_b32_dpp v183, v134 row_ror:8 row_mask:0xf bank_mask:0xf
	v_mov_b32_dpp v189, v136 row_ror:8 row_mask:0xf bank_mask:0xf
	v_mov_b32_dpp v190, v137 row_ror:8 row_mask:0xf bank_mask:0xf
	v_mov_b32_dpp v129, v130 row_ror:8 row_mask:0xf bank_mask:0xf
	v_mov_b32_dpp v172, v132 row_ror:8 row_mask:0xf bank_mask:0xf
	v_mov_b32_dpp v188, v135 row_ror:8 row_mask:0xf bank_mask:0xf
	v_cndmask_b32_e64 v190, v190, v133, s[0:1]
	v_cndmask_b32_e64 v183, v183, v130, s[0:1]
	v_cndmask_b32_e64 v133, v189, v132, s[0:1]
	v_cndmask_b32_e64 v171, v135, v171, s[0:1]
	v_cndmask_b32_e64 v137, v137, v173, s[0:1]
	v_mov_b32_e32 v130, v157
	v_mov_b32_e32 v132, v157
	v_mov_b32_e32 v135, v157
	v_mov_b32_e32 v173, v157
	v_cndmask_b32_e64 v129, v134, v129, s[0:1]
	v_cndmask_b32_e64 v136, v136, v172, s[0:1]
	v_mov_b32_dpp v130, v138 row_ror:8 row_mask:0xf bank_mask:0xf
	v_mov_b32_dpp v132, v140 row_ror:8 row_mask:0xf bank_mask:0xf
	v_mov_b32_e32 v134, v157
	v_mov_b32_dpp v135, v184 row_ror:8 row_mask:0xf bank_mask:0xf
	v_mov_b32_e32 v172, v157
	v_mov_b32_dpp v173, v186 row_ror:8 row_mask:0xf bank_mask:0xf
	v_cndmask_b32_e64 v188, v188, v131, s[0:1]
	v_mov_b32_e32 v131, v157
	v_mov_b32_dpp v134, v141 row_ror:8 row_mask:0xf bank_mask:0xf
	v_mov_b32_dpp v172, v185 row_ror:8 row_mask:0xf bank_mask:0xf
	v_cndmask_b32_e64 v138, v135, v138, s[0:1]
	v_cndmask_b32_e64 v135, v173, v140, s[0:1]
	v_cndmask_b32_e64 v173, v184, v130, s[0:1]
	v_cndmask_b32_e64 v184, v186, v132, s[0:1]
	v_exp_f32_e32 v132, v124
	v_mul_f32_e32 v124, 0xbfb8aa3b, v125
	v_mov_b32_dpp v131, v139 row_ror:8 row_mask:0xf bank_mask:0xf
	v_cndmask_b32_e64 v139, v172, v139, s[0:1]
	v_cndmask_b32_e64 v172, v187, v134, s[0:1]
	v_exp_f32_e32 v134, v124
	v_cndmask_b32_e64 v140, v185, v131, s[0:1]
	v_lshlrev_b64 v[130:131], 13, v[142:143]
	v_lshl_add_u64 v[130:131], s[4:5], 0, v[130:131]
	v_lshl_add_u64 v[130:131], v[130:131], 0, v[166:167]
	v_lshl_add_u64 v[124:125], v[130:131], 0, v[156:157]
	v_add_f32_e32 v131, 1.0, v134
	v_lshlrev_b32_e32 v134, 16, v135
	v_and_b32_e32 v135, 0xffff0000, v135
	v_add_f32_e32 v130, 1.0, v132
	v_pk_mul_f32 v[134:135], v[128:129], v[134:135] op_sel_hi:[0,1]
	v_rcp_f32_e32 v130, v130
	v_rcp_f32_e32 v131, v131
	v_lshlrev_b32_e32 v132, 16, v133
	v_and_b32_e32 v133, 0xffff0000, v133
	v_pk_mul_f32 v[134:135], v[60:61], v[134:135]
	v_mov_b32_e32 v189, v157
	v_pk_fma_f32 v[134:135], v[120:121], v[134:135], v[132:133]
	v_lshlrev_b32_e32 v132, 16, v138
	v_and_b32_e32 v133, 0xffff0000, v138
	v_mov_b32_dpp v189, v187 row_ror:8 row_mask:0xf bank_mask:0xf
	v_pk_mul_f32 v[132:133], v[128:129], v[132:133] op_sel_hi:[0,1]
	v_cndmask_b32_e64 v141, v189, v141, s[0:1]
	v_lshlrev_b32_e32 v120, 16, v183
	v_and_b32_e32 v121, 0xffff0000, v183
	v_pk_mul_f32 v[132:133], v[56:57], v[132:133]
	v_mov_b32_e32 v142, v157
	v_pk_fma_f32 v[120:121], v[130:131], v[132:133], v[120:121]
	v_lshlrev_b32_e32 v132, 16, v141
	v_and_b32_e32 v133, 0xffff0000, v141
	v_pk_mul_f32 v[132:133], v[128:129], v[132:133] op_sel_hi:[0,1]
	v_lshlrev_b32_e32 v130, 16, v190
	v_and_b32_e32 v131, 0xffff0000, v190
	v_pk_mul_f32 v[132:133], v[62:63], v[132:133]
	v_mov_b32_e32 v143, v157
	v_pk_fma_f32 v[130:131], v[122:123], v[132:133], v[130:131]
	v_lshlrev_b32_e32 v132, 16, v139
	v_and_b32_e32 v133, 0xffff0000, v139
	v_pk_mul_f32 v[132:133], v[128:129], v[132:133] op_sel_hi:[0,1]
	v_lshlrev_b32_e32 v122, 16, v188
	v_and_b32_e32 v123, 0xffff0000, v188
	v_pk_mul_f32 v[132:133], v[58:59], v[132:133]
	v_mov_b32_e32 v141, v157
	v_pk_fma_f32 v[122:123], v[126:127], v[132:133], v[122:123]
	v_mov_b32_e32 v126, v157
	v_mov_b32_e32 v127, v157
	v_mov_b32_e32 v185, v157
	v_mov_b32_dpp v126, v122 row_ror:8 row_mask:0xf bank_mask:0xf
	v_mov_b32_dpp v127, v123 row_ror:8 row_mask:0xf bank_mask:0xf
	v_mov_b32_dpp v142, v134 row_ror:8 row_mask:0xf bank_mask:0xf
	v_mov_b32_dpp v143, v135 row_ror:8 row_mask:0xf bank_mask:0xf
	v_mov_b32_e32 v138, v157
	v_mov_b32_e32 v183, v157
	v_mov_b32_dpp v141, v130 row_ror:8 row_mask:0xf bank_mask:0xf
	v_mov_b32_dpp v185, v131 row_ror:8 row_mask:0xf bank_mask:0xf
	v_cndmask_b32_e64 v133, v131, v127, s[0:1]
	v_cndmask_b32_e64 v132, v130, v126, s[0:1]
	v_lshlrev_b32_e32 v126, 16, v184
	v_and_b32_e32 v127, 0xffff0000, v184
	v_mov_b32_dpp v138, v120 row_ror:8 row_mask:0xf bank_mask:0xf
	v_mov_b32_dpp v183, v121 row_ror:8 row_mask:0xf bank_mask:0xf
	v_cndmask_b32_e64 v123, v185, v123, s[0:1]
	v_cndmask_b32_e64 v122, v141, v122, s[0:1]
	v_cndmask_b32_e64 v121, v143, v121, s[0:1]
	v_cndmask_b32_e64 v120, v142, v120, s[0:1]
	v_pk_mul_f32 v[126:127], v[128:129], v[126:127] op_sel_hi:[0,1]
	global_store_dwordx4 v[124:125], v[120:123], off
	v_pk_mul_f32 v[126:127], v[44:45], v[126:127]
	v_cndmask_b32_e64 v131, v135, v183, s[0:1]
	v_lshlrev_b32_e32 v122, 16, v136
	v_and_b32_e32 v123, 0xffff0000, v136
	v_pk_fma_f32 v[122:123], v[112:113], v[126:127], v[122:123]
	v_lshlrev_b32_e32 v126, 16, v173
	v_and_b32_e32 v127, 0xffff0000, v173
	v_pk_mul_f32 v[126:127], v[128:129], v[126:127] op_sel_hi:[0,1]
	v_lshlrev_b32_e32 v112, 16, v129
	v_and_b32_e32 v113, 0xffff0000, v129
; __device__ __forceinline__ float bflo(unsigned w) { return __uint_as_float(w << 16); }
; __device__ __forceinline__ float bfhi(unsigned w) { return __uint_as_float(w & 0xffff0000u); }
;     const bool lo = fr < 8;
;     const int r1 = row - fr + (fr & 7), cb = col0 + (lo ? 0 : boff);
;     const u32x4 l1 = *(const u32x4*)(P + (size_t)r1 * ld + cb), l2 = *(const u32x4*)(P + (size_t)(r1 + 8) * ld + cb);
;     const u32x4 s1 = {dpp_ror8(l1.x), dpp_ror8(l1.y), dpp_ror8(l1.z), dpp_ror8(l1.w)}, s2 = {dpp_ror8(l2.x), dpp_ror8(l2.y), dpp_ror8(l2.z), dpp_ror8(l2.w)};
;     wA = lo ? l1 : s2; wB = lo ? s1 : l2;
; }
;     __device__ __forceinline__ void operator()(const f32x4 (&acc)[2][2][4][2], const Unit& u, int wr, int wc, int fr, int fq) const {
;     ...
;             for (int m = 0; m < 4; ++m) { const int row = row0 + ai * HALF + m * 16; const float ri = __builtin_amdgcn_rsqf(sse[row] * (1.f / D) + EPS);
;                 u32x4 rr[2], ee[2]; load_pair_lines(R, D, row, fr, col0, rr[0], rr[1], 32); load_pair_lines(E, D, row, fr, col0, ee[0], ee[1], 32);
;                 float* orow = OUT + (size_t)(row - fr + (fr & 7)) * D + col0 + (lo ? 0 : 4);
; #pragma unroll
;                 for (int bj = 0; bj < 2; ++bj) { const u32x4 rw = rr[bj], ew = ee[bj];
;                     const float r[8] = {bflo(rw.x), bfhi(rw.x), bflo(rw.y), bfhi(rw.y), bflo(rw.z), bfhi(rw.z), bflo(rw.w), bfhi(rw.w)};
;                     const float e[8] = {bflo(ew.x), bfhi(ew.x), bflo(ew.y), bfhi(ew.y), bflo(ew.z), bfhi(ew.z), bflo(ew.w), bfhi(ew.w)};
;                     float o[8];
; #pragma unroll
;                     for (int j = 0; j < 8; ++j) { const float a = acc[ai][bj][m][j >> 2][j & 3]; const float gg = gv[bj][j >> 2][j & 3];
;                         o[j] = r[j] + e[j] * ri * gg * __builtin_amdgcn_rcpf(1.f + __builtin_amdgcn_exp2f(-a * LOG2E)); }
;                     f32x4 o1, o2;
; #pragma unroll
;                     for (int j = 0; j < 4; ++j) { const unsigned a = __float_as_uint(o[j]), b = __float_as_uint(o[4 + j]); const unsigned sa = dpp_ror8(a), sb = dpp_ror8(b);
;                         o1[j] = __uint_as_float(lo ? a : sb); o2[j] = __uint_as_float(lo ? sa : b); }
;                     *(f32x4*)(orow + 32 * bj) = o1; *(f32x4*)(orow + (size_t)8 * D + 32 * bj) = o2; } }
	v_pk_mul_f32 v[126:127], v[40:41], v[126:127]
	v_mov_b32_e32 v129, v157
	v_pk_fma_f32 v[112:113], v[116:117], v[126:127], v[112:113]
	v_lshlrev_b32_e32 v126, 16, v172
	v_and_b32_e32 v127, 0xffff0000, v172
	v_mov_b32_dpp v129, v112 row_ror:8 row_mask:0xf bank_mask:0xf
	v_pk_mul_f32 v[126:127], v[128:129], v[126:127] op_sel_hi:[0,1]
	v_lshlrev_b32_e32 v116, 16, v137
	v_and_b32_e32 v117, 0xffff0000, v137
	v_pk_mul_f32 v[126:127], v[46:47], v[126:127]
	v_add_co_u32_e32 v120, vcc, s45, v124
	v_pk_fma_f32 v[116:117], v[114:115], v[126:127], v[116:117]
	v_lshlrev_b32_e32 v126, 16, v140
	v_and_b32_e32 v127, 0xffff0000, v140
	v_cndmask_b32_e64 v130, v134, v138, s[0:1]
	v_addc_co_u32_e32 v121, vcc, 0, v125, vcc
	v_pk_mul_f32 v[126:127], v[128:129], v[126:127] op_sel_hi:[0,1]
	global_store_dwordx4 v[120:121], v[130:133], off
	v_mov_b32_e32 v134, v157
	v_lshlrev_b32_e32 v114, 16, v171
	v_mov_b32_e32 v130, v157
	v_mov_b32_e32 v131, v157
	v_mov_b32_e32 v133, v157
	v_and_b32_e32 v115, 0xffff0000, v171
	v_pk_mul_f32 v[126:127], v[42:43], v[126:127]
	v_mov_b32_dpp v130, v122 row_ror:8 row_mask:0xf bank_mask:0xf
	v_mov_b32_dpp v131, v123 row_ror:8 row_mask:0xf bank_mask:0xf
	v_mov_b32_e32 v132, v157
	v_mov_b32_dpp v133, v116 row_ror:8 row_mask:0xf bank_mask:0xf
	v_mov_b32_dpp v134, v117 row_ror:8 row_mask:0xf bank_mask:0xf
	v_pk_fma_f32 v[114:115], v[118:119], v[126:127], v[114:115]
	v_mov_b32_e32 v118, v157
	v_mov_b32_e32 v119, v157
	v_mov_b32_dpp v132, v113 row_ror:8 row_mask:0xf bank_mask:0xf
	v_mov_b32_dpp v118, v114 row_ror:8 row_mask:0xf bank_mask:0xf
	v_mov_b32_dpp v119, v115 row_ror:8 row_mask:0xf bank_mask:0xf
	v_cndmask_b32_e64 v115, v134, v115, s[0:1]
	v_cndmask_b32_e64 v114, v133, v114, s[0:1]
	v_cndmask_b32_e64 v113, v131, v113, s[0:1]
	v_cndmask_b32_e64 v112, v130, v112, s[0:1]
	v_cndmask_b32_e64 v119, v117, v119, s[0:1]
	v_cndmask_b32_e64 v118, v116, v118, s[0:1]
	v_cndmask_b32_e64 v117, v123, v132, s[0:1]
	v_cndmask_b32_e64 v116, v122, v129, s[0:1]
	global_store_dwordx4 v[124:125], v[112:115], off offset:128
	global_store_dwordx4 v[120:121], v[116:119], off offset:128
	v_mov_b32_e32 v137, v157
	v_or_b32_e32 v112, 32, v170
	v_ashrrev_i32_e32 v113, 31, v112
	v_lshl_add_u64 v[114:115], v[112:113], 2, s[6:7]
	v_sub_u32_e32 v112, v112, v174
	v_add_u32_e32 v130, v112, v176
	v_ashrrev_i32_e32 v131, 31, v130
	v_lshlrev_b64 v[112:113], 12, v[130:131]
	v_lshl_add_u64 v[126:127], v[112:113], 0, s[16:17]
	v_lshl_add_u64 v[118:119], s[8:9], 0, v[126:127]
	s_waitcnt vmcnt(4)
	s_nop 0
	v_mov_b32_e32 v132, v228
	v_lshl_add_u64 v[114:115], s[8:9], 0, v[112:113]
	v_lshl_add_u64 v[118:119], v[118:119], 0, v[164:165]
	v_lshl_add_u64 v[112:113], s[10:11], 0, v[112:113]
	v_lshl_add_u64 v[114:115], v[114:115], 0, v[164:165]
	v_mov_b64_e32 v[118:119], v[232:233]
	v_mov_b64_e32 v[120:121], v[234:235]
	v_lshl_add_u64 v[112:113], v[112:113], 0, v[164:165]
	v_mov_b64_e32 v[114:115], v[236:237]
	v_mov_b64_e32 v[116:117], v[238:239]
	v_mov_b32_e32 v138, v157
	v_mov_b64_e32 v[122:123], v[240:241]
	v_mov_b64_e32 v[124:125], v[242:243]
	v_lshl_add_u64 v[112:113], s[10:11], 0, v[126:127]
	v_lshl_add_u64 v[112:113], v[112:113], 0, v[164:165]
	v_mov_b64_e32 v[126:127], v[244:245]
	v_mov_b64_e32 v[128:129], v[246:247]
	s_nop 1
	v_or_b32_e32 v216, 48, v170
	v_ashrrev_i32_e32 v217, 31, v216
	v_lshl_add_u64 v[218:219], v[216:217], 2, s[6:7]
	v_sub_u32_e32 v216, v216, v174
	v_add_u32_e32 v224, v216, v176
	v_ashrrev_i32_e32 v225, 31, v224
	v_lshlrev_b64 v[216:217], 12, v[224:225]
	v_lshl_add_u64 v[222:223], v[216:217], 0, s[16:17]
	v_lshl_add_u64 v[220:221], s[8:9], 0, v[222:223]
	global_load_dword v228, v[218:219], off
	v_lshl_add_u64 v[218:219], s[8:9], 0, v[216:217]
	v_lshl_add_u64 v[220:221], v[220:221], 0, v[164:165]
	v_lshl_add_u64 v[216:217], s[10:11], 0, v[216:217]
	v_lshl_add_u64 v[218:219], v[218:219], 0, v[164:165]
	global_load_dwordx4 v[232:235], v[220:221], off
	v_lshl_add_u64 v[216:217], v[216:217], 0, v[164:165]
	global_load_dwordx4 v[236:239], v[218:219], off
	global_load_dwordx4 v[240:243], v[216:217], off
	v_lshl_add_u64 v[216:217], s[10:11], 0, v[222:223]
	v_lshl_add_u64 v[216:217], v[216:217], 0, v[164:165]
	global_load_dwordx4 v[244:247], v[216:217], off
	v_mov_b32_e32 v113, v157
	v_mov_b32_e32 v133, v157
	v_mov_b32_e32 v134, v157
	v_mov_b32_e32 v136, v157
	v_mov_b32_e32 v135, v157
	v_add_f32_e32 v105, 1.0, v105
	v_mul_f32_e32 v107, 0xbfb8aa3b, v107
	v_rcp_f32_e32 v105, v105
	v_exp_f32_e32 v106, v106
	v_exp_f32_e32 v107, v107
	v_mul_f32_e32 v110, 0xbfb8aa3b, v110
	v_mul_f32_e32 v111, 0xbfb8aa3b, v111
	v_exp_f32_e32 v110, v110
	v_exp_f32_e32 v111, v111
	v_add_f32_e32 v106, 1.0, v106
	v_add_f32_e32 v107, 1.0, v107
	v_rcp_f32_e32 v106, v106
	v_rcp_f32_e32 v107, v107
	v_add_f32_e32 v110, 1.0, v110
	v_add_f32_e32 v111, 1.0, v111
	v_mul_f32_e32 v96, 0xbfb8aa3b, v96
	v_mul_f32_e32 v97, 0xbfb8aa3b, v97
	v_rcp_f32_e32 v110, v110
	v_rcp_f32_e32 v111, v111
	v_exp_f32_e32 v96, v96
	v_exp_f32_e32 v97, v97
	v_mul_f32_e32 v100, 0xbfb8aa3b, v100
	v_mul_f32_e32 v101, 0xbfb8aa3b, v101
	v_exp_f32_e32 v100, v100
	v_exp_f32_e32 v101, v101
	v_add_f32_e32 v96, 1.0, v96
	v_add_f32_e32 v97, 1.0, v97
	v_rcp_f32_e32 v96, v96
	v_rcp_f32_e32 v97, v97
	v_mul_f32_e32 v98, 0xbfb8aa3b, v98
	v_mul_f32_e32 v99, 0xbfb8aa3b, v99
	v_add_f32_e32 v100, 1.0, v100
	v_add_f32_e32 v101, 1.0, v101
	v_exp_f32_e32 v98, v98
	v_exp_f32_e32 v99, v99
	v_rcp_f32_e32 v100, v100
	v_rcp_f32_e32 v101, v101
	v_mul_f32_e32 v102, 0xbfb8aa3b, v102
	v_mul_f32_e32 v103, 0xbfb8aa3b, v103
	v_exp_f32_e32 v102, v102
	v_exp_f32_e32 v103, v103
	v_add_f32_e32 v98, 1.0, v98
	v_add_f32_e32 v99, 1.0, v99
	v_rcp_f32_e32 v98, v98
; __device__ __forceinline__ float bflo(unsigned w) { return __uint_as_float(w << 16); }
; __device__ __forceinline__ float bfhi(unsigned w) { return __uint_as_float(w & 0xffff0000u); }
;     const bool lo = fr < 8;
;     const int r1 = row - fr + (fr & 7), cb = col0 + (lo ? 0 : boff);
;     const u32x4 l1 = *(const u32x4*)(P + (size_t)r1 * ld + cb), l2 = *(const u32x4*)(P + (size_t)(r1 + 8) * ld + cb);
;     const u32x4 s1 = {dpp_ror8(l1.x), dpp_ror8(l1.y), dpp_ror8(l1.z), dpp_ror8(l1.w)}, s2 = {dpp_ror8(l2.x), dpp_ror8(l2.y), dpp_ror8(l2.z), dpp_ror8(l2.w)};
;     wA = lo ? l1 : s2; wB = lo ? s1 : l2;
; }
;     __device__ __forceinline__ void operator()(const f32x4 (&acc)[2][2][4][2], const Unit& u, int wr, int wc, int fr, int fq) const {
;     ...
;             for (int m = 0; m < 4; ++m) { const int row = row0 + ai * HALF + m * 16; const float ri = __builtin_amdgcn_rsqf(sse[row] * (1.f / D) + EPS);
;                 u32x4 rr[2], ee[2]; load_pair_lines(R, D, row, fr, col0, rr[0], rr[1], 32); load_pair_lines(E, D, row, fr, col0, ee[0], ee[1], 32);
;                 float* orow = OUT + (size_t)(row - fr + (fr & 7)) * D + col0 + (lo ? 0 : 4);
; #pragma unroll
;                 for (int bj = 0; bj < 2; ++bj) { const u32x4 rw = rr[bj], ew = ee[bj];
;                     const float r[8] = {bflo(rw.x), bfhi(rw.x), bflo(rw.y), bfhi(rw.y), bflo(rw.z), bfhi(rw.z), bflo(rw.w), bfhi(rw.w)};
;                     const float e[8] = {bflo(ew.x), bfhi(ew.x), bflo(ew.y), bfhi(ew.y), bflo(ew.z), bfhi(ew.z), bflo(ew.w), bfhi(ew.w)};
;                     float o[8];
; #pragma unroll
;                     for (int j = 0; j < 8; ++j) { const float a = acc[ai][bj][m][j >> 2][j & 3]; const float gg = gv[bj][j >> 2][j & 3];
;                         o[j] = r[j] + e[j] * ri * gg * __builtin_amdgcn_rcpf(1.f + __builtin_amdgcn_exp2f(-a * LOG2E)); }
;                     f32x4 o1, o2;
; #pragma unroll
;                     for (int j = 0; j < 4; ++j) { const unsigned a = __float_as_uint(o[j]), b = __float_as_uint(o[4 + j]); const unsigned sa = dpp_ror8(a), sb = dpp_ror8(b);
;                         o1[j] = __uint_as_float(lo ? a : sb); o2[j] = __uint_as_float(lo ? sa : b); }
;                     *(f32x4*)(orow + 32 * bj) = o1; *(f32x4*)(orow + (size_t)8 * D + 32 * bj) = o2; } }
	v_rcp_f32_e32 v99, v99
	v_add_f32_e32 v102, 1.0, v102
	v_add_f32_e32 v103, 1.0, v103
	v_rcp_f32_e32 v102, v102
	v_rcp_f32_e32 v103, v103
	v_mul_f32_e32 v88, 0xbfb8aa3b, v88
	v_mul_f32_e32 v89, 0xbfb8aa3b, v89
	v_mul_f32_e32 v92, 0xbfb8aa3b, v92
	v_exp_f32_e32 v88, v88
	v_exp_f32_e32 v89, v89
	v_mul_f32_e32 v90, 0xbfb8aa3b, v90
	v_mul_f32_e32 v91, 0xbfb8aa3b, v91
	v_add_f32_e32 v88, 1.0, v88
	v_add_f32_e32 v89, 1.0, v89
	v_rcp_f32_e32 v88, v88
	v_rcp_f32_e32 v89, v89
	v_exp_f32_e32 v90, v90
	v_exp_f32_e32 v91, v91
	v_fmamk_f32 v112, v132, 0x3a000000, v182
	v_mov_b32_e32 v132, v157
	v_rsq_f32_e32 v112, v112
	v_mul_f32_e32 v94, 0xbfb8aa3b, v94
	v_mul_f32_e32 v95, 0xbfb8aa3b, v95
	v_mov_b32_dpp v137, v120 row_ror:8 row_mask:0xf bank_mask:0xf
	v_mov_b32_dpp v138, v121 row_ror:8 row_mask:0xf bank_mask:0xf
	v_mov_b32_dpp v113, v114 row_ror:8 row_mask:0xf bank_mask:0xf
	v_mov_b32_dpp v132, v115 row_ror:8 row_mask:0xf bank_mask:0xf
	v_mov_b32_dpp v133, v116 row_ror:8 row_mask:0xf bank_mask:0xf
	v_mov_b32_dpp v134, v117 row_ror:8 row_mask:0xf bank_mask:0xf
	v_mov_b32_dpp v136, v119 row_ror:8 row_mask:0xf bank_mask:0xf
	v_cndmask_b32_e64 v138, v138, v117, s[0:1]
	v_cndmask_b32_e64 v117, v137, v116, s[0:1]
	v_mov_b32_e32 v116, v157
	v_mov_b32_dpp v135, v118 row_ror:8 row_mask:0xf bank_mask:0xf
	v_cndmask_b32_e64 v136, v136, v115, s[0:1]
	v_cndmask_b32_e64 v132, v119, v132, s[0:1]
	v_cndmask_b32_e64 v121, v121, v134, s[0:1]
	v_cndmask_b32_e64 v113, v118, v113, s[0:1]
	v_mov_b32_e32 v115, v157
	v_mov_b32_dpp v116, v124 row_ror:8 row_mask:0xf bank_mask:0xf
	v_mov_b32_e32 v118, v157
	v_mov_b32_e32 v119, v157
	v_mov_b32_e32 v134, v157
	v_cndmask_b32_e64 v135, v135, v114, s[0:1]
	v_cndmask_b32_e64 v120, v120, v133, s[0:1]
	v_mov_b32_e32 v114, v157
	v_mov_b32_dpp v115, v123 row_ror:8 row_mask:0xf bank_mask:0xf
	v_mov_b32_dpp v118, v125 row_ror:8 row_mask:0xf bank_mask:0xf
	v_mov_b32_dpp v119, v126 row_ror:8 row_mask:0xf bank_mask:0xf
	v_mov_b32_e32 v133, v157
	v_mov_b32_dpp v134, v128 row_ror:8 row_mask:0xf bank_mask:0xf
	v_cndmask_b32_e64 v128, v128, v116, s[0:1]
	v_exp_f32_e32 v116, v108
	v_mul_f32_e32 v108, 0xbfb8aa3b, v109
	v_mov_b32_dpp v114, v122 row_ror:8 row_mask:0xf bank_mask:0xf
	v_mov_b32_dpp v133, v127 row_ror:8 row_mask:0xf bank_mask:0xf
	v_cndmask_b32_e64 v122, v119, v122, s[0:1]
	v_cndmask_b32_e64 v119, v134, v124, s[0:1]
	v_cndmask_b32_e64 v124, v127, v115, s[0:1]
	v_cndmask_b32_e64 v127, v129, v118, s[0:1]
	v_exp_f32_e32 v118, v108
	v_cndmask_b32_e64 v126, v126, v114, s[0:1]
	v_lshlrev_b64 v[114:115], 13, v[130:131]
	v_lshl_add_u64 v[114:115], s[4:5], 0, v[114:115]
	v_lshl_add_u64 v[114:115], v[114:115], 0, v[166:167]
	v_lshl_add_u64 v[108:109], v[114:115], 0, v[156:157]
	v_add_f32_e32 v115, 1.0, v118
	v_lshlrev_b32_e32 v118, 16, v119
	v_and_b32_e32 v119, 0xffff0000, v119
	v_add_f32_e32 v114, 1.0, v116
	v_pk_mul_f32 v[118:119], v[112:113], v[118:119] op_sel_hi:[0,1]
	v_rcp_f32_e32 v114, v114
	v_rcp_f32_e32 v115, v115
	v_lshlrev_b32_e32 v116, 16, v117
	v_and_b32_e32 v117, 0xffff0000, v117
	v_pk_mul_f32 v[118:119], v[60:61], v[118:119]
	v_mov_b32_e32 v137, v157
	v_pk_fma_f32 v[118:119], v[104:105], v[118:119], v[116:117]
	v_lshlrev_b32_e32 v116, 16, v122
	v_and_b32_e32 v117, 0xffff0000, v122
	v_mov_b32_dpp v137, v129 row_ror:8 row_mask:0xf bank_mask:0xf
	v_pk_mul_f32 v[116:117], v[112:113], v[116:117] op_sel_hi:[0,1]
	v_cndmask_b32_e64 v125, v137, v125, s[0:1]
	v_lshlrev_b32_e32 v104, 16, v135
	v_and_b32_e32 v105, 0xffff0000, v135
	v_pk_mul_f32 v[116:117], v[56:57], v[116:117]
	v_cndmask_b32_e64 v123, v133, v123, s[0:1]
	v_pk_fma_f32 v[104:105], v[114:115], v[116:117], v[104:105]
	v_lshlrev_b32_e32 v116, 16, v125
	v_and_b32_e32 v117, 0xffff0000, v125
	v_pk_mul_f32 v[116:117], v[112:113], v[116:117] op_sel_hi:[0,1]
	v_lshlrev_b32_e32 v114, 16, v138
	v_and_b32_e32 v115, 0xffff0000, v138
	v_pk_mul_f32 v[116:117], v[62:63], v[116:117]
	v_mov_b32_e32 v129, v157
	v_pk_fma_f32 v[114:115], v[106:107], v[116:117], v[114:115]
	v_lshlrev_b32_e32 v116, 16, v123
	v_and_b32_e32 v117, 0xffff0000, v123
	v_pk_mul_f32 v[116:117], v[112:113], v[116:117] op_sel_hi:[0,1]
	v_lshlrev_b32_e32 v106, 16, v136
	v_and_b32_e32 v107, 0xffff0000, v136
	v_pk_mul_f32 v[116:117], v[58:59], v[116:117]
	v_mov_b32_e32 v130, v157
	v_pk_fma_f32 v[106:107], v[110:111], v[116:117], v[106:107]
	v_mov_b32_e32 v110, v157
	v_mov_b32_e32 v111, v157
	v_mov_b32_e32 v125, v157
	v_mov_b32_e32 v133, v157
	v_mov_b32_dpp v110, v106 row_ror:8 row_mask:0xf bank_mask:0xf
	v_mov_b32_dpp v111, v107 row_ror:8 row_mask:0xf bank_mask:0xf
	v_mov_b32_dpp v129, v118 row_ror:8 row_mask:0xf bank_mask:0xf
	v_mov_b32_dpp v130, v119 row_ror:8 row_mask:0xf bank_mask:0xf
	v_mov_b32_e32 v122, v157
	v_mov_b32_e32 v131, v157
	v_mov_b32_dpp v125, v114 row_ror:8 row_mask:0xf bank_mask:0xf
	v_mov_b32_dpp v133, v115 row_ror:8 row_mask:0xf bank_mask:0xf
	v_cndmask_b32_e64 v117, v115, v111, s[0:1]
	v_cndmask_b32_e64 v116, v114, v110, s[0:1]
	v_lshlrev_b32_e32 v110, 16, v128
	v_and_b32_e32 v111, 0xffff0000, v128
	v_mov_b32_dpp v122, v104 row_ror:8 row_mask:0xf bank_mask:0xf
	v_mov_b32_dpp v131, v105 row_ror:8 row_mask:0xf bank_mask:0xf
	v_cndmask_b32_e64 v107, v133, v107, s[0:1]
	v_cndmask_b32_e64 v106, v125, v106, s[0:1]
	v_cndmask_b32_e64 v105, v130, v105, s[0:1]
	v_cndmask_b32_e64 v104, v129, v104, s[0:1]
	v_pk_mul_f32 v[110:111], v[112:113], v[110:111] op_sel_hi:[0,1]
	global_store_dwordx4 v[108:109], v[104:107], off
	v_pk_mul_f32 v[110:111], v[44:45], v[110:111]
	v_cndmask_b32_e64 v115, v119, v131, s[0:1]
	v_lshlrev_b32_e32 v106, 16, v120
	v_and_b32_e32 v107, 0xffff0000, v120
	v_pk_fma_f32 v[106:107], v[96:97], v[110:111], v[106:107]
; __device__ __forceinline__ float bflo(unsigned w) { return __uint_as_float(w << 16); }
; __device__ __forceinline__ float bfhi(unsigned w) { return __uint_as_float(w & 0xffff0000u); }
;     const bool lo = fr < 8;
;     const int r1 = row - fr + (fr & 7), cb = col0 + (lo ? 0 : boff);
;     const u32x4 l1 = *(const u32x4*)(P + (size_t)r1 * ld + cb), l2 = *(const u32x4*)(P + (size_t)(r1 + 8) * ld + cb);
;     const u32x4 s1 = {dpp_ror8(l1.x), dpp_ror8(l1.y), dpp_ror8(l1.z), dpp_ror8(l1.w)}, s2 = {dpp_ror8(l2.x), dpp_ror8(l2.y), dpp_ror8(l2.z), dpp_ror8(l2.w)};
;     wA = lo ? l1 : s2; wB = lo ? s1 : l2;
; }
;     __device__ __forceinline__ void operator()(const f32x4 (&acc)[2][2][4][2], const Unit& u, int wr, int wc, int fr, int fq) const {
;     ...
;             for (int m = 0; m < 4; ++m) { const int row = row0 + ai * HALF + m * 16; const float ri = __builtin_amdgcn_rsqf(sse[row] * (1.f / D) + EPS);
;                 u32x4 rr[2], ee[2]; load_pair_lines(R, D, row, fr, col0, rr[0], rr[1], 32); load_pair_lines(E, D, row, fr, col0, ee[0], ee[1], 32);
;                 float* orow = OUT + (size_t)(row - fr + (fr & 7)) * D + col0 + (lo ? 0 : 4);
; #pragma unroll
;                 for (int bj = 0; bj < 2; ++bj) { const u32x4 rw = rr[bj], ew = ee[bj];
;                     const float r[8] = {bflo(rw.x), bfhi(rw.x), bflo(rw.y), bfhi(rw.y), bflo(rw.z), bfhi(rw.z), bflo(rw.w), bfhi(rw.w)};
;                     const float e[8] = {bflo(ew.x), bfhi(ew.x), bflo(ew.y), bfhi(ew.y), bflo(ew.z), bfhi(ew.z), bflo(ew.w), bfhi(ew.w)};
;                     float o[8];
; #pragma unroll
;                     for (int j = 0; j < 8; ++j) { const float a = acc[ai][bj][m][j >> 2][j & 3]; const float gg = gv[bj][j >> 2][j & 3];
;                         o[j] = r[j] + e[j] * ri * gg * __builtin_amdgcn_rcpf(1.f + __builtin_amdgcn_exp2f(-a * LOG2E)); }
;                     f32x4 o1, o2;
; #pragma unroll
;                     for (int j = 0; j < 4; ++j) { const unsigned a = __float_as_uint(o[j]), b = __float_as_uint(o[4 + j]); const unsigned sa = dpp_ror8(a), sb = dpp_ror8(b);
;                         o1[j] = __uint_as_float(lo ? a : sb); o2[j] = __uint_as_float(lo ? sa : b); }
;                     *(f32x4*)(orow + 32 * bj) = o1; *(f32x4*)(orow + (size_t)8 * D + 32 * bj) = o2; } }
	v_lshlrev_b32_e32 v110, 16, v126
	v_and_b32_e32 v111, 0xffff0000, v126
	v_pk_mul_f32 v[110:111], v[112:113], v[110:111] op_sel_hi:[0,1]
	v_lshlrev_b32_e32 v96, 16, v113
	v_and_b32_e32 v97, 0xffff0000, v113
	v_pk_mul_f32 v[110:111], v[40:41], v[110:111]
	v_mov_b32_e32 v113, v157
	v_pk_fma_f32 v[96:97], v[100:101], v[110:111], v[96:97]
	v_lshlrev_b32_e32 v110, 16, v127
	v_and_b32_e32 v111, 0xffff0000, v127
	v_mov_b32_dpp v113, v96 row_ror:8 row_mask:0xf bank_mask:0xf
	v_pk_mul_f32 v[110:111], v[112:113], v[110:111] op_sel_hi:[0,1]
	v_lshlrev_b32_e32 v100, 16, v121
	v_and_b32_e32 v101, 0xffff0000, v121
	v_pk_mul_f32 v[110:111], v[46:47], v[110:111]
	v_add_co_u32_e32 v104, vcc, s45, v108
	v_pk_fma_f32 v[100:101], v[98:99], v[110:111], v[100:101]
	v_lshlrev_b32_e32 v110, 16, v124
	v_and_b32_e32 v111, 0xffff0000, v124
	v_cndmask_b32_e64 v114, v118, v122, s[0:1]
	v_addc_co_u32_e32 v105, vcc, 0, v109, vcc
	v_pk_mul_f32 v[110:111], v[112:113], v[110:111] op_sel_hi:[0,1]
	global_store_dwordx4 v[104:105], v[114:117], off
	v_mov_b32_e32 v118, v157
	v_lshlrev_b32_e32 v98, 16, v132
	v_mov_b32_e32 v114, v157
	v_mov_b32_e32 v115, v157
	v_mov_b32_e32 v117, v157
	v_and_b32_e32 v99, 0xffff0000, v132
	v_pk_mul_f32 v[110:111], v[42:43], v[110:111]
	v_mov_b32_dpp v114, v106 row_ror:8 row_mask:0xf bank_mask:0xf
	v_mov_b32_dpp v115, v107 row_ror:8 row_mask:0xf bank_mask:0xf
	v_mov_b32_e32 v116, v157
	v_mov_b32_dpp v117, v100 row_ror:8 row_mask:0xf bank_mask:0xf
	v_mov_b32_dpp v118, v101 row_ror:8 row_mask:0xf bank_mask:0xf
	v_pk_fma_f32 v[98:99], v[102:103], v[110:111], v[98:99]
	v_mov_b32_e32 v102, v157
	v_mov_b32_e32 v103, v157
	v_mov_b32_dpp v116, v97 row_ror:8 row_mask:0xf bank_mask:0xf
	v_mov_b32_dpp v102, v98 row_ror:8 row_mask:0xf bank_mask:0xf
	v_mov_b32_dpp v103, v99 row_ror:8 row_mask:0xf bank_mask:0xf
	v_cndmask_b32_e64 v99, v118, v99, s[0:1]
	v_cndmask_b32_e64 v98, v117, v98, s[0:1]
	v_cndmask_b32_e64 v97, v115, v97, s[0:1]
	v_cndmask_b32_e64 v96, v114, v96, s[0:1]
	v_cndmask_b32_e64 v103, v101, v103, s[0:1]
	v_cndmask_b32_e64 v102, v100, v102, s[0:1]
	v_cndmask_b32_e64 v101, v107, v116, s[0:1]
	v_cndmask_b32_e64 v100, v106, v113, s[0:1]
	global_store_dwordx4 v[108:109], v[96:99], off offset:128
	global_store_dwordx4 v[104:105], v[100:103], off offset:128
	v_mov_b32_e32 v121, v157
	v_or_b32_e32 v96, 48, v170
	v_ashrrev_i32_e32 v97, 31, v96
	v_lshl_add_u64 v[98:99], v[96:97], 2, s[6:7]
	v_sub_u32_e32 v96, v96, v174
	v_add_u32_e32 v114, v96, v176
	v_ashrrev_i32_e32 v115, 31, v114
	v_lshlrev_b64 v[96:97], 12, v[114:115]
	v_lshl_add_u64 v[110:111], v[96:97], 0, s[16:17]
	v_lshl_add_u64 v[102:103], s[8:9], 0, v[110:111]
	s_waitcnt vmcnt(4)
	s_nop 0
	v_mov_b32_e32 v116, v228
	v_lshl_add_u64 v[98:99], s[8:9], 0, v[96:97]
	v_lshl_add_u64 v[102:103], v[102:103], 0, v[164:165]
	v_lshl_add_u64 v[96:97], s[10:11], 0, v[96:97]
	v_lshl_add_u64 v[98:99], v[98:99], 0, v[164:165]
	v_mov_b64_e32 v[102:103], v[232:233]
	v_mov_b64_e32 v[104:105], v[234:235]
	v_lshl_add_u64 v[96:97], v[96:97], 0, v[164:165]
	v_mov_b64_e32 v[98:99], v[236:237]
	v_mov_b64_e32 v[100:101], v[238:239]
	v_mov_b32_e32 v122, v157
	v_mov_b64_e32 v[106:107], v[240:241]
	v_mov_b64_e32 v[108:109], v[242:243]
	v_lshl_add_u64 v[96:97], s[10:11], 0, v[110:111]
	v_lshl_add_u64 v[96:97], v[96:97], 0, v[164:165]
	v_mov_b64_e32 v[110:111], v[244:245]
	v_mov_b64_e32 v[112:113], v[246:247]
	s_nop 1
	global_load_dword v228, v[168:169], off offset:512
	v_sub_u32_e32 v217, v170, v174
	v_add_u32_e32 v217, v217, v176
	v_add_u32_e32 v226, 0x80, v217
	v_ashrrev_i32_e32 v227, 31, v226
	v_lshlrev_b64 v[222:223], 12, v[226:227]
	v_lshl_add_u64 v[224:225], v[222:223], 0, s[16:17]
	v_lshl_add_u64 v[218:219], s[8:9], 0, v[222:223]
	v_lshl_add_u64 v[220:221], s[8:9], 0, v[224:225]
	v_lshl_add_u64 v[218:219], v[218:219], 0, v[164:165]
	v_lshl_add_u64 v[220:221], v[220:221], 0, v[164:165]
	global_load_dwordx4 v[232:235], v[218:219], off
	v_lshl_add_u64 v[222:223], s[10:11], 0, v[222:223]
	global_load_dwordx4 v[236:239], v[220:221], off
	v_lshl_add_u64 v[222:223], v[222:223], 0, v[164:165]
	v_lshl_add_u64 v[224:225], s[10:11], 0, v[224:225]
	global_load_dwordx4 v[240:243], v[222:223], off
	v_lshl_add_u64 v[224:225], v[224:225], 0, v[164:165]
	global_load_dwordx4 v[244:247], v[224:225], off
	v_mov_b32_e32 v97, v157
	v_mov_b32_e32 v117, v157
	v_mov_b32_e32 v118, v157
	v_mov_b32_e32 v120, v157
	v_mov_b32_e32 v119, v157
	v_exp_f32_e32 v94, v94
	v_exp_f32_e32 v95, v95
	v_add_f32_e32 v90, 1.0, v90
	v_add_f32_e32 v91, 1.0, v91
	v_rcp_f32_e32 v90, v90
	v_rcp_f32_e32 v91, v91
	v_add_f32_e32 v94, 1.0, v94
	v_add_f32_e32 v95, 1.0, v95
	v_mul_f32_e32 v80, 0xbfb8aa3b, v80
	v_mul_f32_e32 v81, 0xbfb8aa3b, v81
	v_rcp_f32_e32 v94, v94
	v_rcp_f32_e32 v95, v95
	v_exp_f32_e32 v80, v80
	v_exp_f32_e32 v81, v81
	v_mul_f32_e32 v84, 0xbfb8aa3b, v84
	v_mul_f32_e32 v85, 0xbfb8aa3b, v85
	v_exp_f32_e32 v84, v84
	v_exp_f32_e32 v85, v85
	v_add_f32_e32 v80, 1.0, v80
	v_add_f32_e32 v81, 1.0, v81
	v_rcp_f32_e32 v80, v80
	v_rcp_f32_e32 v81, v81
	v_mul_f32_e32 v82, 0xbfb8aa3b, v82
	v_mul_f32_e32 v83, 0xbfb8aa3b, v83
	v_add_f32_e32 v84, 1.0, v84
	v_add_f32_e32 v85, 1.0, v85
	v_exp_f32_e32 v82, v82
	v_exp_f32_e32 v83, v83
	v_rcp_f32_e32 v84, v84
	v_rcp_f32_e32 v85, v85
	v_mul_f32_e32 v86, 0xbfb8aa3b, v86
	v_mul_f32_e32 v87, 0xbfb8aa3b, v87
	v_exp_f32_e32 v86, v86
	v_exp_f32_e32 v87, v87
	v_add_f32_e32 v82, 1.0, v82
	v_add_f32_e32 v83, 1.0, v83
	v_rcp_f32_e32 v82, v82
	v_rcp_f32_e32 v83, v83
	v_add_f32_e32 v86, 1.0, v86
	v_add_f32_e32 v87, 1.0, v87
	v_rcp_f32_e32 v86, v86
	v_rcp_f32_e32 v87, v87
	v_mul_f32_e32 v72, 0xbfb8aa3b, v72
	v_mul_f32_e32 v73, 0xbfb8aa3b, v73
; __device__ __forceinline__ float bflo(unsigned w) { return __uint_as_float(w << 16); }
; __device__ __forceinline__ float bfhi(unsigned w) { return __uint_as_float(w & 0xffff0000u); }
;     const bool lo = fr < 8;
;     const int r1 = row - fr + (fr & 7), cb = col0 + (lo ? 0 : boff);
;     const u32x4 l1 = *(const u32x4*)(P + (size_t)r1 * ld + cb), l2 = *(const u32x4*)(P + (size_t)(r1 + 8) * ld + cb);
;     const u32x4 s1 = {dpp_ror8(l1.x), dpp_ror8(l1.y), dpp_ror8(l1.z), dpp_ror8(l1.w)}, s2 = {dpp_ror8(l2.x), dpp_ror8(l2.y), dpp_ror8(l2.z), dpp_ror8(l2.w)};
;     wA = lo ? l1 : s2; wB = lo ? s1 : l2;
; }
;     __device__ __forceinline__ void operator()(const f32x4 (&acc)[2][2][4][2], const Unit& u, int wr, int wc, int fr, int fq) const {
;     ...
;             for (int m = 0; m < 4; ++m) { const int row = row0 + ai * HALF + m * 16; const float ri = __builtin_amdgcn_rsqf(sse[row] * (1.f / D) + EPS);
;                 u32x4 rr[2], ee[2]; load_pair_lines(R, D, row, fr, col0, rr[0], rr[1], 32); load_pair_lines(E, D, row, fr, col0, ee[0], ee[1], 32);
;                 float* orow = OUT + (size_t)(row - fr + (fr & 7)) * D + col0 + (lo ? 0 : 4);
; #pragma unroll
;                 for (int bj = 0; bj < 2; ++bj) { const u32x4 rw = rr[bj], ew = ee[bj];
;                     const float r[8] = {bflo(rw.x), bfhi(rw.x), bflo(rw.y), bfhi(rw.y), bflo(rw.z), bfhi(rw.z), bflo(rw.w), bfhi(rw.w)};
;                     const float e[8] = {bflo(ew.x), bfhi(ew.x), bflo(ew.y), bfhi(ew.y), bflo(ew.z), bfhi(ew.z), bflo(ew.w), bfhi(ew.w)};
;                     float o[8];
; #pragma unroll
;                     for (int j = 0; j < 8; ++j) { const float a = acc[ai][bj][m][j >> 2][j & 3]; const float gg = gv[bj][j >> 2][j & 3];
;                         o[j] = r[j] + e[j] * ri * gg * __builtin_amdgcn_rcpf(1.f + __builtin_amdgcn_exp2f(-a * LOG2E)); }
;                     f32x4 o1, o2;
; #pragma unroll
;                     for (int j = 0; j < 4; ++j) { const unsigned a = __float_as_uint(o[j]), b = __float_as_uint(o[4 + j]); const unsigned sa = dpp_ror8(a), sb = dpp_ror8(b);
;                         o1[j] = __uint_as_float(lo ? a : sb); o2[j] = __uint_as_float(lo ? sa : b); }
;                     *(f32x4*)(orow + 32 * bj) = o1; *(f32x4*)(orow + (size_t)8 * D + 32 * bj) = o2; } }
	v_mul_f32_e32 v76, 0xbfb8aa3b, v76
	v_exp_f32_e32 v72, v72
	v_exp_f32_e32 v73, v73
	v_mul_f32_e32 v74, 0xbfb8aa3b, v74
	v_mul_f32_e32 v75, 0xbfb8aa3b, v75
	v_add_f32_e32 v72, 1.0, v72
	v_add_f32_e32 v73, 1.0, v73
	v_rcp_f32_e32 v72, v72
	v_rcp_f32_e32 v73, v73
	v_exp_f32_e32 v74, v74
	v_exp_f32_e32 v75, v75
	v_mul_f32_e32 v78, 0xbfb8aa3b, v78
	v_mul_f32_e32 v79, 0xbfb8aa3b, v79
	v_exp_f32_e32 v78, v78
	v_exp_f32_e32 v79, v79
	v_add_f32_e32 v74, 1.0, v74
	v_add_f32_e32 v75, 1.0, v75
	v_rcp_f32_e32 v74, v74
	v_fmamk_f32 v96, v116, 0x3a000000, v182
	v_mov_b32_e32 v116, v157
	v_rsq_f32_e32 v96, v96
	v_rcp_f32_e32 v75, v75
	v_add_f32_e32 v78, 1.0, v78
	v_mov_b32_dpp v121, v104 row_ror:8 row_mask:0xf bank_mask:0xf
	v_mov_b32_dpp v122, v105 row_ror:8 row_mask:0xf bank_mask:0xf
	v_mov_b32_dpp v97, v98 row_ror:8 row_mask:0xf bank_mask:0xf
	v_mov_b32_dpp v116, v99 row_ror:8 row_mask:0xf bank_mask:0xf
	v_mov_b32_dpp v117, v100 row_ror:8 row_mask:0xf bank_mask:0xf
	v_mov_b32_dpp v118, v101 row_ror:8 row_mask:0xf bank_mask:0xf
	v_mov_b32_dpp v120, v103 row_ror:8 row_mask:0xf bank_mask:0xf
	v_cndmask_b32_e64 v122, v122, v101, s[0:1]
	v_cndmask_b32_e64 v101, v121, v100, s[0:1]
	v_mov_b32_e32 v100, v157
	v_mov_b32_dpp v119, v102 row_ror:8 row_mask:0xf bank_mask:0xf
	v_cndmask_b32_e64 v120, v120, v99, s[0:1]
	v_cndmask_b32_e64 v116, v103, v116, s[0:1]
	v_cndmask_b32_e64 v105, v105, v118, s[0:1]
	v_cndmask_b32_e64 v97, v102, v97, s[0:1]
	v_mov_b32_e32 v99, v157
	v_mov_b32_dpp v100, v108 row_ror:8 row_mask:0xf bank_mask:0xf
	v_mov_b32_e32 v102, v157
	v_mov_b32_e32 v103, v157
	v_mov_b32_e32 v118, v157
	v_cndmask_b32_e64 v119, v119, v98, s[0:1]
	v_cndmask_b32_e64 v104, v104, v117, s[0:1]
	v_mov_b32_e32 v98, v157
	v_mov_b32_dpp v99, v107 row_ror:8 row_mask:0xf bank_mask:0xf
	v_mov_b32_dpp v102, v109 row_ror:8 row_mask:0xf bank_mask:0xf
	v_mov_b32_dpp v103, v110 row_ror:8 row_mask:0xf bank_mask:0xf
	v_mov_b32_e32 v117, v157
	v_mov_b32_dpp v118, v112 row_ror:8 row_mask:0xf bank_mask:0xf
	v_cndmask_b32_e64 v112, v112, v100, s[0:1]
	v_exp_f32_e32 v100, v92
	v_mul_f32_e32 v92, 0xbfb8aa3b, v93
	v_mov_b32_dpp v98, v106 row_ror:8 row_mask:0xf bank_mask:0xf
	v_mov_b32_dpp v117, v111 row_ror:8 row_mask:0xf bank_mask:0xf
	v_cndmask_b32_e64 v106, v103, v106, s[0:1]
	v_cndmask_b32_e64 v103, v118, v108, s[0:1]
	v_cndmask_b32_e64 v108, v111, v99, s[0:1]
	v_cndmask_b32_e64 v111, v113, v102, s[0:1]
	v_exp_f32_e32 v102, v92
	v_cndmask_b32_e64 v110, v110, v98, s[0:1]
	v_lshlrev_b64 v[98:99], 13, v[114:115]
	v_lshl_add_u64 v[98:99], s[4:5], 0, v[98:99]
	v_lshl_add_u64 v[98:99], v[98:99], 0, v[166:167]
	v_lshl_add_u64 v[92:93], v[98:99], 0, v[156:157]
	v_add_f32_e32 v99, 1.0, v102
	v_lshlrev_b32_e32 v102, 16, v103
	v_and_b32_e32 v103, 0xffff0000, v103
	v_add_f32_e32 v98, 1.0, v100
	v_pk_mul_f32 v[102:103], v[96:97], v[102:103] op_sel_hi:[0,1]
	v_rcp_f32_e32 v98, v98
	v_rcp_f32_e32 v99, v99
	v_lshlrev_b32_e32 v100, 16, v101
	v_and_b32_e32 v101, 0xffff0000, v101
	v_pk_mul_f32 v[102:103], v[60:61], v[102:103]
	v_mov_b32_e32 v121, v157
	v_pk_fma_f32 v[102:103], v[88:89], v[102:103], v[100:101]
	v_lshlrev_b32_e32 v100, 16, v106
	v_and_b32_e32 v101, 0xffff0000, v106
	v_mov_b32_dpp v121, v113 row_ror:8 row_mask:0xf bank_mask:0xf
	v_pk_mul_f32 v[100:101], v[96:97], v[100:101] op_sel_hi:[0,1]
	v_cndmask_b32_e64 v109, v121, v109, s[0:1]
	v_lshlrev_b32_e32 v88, 16, v119
	v_and_b32_e32 v89, 0xffff0000, v119
	v_pk_mul_f32 v[100:101], v[56:57], v[100:101]
	v_cndmask_b32_e64 v107, v117, v107, s[0:1]
	v_pk_fma_f32 v[88:89], v[98:99], v[100:101], v[88:89]
	v_lshlrev_b32_e32 v100, 16, v109
	v_and_b32_e32 v101, 0xffff0000, v109
	v_pk_mul_f32 v[100:101], v[96:97], v[100:101] op_sel_hi:[0,1]
	v_lshlrev_b32_e32 v98, 16, v122
	v_and_b32_e32 v99, 0xffff0000, v122
	v_pk_mul_f32 v[100:101], v[62:63], v[100:101]
	v_mov_b32_e32 v113, v157
	v_pk_fma_f32 v[98:99], v[90:91], v[100:101], v[98:99]
	v_lshlrev_b32_e32 v100, 16, v107
	v_and_b32_e32 v101, 0xffff0000, v107
	v_pk_mul_f32 v[100:101], v[96:97], v[100:101] op_sel_hi:[0,1]
	v_lshlrev_b32_e32 v90, 16, v120
	v_and_b32_e32 v91, 0xffff0000, v120
	v_pk_mul_f32 v[100:101], v[58:59], v[100:101]
	v_mov_b32_e32 v114, v157
	v_pk_fma_f32 v[90:91], v[94:95], v[100:101], v[90:91]
	v_mov_b32_e32 v94, v157
	v_mov_b32_e32 v95, v157
	v_mov_b32_e32 v109, v157
	v_mov_b32_e32 v117, v157
	v_mov_b32_dpp v94, v90 row_ror:8 row_mask:0xf bank_mask:0xf
	v_mov_b32_dpp v95, v91 row_ror:8 row_mask:0xf bank_mask:0xf
	v_mov_b32_dpp v113, v102 row_ror:8 row_mask:0xf bank_mask:0xf
	v_mov_b32_dpp v114, v103 row_ror:8 row_mask:0xf bank_mask:0xf
	v_mov_b32_e32 v106, v157
	v_mov_b32_e32 v115, v157
	v_mov_b32_dpp v109, v98 row_ror:8 row_mask:0xf bank_mask:0xf
	v_mov_b32_dpp v117, v99 row_ror:8 row_mask:0xf bank_mask:0xf
	v_cndmask_b32_e64 v101, v99, v95, s[0:1]
	v_cndmask_b32_e64 v100, v98, v94, s[0:1]
	v_lshlrev_b32_e32 v94, 16, v112
	v_and_b32_e32 v95, 0xffff0000, v112
	v_mov_b32_dpp v106, v88 row_ror:8 row_mask:0xf bank_mask:0xf
	v_mov_b32_dpp v115, v89 row_ror:8 row_mask:0xf bank_mask:0xf
	v_cndmask_b32_e64 v91, v117, v91, s[0:1]
	v_cndmask_b32_e64 v90, v109, v90, s[0:1]
	v_cndmask_b32_e64 v89, v114, v89, s[0:1]
	v_cndmask_b32_e64 v88, v113, v88, s[0:1]
	v_pk_mul_f32 v[94:95], v[96:97], v[94:95] op_sel_hi:[0,1]
	global_store_dwordx4 v[92:93], v[88:91], off
	v_pk_mul_f32 v[94:95], v[44:45], v[94:95]
	v_cndmask_b32_e64 v99, v103, v115, s[0:1]
	v_lshlrev_b32_e32 v90, 16, v104
	v_and_b32_e32 v91, 0xffff0000, v104
	v_pk_fma_f32 v[90:91], v[80:81], v[94:95], v[90:91]
	v_lshlrev_b32_e32 v94, 16, v110
	v_and_b32_e32 v95, 0xffff0000, v110
	v_pk_mul_f32 v[94:95], v[96:97], v[94:95] op_sel_hi:[0,1]
; __device__ __forceinline__ float bflo(unsigned w) { return __uint_as_float(w << 16); }
; __device__ __forceinline__ float bfhi(unsigned w) { return __uint_as_float(w & 0xffff0000u); }
;     const bool lo = fr < 8;
;     const int r1 = row - fr + (fr & 7), cb = col0 + (lo ? 0 : boff);
;     const u32x4 l1 = *(const u32x4*)(P + (size_t)r1 * ld + cb), l2 = *(const u32x4*)(P + (size_t)(r1 + 8) * ld + cb);
;     const u32x4 s1 = {dpp_ror8(l1.x), dpp_ror8(l1.y), dpp_ror8(l1.z), dpp_ror8(l1.w)}, s2 = {dpp_ror8(l2.x), dpp_ror8(l2.y), dpp_ror8(l2.z), dpp_ror8(l2.w)};
;     wA = lo ? l1 : s2; wB = lo ? s1 : l2;
; }
;     __device__ __forceinline__ void operator()(const f32x4 (&acc)[2][2][4][2], const Unit& u, int wr, int wc, int fr, int fq) const {
;     ...
;             for (int m = 0; m < 4; ++m) { const int row = row0 + ai * HALF + m * 16; const float ri = __builtin_amdgcn_rsqf(sse[row] * (1.f / D) + EPS);
;                 u32x4 rr[2], ee[2]; load_pair_lines(R, D, row, fr, col0, rr[0], rr[1], 32); load_pair_lines(E, D, row, fr, col0, ee[0], ee[1], 32);
;                 float* orow = OUT + (size_t)(row - fr + (fr & 7)) * D + col0 + (lo ? 0 : 4);
; #pragma unroll
;                 for (int bj = 0; bj < 2; ++bj) { const u32x4 rw = rr[bj], ew = ee[bj];
;                     const float r[8] = {bflo(rw.x), bfhi(rw.x), bflo(rw.y), bfhi(rw.y), bflo(rw.z), bfhi(rw.z), bflo(rw.w), bfhi(rw.w)};
;                     const float e[8] = {bflo(ew.x), bfhi(ew.x), bflo(ew.y), bfhi(ew.y), bflo(ew.z), bfhi(ew.z), bflo(ew.w), bfhi(ew.w)};
;                     float o[8];
; #pragma unroll
;                     for (int j = 0; j < 8; ++j) { const float a = acc[ai][bj][m][j >> 2][j & 3]; const float gg = gv[bj][j >> 2][j & 3];
;                         o[j] = r[j] + e[j] * ri * gg * __builtin_amdgcn_rcpf(1.f + __builtin_amdgcn_exp2f(-a * LOG2E)); }
;                     f32x4 o1, o2;
; #pragma unroll
;                     for (int j = 0; j < 4; ++j) { const unsigned a = __float_as_uint(o[j]), b = __float_as_uint(o[4 + j]); const unsigned sa = dpp_ror8(a), sb = dpp_ror8(b);
;                         o1[j] = __uint_as_float(lo ? a : sb); o2[j] = __uint_as_float(lo ? sa : b); }
;                     *(f32x4*)(orow + 32 * bj) = o1; *(f32x4*)(orow + (size_t)8 * D + 32 * bj) = o2; } }
	v_lshlrev_b32_e32 v80, 16, v97
	v_and_b32_e32 v81, 0xffff0000, v97
	v_pk_mul_f32 v[94:95], v[40:41], v[94:95]
	v_mov_b32_e32 v97, v157
	v_pk_fma_f32 v[80:81], v[84:85], v[94:95], v[80:81]
	v_lshlrev_b32_e32 v94, 16, v111
	v_and_b32_e32 v95, 0xffff0000, v111
	v_mov_b32_dpp v97, v80 row_ror:8 row_mask:0xf bank_mask:0xf
	v_pk_mul_f32 v[94:95], v[96:97], v[94:95] op_sel_hi:[0,1]
	v_lshlrev_b32_e32 v84, 16, v105
	v_and_b32_e32 v85, 0xffff0000, v105
	v_pk_mul_f32 v[94:95], v[46:47], v[94:95]
	v_add_co_u32_e32 v88, vcc, s45, v92
	v_pk_fma_f32 v[84:85], v[82:83], v[94:95], v[84:85]
	v_lshlrev_b32_e32 v94, 16, v108
	v_and_b32_e32 v95, 0xffff0000, v108
	v_cndmask_b32_e64 v98, v102, v106, s[0:1]
	v_addc_co_u32_e32 v89, vcc, 0, v93, vcc
	v_pk_mul_f32 v[94:95], v[96:97], v[94:95] op_sel_hi:[0,1]
	global_store_dwordx4 v[88:89], v[98:101], off
	v_mov_b32_e32 v102, v157
	v_lshlrev_b32_e32 v82, 16, v116
	v_mov_b32_e32 v98, v157
	v_mov_b32_e32 v99, v157
	v_mov_b32_e32 v101, v157
	v_and_b32_e32 v83, 0xffff0000, v116
	v_pk_mul_f32 v[94:95], v[42:43], v[94:95]
	v_mov_b32_dpp v98, v90 row_ror:8 row_mask:0xf bank_mask:0xf
	v_mov_b32_dpp v99, v91 row_ror:8 row_mask:0xf bank_mask:0xf
	v_mov_b32_e32 v100, v157
	v_mov_b32_dpp v101, v84 row_ror:8 row_mask:0xf bank_mask:0xf
	v_mov_b32_dpp v102, v85 row_ror:8 row_mask:0xf bank_mask:0xf
	v_pk_fma_f32 v[82:83], v[86:87], v[94:95], v[82:83]
	v_mov_b32_e32 v86, v157
	v_mov_b32_e32 v87, v157
	v_mov_b32_dpp v100, v81 row_ror:8 row_mask:0xf bank_mask:0xf
	v_mov_b32_dpp v86, v82 row_ror:8 row_mask:0xf bank_mask:0xf
	v_mov_b32_dpp v87, v83 row_ror:8 row_mask:0xf bank_mask:0xf
	v_cndmask_b32_e64 v83, v102, v83, s[0:1]
	v_cndmask_b32_e64 v82, v101, v82, s[0:1]
	v_cndmask_b32_e64 v81, v99, v81, s[0:1]
	v_cndmask_b32_e64 v80, v98, v80, s[0:1]
	v_cndmask_b32_e64 v87, v85, v87, s[0:1]
	v_cndmask_b32_e64 v86, v84, v86, s[0:1]
	v_cndmask_b32_e64 v85, v91, v100, s[0:1]
	v_cndmask_b32_e64 v84, v90, v97, s[0:1]
	global_store_dwordx4 v[92:93], v[80:83], off offset:128
	global_store_dwordx4 v[88:89], v[84:87], off offset:128
	s_waitcnt vmcnt(4)
	s_nop 0
	v_mov_b32_e32 v80, v228
	v_sub_u32_e32 v81, v170, v174
	v_add_u32_e32 v81, v81, v176
	v_add_u32_e32 v98, 0x80, v81
	v_ashrrev_i32_e32 v99, 31, v98
	v_lshlrev_b64 v[90:91], 12, v[98:99]
	v_lshl_add_u64 v[94:95], v[90:91], 0, s[16:17]
	v_lshl_add_u64 v[82:83], s[8:9], 0, v[90:91]
	v_lshl_add_u64 v[86:87], s[8:9], 0, v[94:95]
	v_lshl_add_u64 v[82:83], v[82:83], 0, v[164:165]
	v_lshl_add_u64 v[86:87], v[86:87], 0, v[164:165]
	v_mov_b64_e32 v[82:83], v[232:233]
	v_mov_b64_e32 v[84:85], v[234:235]
	v_lshl_add_u64 v[90:91], s[10:11], 0, v[90:91]
	v_mov_b64_e32 v[86:87], v[236:237]
	v_mov_b64_e32 v[88:89], v[238:239]
	v_lshl_add_u64 v[90:91], v[90:91], 0, v[164:165]
	v_lshl_add_u64 v[94:95], s[10:11], 0, v[94:95]
	v_mov_b64_e32 v[90:91], v[240:241]
	v_mov_b64_e32 v[92:93], v[242:243]
	v_lshl_add_u64 v[94:95], v[94:95], 0, v[164:165]
	v_mov_b64_e32 v[94:95], v[244:245]
	v_mov_b64_e32 v[96:97], v[246:247]
	s_nop 1
	v_add_u32_e32 v222, 0x90, v81
	v_ashrrev_i32_e32 v223, 31, v222
	global_load_dword v228, v[168:169], off offset:576
	v_lshlrev_b64 v[216:217], 12, v[222:223]
	v_lshl_add_u64 v[224:225], v[216:217], 0, s[16:17]
	v_lshl_add_u64 v[220:221], s[8:9], 0, v[224:225]
	v_lshl_add_u64 v[218:219], s[8:9], 0, v[216:217]
	v_lshl_add_u64 v[220:221], v[220:221], 0, v[164:165]
	v_lshl_add_u64 v[216:217], s[10:11], 0, v[216:217]
	v_lshl_add_u64 v[218:219], v[218:219], 0, v[164:165]
	global_load_dwordx4 v[232:235], v[220:221], off
	v_lshl_add_u64 v[216:217], v[216:217], 0, v[164:165]
	global_load_dwordx4 v[236:239], v[218:219], off
	global_load_dwordx4 v[240:243], v[216:217], off
	v_lshl_add_u64 v[216:217], s[10:11], 0, v[224:225]
	v_lshl_add_u64 v[216:217], v[216:217], 0, v[164:165]
	global_load_dwordx4 v[244:247], v[216:217], off
	v_mov_b32_e32 v106, v157
	v_mov_b32_e32 v107, v157
	v_mov_b32_e32 v100, v157
	v_mov_b32_e32 v101, v157
	v_mov_b32_e32 v102, v157
	v_mov_b32_e32 v103, v157
	v_mov_b32_e32 v105, v157
	v_mov_b32_e32 v104, v157
	v_add_f32_e32 v79, 1.0, v79
	v_mul_f32_e32 v64, 0xbfb8aa3b, v64
	v_mul_f32_e32 v65, 0xbfb8aa3b, v65
	v_rcp_f32_e32 v78, v78
	v_rcp_f32_e32 v79, v79
	v_exp_f32_e32 v64, v64
	v_exp_f32_e32 v65, v65
	v_mul_f32_e32 v68, 0xbfb8aa3b, v68
	v_mul_f32_e32 v69, 0xbfb8aa3b, v69
	v_exp_f32_e32 v68, v68
	v_exp_f32_e32 v69, v69
	v_add_f32_e32 v64, 1.0, v64
	v_add_f32_e32 v65, 1.0, v65
	v_rcp_f32_e32 v64, v64
	v_mul_f32_e32 v66, 0xbfb8aa3b, v66
	v_mul_f32_e32 v67, 0xbfb8aa3b, v67
	v_rcp_f32_e32 v65, v65
	v_exp_f32_e32 v66, v66
	v_exp_f32_e32 v67, v67
	v_add_f32_e32 v68, 1.0, v68
	v_add_f32_e32 v69, 1.0, v69
	v_rcp_f32_e32 v68, v68
	v_mul_f32_e32 v70, 0xbfb8aa3b, v70
	v_mul_f32_e32 v71, 0xbfb8aa3b, v71
	v_rcp_f32_e32 v69, v69
	v_exp_f32_e32 v70, v70
	v_exp_f32_e32 v71, v71
	v_add_f32_e32 v66, 1.0, v66
	v_add_f32_e32 v67, 1.0, v67
	v_rcp_f32_e32 v66, v66
	v_rcp_f32_e32 v67, v67
	v_add_f32_e32 v70, 1.0, v70
	v_add_f32_e32 v71, 1.0, v71
	v_rcp_f32_e32 v70, v70
	v_rcp_f32_e32 v71, v71
	v_mul_f32_e32 v48, 0xbfb8aa3b, v48
	v_mul_f32_e32 v49, 0xbfb8aa3b, v49
	v_mul_f32_e32 v52, 0xbfb8aa3b, v52
	v_exp_f32_e32 v48, v48
	v_exp_f32_e32 v49, v49
	v_mul_f32_e32 v50, 0xbfb8aa3b, v50
	v_mul_f32_e32 v51, 0xbfb8aa3b, v51
	v_add_f32_e32 v48, 1.0, v48
	v_add_f32_e32 v49, 1.0, v49
	v_rcp_f32_e32 v48, v48
	v_rcp_f32_e32 v49, v49
	v_exp_f32_e32 v50, v50
	v_exp_f32_e32 v51, v51
	v_mul_f32_e32 v54, 0xbfb8aa3b, v54
	v_mul_f32_e32 v55, 0xbfb8aa3b, v55
	v_exp_f32_e32 v54, v54
	v_exp_f32_e32 v55, v55
	v_add_f32_e32 v50, 1.0, v50
	v_fmamk_f32 v80, v80, 0x3a000000, v182
	v_rsq_f32_e32 v80, v80
	v_add_f32_e32 v51, 1.0, v51
; __device__ __forceinline__ float bflo(unsigned w) { return __uint_as_float(w << 16); }
; __device__ __forceinline__ float bfhi(unsigned w) { return __uint_as_float(w & 0xffff0000u); }
;     const bool lo = fr < 8;
;     const int r1 = row - fr + (fr & 7), cb = col0 + (lo ? 0 : boff);
;     const u32x4 l1 = *(const u32x4*)(P + (size_t)r1 * ld + cb), l2 = *(const u32x4*)(P + (size_t)(r1 + 8) * ld + cb);
;     const u32x4 s1 = {dpp_ror8(l1.x), dpp_ror8(l1.y), dpp_ror8(l1.z), dpp_ror8(l1.w)}, s2 = {dpp_ror8(l2.x), dpp_ror8(l2.y), dpp_ror8(l2.z), dpp_ror8(l2.w)};
;     wA = lo ? l1 : s2; wB = lo ? s1 : l2;
; }
;     __device__ __forceinline__ void operator()(const f32x4 (&acc)[2][2][4][2], const Unit& u, int wr, int wc, int fr, int fq) const {
;     ...
;             for (int m = 0; m < 4; ++m) { const int row = row0 + ai * HALF + m * 16; const float ri = __builtin_amdgcn_rsqf(sse[row] * (1.f / D) + EPS);
;                 u32x4 rr[2], ee[2]; load_pair_lines(R, D, row, fr, col0, rr[0], rr[1], 32); load_pair_lines(E, D, row, fr, col0, ee[0], ee[1], 32);
;                 float* orow = OUT + (size_t)(row - fr + (fr & 7)) * D + col0 + (lo ? 0 : 4);
; #pragma unroll
;                 for (int bj = 0; bj < 2; ++bj) { const u32x4 rw = rr[bj], ew = ee[bj];
;                     const float r[8] = {bflo(rw.x), bfhi(rw.x), bflo(rw.y), bfhi(rw.y), bflo(rw.z), bfhi(rw.z), bflo(rw.w), bfhi(rw.w)};
;                     const float e[8] = {bflo(ew.x), bfhi(ew.x), bflo(ew.y), bfhi(ew.y), bflo(ew.z), bfhi(ew.z), bflo(ew.w), bfhi(ew.w)};
;                     float o[8];
; #pragma unroll
;                     for (int j = 0; j < 8; ++j) { const float a = acc[ai][bj][m][j >> 2][j & 3]; const float gg = gv[bj][j >> 2][j & 3];
;                         o[j] = r[j] + e[j] * ri * gg * __builtin_amdgcn_rcpf(1.f + __builtin_amdgcn_exp2f(-a * LOG2E)); }
;                     f32x4 o1, o2;
; #pragma unroll
;                     for (int j = 0; j < 4; ++j) { const unsigned a = __float_as_uint(o[j]), b = __float_as_uint(o[4 + j]); const unsigned sa = dpp_ror8(a), sb = dpp_ror8(b);
;                         o1[j] = __uint_as_float(lo ? a : sb); o2[j] = __uint_as_float(lo ? sa : b); }
;                     *(f32x4*)(orow + 32 * bj) = o1; *(f32x4*)(orow + (size_t)8 * D + 32 * bj) = o2; } }
	v_rcp_f32_e32 v50, v50
	v_rcp_f32_e32 v51, v51
	v_add_f32_e32 v54, 1.0, v54
	v_add_f32_e32 v55, 1.0, v55
	v_mul_f32_e32 v32, 0xbfb8aa3b, v32
	v_mul_f32_e32 v33, 0xbfb8aa3b, v33
	v_rcp_f32_e32 v54, v54
	v_rcp_f32_e32 v55, v55
	v_mov_b32_dpp v100, v82 row_ror:8 row_mask:0xf bank_mask:0xf
	v_mov_b32_dpp v101, v83 row_ror:8 row_mask:0xf bank_mask:0xf
	v_mov_b32_dpp v106, v88 row_ror:8 row_mask:0xf bank_mask:0xf
	v_mov_b32_dpp v107, v89 row_ror:8 row_mask:0xf bank_mask:0xf
	v_mov_b32_dpp v102, v84 row_ror:8 row_mask:0xf bank_mask:0xf
	v_mov_b32_dpp v103, v85 row_ror:8 row_mask:0xf bank_mask:0xf
	v_mov_b32_dpp v105, v87 row_ror:8 row_mask:0xf bank_mask:0xf
	v_cndmask_b32_e64 v107, v107, v85, s[0:1]
	v_cndmask_b32_e64 v85, v106, v84, s[0:1]
	v_mov_b32_e32 v84, v157
	v_mov_b32_dpp v104, v86 row_ror:8 row_mask:0xf bank_mask:0xf
	v_cndmask_b32_e64 v105, v105, v83, s[0:1]
	v_cndmask_b32_e64 v101, v87, v101, s[0:1]
	v_cndmask_b32_e64 v89, v89, v103, s[0:1]
	v_cndmask_b32_e64 v100, v86, v100, s[0:1]
	v_mov_b32_e32 v83, v157
	v_mov_b32_dpp v84, v92 row_ror:8 row_mask:0xf bank_mask:0xf
	v_mov_b32_e32 v86, v157
	v_mov_b32_e32 v87, v157
	v_mov_b32_e32 v103, v157
	v_cndmask_b32_e64 v104, v104, v82, s[0:1]
	v_cndmask_b32_e64 v88, v88, v102, s[0:1]
	v_mov_b32_e32 v82, v157
	v_mov_b32_dpp v83, v91 row_ror:8 row_mask:0xf bank_mask:0xf
	v_mov_b32_dpp v86, v93 row_ror:8 row_mask:0xf bank_mask:0xf
	v_mov_b32_dpp v87, v94 row_ror:8 row_mask:0xf bank_mask:0xf
	v_mov_b32_e32 v102, v157
	v_mov_b32_dpp v103, v96 row_ror:8 row_mask:0xf bank_mask:0xf
	v_cndmask_b32_e64 v96, v96, v84, s[0:1]
	v_exp_f32_e32 v84, v76
	v_mul_f32_e32 v76, 0xbfb8aa3b, v77
	v_mov_b32_dpp v82, v90 row_ror:8 row_mask:0xf bank_mask:0xf
	v_mov_b32_dpp v102, v95 row_ror:8 row_mask:0xf bank_mask:0xf
	v_cndmask_b32_e64 v90, v87, v90, s[0:1]
	v_cndmask_b32_e64 v87, v103, v92, s[0:1]
	v_cndmask_b32_e64 v92, v95, v83, s[0:1]
	v_cndmask_b32_e64 v95, v97, v86, s[0:1]
	v_exp_f32_e32 v86, v76
	v_cndmask_b32_e64 v94, v94, v82, s[0:1]
	v_lshlrev_b64 v[82:83], 13, v[98:99]
	v_lshl_add_u64 v[82:83], s[4:5], 0, v[82:83]
	v_lshl_add_u64 v[82:83], v[82:83], 0, v[166:167]
	v_lshl_add_u64 v[76:77], v[82:83], 0, v[156:157]
	v_add_f32_e32 v83, 1.0, v86
	v_lshlrev_b32_e32 v86, 16, v87
	v_and_b32_e32 v87, 0xffff0000, v87
	v_add_f32_e32 v82, 1.0, v84
	v_pk_mul_f32 v[86:87], v[80:81], v[86:87] op_sel_hi:[0,1]
	v_rcp_f32_e32 v82, v82
	v_rcp_f32_e32 v83, v83
	v_lshlrev_b32_e32 v84, 16, v85
	v_and_b32_e32 v85, 0xffff0000, v85
	v_pk_mul_f32 v[86:87], v[60:61], v[86:87]
	v_mov_b32_e32 v106, v157
	v_pk_fma_f32 v[86:87], v[72:73], v[86:87], v[84:85]
	v_lshlrev_b32_e32 v84, 16, v90
	v_and_b32_e32 v85, 0xffff0000, v90
	v_mov_b32_dpp v106, v97 row_ror:8 row_mask:0xf bank_mask:0xf
	v_pk_mul_f32 v[84:85], v[80:81], v[84:85] op_sel_hi:[0,1]
	v_cndmask_b32_e64 v93, v106, v93, s[0:1]
	v_lshlrev_b32_e32 v72, 16, v104
	v_and_b32_e32 v73, 0xffff0000, v104
	v_pk_mul_f32 v[84:85], v[56:57], v[84:85]
	v_cndmask_b32_e64 v91, v102, v91, s[0:1]
	v_pk_fma_f32 v[72:73], v[82:83], v[84:85], v[72:73]
	v_lshlrev_b32_e32 v84, 16, v93
	v_and_b32_e32 v85, 0xffff0000, v93
	v_pk_mul_f32 v[84:85], v[80:81], v[84:85] op_sel_hi:[0,1]
	v_lshlrev_b32_e32 v82, 16, v107
	v_and_b32_e32 v83, 0xffff0000, v107
	v_pk_mul_f32 v[84:85], v[62:63], v[84:85]
	v_mov_b32_e32 v97, v157
	v_pk_fma_f32 v[82:83], v[74:75], v[84:85], v[82:83]
	v_lshlrev_b32_e32 v84, 16, v91
	v_and_b32_e32 v85, 0xffff0000, v91
	v_pk_mul_f32 v[84:85], v[80:81], v[84:85] op_sel_hi:[0,1]
	v_lshlrev_b32_e32 v74, 16, v105
	v_and_b32_e32 v75, 0xffff0000, v105
	v_pk_mul_f32 v[84:85], v[58:59], v[84:85]
	v_mov_b32_e32 v98, v157
	v_pk_fma_f32 v[74:75], v[78:79], v[84:85], v[74:75]
	v_mov_b32_e32 v78, v157
	v_mov_b32_e32 v79, v157
	v_mov_b32_e32 v93, v157
	v_mov_b32_e32 v102, v157
	v_mov_b32_dpp v78, v74 row_ror:8 row_mask:0xf bank_mask:0xf
	v_mov_b32_dpp v79, v75 row_ror:8 row_mask:0xf bank_mask:0xf
	v_mov_b32_dpp v97, v86 row_ror:8 row_mask:0xf bank_mask:0xf
	v_mov_b32_dpp v98, v87 row_ror:8 row_mask:0xf bank_mask:0xf
	v_mov_b32_e32 v90, v157
	v_mov_b32_e32 v99, v157
	v_mov_b32_dpp v93, v82 row_ror:8 row_mask:0xf bank_mask:0xf
	v_mov_b32_dpp v102, v83 row_ror:8 row_mask:0xf bank_mask:0xf
	v_cndmask_b32_e64 v85, v83, v79, s[0:1]
	v_cndmask_b32_e64 v84, v82, v78, s[0:1]
	v_lshlrev_b32_e32 v78, 16, v96
	v_and_b32_e32 v79, 0xffff0000, v96
	v_mov_b32_dpp v90, v72 row_ror:8 row_mask:0xf bank_mask:0xf
	v_mov_b32_dpp v99, v73 row_ror:8 row_mask:0xf bank_mask:0xf
	v_cndmask_b32_e64 v75, v102, v75, s[0:1]
	v_cndmask_b32_e64 v74, v93, v74, s[0:1]
	v_cndmask_b32_e64 v73, v98, v73, s[0:1]
	v_cndmask_b32_e64 v72, v97, v72, s[0:1]
	v_pk_mul_f32 v[78:79], v[80:81], v[78:79] op_sel_hi:[0,1]
	global_store_dwordx4 v[76:77], v[72:75], off
	v_pk_mul_f32 v[78:79], v[44:45], v[78:79]
	v_cndmask_b32_e64 v83, v87, v99, s[0:1]
	v_lshlrev_b32_e32 v74, 16, v88
	v_and_b32_e32 v75, 0xffff0000, v88
	v_pk_fma_f32 v[74:75], v[64:65], v[78:79], v[74:75]
	v_lshlrev_b32_e32 v78, 16, v94
	v_and_b32_e32 v79, 0xffff0000, v94
	v_pk_mul_f32 v[78:79], v[80:81], v[78:79] op_sel_hi:[0,1]
	v_lshlrev_b32_e32 v64, 16, v100
	v_and_b32_e32 v65, 0xffff0000, v100
	v_pk_mul_f32 v[78:79], v[40:41], v[78:79]
	v_add_co_u32_e32 v72, vcc, s45, v76
	v_pk_fma_f32 v[64:65], v[68:69], v[78:79], v[64:65]
	v_lshlrev_b32_e32 v78, 16, v95
	v_and_b32_e32 v79, 0xffff0000, v95
	v_pk_mul_f32 v[78:79], v[80:81], v[78:79] op_sel_hi:[0,1]
	v_lshlrev_b32_e32 v68, 16, v89
	v_and_b32_e32 v69, 0xffff0000, v89
	v_pk_mul_f32 v[78:79], v[46:47], v[78:79]
	v_cndmask_b32_e64 v82, v86, v90, s[0:1]
	v_pk_fma_f32 v[68:69], v[66:67], v[78:79], v[68:69]
	v_lshlrev_b32_e32 v78, 16, v92
; __device__ __forceinline__ float bflo(unsigned w) { return __uint_as_float(w << 16); }
; __device__ __forceinline__ float bfhi(unsigned w) { return __uint_as_float(w & 0xffff0000u); }
;     const bool lo = fr < 8;
;     const int r1 = row - fr + (fr & 7), cb = col0 + (lo ? 0 : boff);
;     const u32x4 l1 = *(const u32x4*)(P + (size_t)r1 * ld + cb), l2 = *(const u32x4*)(P + (size_t)(r1 + 8) * ld + cb);
;     const u32x4 s1 = {dpp_ror8(l1.x), dpp_ror8(l1.y), dpp_ror8(l1.z), dpp_ror8(l1.w)}, s2 = {dpp_ror8(l2.x), dpp_ror8(l2.y), dpp_ror8(l2.z), dpp_ror8(l2.w)};
;     wA = lo ? l1 : s2; wB = lo ? s1 : l2;
; }
;     __device__ __forceinline__ void operator()(const f32x4 (&acc)[2][2][4][2], const Unit& u, int wr, int wc, int fr, int fq) const {
;     ...
;             for (int m = 0; m < 4; ++m) { const int row = row0 + ai * HALF + m * 16; const float ri = __builtin_amdgcn_rsqf(sse[row] * (1.f / D) + EPS);
;                 u32x4 rr[2], ee[2]; load_pair_lines(R, D, row, fr, col0, rr[0], rr[1], 32); load_pair_lines(E, D, row, fr, col0, ee[0], ee[1], 32);
;                 float* orow = OUT + (size_t)(row - fr + (fr & 7)) * D + col0 + (lo ? 0 : 4);
; #pragma unroll
;                 for (int bj = 0; bj < 2; ++bj) { const u32x4 rw = rr[bj], ew = ee[bj];
;                     const float r[8] = {bflo(rw.x), bfhi(rw.x), bflo(rw.y), bfhi(rw.y), bflo(rw.z), bfhi(rw.z), bflo(rw.w), bfhi(rw.w)};
;                     const float e[8] = {bflo(ew.x), bfhi(ew.x), bflo(ew.y), bfhi(ew.y), bflo(ew.z), bfhi(ew.z), bflo(ew.w), bfhi(ew.w)};
;                     float o[8];
; #pragma unroll
;                     for (int j = 0; j < 8; ++j) { const float a = acc[ai][bj][m][j >> 2][j & 3]; const float gg = gv[bj][j >> 2][j & 3];
;                         o[j] = r[j] + e[j] * ri * gg * __builtin_amdgcn_rcpf(1.f + __builtin_amdgcn_exp2f(-a * LOG2E)); }
;                     f32x4 o1, o2;
; #pragma unroll
;                     for (int j = 0; j < 4; ++j) { const unsigned a = __float_as_uint(o[j]), b = __float_as_uint(o[4 + j]); const unsigned sa = dpp_ror8(a), sb = dpp_ror8(b);
;                         o1[j] = __uint_as_float(lo ? a : sb); o2[j] = __uint_as_float(lo ? sa : b); }
;                     *(f32x4*)(orow + 32 * bj) = o1; *(f32x4*)(orow + (size_t)8 * D + 32 * bj) = o2; } }
	v_and_b32_e32 v79, 0xffff0000, v92
	v_addc_co_u32_e32 v73, vcc, 0, v77, vcc
	v_pk_mul_f32 v[78:79], v[80:81], v[78:79] op_sel_hi:[0,1]
	global_store_dwordx4 v[72:73], v[82:85], off
	v_mov_b32_e32 v86, v157
	v_mov_b32_e32 v87, v157
	v_mov_b32_e32 v82, v157
	v_mov_b32_e32 v83, v157
	v_lshlrev_b32_e32 v66, 16, v101
	v_and_b32_e32 v67, 0xffff0000, v101
	v_pk_mul_f32 v[78:79], v[42:43], v[78:79]
	v_mov_b32_dpp v82, v74 row_ror:8 row_mask:0xf bank_mask:0xf
	v_mov_b32_dpp v83, v75 row_ror:8 row_mask:0xf bank_mask:0xf
	v_mov_b32_e32 v84, v157
	v_mov_b32_e32 v85, v157
	v_mov_b32_dpp v86, v68 row_ror:8 row_mask:0xf bank_mask:0xf
	v_mov_b32_dpp v87, v69 row_ror:8 row_mask:0xf bank_mask:0xf
	v_pk_fma_f32 v[66:67], v[70:71], v[78:79], v[66:67]
	v_mov_b32_e32 v70, v157
	v_mov_b32_e32 v71, v157
	v_add_u32_e32 v78, 0x90, v81
	v_mov_b32_dpp v84, v64 row_ror:8 row_mask:0xf bank_mask:0xf
	v_mov_b32_dpp v85, v65 row_ror:8 row_mask:0xf bank_mask:0xf
	v_mov_b32_dpp v70, v66 row_ror:8 row_mask:0xf bank_mask:0xf
	v_mov_b32_dpp v71, v67 row_ror:8 row_mask:0xf bank_mask:0xf
	v_cndmask_b32_e64 v67, v87, v67, s[0:1]
	v_cndmask_b32_e64 v66, v86, v66, s[0:1]
	v_cndmask_b32_e64 v65, v83, v65, s[0:1]
	v_cndmask_b32_e64 v64, v82, v64, s[0:1]
	v_ashrrev_i32_e32 v79, 31, v78
	v_cndmask_b32_e64 v71, v69, v71, s[0:1]
	v_cndmask_b32_e64 v70, v68, v70, s[0:1]
	v_cndmask_b32_e64 v69, v75, v85, s[0:1]
	v_cndmask_b32_e64 v68, v74, v84, s[0:1]
	global_store_dwordx4 v[76:77], v[64:67], off offset:128
	global_store_dwordx4 v[72:73], v[68:71], off offset:128
	s_waitcnt vmcnt(4)
	s_nop 0
	v_mov_b32_e32 v80, v228
	v_lshlrev_b64 v[64:65], 12, v[78:79]
	v_lshl_add_u64 v[82:83], v[64:65], 0, s[16:17]
	v_lshl_add_u64 v[70:71], s[8:9], 0, v[82:83]
	v_lshl_add_u64 v[66:67], s[8:9], 0, v[64:65]
	v_lshl_add_u64 v[70:71], v[70:71], 0, v[164:165]
	v_lshl_add_u64 v[64:65], s[10:11], 0, v[64:65]
	v_lshl_add_u64 v[66:67], v[66:67], 0, v[164:165]
	v_mov_b64_e32 v[70:71], v[232:233]
	v_mov_b64_e32 v[72:73], v[234:235]
	v_lshl_add_u64 v[64:65], v[64:65], 0, v[164:165]
	v_mov_b64_e32 v[66:67], v[236:237]
	v_mov_b64_e32 v[68:69], v[238:239]
	v_mov_b32_e32 v90, v157
	v_mov_b64_e32 v[74:75], v[240:241]
	v_mov_b64_e32 v[76:77], v[242:243]
	v_lshl_add_u64 v[64:65], s[10:11], 0, v[82:83]
	v_lshl_add_u64 v[64:65], v[64:65], 0, v[164:165]
	v_mov_b64_e32 v[82:83], v[244:245]
	v_mov_b64_e32 v[84:85], v[246:247]
	s_nop 1
	global_load_dword v228, v[168:169], off offset:640
	v_add_u32_e32 v220, 0xa0, v81
	v_ashrrev_i32_e32 v221, 31, v220
	v_lshlrev_b64 v[216:217], 12, v[220:221]
	v_lshl_add_u64 v[224:225], v[216:217], 0, s[16:17]
	v_lshl_add_u64 v[222:223], s[8:9], 0, v[224:225]
	v_lshl_add_u64 v[218:219], s[8:9], 0, v[216:217]
	v_lshl_add_u64 v[222:223], v[222:223], 0, v[164:165]
	v_lshl_add_u64 v[216:217], s[10:11], 0, v[216:217]
	v_lshl_add_u64 v[218:219], v[218:219], 0, v[164:165]
	global_load_dwordx4 v[232:235], v[222:223], off
	v_lshl_add_u64 v[216:217], v[216:217], 0, v[164:165]
	global_load_dwordx4 v[236:239], v[218:219], off
	global_load_dwordx4 v[240:243], v[216:217], off
	v_lshl_add_u64 v[216:217], s[10:11], 0, v[224:225]
	v_lshl_add_u64 v[216:217], v[216:217], 0, v[164:165]
	global_load_dwordx4 v[244:247], v[216:217], off
	v_mov_b32_e32 v91, v157
	v_mov_b32_e32 v65, v157
	v_mov_b32_e32 v86, v157
	v_mov_b32_e32 v87, v157
	v_mov_b32_e32 v89, v157
	v_mov_b32_e32 v88, v157
	v_exp_f32_e32 v32, v32
	v_exp_f32_e32 v33, v33
	v_mul_f32_e32 v36, 0xbfb8aa3b, v36
	v_mul_f32_e32 v37, 0xbfb8aa3b, v37
	v_exp_f32_e32 v36, v36
	v_exp_f32_e32 v37, v37
	v_add_f32_e32 v32, 1.0, v32
	v_add_f32_e32 v33, 1.0, v33
	v_rcp_f32_e32 v32, v32
	v_rcp_f32_e32 v33, v33
	v_mul_f32_e32 v34, 0xbfb8aa3b, v34
	v_mul_f32_e32 v35, 0xbfb8aa3b, v35
	v_add_f32_e32 v36, 1.0, v36
	v_add_f32_e32 v37, 1.0, v37
	v_exp_f32_e32 v34, v34
	v_exp_f32_e32 v35, v35
	v_rcp_f32_e32 v36, v36
	v_rcp_f32_e32 v37, v37
	v_mul_f32_e32 v38, 0xbfb8aa3b, v38
	v_mul_f32_e32 v39, 0xbfb8aa3b, v39
	v_exp_f32_e32 v38, v38
	v_exp_f32_e32 v39, v39
	v_add_f32_e32 v34, 1.0, v34
	v_add_f32_e32 v35, 1.0, v35
	v_rcp_f32_e32 v34, v34
	v_rcp_f32_e32 v35, v35
	v_add_f32_e32 v38, 1.0, v38
	v_add_f32_e32 v39, 1.0, v39
	v_rcp_f32_e32 v38, v38
	v_rcp_f32_e32 v39, v39
	v_mul_f32_e32 v24, 0xbfb8aa3b, v24
	v_mul_f32_e32 v25, 0xbfb8aa3b, v25
	v_mul_f32_e32 v28, 0xbfb8aa3b, v28
	v_exp_f32_e32 v24, v24
	v_exp_f32_e32 v25, v25
	v_mul_f32_e32 v26, 0xbfb8aa3b, v26
	v_mul_f32_e32 v27, 0xbfb8aa3b, v27
	v_add_f32_e32 v24, 1.0, v24
	v_add_f32_e32 v25, 1.0, v25
	v_rcp_f32_e32 v24, v24
	v_rcp_f32_e32 v25, v25
	v_exp_f32_e32 v26, v26
	v_exp_f32_e32 v27, v27
	v_mul_f32_e32 v30, 0xbfb8aa3b, v30
	v_mul_f32_e32 v31, 0xbfb8aa3b, v31
	v_exp_f32_e32 v30, v30
	v_exp_f32_e32 v31, v31
	v_add_f32_e32 v26, 1.0, v26
	v_add_f32_e32 v27, 1.0, v27
	v_rcp_f32_e32 v26, v26
	v_rcp_f32_e32 v27, v27
	v_add_f32_e32 v30, 1.0, v30
	v_add_f32_e32 v31, 1.0, v31
	v_mul_f32_e32 v16, 0xbfb8aa3b, v16
	v_mul_f32_e32 v17, 0xbfb8aa3b, v17
	v_rcp_f32_e32 v30, v30
	v_rcp_f32_e32 v31, v31
	v_exp_f32_e32 v16, v16
	v_fmamk_f32 v64, v80, 0x3a000000, v182
	v_mov_b32_e32 v80, v157
	v_rsq_f32_e32 v64, v64
	v_exp_f32_e32 v17, v17
	v_mul_f32_e32 v20, 0xbfb8aa3b, v20
	v_mul_f32_e32 v21, 0xbfb8aa3b, v21
	v_exp_f32_e32 v20, v20
	v_exp_f32_e32 v21, v21
	v_mov_b32_dpp v90, v72 row_ror:8 row_mask:0xf bank_mask:0xf
	v_mov_b32_dpp v91, v73 row_ror:8 row_mask:0xf bank_mask:0xf
	v_mov_b32_dpp v65, v66 row_ror:8 row_mask:0xf bank_mask:0xf
	v_mov_b32_dpp v80, v67 row_ror:8 row_mask:0xf bank_mask:0xf
	v_mov_b32_dpp v86, v68 row_ror:8 row_mask:0xf bank_mask:0xf
	v_mov_b32_dpp v87, v69 row_ror:8 row_mask:0xf bank_mask:0xf
	v_mov_b32_dpp v89, v71 row_ror:8 row_mask:0xf bank_mask:0xf
; __device__ __forceinline__ float bflo(unsigned w) { return __uint_as_float(w << 16); }
; __device__ __forceinline__ float bfhi(unsigned w) { return __uint_as_float(w & 0xffff0000u); }
;     const bool lo = fr < 8;
;     const int r1 = row - fr + (fr & 7), cb = col0 + (lo ? 0 : boff);
;     const u32x4 l1 = *(const u32x4*)(P + (size_t)r1 * ld + cb), l2 = *(const u32x4*)(P + (size_t)(r1 + 8) * ld + cb);
;     const u32x4 s1 = {dpp_ror8(l1.x), dpp_ror8(l1.y), dpp_ror8(l1.z), dpp_ror8(l1.w)}, s2 = {dpp_ror8(l2.x), dpp_ror8(l2.y), dpp_ror8(l2.z), dpp_ror8(l2.w)};
;     wA = lo ? l1 : s2; wB = lo ? s1 : l2;
; }
;     __device__ __forceinline__ void operator()(const f32x4 (&acc)[2][2][4][2], const Unit& u, int wr, int wc, int fr, int fq) const {
;     ...
;             for (int m = 0; m < 4; ++m) { const int row = row0 + ai * HALF + m * 16; const float ri = __builtin_amdgcn_rsqf(sse[row] * (1.f / D) + EPS);
;                 u32x4 rr[2], ee[2]; load_pair_lines(R, D, row, fr, col0, rr[0], rr[1], 32); load_pair_lines(E, D, row, fr, col0, ee[0], ee[1], 32);
;                 float* orow = OUT + (size_t)(row - fr + (fr & 7)) * D + col0 + (lo ? 0 : 4);
; #pragma unroll
;                 for (int bj = 0; bj < 2; ++bj) { const u32x4 rw = rr[bj], ew = ee[bj];
;                     const float r[8] = {bflo(rw.x), bfhi(rw.x), bflo(rw.y), bfhi(rw.y), bflo(rw.z), bfhi(rw.z), bflo(rw.w), bfhi(rw.w)};
;                     const float e[8] = {bflo(ew.x), bfhi(ew.x), bflo(ew.y), bfhi(ew.y), bflo(ew.z), bfhi(ew.z), bflo(ew.w), bfhi(ew.w)};
;                     float o[8];
; #pragma unroll
;                     for (int j = 0; j < 8; ++j) { const float a = acc[ai][bj][m][j >> 2][j & 3]; const float gg = gv[bj][j >> 2][j & 3];
;                         o[j] = r[j] + e[j] * ri * gg * __builtin_amdgcn_rcpf(1.f + __builtin_amdgcn_exp2f(-a * LOG2E)); }
;                     f32x4 o1, o2;
; #pragma unroll
;                     for (int j = 0; j < 4; ++j) { const unsigned a = __float_as_uint(o[j]), b = __float_as_uint(o[4 + j]); const unsigned sa = dpp_ror8(a), sb = dpp_ror8(b);
;                         o1[j] = __uint_as_float(lo ? a : sb); o2[j] = __uint_as_float(lo ? sa : b); }
;                     *(f32x4*)(orow + 32 * bj) = o1; *(f32x4*)(orow + (size_t)8 * D + 32 * bj) = o2; } }
	v_cndmask_b32_e64 v91, v91, v69, s[0:1]
	v_cndmask_b32_e64 v69, v90, v68, s[0:1]
	v_mov_b32_e32 v68, v157
	v_mov_b32_dpp v88, v70 row_ror:8 row_mask:0xf bank_mask:0xf
	v_cndmask_b32_e64 v89, v89, v67, s[0:1]
	v_cndmask_b32_e64 v80, v71, v80, s[0:1]
	v_cndmask_b32_e64 v73, v73, v87, s[0:1]
	v_cndmask_b32_e64 v65, v70, v65, s[0:1]
	v_mov_b32_e32 v67, v157
	v_mov_b32_dpp v68, v76 row_ror:8 row_mask:0xf bank_mask:0xf
	v_mov_b32_e32 v70, v157
	v_mov_b32_e32 v71, v157
	v_mov_b32_e32 v87, v157
	v_cndmask_b32_e64 v88, v88, v66, s[0:1]
	v_cndmask_b32_e64 v72, v72, v86, s[0:1]
	v_mov_b32_e32 v66, v157
	v_mov_b32_dpp v67, v75 row_ror:8 row_mask:0xf bank_mask:0xf
	v_mov_b32_dpp v70, v77 row_ror:8 row_mask:0xf bank_mask:0xf
	v_mov_b32_dpp v71, v82 row_ror:8 row_mask:0xf bank_mask:0xf
	v_mov_b32_e32 v86, v157
	v_mov_b32_dpp v87, v84 row_ror:8 row_mask:0xf bank_mask:0xf
	v_cndmask_b32_e64 v84, v84, v68, s[0:1]
	v_exp_f32_e32 v68, v52
	v_mul_f32_e32 v52, 0xbfb8aa3b, v53
	v_mov_b32_dpp v66, v74 row_ror:8 row_mask:0xf bank_mask:0xf
	v_mov_b32_dpp v86, v83 row_ror:8 row_mask:0xf bank_mask:0xf
	v_cndmask_b32_e64 v74, v71, v74, s[0:1]
	v_cndmask_b32_e64 v71, v87, v76, s[0:1]
	v_cndmask_b32_e64 v76, v83, v67, s[0:1]
	v_cndmask_b32_e64 v83, v85, v70, s[0:1]
	v_exp_f32_e32 v70, v52
	v_cndmask_b32_e64 v82, v82, v66, s[0:1]
	v_lshlrev_b64 v[66:67], 13, v[78:79]
	v_lshl_add_u64 v[66:67], s[4:5], 0, v[66:67]
	v_lshl_add_u64 v[66:67], v[66:67], 0, v[166:167]
	v_lshl_add_u64 v[52:53], v[66:67], 0, v[156:157]
	v_add_f32_e32 v67, 1.0, v70
	v_lshlrev_b32_e32 v70, 16, v71
	v_and_b32_e32 v71, 0xffff0000, v71
	v_add_f32_e32 v66, 1.0, v68
	v_pk_mul_f32 v[70:71], v[64:65], v[70:71] op_sel_hi:[0,1]
	v_rcp_f32_e32 v66, v66
	v_rcp_f32_e32 v67, v67
	v_lshlrev_b32_e32 v68, 16, v69
	v_and_b32_e32 v69, 0xffff0000, v69
	v_pk_mul_f32 v[70:71], v[60:61], v[70:71]
	v_mov_b32_e32 v90, v157
	v_pk_fma_f32 v[70:71], v[48:49], v[70:71], v[68:69]
	v_lshlrev_b32_e32 v68, 16, v74
	v_and_b32_e32 v69, 0xffff0000, v74
	v_mov_b32_dpp v90, v85 row_ror:8 row_mask:0xf bank_mask:0xf
	v_pk_mul_f32 v[68:69], v[64:65], v[68:69] op_sel_hi:[0,1]
	v_cndmask_b32_e64 v77, v90, v77, s[0:1]
	v_lshlrev_b32_e32 v48, 16, v88
	v_and_b32_e32 v49, 0xffff0000, v88
	v_pk_mul_f32 v[68:69], v[56:57], v[68:69]
	v_cndmask_b32_e64 v75, v86, v75, s[0:1]
	v_pk_fma_f32 v[48:49], v[66:67], v[68:69], v[48:49]
	v_lshlrev_b32_e32 v68, 16, v77
	v_and_b32_e32 v69, 0xffff0000, v77
	v_pk_mul_f32 v[68:69], v[64:65], v[68:69] op_sel_hi:[0,1]
	v_lshlrev_b32_e32 v66, 16, v91
	v_and_b32_e32 v67, 0xffff0000, v91
	v_pk_mul_f32 v[68:69], v[62:63], v[68:69]
	v_mov_b32_e32 v78, v157
	v_pk_fma_f32 v[66:67], v[50:51], v[68:69], v[66:67]
	v_lshlrev_b32_e32 v68, 16, v75
	v_and_b32_e32 v69, 0xffff0000, v75
	v_pk_mul_f32 v[68:69], v[64:65], v[68:69] op_sel_hi:[0,1]
	v_lshlrev_b32_e32 v50, 16, v89
	v_and_b32_e32 v51, 0xffff0000, v89
	v_pk_mul_f32 v[68:69], v[58:59], v[68:69]
	v_mov_b32_e32 v79, v157
	v_pk_fma_f32 v[50:51], v[54:55], v[68:69], v[50:51]
	v_mov_b32_e32 v54, v157
	v_mov_b32_e32 v55, v157
	v_mov_b32_e32 v77, v157
	v_mov_b32_e32 v86, v157
	v_mov_b32_dpp v54, v50 row_ror:8 row_mask:0xf bank_mask:0xf
	v_mov_b32_dpp v55, v51 row_ror:8 row_mask:0xf bank_mask:0xf
	v_mov_b32_dpp v78, v70 row_ror:8 row_mask:0xf bank_mask:0xf
	v_mov_b32_dpp v79, v71 row_ror:8 row_mask:0xf bank_mask:0xf
	v_mov_b32_e32 v74, v157
	v_mov_b32_e32 v85, v157
	v_mov_b32_dpp v77, v66 row_ror:8 row_mask:0xf bank_mask:0xf
	v_mov_b32_dpp v86, v67 row_ror:8 row_mask:0xf bank_mask:0xf
	v_cndmask_b32_e64 v69, v67, v55, s[0:1]
	v_cndmask_b32_e64 v68, v66, v54, s[0:1]
	v_lshlrev_b32_e32 v54, 16, v84
	v_and_b32_e32 v55, 0xffff0000, v84
	v_mov_b32_dpp v74, v48 row_ror:8 row_mask:0xf bank_mask:0xf
	v_mov_b32_dpp v85, v49 row_ror:8 row_mask:0xf bank_mask:0xf
	v_cndmask_b32_e64 v51, v86, v51, s[0:1]
	v_cndmask_b32_e64 v50, v77, v50, s[0:1]
	v_cndmask_b32_e64 v49, v79, v49, s[0:1]
	v_cndmask_b32_e64 v48, v78, v48, s[0:1]
	v_pk_mul_f32 v[54:55], v[64:65], v[54:55] op_sel_hi:[0,1]
	global_store_dwordx4 v[52:53], v[48:51], off
	v_pk_mul_f32 v[54:55], v[44:45], v[54:55]
	v_cndmask_b32_e64 v67, v71, v85, s[0:1]
	v_lshlrev_b32_e32 v50, 16, v72
	v_and_b32_e32 v51, 0xffff0000, v72
	v_pk_fma_f32 v[50:51], v[32:33], v[54:55], v[50:51]
	v_lshlrev_b32_e32 v54, 16, v82
	v_and_b32_e32 v55, 0xffff0000, v82
	v_pk_mul_f32 v[54:55], v[64:65], v[54:55] op_sel_hi:[0,1]
	v_lshlrev_b32_e32 v32, 16, v65
	v_and_b32_e32 v33, 0xffff0000, v65
	v_pk_mul_f32 v[54:55], v[40:41], v[54:55]
	v_mov_b32_e32 v65, v157
	v_pk_fma_f32 v[32:33], v[36:37], v[54:55], v[32:33]
	v_lshlrev_b32_e32 v54, 16, v83
	v_and_b32_e32 v55, 0xffff0000, v83
	v_mov_b32_dpp v65, v32 row_ror:8 row_mask:0xf bank_mask:0xf
	v_pk_mul_f32 v[54:55], v[64:65], v[54:55] op_sel_hi:[0,1]
	v_lshlrev_b32_e32 v36, 16, v73
	v_and_b32_e32 v37, 0xffff0000, v73
	v_pk_mul_f32 v[54:55], v[46:47], v[54:55]
	v_add_co_u32_e32 v48, vcc, s45, v52
	v_pk_fma_f32 v[36:37], v[34:35], v[54:55], v[36:37]
	v_lshlrev_b32_e32 v54, 16, v76
	v_and_b32_e32 v55, 0xffff0000, v76
	v_pk_mul_f32 v[54:55], v[64:65], v[54:55] op_sel_hi:[0,1]
	v_cndmask_b32_e64 v66, v70, v74, s[0:1]
	v_addc_co_u32_e32 v49, vcc, 0, v53, vcc
	v_lshlrev_b32_e32 v34, 16, v80
	v_and_b32_e32 v35, 0xffff0000, v80
	v_pk_mul_f32 v[54:55], v[42:43], v[54:55]
	global_store_dwordx4 v[48:49], v[66:69], off
	v_mov_b32_e32 v70, v157
	v_pk_fma_f32 v[34:35], v[38:39], v[54:55], v[34:35]
	v_mov_b32_e32 v66, v157
	v_mov_b32_e32 v67, v157
	v_mov_b32_e32 v69, v157
	v_mov_b32_e32 v38, v157
	v_mov_b32_dpp v66, v50 row_ror:8 row_mask:0xf bank_mask:0xf
	v_mov_b32_dpp v67, v51 row_ror:8 row_mask:0xf bank_mask:0xf
	v_mov_b32_e32 v68, v157
	v_mov_b32_dpp v69, v36 row_ror:8 row_mask:0xf bank_mask:0xf
	v_mov_b32_dpp v70, v37 row_ror:8 row_mask:0xf bank_mask:0xf
	v_mov_b32_dpp v38, v34 row_ror:8 row_mask:0xf bank_mask:0xf
	v_mov_b32_e32 v39, v157
	v_mov_b32_dpp v68, v33 row_ror:8 row_mask:0xf bank_mask:0xf
	v_cndmask_b32_e64 v34, v69, v34, s[0:1]
	v_mov_b32_dpp v39, v35 row_ror:8 row_mask:0xf bank_mask:0xf
	v_cndmask_b32_e64 v35, v70, v35, s[0:1]
	v_cndmask_b32_e64 v33, v67, v33, s[0:1]
	v_cndmask_b32_e64 v32, v66, v32, s[0:1]
	v_cndmask_b32_e64 v38, v36, v38, s[0:1]
	v_cndmask_b32_e64 v39, v37, v39, s[0:1]
	v_cndmask_b32_e64 v37, v51, v68, s[0:1]
	v_cndmask_b32_e64 v36, v50, v65, s[0:1]
	global_store_dwordx4 v[52:53], v[32:35], off offset:128
	global_store_dwordx4 v[48:49], v[36:39], off offset:128
	s_waitcnt vmcnt(4)
; __device__ __forceinline__ float bflo(unsigned w) { return __uint_as_float(w << 16); }
; __device__ __forceinline__ float bfhi(unsigned w) { return __uint_as_float(w & 0xffff0000u); }
;     const bool lo = fr < 8;
;     const int r1 = row - fr + (fr & 7), cb = col0 + (lo ? 0 : boff);
;     const u32x4 l1 = *(const u32x4*)(P + (size_t)r1 * ld + cb), l2 = *(const u32x4*)(P + (size_t)(r1 + 8) * ld + cb);
;     const u32x4 s1 = {dpp_ror8(l1.x), dpp_ror8(l1.y), dpp_ror8(l1.z), dpp_ror8(l1.w)}, s2 = {dpp_ror8(l2.x), dpp_ror8(l2.y), dpp_ror8(l2.z), dpp_ror8(l2.w)};
;     wA = lo ? l1 : s2; wB = lo ? s1 : l2;
; }
;     __device__ __forceinline__ void operator()(const f32x4 (&acc)[2][2][4][2], const Unit& u, int wr, int wc, int fr, int fq) const {
;     ...
;             for (int m = 0; m < 4; ++m) { const int row = row0 + ai * HALF + m * 16; const float ri = __builtin_amdgcn_rsqf(sse[row] * (1.f / D) + EPS);
;                 u32x4 rr[2], ee[2]; load_pair_lines(R, D, row, fr, col0, rr[0], rr[1], 32); load_pair_lines(E, D, row, fr, col0, ee[0], ee[1], 32);
;                 float* orow = OUT + (size_t)(row - fr + (fr & 7)) * D + col0 + (lo ? 0 : 4);
; #pragma unroll
;                 for (int bj = 0; bj < 2; ++bj) { const u32x4 rw = rr[bj], ew = ee[bj];
;                     const float r[8] = {bflo(rw.x), bfhi(rw.x), bflo(rw.y), bfhi(rw.y), bflo(rw.z), bfhi(rw.z), bflo(rw.w), bfhi(rw.w)};
;                     const float e[8] = {bflo(ew.x), bfhi(ew.x), bflo(ew.y), bfhi(ew.y), bflo(ew.z), bfhi(ew.z), bflo(ew.w), bfhi(ew.w)};
;                     float o[8];
; #pragma unroll
;                     for (int j = 0; j < 8; ++j) { const float a = acc[ai][bj][m][j >> 2][j & 3]; const float gg = gv[bj][j >> 2][j & 3];
;                         o[j] = r[j] + e[j] * ri * gg * __builtin_amdgcn_rcpf(1.f + __builtin_amdgcn_exp2f(-a * LOG2E)); }
;                     f32x4 o1, o2;
; #pragma unroll
;                     for (int j = 0; j < 4; ++j) { const unsigned a = __float_as_uint(o[j]), b = __float_as_uint(o[4 + j]); const unsigned sa = dpp_ror8(a), sb = dpp_ror8(b);
;                         o1[j] = __uint_as_float(lo ? a : sb); o2[j] = __uint_as_float(lo ? sa : b); }
;                     *(f32x4*)(orow + 32 * bj) = o1; *(f32x4*)(orow + (size_t)8 * D + 32 * bj) = o2; } }
	s_nop 0
	v_mov_b32_e32 v68, v228
	v_mov_b32_e32 v73, v157
	v_add_u32_e32 v38, 0xa0, v81
	v_ashrrev_i32_e32 v39, 31, v38
	v_lshlrev_b64 v[32:33], 12, v[38:39]
	v_lshl_add_u64 v[64:65], v[32:33], 0, s[16:17]
	v_lshl_add_u64 v[48:49], s[8:9], 0, v[64:65]
	v_lshl_add_u64 v[34:35], s[8:9], 0, v[32:33]
	v_lshl_add_u64 v[48:49], v[48:49], 0, v[164:165]
	v_lshl_add_u64 v[32:33], s[10:11], 0, v[32:33]
	v_lshl_add_u64 v[34:35], v[34:35], 0, v[164:165]
	v_mov_b64_e32 v[48:49], v[232:233]
	v_mov_b64_e32 v[50:51], v[234:235]
	v_lshl_add_u64 v[32:33], v[32:33], 0, v[164:165]
	v_mov_b64_e32 v[34:35], v[236:237]
	v_mov_b64_e32 v[36:37], v[238:239]
	v_mov_b32_e32 v74, v157
	v_mov_b64_e32 v[52:53], v[240:241]
	v_mov_b64_e32 v[54:55], v[242:243]
	v_lshl_add_u64 v[32:33], s[10:11], 0, v[64:65]
	v_lshl_add_u64 v[32:33], v[32:33], 0, v[164:165]
	v_mov_b64_e32 v[64:65], v[244:245]
	v_mov_b64_e32 v[66:67], v[246:247]
	s_nop 1
	v_add_u32_e32 v224, 0xb0, v81
	v_ashrrev_i32_e32 v225, 31, v224
	global_load_dword v228, v[168:169], off offset:704
	v_lshlrev_b64 v[216:217], 12, v[224:225]
	v_lshl_add_u64 v[222:223], v[216:217], 0, s[16:17]
	v_lshl_add_u64 v[220:221], s[8:9], 0, v[222:223]
	v_lshl_add_u64 v[218:219], s[8:9], 0, v[216:217]
	v_lshl_add_u64 v[220:221], v[220:221], 0, v[164:165]
	v_lshl_add_u64 v[216:217], s[10:11], 0, v[216:217]
	v_lshl_add_u64 v[218:219], v[218:219], 0, v[164:165]
	global_load_dwordx4 v[232:235], v[220:221], off
	v_lshl_add_u64 v[216:217], v[216:217], 0, v[164:165]
	global_load_dwordx4 v[236:239], v[218:219], off
	global_load_dwordx4 v[240:243], v[216:217], off
	v_lshl_add_u64 v[216:217], s[10:11], 0, v[222:223]
	v_lshl_add_u64 v[216:217], v[216:217], 0, v[164:165]
	global_load_dwordx4 v[244:247], v[216:217], off
	v_mov_b32_e32 v69, v157
	v_mov_b32_e32 v70, v157
	v_mov_b32_e32 v71, v157
	v_mov_b32_e32 v72, v157
	v_mov_b32_e32 v33, v157
	v_add_f32_e32 v16, 1.0, v16
	v_add_f32_e32 v17, 1.0, v17
	v_rcp_f32_e32 v16, v16
	v_rcp_f32_e32 v17, v17
	v_mul_f32_e32 v18, 0xbfb8aa3b, v18
	v_mul_f32_e32 v19, 0xbfb8aa3b, v19
	v_add_f32_e32 v20, 1.0, v20
	v_add_f32_e32 v21, 1.0, v21
	v_exp_f32_e32 v18, v18
	v_exp_f32_e32 v19, v19
	v_rcp_f32_e32 v20, v20
	v_rcp_f32_e32 v21, v21
	v_mul_f32_e32 v22, 0xbfb8aa3b, v22
	v_mul_f32_e32 v23, 0xbfb8aa3b, v23
	v_exp_f32_e32 v22, v22
	v_exp_f32_e32 v23, v23
	v_add_f32_e32 v18, 1.0, v18
	v_add_f32_e32 v19, 1.0, v19
	v_rcp_f32_e32 v18, v18
	v_rcp_f32_e32 v19, v19
	v_add_f32_e32 v22, 1.0, v22
	v_add_f32_e32 v23, 1.0, v23
	v_rcp_f32_e32 v22, v22
	v_rcp_f32_e32 v23, v23
	v_mul_f32_e32 v8, 0xbfb8aa3b, v8
	v_mul_f32_e32 v9, 0xbfb8aa3b, v9
	v_mul_f32_e32 v12, 0xbfb8aa3b, v12
	v_exp_f32_e32 v8, v8
	v_exp_f32_e32 v9, v9
	v_mul_f32_e32 v10, 0xbfb8aa3b, v10
	v_mul_f32_e32 v11, 0xbfb8aa3b, v11
	v_add_f32_e32 v8, 1.0, v8
	v_add_f32_e32 v9, 1.0, v9
	v_rcp_f32_e32 v8, v8
	v_rcp_f32_e32 v9, v9
	v_exp_f32_e32 v10, v10
	v_exp_f32_e32 v11, v11
	v_mul_f32_e32 v14, 0xbfb8aa3b, v14
	v_mul_f32_e32 v15, 0xbfb8aa3b, v15
	v_exp_f32_e32 v14, v14
	v_exp_f32_e32 v15, v15
	v_add_f32_e32 v10, 1.0, v10
	v_add_f32_e32 v11, 1.0, v11
	v_rcp_f32_e32 v10, v10
	v_rcp_f32_e32 v11, v11
	v_add_f32_e32 v14, 1.0, v14
	v_add_f32_e32 v15, 1.0, v15
	v_mul_f32_e32 v0, 0xbfb8aa3b, v0
	v_mul_f32_e32 v1, 0xbfb8aa3b, v1
	v_rcp_f32_e32 v14, v14
	v_rcp_f32_e32 v15, v15
	v_exp_f32_e32 v0, v0
	v_exp_f32_e32 v1, v1
	v_mul_f32_e32 v4, 0xbfb8aa3b, v4
	v_mul_f32_e32 v5, 0xbfb8aa3b, v5
	v_exp_f32_e32 v4, v4
	v_fmamk_f32 v32, v68, 0x3a000000, v182
	v_mov_b32_e32 v68, v157
	v_rsq_f32_e32 v32, v32
	v_exp_f32_e32 v5, v5
	v_add_f32_e32 v0, 1.0, v0
	v_add_f32_e32 v1, 1.0, v1
	v_rcp_f32_e32 v0, v0
	v_rcp_f32_e32 v1, v1
	v_mul_f32_e32 v2, 0xbfb8aa3b, v2
	v_mul_f32_e32 v3, 0xbfb8aa3b, v3
	v_add_f32_e32 v4, 1.0, v4
	v_mov_b32_dpp v73, v50 row_ror:8 row_mask:0xf bank_mask:0xf
	v_mov_b32_dpp v74, v51 row_ror:8 row_mask:0xf bank_mask:0xf
	v_mov_b32_dpp v69, v36 row_ror:8 row_mask:0xf bank_mask:0xf
	v_mov_b32_dpp v70, v37 row_ror:8 row_mask:0xf bank_mask:0xf
	v_mov_b32_dpp v71, v48 row_ror:8 row_mask:0xf bank_mask:0xf
	v_mov_b32_dpp v72, v49 row_ror:8 row_mask:0xf bank_mask:0xf
	v_cndmask_b32_e64 v74, v74, v37, s[0:1]
	v_cndmask_b32_e64 v37, v73, v36, s[0:1]
	v_mov_b32_e32 v36, v157
	v_mov_b32_dpp v33, v34 row_ror:8 row_mask:0xf bank_mask:0xf
	v_mov_b32_dpp v68, v35 row_ror:8 row_mask:0xf bank_mask:0xf
	v_cndmask_b32_e64 v72, v72, v35, s[0:1]
	v_cndmask_b32_e64 v71, v71, v34, s[0:1]
	v_cndmask_b32_e64 v51, v51, v70, s[0:1]
	v_mov_b32_e32 v34, v157
	v_mov_b32_e32 v35, v157
	v_mov_b32_dpp v36, v54 row_ror:8 row_mask:0xf bank_mask:0xf
	v_mov_b32_e32 v70, v157
	v_cndmask_b32_e64 v49, v49, v68, s[0:1]
	v_cndmask_b32_e64 v33, v48, v33, s[0:1]
	v_cndmask_b32_e64 v48, v50, v69, s[0:1]
	v_mov_b32_dpp v34, v52 row_ror:8 row_mask:0xf bank_mask:0xf
	v_mov_b32_dpp v35, v53 row_ror:8 row_mask:0xf bank_mask:0xf
	v_mov_b32_e32 v68, v157
	v_mov_b32_e32 v69, v157
	v_mov_b32_dpp v70, v66 row_ror:8 row_mask:0xf bank_mask:0xf
	v_cndmask_b32_e64 v66, v66, v36, s[0:1]
	v_exp_f32_e32 v36, v28
	v_mul_f32_e32 v28, 0xbfb8aa3b, v29
	v_mov_b32_dpp v68, v64 row_ror:8 row_mask:0xf bank_mask:0xf
	v_mov_b32_dpp v69, v65 row_ror:8 row_mask:0xf bank_mask:0xf
	v_cndmask_b32_e64 v65, v65, v35, s[0:1]
	v_cndmask_b32_e64 v64, v64, v34, s[0:1]
	v_lshlrev_b64 v[34:35], 13, v[38:39]
	v_exp_f32_e32 v38, v28
	v_lshl_add_u64 v[34:35], s[4:5], 0, v[34:35]
	v_cndmask_b32_e64 v54, v70, v54, s[0:1]
	v_lshl_add_u64 v[34:35], v[34:35], 0, v[166:167]
	v_lshl_add_u64 v[28:29], v[34:35], 0, v[156:157]
	v_add_f32_e32 v35, 1.0, v38
	v_lshlrev_b32_e32 v38, 16, v54
	v_and_b32_e32 v39, 0xffff0000, v54
	v_add_f32_e32 v34, 1.0, v36
; __device__ __forceinline__ float bflo(unsigned w) { return __uint_as_float(w << 16); }
; __device__ __forceinline__ float bfhi(unsigned w) { return __uint_as_float(w & 0xffff0000u); }
;     const bool lo = fr < 8;
;     const int r1 = row - fr + (fr & 7), cb = col0 + (lo ? 0 : boff);
;     const u32x4 l1 = *(const u32x4*)(P + (size_t)r1 * ld + cb), l2 = *(const u32x4*)(P + (size_t)(r1 + 8) * ld + cb);
;     const u32x4 s1 = {dpp_ror8(l1.x), dpp_ror8(l1.y), dpp_ror8(l1.z), dpp_ror8(l1.w)}, s2 = {dpp_ror8(l2.x), dpp_ror8(l2.y), dpp_ror8(l2.z), dpp_ror8(l2.w)};
;     wA = lo ? l1 : s2; wB = lo ? s1 : l2;
; }
;     __device__ __forceinline__ void operator()(const f32x4 (&acc)[2][2][4][2], const Unit& u, int wr, int wc, int fr, int fq) const {
;     ...
;             for (int m = 0; m < 4; ++m) { const int row = row0 + ai * HALF + m * 16; const float ri = __builtin_amdgcn_rsqf(sse[row] * (1.f / D) + EPS);
;                 u32x4 rr[2], ee[2]; load_pair_lines(R, D, row, fr, col0, rr[0], rr[1], 32); load_pair_lines(E, D, row, fr, col0, ee[0], ee[1], 32);
;                 float* orow = OUT + (size_t)(row - fr + (fr & 7)) * D + col0 + (lo ? 0 : 4);
; #pragma unroll
;                 for (int bj = 0; bj < 2; ++bj) { const u32x4 rw = rr[bj], ew = ee[bj];
;                     const float r[8] = {bflo(rw.x), bfhi(rw.x), bflo(rw.y), bfhi(rw.y), bflo(rw.z), bfhi(rw.z), bflo(rw.w), bfhi(rw.w)};
;                     const float e[8] = {bflo(ew.x), bfhi(ew.x), bflo(ew.y), bfhi(ew.y), bflo(ew.z), bfhi(ew.z), bflo(ew.w), bfhi(ew.w)};
;                     float o[8];
; #pragma unroll
;                     for (int j = 0; j < 8; ++j) { const float a = acc[ai][bj][m][j >> 2][j & 3]; const float gg = gv[bj][j >> 2][j & 3];
;                         o[j] = r[j] + e[j] * ri * gg * __builtin_amdgcn_rcpf(1.f + __builtin_amdgcn_exp2f(-a * LOG2E)); }
;                     f32x4 o1, o2;
; #pragma unroll
;                     for (int j = 0; j < 4; ++j) { const unsigned a = __float_as_uint(o[j]), b = __float_as_uint(o[4 + j]); const unsigned sa = dpp_ror8(a), sb = dpp_ror8(b);
;                         o1[j] = __uint_as_float(lo ? a : sb); o2[j] = __uint_as_float(lo ? sa : b); }
;                     *(f32x4*)(orow + 32 * bj) = o1; *(f32x4*)(orow + (size_t)8 * D + 32 * bj) = o2; } }
	v_pk_mul_f32 v[38:39], v[32:33], v[38:39] op_sel_hi:[0,1]
	v_cndmask_b32_e64 v52, v68, v52, s[0:1]
	v_rcp_f32_e32 v34, v34
	v_rcp_f32_e32 v35, v35
	v_lshlrev_b32_e32 v36, 16, v37
	v_and_b32_e32 v37, 0xffff0000, v37
	v_pk_mul_f32 v[38:39], v[60:61], v[38:39]
	v_mov_b32_e32 v73, v157
	v_pk_fma_f32 v[38:39], v[24:25], v[38:39], v[36:37]
	v_lshlrev_b32_e32 v36, 16, v52
	v_and_b32_e32 v37, 0xffff0000, v52
	v_mov_b32_e32 v50, v157
	v_mov_b32_dpp v73, v67 row_ror:8 row_mask:0xf bank_mask:0xf
	v_pk_mul_f32 v[36:37], v[32:33], v[36:37] op_sel_hi:[0,1]
	v_mov_b32_dpp v50, v55 row_ror:8 row_mask:0xf bank_mask:0xf
	v_cndmask_b32_e64 v55, v73, v55, s[0:1]
	v_lshlrev_b32_e32 v24, 16, v71
	v_and_b32_e32 v25, 0xffff0000, v71
	v_pk_mul_f32 v[36:37], v[56:57], v[36:37]
	v_cndmask_b32_e64 v53, v69, v53, s[0:1]
	v_pk_fma_f32 v[24:25], v[34:35], v[36:37], v[24:25]
	v_lshlrev_b32_e32 v36, 16, v55
	v_and_b32_e32 v37, 0xffff0000, v55
	v_pk_mul_f32 v[36:37], v[32:33], v[36:37] op_sel_hi:[0,1]
	v_lshlrev_b32_e32 v34, 16, v74
	v_and_b32_e32 v35, 0xffff0000, v74
	v_pk_mul_f32 v[36:37], v[62:63], v[36:37]
	v_cndmask_b32_e64 v50, v67, v50, s[0:1]
	v_pk_fma_f32 v[34:35], v[26:27], v[36:37], v[34:35]
	v_lshlrev_b32_e32 v36, 16, v53
	v_and_b32_e32 v37, 0xffff0000, v53
	v_pk_mul_f32 v[36:37], v[32:33], v[36:37] op_sel_hi:[0,1]
	v_lshlrev_b32_e32 v26, 16, v72
	v_and_b32_e32 v27, 0xffff0000, v72
	v_pk_mul_f32 v[36:37], v[58:59], v[36:37]
	v_mov_b32_e32 v54, v157
	v_pk_fma_f32 v[26:27], v[30:31], v[36:37], v[26:27]
	v_mov_b32_e32 v30, v157
	v_mov_b32_e32 v31, v157
	v_mov_b32_e32 v67, v157
	v_mov_b32_e32 v55, v157
	v_mov_b32_e32 v69, v157
	v_mov_b32_dpp v30, v26 row_ror:8 row_mask:0xf bank_mask:0xf
	v_mov_b32_dpp v31, v27 row_ror:8 row_mask:0xf bank_mask:0xf
	v_mov_b32_dpp v54, v38 row_ror:8 row_mask:0xf bank_mask:0xf
	v_mov_b32_dpp v67, v39 row_ror:8 row_mask:0xf bank_mask:0xf
	v_mov_b32_e32 v52, v157
	v_mov_b32_e32 v68, v157
	v_mov_b32_dpp v55, v34 row_ror:8 row_mask:0xf bank_mask:0xf
	v_mov_b32_dpp v69, v35 row_ror:8 row_mask:0xf bank_mask:0xf
	v_cndmask_b32_e64 v37, v35, v31, s[0:1]
	v_cndmask_b32_e64 v36, v34, v30, s[0:1]
	v_lshlrev_b32_e32 v30, 16, v66
	v_and_b32_e32 v31, 0xffff0000, v66
	v_mov_b32_dpp v52, v24 row_ror:8 row_mask:0xf bank_mask:0xf
	v_mov_b32_dpp v68, v25 row_ror:8 row_mask:0xf bank_mask:0xf
	v_cndmask_b32_e64 v27, v69, v27, s[0:1]
	v_cndmask_b32_e64 v26, v55, v26, s[0:1]
	v_cndmask_b32_e64 v25, v67, v25, s[0:1]
	v_cndmask_b32_e64 v24, v54, v24, s[0:1]
	v_pk_mul_f32 v[30:31], v[32:33], v[30:31] op_sel_hi:[0,1]
	global_store_dwordx4 v[28:29], v[24:27], off
	v_pk_mul_f32 v[30:31], v[44:45], v[30:31]
	v_cndmask_b32_e64 v35, v39, v68, s[0:1]
	v_lshlrev_b32_e32 v26, 16, v48
	v_and_b32_e32 v27, 0xffff0000, v48
	v_pk_fma_f32 v[26:27], v[16:17], v[30:31], v[26:27]
	v_lshlrev_b32_e32 v30, 16, v64
	v_and_b32_e32 v31, 0xffff0000, v64
	v_pk_mul_f32 v[30:31], v[32:33], v[30:31] op_sel_hi:[0,1]
	v_lshlrev_b32_e32 v16, 16, v33
	v_and_b32_e32 v17, 0xffff0000, v33
	v_pk_mul_f32 v[30:31], v[40:41], v[30:31]
	v_mov_b32_e32 v33, v157
	v_pk_fma_f32 v[16:17], v[20:21], v[30:31], v[16:17]
	v_lshlrev_b32_e32 v30, 16, v50
	v_and_b32_e32 v31, 0xffff0000, v50
	v_mov_b32_dpp v33, v16 row_ror:8 row_mask:0xf bank_mask:0xf
	v_pk_mul_f32 v[30:31], v[32:33], v[30:31] op_sel_hi:[0,1]
	v_add_co_u32_e32 v24, vcc, s45, v28
	v_lshlrev_b32_e32 v20, 16, v51
	v_and_b32_e32 v21, 0xffff0000, v51
	v_pk_mul_f32 v[30:31], v[46:47], v[30:31]
	v_cndmask_b32_e64 v34, v38, v52, s[0:1]
	v_addc_co_u32_e32 v25, vcc, 0, v29, vcc
	v_pk_fma_f32 v[20:21], v[18:19], v[30:31], v[20:21]
	v_lshlrev_b32_e32 v30, 16, v65
	v_and_b32_e32 v31, 0xffff0000, v65
	global_store_dwordx4 v[24:25], v[34:37], off
	v_pk_mul_f32 v[30:31], v[32:33], v[30:31] op_sel_hi:[0,1]
	v_mov_b32_e32 v38, v157
	v_mov_b32_e32 v34, v157
	v_mov_b32_e32 v35, v157
	v_mov_b32_e32 v37, v157
	v_mov_b32_dpp v34, v26 row_ror:8 row_mask:0xf bank_mask:0xf
	v_lshlrev_b32_e32 v18, 16, v49
	v_and_b32_e32 v19, 0xffff0000, v49
	v_pk_mul_f32 v[30:31], v[42:43], v[30:31]
	v_mov_b32_dpp v35, v27 row_ror:8 row_mask:0xf bank_mask:0xf
	v_mov_b32_e32 v36, v157
	v_mov_b32_dpp v37, v20 row_ror:8 row_mask:0xf bank_mask:0xf
	v_mov_b32_dpp v38, v21 row_ror:8 row_mask:0xf bank_mask:0xf
	v_pk_fma_f32 v[18:19], v[22:23], v[30:31], v[18:19]
	v_mov_b32_e32 v22, v157
	v_mov_b32_e32 v23, v157
	v_cndmask_b32_e64 v16, v34, v16, s[0:1]
	v_add_u32_e32 v34, 0xb0, v81
	v_mov_b32_dpp v36, v17 row_ror:8 row_mask:0xf bank_mask:0xf
	v_mov_b32_dpp v22, v18 row_ror:8 row_mask:0xf bank_mask:0xf
	v_mov_b32_dpp v23, v19 row_ror:8 row_mask:0xf bank_mask:0xf
	v_cndmask_b32_e64 v19, v38, v19, s[0:1]
	v_cndmask_b32_e64 v18, v37, v18, s[0:1]
	v_cndmask_b32_e64 v17, v35, v17, s[0:1]
	v_ashrrev_i32_e32 v35, 31, v34
	v_cndmask_b32_e64 v23, v21, v23, s[0:1]
	v_cndmask_b32_e64 v22, v20, v22, s[0:1]
	v_cndmask_b32_e64 v21, v27, v36, s[0:1]
	v_cndmask_b32_e64 v20, v26, v33, s[0:1]
	global_store_dwordx4 v[28:29], v[16:19], off offset:128
	global_store_dwordx4 v[24:25], v[20:23], off offset:128
	s_waitcnt vmcnt(4)
; __device__ __forceinline__ float bflo(unsigned w) { return __uint_as_float(w << 16); }
; __device__ __forceinline__ float bfhi(unsigned w) { return __uint_as_float(w & 0xffff0000u); }
;     const bool lo = fr < 8;
;     const int r1 = row - fr + (fr & 7), cb = col0 + (lo ? 0 : boff);
;     const u32x4 l1 = *(const u32x4*)(P + (size_t)r1 * ld + cb), l2 = *(const u32x4*)(P + (size_t)(r1 + 8) * ld + cb);
;     const u32x4 s1 = {dpp_ror8(l1.x), dpp_ror8(l1.y), dpp_ror8(l1.z), dpp_ror8(l1.w)}, s2 = {dpp_ror8(l2.x), dpp_ror8(l2.y), dpp_ror8(l2.z), dpp_ror8(l2.w)};
;     wA = lo ? l1 : s2; wB = lo ? s1 : l2;
; }
;     __device__ __forceinline__ void operator()(const f32x4 (&acc)[2][2][4][2], const Unit& u, int wr, int wc, int fr, int fq) const {
;     ...
;             for (int m = 0; m < 4; ++m) { const int row = row0 + ai * HALF + m * 16; const float ri = __builtin_amdgcn_rsqf(sse[row] * (1.f / D) + EPS);
;                 u32x4 rr[2], ee[2]; load_pair_lines(R, D, row, fr, col0, rr[0], rr[1], 32); load_pair_lines(E, D, row, fr, col0, ee[0], ee[1], 32);
;                 float* orow = OUT + (size_t)(row - fr + (fr & 7)) * D + col0 + (lo ? 0 : 4);
; #pragma unroll
;                 for (int bj = 0; bj < 2; ++bj) { const u32x4 rw = rr[bj], ew = ee[bj];
;                     const float r[8] = {bflo(rw.x), bfhi(rw.x), bflo(rw.y), bfhi(rw.y), bflo(rw.z), bfhi(rw.z), bflo(rw.w), bfhi(rw.w)};
;                     const float e[8] = {bflo(ew.x), bfhi(ew.x), bflo(ew.y), bfhi(ew.y), bflo(ew.z), bfhi(ew.z), bflo(ew.w), bfhi(ew.w)};
;                     float o[8];
; #pragma unroll
;                     for (int j = 0; j < 8; ++j) { const float a = acc[ai][bj][m][j >> 2][j & 3]; const float gg = gv[bj][j >> 2][j & 3];
;                         o[j] = r[j] + e[j] * ri * gg * __builtin_amdgcn_rcpf(1.f + __builtin_amdgcn_exp2f(-a * LOG2E)); }
;                     f32x4 o1, o2;
; #pragma unroll
;                     for (int j = 0; j < 4; ++j) { const unsigned a = __float_as_uint(o[j]), b = __float_as_uint(o[4 + j]); const unsigned sa = dpp_ror8(a), sb = dpp_ror8(b);
;                         o1[j] = __uint_as_float(lo ? a : sb); o2[j] = __uint_as_float(lo ? sa : b); }
;                     *(f32x4*)(orow + 32 * bj) = o1; *(f32x4*)(orow + (size_t)8 * D + 32 * bj) = o2; } }
	s_nop 0
	v_mov_b32_e32 v36, v228
	v_lshlrev_b64 v[16:17], 12, v[34:35]
	v_lshl_add_u64 v[30:31], v[16:17], 0, s[16:17]
	v_lshl_add_u64 v[22:23], s[8:9], 0, v[30:31]
	v_lshl_add_u64 v[18:19], s[8:9], 0, v[16:17]
	v_lshl_add_u64 v[22:23], v[22:23], 0, v[164:165]
	v_lshl_add_u64 v[16:17], s[10:11], 0, v[16:17]
	v_lshl_add_u64 v[18:19], v[18:19], 0, v[164:165]
	v_mov_b64_e32 v[22:23], v[232:233]
	v_mov_b64_e32 v[24:25], v[234:235]
	v_lshl_add_u64 v[16:17], v[16:17], 0, v[164:165]
	v_mov_b64_e32 v[18:19], v[236:237]
	v_mov_b64_e32 v[20:21], v[238:239]
	v_mov_b32_e32 v49, v157
	v_mov_b64_e32 v[26:27], v[240:241]
	v_mov_b64_e32 v[28:29], v[242:243]
	v_lshl_add_u64 v[16:17], s[10:11], 0, v[30:31]
	v_lshl_add_u64 v[16:17], v[16:17], 0, v[164:165]
	v_mov_b64_e32 v[30:31], v[244:245]
	v_mov_b64_e32 v[32:33], v[246:247]
	s_nop 1
	v_mov_b32_e32 v50, v157
	v_mov_b32_e32 v17, v157
	v_mov_b32_e32 v37, v157
	v_mov_b32_e32 v38, v157
	v_mov_b32_e32 v48, v157
	v_mov_b32_e32 v39, v157
	v_add_f32_e32 v5, 1.0, v5
	v_exp_f32_e32 v2, v2
	v_exp_f32_e32 v3, v3
	v_rcp_f32_e32 v4, v4
	v_rcp_f32_e32 v5, v5
	v_mul_f32_e32 v6, 0xbfb8aa3b, v6
	v_mul_f32_e32 v7, 0xbfb8aa3b, v7
	v_exp_f32_e32 v6, v6
	v_exp_f32_e32 v7, v7
	v_add_f32_e32 v2, 1.0, v2
	v_add_f32_e32 v3, 1.0, v3
	v_rcp_f32_e32 v2, v2
	v_rcp_f32_e32 v3, v3
	v_add_f32_e32 v6, 1.0, v6
	v_add_f32_e32 v7, 1.0, v7
	v_rcp_f32_e32 v6, v6
	v_rcp_f32_e32 v7, v7
	s_mov_b32 s53, s18
	s_mov_b32 s30, s22
	s_mov_b64 s[36:37], s[28:29]
	s_mov_b64 s[34:35], s[24:25]
	v_fmamk_f32 v16, v36, 0x3a000000, v182
	v_mov_b32_e32 v36, v157
	v_rsq_f32_e32 v16, v16
	v_mov_b32_dpp v49, v24 row_ror:8 row_mask:0xf bank_mask:0xf
	v_mov_b32_dpp v50, v25 row_ror:8 row_mask:0xf bank_mask:0xf
	v_mov_b32_dpp v17, v18 row_ror:8 row_mask:0xf bank_mask:0xf
	v_mov_b32_dpp v36, v19 row_ror:8 row_mask:0xf bank_mask:0xf
	v_mov_b32_dpp v37, v20 row_ror:8 row_mask:0xf bank_mask:0xf
	v_mov_b32_dpp v38, v21 row_ror:8 row_mask:0xf bank_mask:0xf
	v_mov_b32_dpp v48, v23 row_ror:8 row_mask:0xf bank_mask:0xf
	v_cndmask_b32_e64 v50, v50, v21, s[0:1]
	v_cndmask_b32_e64 v21, v49, v20, s[0:1]
	v_mov_b32_e32 v20, v157
	v_mov_b32_dpp v39, v22 row_ror:8 row_mask:0xf bank_mask:0xf
	v_cndmask_b32_e64 v48, v48, v19, s[0:1]
	v_cndmask_b32_e64 v36, v23, v36, s[0:1]
	v_cndmask_b32_e64 v25, v25, v38, s[0:1]
	v_cndmask_b32_e64 v17, v22, v17, s[0:1]
	v_mov_b32_e32 v19, v157
	v_mov_b32_dpp v20, v28 row_ror:8 row_mask:0xf bank_mask:0xf
	v_mov_b32_e32 v22, v157
	v_mov_b32_e32 v23, v157
	v_mov_b32_e32 v38, v157
	v_cndmask_b32_e64 v39, v39, v18, s[0:1]
	v_cndmask_b32_e64 v24, v24, v37, s[0:1]
	v_mov_b32_e32 v18, v157
	v_mov_b32_dpp v19, v27 row_ror:8 row_mask:0xf bank_mask:0xf
	v_mov_b32_dpp v22, v29 row_ror:8 row_mask:0xf bank_mask:0xf
	v_mov_b32_dpp v23, v30 row_ror:8 row_mask:0xf bank_mask:0xf
	v_mov_b32_e32 v37, v157
	v_mov_b32_dpp v38, v32 row_ror:8 row_mask:0xf bank_mask:0xf
	v_cndmask_b32_e64 v32, v32, v20, s[0:1]
	v_exp_f32_e32 v20, v12
	v_mul_f32_e32 v12, 0xbfb8aa3b, v13
	v_mov_b32_dpp v18, v26 row_ror:8 row_mask:0xf bank_mask:0xf
	v_mov_b32_dpp v37, v31 row_ror:8 row_mask:0xf bank_mask:0xf
	v_cndmask_b32_e64 v26, v23, v26, s[0:1]
	v_cndmask_b32_e64 v23, v38, v28, s[0:1]
	v_cndmask_b32_e64 v28, v31, v19, s[0:1]
	v_cndmask_b32_e64 v31, v33, v22, s[0:1]
	v_exp_f32_e32 v22, v12
	v_cndmask_b32_e64 v30, v30, v18, s[0:1]
	v_lshlrev_b64 v[18:19], 13, v[34:35]
	v_lshl_add_u64 v[18:19], s[4:5], 0, v[18:19]
	v_lshl_add_u64 v[18:19], v[18:19], 0, v[166:167]
	v_lshl_add_u64 v[12:13], v[18:19], 0, v[156:157]
	v_add_f32_e32 v19, 1.0, v22
	v_lshlrev_b32_e32 v22, 16, v23
	v_and_b32_e32 v23, 0xffff0000, v23
	v_add_f32_e32 v18, 1.0, v20
	v_pk_mul_f32 v[22:23], v[16:17], v[22:23] op_sel_hi:[0,1]
	v_rcp_f32_e32 v18, v18
	v_rcp_f32_e32 v19, v19
	v_lshlrev_b32_e32 v20, 16, v21
	v_and_b32_e32 v21, 0xffff0000, v21
	v_pk_mul_f32 v[22:23], v[60:61], v[22:23]
	v_mov_b32_e32 v49, v157
	v_pk_fma_f32 v[22:23], v[8:9], v[22:23], v[20:21]
	v_lshlrev_b32_e32 v20, 16, v26
	v_and_b32_e32 v21, 0xffff0000, v26
	v_mov_b32_dpp v49, v33 row_ror:8 row_mask:0xf bank_mask:0xf
	v_pk_mul_f32 v[20:21], v[16:17], v[20:21] op_sel_hi:[0,1]
	v_cndmask_b32_e64 v29, v49, v29, s[0:1]
	v_lshlrev_b32_e32 v8, 16, v39
	v_and_b32_e32 v9, 0xffff0000, v39
; __device__ __forceinline__ unsigned dpp_ror8(unsigned x) { return (unsigned)__builtin_amdgcn_update_dpp(0, (int)x, 0x128, 0xf, 0xf, false); }
; #define PG8_WAIT_V(n) asm volatile("s_waitcnt vmcnt(" #n ")" ::: "memory")
; #define PG8_BAR __builtin_amdgcn_s_barrier()
;     __device__ __forceinline__ void operator()(const f32x4 (&acc)[2][2][4][2], const Unit& u, int wr, int wc, int fr, int fq) const {
;     ...
;                     for (int j = 0; j < 8; ++j) { const float a = acc[ai][bj][m][j >> 2][j & 3]; const float gg = gv[bj][j >> 2][j & 3];
;                         o[j] = r[j] + e[j] * ri * gg * __builtin_amdgcn_rcpf(1.f + __builtin_amdgcn_exp2f(-a * LOG2E)); }
;                     f32x4 o1, o2;
; #pragma unroll
;                     for (int j = 0; j < 4; ++j) { const unsigned a = __float_as_uint(o[j]), b = __float_as_uint(o[4 + j]); const unsigned sa = dpp_ror8(a), sb = dpp_ror8(b);
;                         o1[j] = __uint_as_float(lo ? a : sb); o2[j] = __uint_as_float(lo ? sa : b); }
;                     *(f32x4*)(orow + 32 * bj) = o1; *(f32x4*)(orow + (size_t)8 * D + 32 * bj) = o2; } }
; template <class Epi>
; __device__ __forceinline__ void gemm_phase(LAS unsigned char* lds, const Gemm g, const StaticOrder& S, const Epi& E) {
;     ...
;     PG8_WAIT_V(0);
;     if (wr == 0) PG8_BAR;
;     PG8_BAR;
	v_pk_mul_f32 v[20:21], v[56:57], v[20:21]
	v_cndmask_b32_e64 v27, v37, v27, s[0:1]
	v_pk_fma_f32 v[8:9], v[18:19], v[20:21], v[8:9]
	v_lshlrev_b32_e32 v20, 16, v29
	v_and_b32_e32 v21, 0xffff0000, v29
	v_pk_mul_f32 v[20:21], v[16:17], v[20:21] op_sel_hi:[0,1]
	v_lshlrev_b32_e32 v18, 16, v50
	v_and_b32_e32 v19, 0xffff0000, v50
	v_pk_mul_f32 v[20:21], v[62:63], v[20:21]
	v_mov_b32_e32 v33, v157
	v_pk_fma_f32 v[18:19], v[10:11], v[20:21], v[18:19]
	v_lshlrev_b32_e32 v20, 16, v27
	v_and_b32_e32 v21, 0xffff0000, v27
	v_pk_mul_f32 v[20:21], v[16:17], v[20:21] op_sel_hi:[0,1]
	v_lshlrev_b32_e32 v10, 16, v48
	v_and_b32_e32 v11, 0xffff0000, v48
	v_pk_mul_f32 v[20:21], v[58:59], v[20:21]
	v_mov_b32_e32 v34, v157
	v_pk_fma_f32 v[10:11], v[14:15], v[20:21], v[10:11]
	v_mov_b32_e32 v14, v157
	v_mov_b32_e32 v15, v157
	v_mov_b32_e32 v29, v157
	v_mov_b32_e32 v37, v157
	v_mov_b32_dpp v14, v10 row_ror:8 row_mask:0xf bank_mask:0xf
	v_mov_b32_dpp v15, v11 row_ror:8 row_mask:0xf bank_mask:0xf
	v_mov_b32_dpp v33, v22 row_ror:8 row_mask:0xf bank_mask:0xf
	v_mov_b32_dpp v34, v23 row_ror:8 row_mask:0xf bank_mask:0xf
	v_mov_b32_e32 v26, v157
	v_mov_b32_e32 v35, v157
	v_mov_b32_dpp v29, v18 row_ror:8 row_mask:0xf bank_mask:0xf
	v_mov_b32_dpp v37, v19 row_ror:8 row_mask:0xf bank_mask:0xf
	v_cndmask_b32_e64 v21, v19, v15, s[0:1]
	v_cndmask_b32_e64 v20, v18, v14, s[0:1]
	v_lshlrev_b32_e32 v14, 16, v32
	v_and_b32_e32 v15, 0xffff0000, v32
	v_mov_b32_dpp v26, v8 row_ror:8 row_mask:0xf bank_mask:0xf
	v_mov_b32_dpp v35, v9 row_ror:8 row_mask:0xf bank_mask:0xf
	v_cndmask_b32_e64 v11, v37, v11, s[0:1]
	v_cndmask_b32_e64 v10, v29, v10, s[0:1]
	v_cndmask_b32_e64 v9, v34, v9, s[0:1]
	v_cndmask_b32_e64 v8, v33, v8, s[0:1]
	v_pk_mul_f32 v[14:15], v[16:17], v[14:15] op_sel_hi:[0,1]
	global_store_dwordx4 v[12:13], v[8:11], off
	v_pk_mul_f32 v[14:15], v[44:45], v[14:15]
	v_cndmask_b32_e64 v19, v23, v35, s[0:1]
	v_lshlrev_b32_e32 v10, 16, v24
	v_and_b32_e32 v11, 0xffff0000, v24
	v_pk_fma_f32 v[10:11], v[0:1], v[14:15], v[10:11]
	v_lshlrev_b32_e32 v14, 16, v30
	v_and_b32_e32 v15, 0xffff0000, v30
	v_pk_mul_f32 v[14:15], v[16:17], v[14:15] op_sel_hi:[0,1]
	v_lshlrev_b32_e32 v0, 16, v17
	v_and_b32_e32 v1, 0xffff0000, v17
	v_pk_mul_f32 v[14:15], v[40:41], v[14:15]
	v_mov_b32_e32 v17, v157
	v_pk_fma_f32 v[0:1], v[4:5], v[14:15], v[0:1]
	v_lshlrev_b32_e32 v14, 16, v31
	v_and_b32_e32 v15, 0xffff0000, v31
	v_mov_b32_dpp v17, v0 row_ror:8 row_mask:0xf bank_mask:0xf
	v_pk_mul_f32 v[14:15], v[16:17], v[14:15] op_sel_hi:[0,1]
	v_lshlrev_b32_e32 v4, 16, v25
	v_and_b32_e32 v5, 0xffff0000, v25
	v_pk_mul_f32 v[14:15], v[46:47], v[14:15]
	v_add_co_u32_e32 v8, vcc, s45, v12
	v_pk_fma_f32 v[4:5], v[2:3], v[14:15], v[4:5]
	v_lshlrev_b32_e32 v14, 16, v28
	v_and_b32_e32 v15, 0xffff0000, v28
	v_cndmask_b32_e64 v18, v22, v26, s[0:1]
	v_addc_co_u32_e32 v9, vcc, 0, v13, vcc
	v_pk_mul_f32 v[14:15], v[16:17], v[14:15] op_sel_hi:[0,1]
	global_store_dwordx4 v[8:9], v[18:21], off
	v_mov_b32_e32 v22, v157
	v_lshlrev_b32_e32 v2, 16, v36
	v_mov_b32_e32 v18, v157
	v_mov_b32_e32 v19, v157
	v_mov_b32_e32 v21, v157
	v_and_b32_e32 v3, 0xffff0000, v36
	v_pk_mul_f32 v[14:15], v[42:43], v[14:15]
	v_mov_b32_dpp v18, v10 row_ror:8 row_mask:0xf bank_mask:0xf
	v_mov_b32_dpp v19, v11 row_ror:8 row_mask:0xf bank_mask:0xf
	v_mov_b32_e32 v20, v157
	v_mov_b32_dpp v21, v4 row_ror:8 row_mask:0xf bank_mask:0xf
	v_mov_b32_dpp v22, v5 row_ror:8 row_mask:0xf bank_mask:0xf
	v_pk_fma_f32 v[2:3], v[6:7], v[14:15], v[2:3]
	v_mov_b32_e32 v6, v157
	v_mov_b32_e32 v7, v157
	v_mov_b32_dpp v20, v1 row_ror:8 row_mask:0xf bank_mask:0xf
	v_mov_b32_dpp v6, v2 row_ror:8 row_mask:0xf bank_mask:0xf
	v_mov_b32_dpp v7, v3 row_ror:8 row_mask:0xf bank_mask:0xf
	v_cndmask_b32_e64 v3, v22, v3, s[0:1]
	v_cndmask_b32_e64 v2, v21, v2, s[0:1]
	v_cndmask_b32_e64 v1, v19, v1, s[0:1]
	v_cndmask_b32_e64 v0, v18, v0, s[0:1]
	s_and_b64 vcc, exec, s[26:27]
	v_cndmask_b32_e64 v7, v5, v7, s[0:1]
	v_cndmask_b32_e64 v6, v4, v6, s[0:1]
	v_cndmask_b32_e64 v5, v11, v20, s[0:1]
	v_cndmask_b32_e64 v4, v10, v17, s[0:1]
	global_store_dwordx4 v[12:13], v[0:3], off offset:128
	global_store_dwordx4 v[8:9], v[4:7], off offset:128
	s_cbranch_vccz .LBB0_1595
	s_waitcnt vmcnt(0)
	s_cmpk_gt_u32 s3, 0xff
	s_cbranch_scc1 .LBB0_1607
	s_barrier
